# non-temporal cache policy on the once-read ZS row loads of the prep phase
# baseline (speedup 1.0000x reference)
; __device__ __forceinline__ void prep_phase(const Params& p) {
;     const int lane = threadIdx.x & 63, wid = threadIdx.x >> 6, c = lane * 16;
;     const u16* ZS = (const u16*)(p.ws + O_ZS);
;     float* R = (float*)(p.ws + O_R); float* A = (float*)(p.ws + O_A); u16* V = (u16*)(p.ws + O_V); u16* Kb = (u16*)(p.ws + O_K); u16* AL = (u16*)(p.ws + O_AL); float* BON = (float*)(p.ws + O_BON);
;     for (int t0 = (blockIdx.x * 8 + wid) * 16; t0 < NTOK; t0 += gridDim.x * 8 * 16) {
;         const int tt0 = t0 & (SEQ - 1);
;         {
;             float mpk[16], mnk[16], kkc[16]; ld16f(p.mu_prev + 1024 + c, mpk); ld16f(p.mu_next + 1024 + c, mnk); ld16f(p.k_k + c, kkc);
;             const u16* zc = ZS + (size_t)t0 * 3328 + 1024 + c;
;             Z16 kp = tt0 > 0 ? ldz(zc - 3328) : zz(), kc = ldz(zc);
; #pragma unroll 2
;             for (int i = 0; i < 16; ++i) {
;                 const bool hn = (tt0 + i) < SEQ - 1; const Z16 kn = hn ? ldz(zc + (size_t)(i + 1) * 3328) : zz();
;                 float k[16], kk[16]; mix16(kp, kc, kn, mpk, mnk, k);
;                 float s2 = 0.f;
; #pragma unroll
;                 for (int q = 0; q < 16; ++q) { kk[q] = k[q] * kkc[q]; s2 += kk[q] * kk[q]; }
.Lmy_prep_item:
	s_cmpk_gt_i32 s0, 0x7fff
	s_cbranch_scc1 .Lmy_prep_end
	s_lshr_b32 s4, s0, 14
	s_mul_i32 s4, s4, 0x6800000
	s_add_u32 s4, s4, 0xb800000
	s_add_u32 s64, s56, s4
	s_addc_u32 s65, s57, 0
	s_and_b32 s65, s65, 0xffff
	s_mov_b32 s66, 0x6800000
	s_mov_b32 s67, 0x27000
	s_and_b32 s5, s0, 0x3fff
	s_add_i32 s5, s5, -1
	s_mul_i32 s5, s5, 6656
	v_lshl_add_u32 v232, v240, 5, s5
	v_lshlrev_b32_e32 v224, 6, v240
	v_add_u32_e32 v226, 0x1000, v224
	global_load_dwordx4 v[96:99], v226, s[20:21] offset:0
	global_load_dwordx4 v[100:103], v226, s[20:21] offset:16
	global_load_dwordx4 v[104:107], v226, s[20:21] offset:32
	global_load_dwordx4 v[108:111], v226, s[20:21] offset:48
	global_load_dwordx4 v[112:115], v226, s[22:23] offset:0
	global_load_dwordx4 v[116:119], v226, s[22:23] offset:16
	global_load_dwordx4 v[120:123], v226, s[22:23] offset:32
	global_load_dwordx4 v[124:127], v226, s[22:23] offset:48
	global_load_dwordx4 v[128:131], v224, s[40:41] offset:0
	global_load_dwordx4 v[132:135], v224, s[40:41] offset:16
	global_load_dwordx4 v[136:139], v224, s[40:41] offset:32
	global_load_dwordx4 v[140:143], v224, s[40:41] offset:48
	buffer_load_dwordx4 v[0:3], v232, s[64:67], 0 offen offset:2048 nt
	buffer_load_dwordx4 v[4:7], v232, s[64:67], 0 offen offset:2064 nt
	v_add_u32_e32 v232, 6656, v232
	buffer_load_dwordx4 v[12:15], v232, s[64:67], 0 offen offset:2048 nt
	buffer_load_dwordx4 v[16:19], v232, s[64:67], 0 offen offset:2064 nt
	v_add_u32_e32 v232, 6656, v232
	buffer_load_dwordx4 v[24:27], v232, s[64:67], 0 offen offset:2048 nt
	buffer_load_dwordx4 v[28:31], v232, s[64:67], 0 offen offset:2064 nt
	v_add_u32_e32 v232, 6656, v232
	buffer_load_dwordx4 v[36:39], v232, s[64:67], 0 offen offset:2048 nt
	buffer_load_dwordx4 v[40:43], v232, s[64:67], 0 offen offset:2064 nt
	v_add_u32_e32 v232, 6656, v232
	buffer_load_dwordx4 v[48:51], v232, s[64:67], 0 offen offset:2048 nt
	buffer_load_dwordx4 v[52:55], v232, s[64:67], 0 offen offset:2064 nt
	v_add_u32_e32 v232, 6656, v232
	buffer_load_dwordx4 v[60:63], v232, s[64:67], 0 offen offset:2048 nt
	buffer_load_dwordx4 v[64:67], v232, s[64:67], 0 offen offset:2064 nt
	v_add_u32_e32 v232, 6656, v232
	buffer_load_dwordx4 v[72:75], v232, s[64:67], 0 offen offset:2048 nt
	buffer_load_dwordx4 v[76:79], v232, s[64:67], 0 offen offset:2064 nt
	v_add_u32_e32 v232, 6656, v232
	buffer_load_dwordx4 v[84:87], v232, s[64:67], 0 offen offset:2048 nt
	buffer_load_dwordx4 v[88:91], v232, s[64:67], 0 offen offset:2064 nt
	v_add_u32_e32 v232, 6656, v232
	s_lshl_b32 s72, s0, 12
	s_lshl_b32 s73, s0, 11
	s_lshl_b32 s74, s0, 9
	s_lshl_b32 s75, s0, 6
	s_waitcnt vmcnt(10)
	v_lshlrev_b32_e32 v144, 16, v0
	v_and_b32_e32 v145, 0xffff0000, v0
	v_lshlrev_b32_e32 v146, 16, v1
	v_and_b32_e32 v147, 0xffff0000, v1
	v_lshlrev_b32_e32 v148, 16, v2
	v_and_b32_e32 v149, 0xffff0000, v2
	v_lshlrev_b32_e32 v150, 16, v3
	v_and_b32_e32 v151, 0xffff0000, v3
	v_lshlrev_b32_e32 v152, 16, v4
	v_and_b32_e32 v153, 0xffff0000, v4
	v_lshlrev_b32_e32 v154, 16, v5
	v_and_b32_e32 v155, 0xffff0000, v5
	v_lshlrev_b32_e32 v156, 16, v6
	v_and_b32_e32 v157, 0xffff0000, v6
	v_lshlrev_b32_e32 v158, 16, v7
	v_and_b32_e32 v159, 0xffff0000, v7
	v_lshlrev_b32_e32 v160, 16, v12
	v_and_b32_e32 v161, 0xffff0000, v12
	v_lshlrev_b32_e32 v162, 16, v13
	v_and_b32_e32 v163, 0xffff0000, v13
	v_lshlrev_b32_e32 v164, 16, v14
	v_and_b32_e32 v165, 0xffff0000, v14
	v_lshlrev_b32_e32 v166, 16, v15
	v_and_b32_e32 v167, 0xffff0000, v15
	v_lshlrev_b32_e32 v168, 16, v16
	v_and_b32_e32 v169, 0xffff0000, v16
	v_lshlrev_b32_e32 v170, 16, v17
	v_and_b32_e32 v171, 0xffff0000, v17
	v_lshlrev_b32_e32 v172, 16, v18
	v_and_b32_e32 v173, 0xffff0000, v18
	v_lshlrev_b32_e32 v174, 16, v19
	v_and_b32_e32 v175, 0xffff0000, v19
	v_lshlrev_b32_e32 v176, 16, v24
	v_and_b32_e32 v177, 0xffff0000, v24
	v_lshlrev_b32_e32 v178, 16, v25
	v_and_b32_e32 v179, 0xffff0000, v25
	v_lshlrev_b32_e32 v180, 16, v26
	v_and_b32_e32 v181, 0xffff0000, v26
	v_lshlrev_b32_e32 v182, 16, v27
	v_and_b32_e32 v183, 0xffff0000, v27
	v_lshlrev_b32_e32 v184, 16, v28
	v_and_b32_e32 v185, 0xffff0000, v28
	v_lshlrev_b32_e32 v186, 16, v29
	v_and_b32_e32 v187, 0xffff0000, v29
	v_lshlrev_b32_e32 v188, 16, v30
	v_and_b32_e32 v189, 0xffff0000, v30
	v_lshlrev_b32_e32 v190, 16, v31
	v_and_b32_e32 v191, 0xffff0000, v31
	buffer_load_dwordx4 v[0:3], v232, s[64:67], 0 offen offset:2048 nt
	buffer_load_dwordx4 v[4:7], v232, s[64:67], 0 offen offset:2064 nt
	v_add_u32_e32 v232, 6656, v232
	v_pk_add_f32 v[224:225], v[144:145], v[160:161] neg_lo:[0,1] neg_hi:[0,1]
	v_pk_add_f32 v[226:227], v[176:177], v[160:161] neg_lo:[0,1] neg_hi:[0,1]
	v_pk_fma_f32 v[192:193], v[96:97], v[224:225], v[160:161]
	v_pk_fma_f32 v[192:193], v[112:113], v[226:227], v[192:193]
	v_pk_add_f32 v[224:225], v[146:147], v[162:163] neg_lo:[0,1] neg_hi:[0,1]
	v_pk_add_f32 v[226:227], v[178:179], v[162:163] neg_lo:[0,1] neg_hi:[0,1]
	v_pk_fma_f32 v[194:195], v[98:99], v[224:225], v[162:163]
	v_pk_fma_f32 v[194:195], v[114:115], v[226:227], v[194:195]
	v_pk_add_f32 v[224:225], v[148:149], v[164:165] neg_lo:[0,1] neg_hi:[0,1]
	v_pk_add_f32 v[226:227], v[180:181], v[164:165] neg_lo:[0,1] neg_hi:[0,1]
	v_pk_fma_f32 v[196:197], v[100:101], v[224:225], v[164:165]
	v_pk_fma_f32 v[196:197], v[116:117], v[226:227], v[196:197]
	v_pk_add_f32 v[224:225], v[150:151], v[166:167] neg_lo:[0,1] neg_hi:[0,1]
	v_pk_add_f32 v[226:227], v[182:183], v[166:167] neg_lo:[0,1] neg_hi:[0,1]
	v_pk_fma_f32 v[198:199], v[102:103], v[224:225], v[166:167]
	v_pk_fma_f32 v[198:199], v[118:119], v[226:227], v[198:199]
	v_pk_add_f32 v[224:225], v[152:153], v[168:169] neg_lo:[0,1] neg_hi:[0,1]
; __device__ __forceinline__ void prep_phase(const Params& p) {
;     ...
;                 float k[16], kk[16]; mix16(kp, kc, kn, mpk, mnk, k);
;                 float s2 = 0.f;
; #pragma unroll
;                 for (int q = 0; q < 16; ++q) { kk[q] = k[q] * kkc[q]; s2 += kk[q] * kk[q]; }
;                 s2 += __shfl_xor(s2, 1); s2 += __shfl_xor(s2, 2);
;                 const float inv = -1.0f / fmaxf(sqrtf(s2), 1e-12f);
;                 const size_t o = (size_t)(t0 + i) * RW + c;
; #pragma unroll
;                 for (int j4 = 0; j4 < 4; ++j4) *(f32x4*)(A + o + j4 * 4) = (f32x4){kk[j4 * 4] * inv, kk[j4 * 4 + 1] * inv, kk[j4 * 4 + 2] * inv, kk[j4 * 4 + 3] * inv};
;                 st16bf(Kb + o, k);
;                 kp = kc; kc = kn;
	v_pk_add_f32 v[226:227], v[184:185], v[168:169] neg_lo:[0,1] neg_hi:[0,1]
	v_pk_fma_f32 v[200:201], v[104:105], v[224:225], v[168:169]
	v_pk_fma_f32 v[200:201], v[120:121], v[226:227], v[200:201]
	v_pk_add_f32 v[224:225], v[154:155], v[170:171] neg_lo:[0,1] neg_hi:[0,1]
	v_pk_add_f32 v[226:227], v[186:187], v[170:171] neg_lo:[0,1] neg_hi:[0,1]
	v_pk_fma_f32 v[202:203], v[106:107], v[224:225], v[170:171]
	v_pk_fma_f32 v[202:203], v[122:123], v[226:227], v[202:203]
	v_pk_add_f32 v[224:225], v[156:157], v[172:173] neg_lo:[0,1] neg_hi:[0,1]
	v_pk_add_f32 v[226:227], v[188:189], v[172:173] neg_lo:[0,1] neg_hi:[0,1]
	v_pk_fma_f32 v[204:205], v[108:109], v[224:225], v[172:173]
	v_pk_fma_f32 v[204:205], v[124:125], v[226:227], v[204:205]
	v_pk_add_f32 v[224:225], v[158:159], v[174:175] neg_lo:[0,1] neg_hi:[0,1]
	v_pk_add_f32 v[226:227], v[190:191], v[174:175] neg_lo:[0,1] neg_hi:[0,1]
	v_pk_fma_f32 v[206:207], v[110:111], v[224:225], v[174:175]
	v_pk_fma_f32 v[206:207], v[126:127], v[226:227], v[206:207]
	v_pk_mul_f32 v[208:209], v[192:193], v[128:129]
	v_pk_mul_f32 v[210:211], v[194:195], v[130:131]
	v_pk_mul_f32 v[212:213], v[196:197], v[132:133]
	v_pk_mul_f32 v[214:215], v[198:199], v[134:135]
	v_pk_mul_f32 v[216:217], v[200:201], v[136:137]
	v_pk_mul_f32 v[218:219], v[202:203], v[138:139]
	v_pk_mul_f32 v[220:221], v[204:205], v[140:141]
	v_pk_mul_f32 v[222:223], v[206:207], v[142:143]
	v_mul_f32_e32 v224, v208, v208
	v_fmac_f32_e32 v224, v209, v209
	v_fmac_f32_e32 v224, v210, v210
	v_fmac_f32_e32 v224, v211, v211
	v_fmac_f32_e32 v224, v212, v212
	v_fmac_f32_e32 v224, v213, v213
	v_fmac_f32_e32 v224, v214, v214
	v_fmac_f32_e32 v224, v215, v215
	v_fmac_f32_e32 v224, v216, v216
	v_fmac_f32_e32 v224, v217, v217
	v_fmac_f32_e32 v224, v218, v218
	v_fmac_f32_e32 v224, v219, v219
	v_fmac_f32_e32 v224, v220, v220
	v_fmac_f32_e32 v224, v221, v221
	v_fmac_f32_e32 v224, v222, v222
	v_fmac_f32_e32 v224, v223, v223
	s_nop 1
	v_add_f32_dpp v224, v224, v224 quad_perm:[1,0,3,2] row_mask:0xf bank_mask:0xf
	s_nop 1
	v_add_f32_dpp v224, v224, v224 quad_perm:[2,3,0,1] row_mask:0xf bank_mask:0xf
	v_sqrt_f32_e32 v224, v224
	s_nop 0
	v_max_f32_e32 v224, 0x2b8cbccc, v224
	v_rcp_f32_e32 v224, v224
	s_nop 0
	v_xor_b32_e32 v224, 0x80000000, v224
	v_mov_b32_e32 v225, v224
	v_cvt_pk_bf16_f32 v144, v192, v193
	v_cvt_pk_bf16_f32 v145, v194, v195
	v_cvt_pk_bf16_f32 v146, v196, v197
	v_cvt_pk_bf16_f32 v147, v198, v199
	v_cvt_pk_bf16_f32 v148, v200, v201
	v_cvt_pk_bf16_f32 v149, v202, v203
	v_cvt_pk_bf16_f32 v150, v204, v205
	v_cvt_pk_bf16_f32 v151, v206, v207
	v_pk_mul_f32 v[208:209], v[208:209], v[224:225]
	v_pk_mul_f32 v[210:211], v[210:211], v[224:225]
	v_pk_mul_f32 v[212:213], v[212:213], v[224:225]
	v_pk_mul_f32 v[214:215], v[214:215], v[224:225]
	v_pk_mul_f32 v[216:217], v[216:217], v[224:225]
	v_pk_mul_f32 v[218:219], v[218:219], v[224:225]
	v_pk_mul_f32 v[220:221], v[220:221], v[224:225]
	v_pk_mul_f32 v[222:223], v[222:223], v[224:225]
	buffer_store_dwordx4 v[208:211], v234, s[68:71], s72 offen offset:0
	buffer_store_dwordx4 v[212:215], v234, s[68:71], s72 offen offset:16
	buffer_store_dwordx4 v[216:219], v234, s[68:71], s72 offen offset:32
	buffer_store_dwordx4 v[220:223], v234, s[68:71], s72 offen offset:48
	buffer_store_dwordx4 v[144:147], v236, s[68:71], s73 offen offset:0
	buffer_store_dwordx4 v[148:151], v236, s[68:71], s73 offen offset:16
	s_add_u32 s72, s72, 0x1000
	s_add_u32 s73, s73, 0x800
	s_add_u32 s74, s74, 0x200
	s_add_u32 s75, s75, 0x40
	s_waitcnt vmcnt(16)
	v_lshlrev_b32_e32 v144, 16, v12
	v_and_b32_e32 v145, 0xffff0000, v12
	v_lshlrev_b32_e32 v146, 16, v13
	v_and_b32_e32 v147, 0xffff0000, v13
	v_lshlrev_b32_e32 v148, 16, v14
	v_and_b32_e32 v149, 0xffff0000, v14
	v_lshlrev_b32_e32 v150, 16, v15
	v_and_b32_e32 v151, 0xffff0000, v15
	v_lshlrev_b32_e32 v152, 16, v16
	v_and_b32_e32 v153, 0xffff0000, v16
	v_lshlrev_b32_e32 v154, 16, v17
	v_and_b32_e32 v155, 0xffff0000, v17
	v_lshlrev_b32_e32 v156, 16, v18
	v_and_b32_e32 v157, 0xffff0000, v18
	v_lshlrev_b32_e32 v158, 16, v19
	v_and_b32_e32 v159, 0xffff0000, v19
	v_lshlrev_b32_e32 v160, 16, v24
	v_and_b32_e32 v161, 0xffff0000, v24
	v_lshlrev_b32_e32 v162, 16, v25
	v_and_b32_e32 v163, 0xffff0000, v25
	v_lshlrev_b32_e32 v164, 16, v26
	v_and_b32_e32 v165, 0xffff0000, v26
	v_lshlrev_b32_e32 v166, 16, v27
	v_and_b32_e32 v167, 0xffff0000, v27
	v_lshlrev_b32_e32 v168, 16, v28
	v_and_b32_e32 v169, 0xffff0000, v28
	v_lshlrev_b32_e32 v170, 16, v29
	v_and_b32_e32 v171, 0xffff0000, v29
	v_lshlrev_b32_e32 v172, 16, v30
	v_and_b32_e32 v173, 0xffff0000, v30
	v_lshlrev_b32_e32 v174, 16, v31
	v_and_b32_e32 v175, 0xffff0000, v31
	v_lshlrev_b32_e32 v176, 16, v36
	v_and_b32_e32 v177, 0xffff0000, v36
	v_lshlrev_b32_e32 v178, 16, v37
	v_and_b32_e32 v179, 0xffff0000, v37
	v_lshlrev_b32_e32 v180, 16, v38
	v_and_b32_e32 v181, 0xffff0000, v38
	v_lshlrev_b32_e32 v182, 16, v39
	v_and_b32_e32 v183, 0xffff0000, v39
	v_lshlrev_b32_e32 v184, 16, v40
	v_and_b32_e32 v185, 0xffff0000, v40
	v_lshlrev_b32_e32 v186, 16, v41
	v_and_b32_e32 v187, 0xffff0000, v41
	v_lshlrev_b32_e32 v188, 16, v42
	v_and_b32_e32 v189, 0xffff0000, v42
	v_lshlrev_b32_e32 v190, 16, v43
	v_and_b32_e32 v191, 0xffff0000, v43
	buffer_load_dwordx4 v[12:15], v232, s[64:67], 0 offen offset:2048 nt
	buffer_load_dwordx4 v[16:19], v232, s[64:67], 0 offen offset:2064 nt
	v_add_u32_e32 v232, 6656, v232
	v_pk_add_f32 v[224:225], v[144:145], v[160:161] neg_lo:[0,1] neg_hi:[0,1]
	v_pk_add_f32 v[226:227], v[176:177], v[160:161] neg_lo:[0,1] neg_hi:[0,1]
	v_pk_fma_f32 v[192:193], v[96:97], v[224:225], v[160:161]
	v_pk_fma_f32 v[192:193], v[112:113], v[226:227], v[192:193]
; __device__ __forceinline__ void prep_phase(const Params& p) {
;     ...
;             for (int i = 0; i < 16; ++i) {
;                 const bool hn = (tt0 + i) < SEQ - 1; const Z16 kn = hn ? ldz(zc + (size_t)(i + 1) * 3328) : zz();
;                 float k[16], kk[16]; mix16(kp, kc, kn, mpk, mnk, k);
;                 float s2 = 0.f;
; #pragma unroll
;                 for (int q = 0; q < 16; ++q) { kk[q] = k[q] * kkc[q]; s2 += kk[q] * kk[q]; }
;                 s2 += __shfl_xor(s2, 1); s2 += __shfl_xor(s2, 2);
;                 const float inv = -1.0f / fmaxf(sqrtf(s2), 1e-12f);
;                 const size_t o = (size_t)(t0 + i) * RW + c;
; #pragma unroll
;                 for (int j4 = 0; j4 < 4; ++j4) *(f32x4*)(A + o + j4 * 4) = (f32x4){kk[j4 * 4] * inv, kk[j4 * 4 + 1] * inv, kk[j4 * 4 + 2] * inv, kk[j4 * 4 + 3] * inv};
;                 st16bf(Kb + o, k);
;                 kp = kc; kc = kn;
	v_pk_add_f32 v[224:225], v[146:147], v[162:163] neg_lo:[0,1] neg_hi:[0,1]
	v_pk_add_f32 v[226:227], v[178:179], v[162:163] neg_lo:[0,1] neg_hi:[0,1]
	v_pk_fma_f32 v[194:195], v[98:99], v[224:225], v[162:163]
	v_pk_fma_f32 v[194:195], v[114:115], v[226:227], v[194:195]
	v_pk_add_f32 v[224:225], v[148:149], v[164:165] neg_lo:[0,1] neg_hi:[0,1]
	v_pk_add_f32 v[226:227], v[180:181], v[164:165] neg_lo:[0,1] neg_hi:[0,1]
	v_pk_fma_f32 v[196:197], v[100:101], v[224:225], v[164:165]
	v_pk_fma_f32 v[196:197], v[116:117], v[226:227], v[196:197]
	v_pk_add_f32 v[224:225], v[150:151], v[166:167] neg_lo:[0,1] neg_hi:[0,1]
	v_pk_add_f32 v[226:227], v[182:183], v[166:167] neg_lo:[0,1] neg_hi:[0,1]
	v_pk_fma_f32 v[198:199], v[102:103], v[224:225], v[166:167]
	v_pk_fma_f32 v[198:199], v[118:119], v[226:227], v[198:199]
	v_pk_add_f32 v[224:225], v[152:153], v[168:169] neg_lo:[0,1] neg_hi:[0,1]
	v_pk_add_f32 v[226:227], v[184:185], v[168:169] neg_lo:[0,1] neg_hi:[0,1]
	v_pk_fma_f32 v[200:201], v[104:105], v[224:225], v[168:169]
	v_pk_fma_f32 v[200:201], v[120:121], v[226:227], v[200:201]
	v_pk_add_f32 v[224:225], v[154:155], v[170:171] neg_lo:[0,1] neg_hi:[0,1]
	v_pk_add_f32 v[226:227], v[186:187], v[170:171] neg_lo:[0,1] neg_hi:[0,1]
	v_pk_fma_f32 v[202:203], v[106:107], v[224:225], v[170:171]
	v_pk_fma_f32 v[202:203], v[122:123], v[226:227], v[202:203]
	v_pk_add_f32 v[224:225], v[156:157], v[172:173] neg_lo:[0,1] neg_hi:[0,1]
	v_pk_add_f32 v[226:227], v[188:189], v[172:173] neg_lo:[0,1] neg_hi:[0,1]
	v_pk_fma_f32 v[204:205], v[108:109], v[224:225], v[172:173]
	v_pk_fma_f32 v[204:205], v[124:125], v[226:227], v[204:205]
	v_pk_add_f32 v[224:225], v[158:159], v[174:175] neg_lo:[0,1] neg_hi:[0,1]
	v_pk_add_f32 v[226:227], v[190:191], v[174:175] neg_lo:[0,1] neg_hi:[0,1]
	v_pk_fma_f32 v[206:207], v[110:111], v[224:225], v[174:175]
	v_pk_fma_f32 v[206:207], v[126:127], v[226:227], v[206:207]
	v_pk_mul_f32 v[208:209], v[192:193], v[128:129]
	v_pk_mul_f32 v[210:211], v[194:195], v[130:131]
	v_pk_mul_f32 v[212:213], v[196:197], v[132:133]
	v_pk_mul_f32 v[214:215], v[198:199], v[134:135]
	v_pk_mul_f32 v[216:217], v[200:201], v[136:137]
	v_pk_mul_f32 v[218:219], v[202:203], v[138:139]
	v_pk_mul_f32 v[220:221], v[204:205], v[140:141]
	v_pk_mul_f32 v[222:223], v[206:207], v[142:143]
	v_mul_f32_e32 v224, v208, v208
	v_fmac_f32_e32 v224, v209, v209
	v_fmac_f32_e32 v224, v210, v210
	v_fmac_f32_e32 v224, v211, v211
	v_fmac_f32_e32 v224, v212, v212
	v_fmac_f32_e32 v224, v213, v213
	v_fmac_f32_e32 v224, v214, v214
	v_fmac_f32_e32 v224, v215, v215
	v_fmac_f32_e32 v224, v216, v216
	v_fmac_f32_e32 v224, v217, v217
	v_fmac_f32_e32 v224, v218, v218
	v_fmac_f32_e32 v224, v219, v219
	v_fmac_f32_e32 v224, v220, v220
	v_fmac_f32_e32 v224, v221, v221
	v_fmac_f32_e32 v224, v222, v222
	v_fmac_f32_e32 v224, v223, v223
	s_nop 1
	v_add_f32_dpp v224, v224, v224 quad_perm:[1,0,3,2] row_mask:0xf bank_mask:0xf
	s_nop 1
	v_add_f32_dpp v224, v224, v224 quad_perm:[2,3,0,1] row_mask:0xf bank_mask:0xf
	v_sqrt_f32_e32 v224, v224
	s_nop 0
	v_max_f32_e32 v224, 0x2b8cbccc, v224
	v_rcp_f32_e32 v224, v224
	s_nop 0
	v_xor_b32_e32 v224, 0x80000000, v224
	v_mov_b32_e32 v225, v224
	v_cvt_pk_bf16_f32 v144, v192, v193
	v_cvt_pk_bf16_f32 v145, v194, v195
	v_cvt_pk_bf16_f32 v146, v196, v197
	v_cvt_pk_bf16_f32 v147, v198, v199
	v_cvt_pk_bf16_f32 v148, v200, v201
	v_cvt_pk_bf16_f32 v149, v202, v203
	v_cvt_pk_bf16_f32 v150, v204, v205
	v_cvt_pk_bf16_f32 v151, v206, v207
	v_pk_mul_f32 v[208:209], v[208:209], v[224:225]
	v_pk_mul_f32 v[210:211], v[210:211], v[224:225]
	v_pk_mul_f32 v[212:213], v[212:213], v[224:225]
	v_pk_mul_f32 v[214:215], v[214:215], v[224:225]
	v_pk_mul_f32 v[216:217], v[216:217], v[224:225]
	v_pk_mul_f32 v[218:219], v[218:219], v[224:225]
	v_pk_mul_f32 v[220:221], v[220:221], v[224:225]
	v_pk_mul_f32 v[222:223], v[222:223], v[224:225]
	buffer_store_dwordx4 v[208:211], v234, s[68:71], s72 offen offset:0
	buffer_store_dwordx4 v[212:215], v234, s[68:71], s72 offen offset:16
	buffer_store_dwordx4 v[216:219], v234, s[68:71], s72 offen offset:32
	buffer_store_dwordx4 v[220:223], v234, s[68:71], s72 offen offset:48
	buffer_store_dwordx4 v[144:147], v236, s[68:71], s73 offen offset:0
	buffer_store_dwordx4 v[148:151], v236, s[68:71], s73 offen offset:16
	s_add_u32 s72, s72, 0x1000
	s_add_u32 s73, s73, 0x800
	s_add_u32 s74, s74, 0x200
	s_add_u32 s75, s75, 0x40
	s_waitcnt vmcnt(22)
; __device__ __forceinline__ void prep_phase(const Params& p) {
;     ...
;             for (int i = 0; i < 16; ++i) {
;                 const bool hn = (tt0 + i) < SEQ - 1; const Z16 kn = hn ? ldz(zc + (size_t)(i + 1) * 3328) : zz();
;                 float k[16], kk[16]; mix16(kp, kc, kn, mpk, mnk, k);
;                 float s2 = 0.f;
; #pragma unroll
;                 for (int q = 0; q < 16; ++q) { kk[q] = k[q] * kkc[q]; s2 += kk[q] * kk[q]; }
;                 s2 += __shfl_xor(s2, 1); s2 += __shfl_xor(s2, 2);
;                 const float inv = -1.0f / fmaxf(sqrtf(s2), 1e-12f);
;                 const size_t o = (size_t)(t0 + i) * RW + c;
; #pragma unroll
;                 for (int j4 = 0; j4 < 4; ++j4) *(f32x4*)(A + o + j4 * 4) = (f32x4){kk[j4 * 4] * inv, kk[j4 * 4 + 1] * inv, kk[j4 * 4 + 2] * inv, kk[j4 * 4 + 3] * inv};
;                 st16bf(Kb + o, k);
;                 kp = kc; kc = kn;
	v_lshlrev_b32_e32 v144, 16, v24
	v_and_b32_e32 v145, 0xffff0000, v24
	v_lshlrev_b32_e32 v146, 16, v25
	v_and_b32_e32 v147, 0xffff0000, v25
	v_lshlrev_b32_e32 v148, 16, v26
	v_and_b32_e32 v149, 0xffff0000, v26
	v_lshlrev_b32_e32 v150, 16, v27
	v_and_b32_e32 v151, 0xffff0000, v27
	v_lshlrev_b32_e32 v152, 16, v28
	v_and_b32_e32 v153, 0xffff0000, v28
	v_lshlrev_b32_e32 v154, 16, v29
	v_and_b32_e32 v155, 0xffff0000, v29
	v_lshlrev_b32_e32 v156, 16, v30
	v_and_b32_e32 v157, 0xffff0000, v30
	v_lshlrev_b32_e32 v158, 16, v31
	v_and_b32_e32 v159, 0xffff0000, v31
	v_lshlrev_b32_e32 v160, 16, v36
	v_and_b32_e32 v161, 0xffff0000, v36
	v_lshlrev_b32_e32 v162, 16, v37
	v_and_b32_e32 v163, 0xffff0000, v37
	v_lshlrev_b32_e32 v164, 16, v38
	v_and_b32_e32 v165, 0xffff0000, v38
	v_lshlrev_b32_e32 v166, 16, v39
	v_and_b32_e32 v167, 0xffff0000, v39
	v_lshlrev_b32_e32 v168, 16, v40
	v_and_b32_e32 v169, 0xffff0000, v40
	v_lshlrev_b32_e32 v170, 16, v41
	v_and_b32_e32 v171, 0xffff0000, v41
	v_lshlrev_b32_e32 v172, 16, v42
	v_and_b32_e32 v173, 0xffff0000, v42
	v_lshlrev_b32_e32 v174, 16, v43
	v_and_b32_e32 v175, 0xffff0000, v43
	v_lshlrev_b32_e32 v176, 16, v48
	v_and_b32_e32 v177, 0xffff0000, v48
	v_lshlrev_b32_e32 v178, 16, v49
	v_and_b32_e32 v179, 0xffff0000, v49
	v_lshlrev_b32_e32 v180, 16, v50
	v_and_b32_e32 v181, 0xffff0000, v50
	v_lshlrev_b32_e32 v182, 16, v51
	v_and_b32_e32 v183, 0xffff0000, v51
	v_lshlrev_b32_e32 v184, 16, v52
	v_and_b32_e32 v185, 0xffff0000, v52
	v_lshlrev_b32_e32 v186, 16, v53
	v_and_b32_e32 v187, 0xffff0000, v53
	v_lshlrev_b32_e32 v188, 16, v54
	v_and_b32_e32 v189, 0xffff0000, v54
	v_lshlrev_b32_e32 v190, 16, v55
	v_and_b32_e32 v191, 0xffff0000, v55
	buffer_load_dwordx4 v[24:27], v232, s[64:67], 0 offen offset:2048 nt
	buffer_load_dwordx4 v[28:31], v232, s[64:67], 0 offen offset:2064 nt
	v_add_u32_e32 v232, 6656, v232
	v_pk_add_f32 v[224:225], v[144:145], v[160:161] neg_lo:[0,1] neg_hi:[0,1]
	v_pk_add_f32 v[226:227], v[176:177], v[160:161] neg_lo:[0,1] neg_hi:[0,1]
	v_pk_fma_f32 v[192:193], v[96:97], v[224:225], v[160:161]
	v_pk_fma_f32 v[192:193], v[112:113], v[226:227], v[192:193]
	v_pk_add_f32 v[224:225], v[146:147], v[162:163] neg_lo:[0,1] neg_hi:[0,1]
	v_pk_add_f32 v[226:227], v[178:179], v[162:163] neg_lo:[0,1] neg_hi:[0,1]
	v_pk_fma_f32 v[194:195], v[98:99], v[224:225], v[162:163]
	v_pk_fma_f32 v[194:195], v[114:115], v[226:227], v[194:195]
	v_pk_add_f32 v[224:225], v[148:149], v[164:165] neg_lo:[0,1] neg_hi:[0,1]
	v_pk_add_f32 v[226:227], v[180:181], v[164:165] neg_lo:[0,1] neg_hi:[0,1]
	v_pk_fma_f32 v[196:197], v[100:101], v[224:225], v[164:165]
	v_pk_fma_f32 v[196:197], v[116:117], v[226:227], v[196:197]
	v_pk_add_f32 v[224:225], v[150:151], v[166:167] neg_lo:[0,1] neg_hi:[0,1]
	v_pk_add_f32 v[226:227], v[182:183], v[166:167] neg_lo:[0,1] neg_hi:[0,1]
	v_pk_fma_f32 v[198:199], v[102:103], v[224:225], v[166:167]
	v_pk_fma_f32 v[198:199], v[118:119], v[226:227], v[198:199]
	v_pk_add_f32 v[224:225], v[152:153], v[168:169] neg_lo:[0,1] neg_hi:[0,1]
	v_pk_add_f32 v[226:227], v[184:185], v[168:169] neg_lo:[0,1] neg_hi:[0,1]
	v_pk_fma_f32 v[200:201], v[104:105], v[224:225], v[168:169]
	v_pk_fma_f32 v[200:201], v[120:121], v[226:227], v[200:201]
	v_pk_add_f32 v[224:225], v[154:155], v[170:171] neg_lo:[0,1] neg_hi:[0,1]
	v_pk_add_f32 v[226:227], v[186:187], v[170:171] neg_lo:[0,1] neg_hi:[0,1]
	v_pk_fma_f32 v[202:203], v[106:107], v[224:225], v[170:171]
	v_pk_fma_f32 v[202:203], v[122:123], v[226:227], v[202:203]
	v_pk_add_f32 v[224:225], v[156:157], v[172:173] neg_lo:[0,1] neg_hi:[0,1]
	v_pk_add_f32 v[226:227], v[188:189], v[172:173] neg_lo:[0,1] neg_hi:[0,1]
	v_pk_fma_f32 v[204:205], v[108:109], v[224:225], v[172:173]
	v_pk_fma_f32 v[204:205], v[124:125], v[226:227], v[204:205]
	v_pk_add_f32 v[224:225], v[158:159], v[174:175] neg_lo:[0,1] neg_hi:[0,1]
	v_pk_add_f32 v[226:227], v[190:191], v[174:175] neg_lo:[0,1] neg_hi:[0,1]
	v_pk_fma_f32 v[206:207], v[110:111], v[224:225], v[174:175]
	v_pk_fma_f32 v[206:207], v[126:127], v[226:227], v[206:207]
	v_pk_mul_f32 v[208:209], v[192:193], v[128:129]
	v_pk_mul_f32 v[210:211], v[194:195], v[130:131]
	v_pk_mul_f32 v[212:213], v[196:197], v[132:133]
	v_pk_mul_f32 v[214:215], v[198:199], v[134:135]
	v_pk_mul_f32 v[216:217], v[200:201], v[136:137]
	v_pk_mul_f32 v[218:219], v[202:203], v[138:139]
	v_pk_mul_f32 v[220:221], v[204:205], v[140:141]
	v_pk_mul_f32 v[222:223], v[206:207], v[142:143]
	v_mul_f32_e32 v224, v208, v208
	v_fmac_f32_e32 v224, v209, v209
	v_fmac_f32_e32 v224, v210, v210
	v_fmac_f32_e32 v224, v211, v211
	v_fmac_f32_e32 v224, v212, v212
	v_fmac_f32_e32 v224, v213, v213
	v_fmac_f32_e32 v224, v214, v214
	v_fmac_f32_e32 v224, v215, v215
	v_fmac_f32_e32 v224, v216, v216
	v_fmac_f32_e32 v224, v217, v217
	v_fmac_f32_e32 v224, v218, v218
	v_fmac_f32_e32 v224, v219, v219
	v_fmac_f32_e32 v224, v220, v220
	v_fmac_f32_e32 v224, v221, v221
	v_fmac_f32_e32 v224, v222, v222
	v_fmac_f32_e32 v224, v223, v223
	s_nop 1
	v_add_f32_dpp v224, v224, v224 quad_perm:[1,0,3,2] row_mask:0xf bank_mask:0xf
	s_nop 1
	v_add_f32_dpp v224, v224, v224 quad_perm:[2,3,0,1] row_mask:0xf bank_mask:0xf
	v_sqrt_f32_e32 v224, v224
	s_nop 0
	v_max_f32_e32 v224, 0x2b8cbccc, v224
	v_rcp_f32_e32 v224, v224
	s_nop 0
	v_xor_b32_e32 v224, 0x80000000, v224
	v_mov_b32_e32 v225, v224
	v_cvt_pk_bf16_f32 v144, v192, v193
	v_cvt_pk_bf16_f32 v145, v194, v195
	v_cvt_pk_bf16_f32 v146, v196, v197
	v_cvt_pk_bf16_f32 v147, v198, v199
	v_cvt_pk_bf16_f32 v148, v200, v201
	v_cvt_pk_bf16_f32 v149, v202, v203
	v_cvt_pk_bf16_f32 v150, v204, v205
	v_cvt_pk_bf16_f32 v151, v206, v207
	v_pk_mul_f32 v[208:209], v[208:209], v[224:225]
	v_pk_mul_f32 v[210:211], v[210:211], v[224:225]
	v_pk_mul_f32 v[212:213], v[212:213], v[224:225]
	v_pk_mul_f32 v[214:215], v[214:215], v[224:225]
	v_pk_mul_f32 v[216:217], v[216:217], v[224:225]
	v_pk_mul_f32 v[218:219], v[218:219], v[224:225]
	v_pk_mul_f32 v[220:221], v[220:221], v[224:225]
	v_pk_mul_f32 v[222:223], v[222:223], v[224:225]
	buffer_store_dwordx4 v[208:211], v234, s[68:71], s72 offen offset:0
	buffer_store_dwordx4 v[212:215], v234, s[68:71], s72 offen offset:16
	buffer_store_dwordx4 v[216:219], v234, s[68:71], s72 offen offset:32
	buffer_store_dwordx4 v[220:223], v234, s[68:71], s72 offen offset:48
	buffer_store_dwordx4 v[144:147], v236, s[68:71], s73 offen offset:0
	buffer_store_dwordx4 v[148:151], v236, s[68:71], s73 offen offset:16
	s_add_u32 s72, s72, 0x1000
	s_add_u32 s73, s73, 0x800
	s_add_u32 s74, s74, 0x200
	s_add_u32 s75, s75, 0x40
	s_waitcnt vmcnt(28)
; __device__ __forceinline__ void prep_phase(const Params& p) {
;     ...
;             for (int i = 0; i < 16; ++i) {
;                 const bool hn = (tt0 + i) < SEQ - 1; const Z16 kn = hn ? ldz(zc + (size_t)(i + 1) * 3328) : zz();
;                 float k[16], kk[16]; mix16(kp, kc, kn, mpk, mnk, k);
;                 float s2 = 0.f;
; #pragma unroll
;                 for (int q = 0; q < 16; ++q) { kk[q] = k[q] * kkc[q]; s2 += kk[q] * kk[q]; }
;                 s2 += __shfl_xor(s2, 1); s2 += __shfl_xor(s2, 2);
;                 const float inv = -1.0f / fmaxf(sqrtf(s2), 1e-12f);
;                 const size_t o = (size_t)(t0 + i) * RW + c;
; #pragma unroll
;                 for (int j4 = 0; j4 < 4; ++j4) *(f32x4*)(A + o + j4 * 4) = (f32x4){kk[j4 * 4] * inv, kk[j4 * 4 + 1] * inv, kk[j4 * 4 + 2] * inv, kk[j4 * 4 + 3] * inv};
;                 st16bf(Kb + o, k);
;                 kp = kc; kc = kn;
	v_lshlrev_b32_e32 v144, 16, v36
	v_and_b32_e32 v145, 0xffff0000, v36
	v_lshlrev_b32_e32 v146, 16, v37
	v_and_b32_e32 v147, 0xffff0000, v37
	v_lshlrev_b32_e32 v148, 16, v38
	v_and_b32_e32 v149, 0xffff0000, v38
	v_lshlrev_b32_e32 v150, 16, v39
	v_and_b32_e32 v151, 0xffff0000, v39
	v_lshlrev_b32_e32 v152, 16, v40
	v_and_b32_e32 v153, 0xffff0000, v40
	v_lshlrev_b32_e32 v154, 16, v41
	v_and_b32_e32 v155, 0xffff0000, v41
	v_lshlrev_b32_e32 v156, 16, v42
	v_and_b32_e32 v157, 0xffff0000, v42
	v_lshlrev_b32_e32 v158, 16, v43
	v_and_b32_e32 v159, 0xffff0000, v43
	v_lshlrev_b32_e32 v160, 16, v48
	v_and_b32_e32 v161, 0xffff0000, v48
	v_lshlrev_b32_e32 v162, 16, v49
	v_and_b32_e32 v163, 0xffff0000, v49
	v_lshlrev_b32_e32 v164, 16, v50
	v_and_b32_e32 v165, 0xffff0000, v50
	v_lshlrev_b32_e32 v166, 16, v51
	v_and_b32_e32 v167, 0xffff0000, v51
	v_lshlrev_b32_e32 v168, 16, v52
	v_and_b32_e32 v169, 0xffff0000, v52
	v_lshlrev_b32_e32 v170, 16, v53
	v_and_b32_e32 v171, 0xffff0000, v53
	v_lshlrev_b32_e32 v172, 16, v54
	v_and_b32_e32 v173, 0xffff0000, v54
	v_lshlrev_b32_e32 v174, 16, v55
	v_and_b32_e32 v175, 0xffff0000, v55
	v_lshlrev_b32_e32 v176, 16, v60
	v_and_b32_e32 v177, 0xffff0000, v60
	v_lshlrev_b32_e32 v178, 16, v61
	v_and_b32_e32 v179, 0xffff0000, v61
	v_lshlrev_b32_e32 v180, 16, v62
	v_and_b32_e32 v181, 0xffff0000, v62
	v_lshlrev_b32_e32 v182, 16, v63
	v_and_b32_e32 v183, 0xffff0000, v63
	v_lshlrev_b32_e32 v184, 16, v64
	v_and_b32_e32 v185, 0xffff0000, v64
	v_lshlrev_b32_e32 v186, 16, v65
	v_and_b32_e32 v187, 0xffff0000, v65
	v_lshlrev_b32_e32 v188, 16, v66
	v_and_b32_e32 v189, 0xffff0000, v66
	v_lshlrev_b32_e32 v190, 16, v67
	v_and_b32_e32 v191, 0xffff0000, v67
	buffer_load_dwordx4 v[36:39], v232, s[64:67], 0 offen offset:2048 nt
	buffer_load_dwordx4 v[40:43], v232, s[64:67], 0 offen offset:2064 nt
	v_add_u32_e32 v232, 6656, v232
	v_pk_add_f32 v[224:225], v[144:145], v[160:161] neg_lo:[0,1] neg_hi:[0,1]
	v_pk_add_f32 v[226:227], v[176:177], v[160:161] neg_lo:[0,1] neg_hi:[0,1]
	v_pk_fma_f32 v[192:193], v[96:97], v[224:225], v[160:161]
	v_pk_fma_f32 v[192:193], v[112:113], v[226:227], v[192:193]
	v_pk_add_f32 v[224:225], v[146:147], v[162:163] neg_lo:[0,1] neg_hi:[0,1]
	v_pk_add_f32 v[226:227], v[178:179], v[162:163] neg_lo:[0,1] neg_hi:[0,1]
	v_pk_fma_f32 v[194:195], v[98:99], v[224:225], v[162:163]
	v_pk_fma_f32 v[194:195], v[114:115], v[226:227], v[194:195]
	v_pk_add_f32 v[224:225], v[148:149], v[164:165] neg_lo:[0,1] neg_hi:[0,1]
	v_pk_add_f32 v[226:227], v[180:181], v[164:165] neg_lo:[0,1] neg_hi:[0,1]
	v_pk_fma_f32 v[196:197], v[100:101], v[224:225], v[164:165]
	v_pk_fma_f32 v[196:197], v[116:117], v[226:227], v[196:197]
	v_pk_add_f32 v[224:225], v[150:151], v[166:167] neg_lo:[0,1] neg_hi:[0,1]
	v_pk_add_f32 v[226:227], v[182:183], v[166:167] neg_lo:[0,1] neg_hi:[0,1]
	v_pk_fma_f32 v[198:199], v[102:103], v[224:225], v[166:167]
	v_pk_fma_f32 v[198:199], v[118:119], v[226:227], v[198:199]
	v_pk_add_f32 v[224:225], v[152:153], v[168:169] neg_lo:[0,1] neg_hi:[0,1]
	v_pk_add_f32 v[226:227], v[184:185], v[168:169] neg_lo:[0,1] neg_hi:[0,1]
	v_pk_fma_f32 v[200:201], v[104:105], v[224:225], v[168:169]
	v_pk_fma_f32 v[200:201], v[120:121], v[226:227], v[200:201]
	v_pk_add_f32 v[224:225], v[154:155], v[170:171] neg_lo:[0,1] neg_hi:[0,1]
	v_pk_add_f32 v[226:227], v[186:187], v[170:171] neg_lo:[0,1] neg_hi:[0,1]
	v_pk_fma_f32 v[202:203], v[106:107], v[224:225], v[170:171]
	v_pk_fma_f32 v[202:203], v[122:123], v[226:227], v[202:203]
	v_pk_add_f32 v[224:225], v[156:157], v[172:173] neg_lo:[0,1] neg_hi:[0,1]
	v_pk_add_f32 v[226:227], v[188:189], v[172:173] neg_lo:[0,1] neg_hi:[0,1]
	v_pk_fma_f32 v[204:205], v[108:109], v[224:225], v[172:173]
	v_pk_fma_f32 v[204:205], v[124:125], v[226:227], v[204:205]
	v_pk_add_f32 v[224:225], v[158:159], v[174:175] neg_lo:[0,1] neg_hi:[0,1]
	v_pk_add_f32 v[226:227], v[190:191], v[174:175] neg_lo:[0,1] neg_hi:[0,1]
	v_pk_fma_f32 v[206:207], v[110:111], v[224:225], v[174:175]
	v_pk_fma_f32 v[206:207], v[126:127], v[226:227], v[206:207]
	v_pk_mul_f32 v[208:209], v[192:193], v[128:129]
	v_pk_mul_f32 v[210:211], v[194:195], v[130:131]
	v_pk_mul_f32 v[212:213], v[196:197], v[132:133]
	v_pk_mul_f32 v[214:215], v[198:199], v[134:135]
	v_pk_mul_f32 v[216:217], v[200:201], v[136:137]
	v_pk_mul_f32 v[218:219], v[202:203], v[138:139]
	v_pk_mul_f32 v[220:221], v[204:205], v[140:141]
	v_pk_mul_f32 v[222:223], v[206:207], v[142:143]
	v_mul_f32_e32 v224, v208, v208
	v_fmac_f32_e32 v224, v209, v209
	v_fmac_f32_e32 v224, v210, v210
	v_fmac_f32_e32 v224, v211, v211
	v_fmac_f32_e32 v224, v212, v212
	v_fmac_f32_e32 v224, v213, v213
	v_fmac_f32_e32 v224, v214, v214
	v_fmac_f32_e32 v224, v215, v215
	v_fmac_f32_e32 v224, v216, v216
	v_fmac_f32_e32 v224, v217, v217
	v_fmac_f32_e32 v224, v218, v218
	v_fmac_f32_e32 v224, v219, v219
	v_fmac_f32_e32 v224, v220, v220
	v_fmac_f32_e32 v224, v221, v221
	v_fmac_f32_e32 v224, v222, v222
	v_fmac_f32_e32 v224, v223, v223
	s_nop 1
	v_add_f32_dpp v224, v224, v224 quad_perm:[1,0,3,2] row_mask:0xf bank_mask:0xf
	s_nop 1
	v_add_f32_dpp v224, v224, v224 quad_perm:[2,3,0,1] row_mask:0xf bank_mask:0xf
	v_sqrt_f32_e32 v224, v224
	s_nop 0
	v_max_f32_e32 v224, 0x2b8cbccc, v224
	v_rcp_f32_e32 v224, v224
	s_nop 0
	v_xor_b32_e32 v224, 0x80000000, v224
	v_mov_b32_e32 v225, v224
	v_cvt_pk_bf16_f32 v144, v192, v193
	v_cvt_pk_bf16_f32 v145, v194, v195
	v_cvt_pk_bf16_f32 v146, v196, v197
	v_cvt_pk_bf16_f32 v147, v198, v199
	v_cvt_pk_bf16_f32 v148, v200, v201
	v_cvt_pk_bf16_f32 v149, v202, v203
	v_cvt_pk_bf16_f32 v150, v204, v205
	v_cvt_pk_bf16_f32 v151, v206, v207
	v_pk_mul_f32 v[208:209], v[208:209], v[224:225]
	v_pk_mul_f32 v[210:211], v[210:211], v[224:225]
	v_pk_mul_f32 v[212:213], v[212:213], v[224:225]
	v_pk_mul_f32 v[214:215], v[214:215], v[224:225]
	v_pk_mul_f32 v[216:217], v[216:217], v[224:225]
	v_pk_mul_f32 v[218:219], v[218:219], v[224:225]
	v_pk_mul_f32 v[220:221], v[220:221], v[224:225]
	v_pk_mul_f32 v[222:223], v[222:223], v[224:225]
	buffer_store_dwordx4 v[208:211], v234, s[68:71], s72 offen offset:0
	buffer_store_dwordx4 v[212:215], v234, s[68:71], s72 offen offset:16
	buffer_store_dwordx4 v[216:219], v234, s[68:71], s72 offen offset:32
	buffer_store_dwordx4 v[220:223], v234, s[68:71], s72 offen offset:48
	buffer_store_dwordx4 v[144:147], v236, s[68:71], s73 offen offset:0
	buffer_store_dwordx4 v[148:151], v236, s[68:71], s73 offen offset:16
	s_add_u32 s72, s72, 0x1000
	s_add_u32 s73, s73, 0x800
	s_add_u32 s74, s74, 0x200
	s_add_u32 s75, s75, 0x40
	s_waitcnt vmcnt(34)
; __device__ __forceinline__ void prep_phase(const Params& p) {
;     ...
;             for (int i = 0; i < 16; ++i) {
;                 const bool hn = (tt0 + i) < SEQ - 1; const Z16 kn = hn ? ldz(zc + (size_t)(i + 1) * 3328) : zz();
;                 float k[16], kk[16]; mix16(kp, kc, kn, mpk, mnk, k);
;                 float s2 = 0.f;
; #pragma unroll
;                 for (int q = 0; q < 16; ++q) { kk[q] = k[q] * kkc[q]; s2 += kk[q] * kk[q]; }
;                 s2 += __shfl_xor(s2, 1); s2 += __shfl_xor(s2, 2);
;                 const float inv = -1.0f / fmaxf(sqrtf(s2), 1e-12f);
;                 const size_t o = (size_t)(t0 + i) * RW + c;
; #pragma unroll
;                 for (int j4 = 0; j4 < 4; ++j4) *(f32x4*)(A + o + j4 * 4) = (f32x4){kk[j4 * 4] * inv, kk[j4 * 4 + 1] * inv, kk[j4 * 4 + 2] * inv, kk[j4 * 4 + 3] * inv};
;                 st16bf(Kb + o, k);
;                 kp = kc; kc = kn;
	v_lshlrev_b32_e32 v144, 16, v48
	v_and_b32_e32 v145, 0xffff0000, v48
	v_lshlrev_b32_e32 v146, 16, v49
	v_and_b32_e32 v147, 0xffff0000, v49
	v_lshlrev_b32_e32 v148, 16, v50
	v_and_b32_e32 v149, 0xffff0000, v50
	v_lshlrev_b32_e32 v150, 16, v51
	v_and_b32_e32 v151, 0xffff0000, v51
	v_lshlrev_b32_e32 v152, 16, v52
	v_and_b32_e32 v153, 0xffff0000, v52
	v_lshlrev_b32_e32 v154, 16, v53
	v_and_b32_e32 v155, 0xffff0000, v53
	v_lshlrev_b32_e32 v156, 16, v54
	v_and_b32_e32 v157, 0xffff0000, v54
	v_lshlrev_b32_e32 v158, 16, v55
	v_and_b32_e32 v159, 0xffff0000, v55
	v_lshlrev_b32_e32 v160, 16, v60
	v_and_b32_e32 v161, 0xffff0000, v60
	v_lshlrev_b32_e32 v162, 16, v61
	v_and_b32_e32 v163, 0xffff0000, v61
	v_lshlrev_b32_e32 v164, 16, v62
	v_and_b32_e32 v165, 0xffff0000, v62
	v_lshlrev_b32_e32 v166, 16, v63
	v_and_b32_e32 v167, 0xffff0000, v63
	v_lshlrev_b32_e32 v168, 16, v64
	v_and_b32_e32 v169, 0xffff0000, v64
	v_lshlrev_b32_e32 v170, 16, v65
	v_and_b32_e32 v171, 0xffff0000, v65
	v_lshlrev_b32_e32 v172, 16, v66
	v_and_b32_e32 v173, 0xffff0000, v66
	v_lshlrev_b32_e32 v174, 16, v67
	v_and_b32_e32 v175, 0xffff0000, v67
	v_lshlrev_b32_e32 v176, 16, v72
	v_and_b32_e32 v177, 0xffff0000, v72
	v_lshlrev_b32_e32 v178, 16, v73
	v_and_b32_e32 v179, 0xffff0000, v73
	v_lshlrev_b32_e32 v180, 16, v74
	v_and_b32_e32 v181, 0xffff0000, v74
	v_lshlrev_b32_e32 v182, 16, v75
	v_and_b32_e32 v183, 0xffff0000, v75
	v_lshlrev_b32_e32 v184, 16, v76
	v_and_b32_e32 v185, 0xffff0000, v76
	v_lshlrev_b32_e32 v186, 16, v77
	v_and_b32_e32 v187, 0xffff0000, v77
	v_lshlrev_b32_e32 v188, 16, v78
	v_and_b32_e32 v189, 0xffff0000, v78
	v_lshlrev_b32_e32 v190, 16, v79
	v_and_b32_e32 v191, 0xffff0000, v79
	buffer_load_dwordx4 v[48:51], v232, s[64:67], 0 offen offset:2048 nt
	buffer_load_dwordx4 v[52:55], v232, s[64:67], 0 offen offset:2064 nt
	v_add_u32_e32 v232, 6656, v232
	v_pk_add_f32 v[224:225], v[144:145], v[160:161] neg_lo:[0,1] neg_hi:[0,1]
	v_pk_add_f32 v[226:227], v[176:177], v[160:161] neg_lo:[0,1] neg_hi:[0,1]
	v_pk_fma_f32 v[192:193], v[96:97], v[224:225], v[160:161]
	v_pk_fma_f32 v[192:193], v[112:113], v[226:227], v[192:193]
	v_pk_add_f32 v[224:225], v[146:147], v[162:163] neg_lo:[0,1] neg_hi:[0,1]
	v_pk_add_f32 v[226:227], v[178:179], v[162:163] neg_lo:[0,1] neg_hi:[0,1]
	v_pk_fma_f32 v[194:195], v[98:99], v[224:225], v[162:163]
	v_pk_fma_f32 v[194:195], v[114:115], v[226:227], v[194:195]
	v_pk_add_f32 v[224:225], v[148:149], v[164:165] neg_lo:[0,1] neg_hi:[0,1]
	v_pk_add_f32 v[226:227], v[180:181], v[164:165] neg_lo:[0,1] neg_hi:[0,1]
	v_pk_fma_f32 v[196:197], v[100:101], v[224:225], v[164:165]
	v_pk_fma_f32 v[196:197], v[116:117], v[226:227], v[196:197]
	v_pk_add_f32 v[224:225], v[150:151], v[166:167] neg_lo:[0,1] neg_hi:[0,1]
	v_pk_add_f32 v[226:227], v[182:183], v[166:167] neg_lo:[0,1] neg_hi:[0,1]
	v_pk_fma_f32 v[198:199], v[102:103], v[224:225], v[166:167]
	v_pk_fma_f32 v[198:199], v[118:119], v[226:227], v[198:199]
	v_pk_add_f32 v[224:225], v[152:153], v[168:169] neg_lo:[0,1] neg_hi:[0,1]
	v_pk_add_f32 v[226:227], v[184:185], v[168:169] neg_lo:[0,1] neg_hi:[0,1]
	v_pk_fma_f32 v[200:201], v[104:105], v[224:225], v[168:169]
	v_pk_fma_f32 v[200:201], v[120:121], v[226:227], v[200:201]
	v_pk_add_f32 v[224:225], v[154:155], v[170:171] neg_lo:[0,1] neg_hi:[0,1]
	v_pk_add_f32 v[226:227], v[186:187], v[170:171] neg_lo:[0,1] neg_hi:[0,1]
	v_pk_fma_f32 v[202:203], v[106:107], v[224:225], v[170:171]
	v_pk_fma_f32 v[202:203], v[122:123], v[226:227], v[202:203]
	v_pk_add_f32 v[224:225], v[156:157], v[172:173] neg_lo:[0,1] neg_hi:[0,1]
	v_pk_add_f32 v[226:227], v[188:189], v[172:173] neg_lo:[0,1] neg_hi:[0,1]
	v_pk_fma_f32 v[204:205], v[108:109], v[224:225], v[172:173]
	v_pk_fma_f32 v[204:205], v[124:125], v[226:227], v[204:205]
	v_pk_add_f32 v[224:225], v[158:159], v[174:175] neg_lo:[0,1] neg_hi:[0,1]
	v_pk_add_f32 v[226:227], v[190:191], v[174:175] neg_lo:[0,1] neg_hi:[0,1]
	v_pk_fma_f32 v[206:207], v[110:111], v[224:225], v[174:175]
	v_pk_fma_f32 v[206:207], v[126:127], v[226:227], v[206:207]
	v_pk_mul_f32 v[208:209], v[192:193], v[128:129]
	v_pk_mul_f32 v[210:211], v[194:195], v[130:131]
	v_pk_mul_f32 v[212:213], v[196:197], v[132:133]
	v_pk_mul_f32 v[214:215], v[198:199], v[134:135]
	v_pk_mul_f32 v[216:217], v[200:201], v[136:137]
	v_pk_mul_f32 v[218:219], v[202:203], v[138:139]
	v_pk_mul_f32 v[220:221], v[204:205], v[140:141]
	v_pk_mul_f32 v[222:223], v[206:207], v[142:143]
	v_mul_f32_e32 v224, v208, v208
	v_fmac_f32_e32 v224, v209, v209
	v_fmac_f32_e32 v224, v210, v210
	v_fmac_f32_e32 v224, v211, v211
	v_fmac_f32_e32 v224, v212, v212
	v_fmac_f32_e32 v224, v213, v213
	v_fmac_f32_e32 v224, v214, v214
	v_fmac_f32_e32 v224, v215, v215
	v_fmac_f32_e32 v224, v216, v216
	v_fmac_f32_e32 v224, v217, v217
	v_fmac_f32_e32 v224, v218, v218
	v_fmac_f32_e32 v224, v219, v219
	v_fmac_f32_e32 v224, v220, v220
	v_fmac_f32_e32 v224, v221, v221
	v_fmac_f32_e32 v224, v222, v222
	v_fmac_f32_e32 v224, v223, v223
	s_nop 1
	v_add_f32_dpp v224, v224, v224 quad_perm:[1,0,3,2] row_mask:0xf bank_mask:0xf
	s_nop 1
	v_add_f32_dpp v224, v224, v224 quad_perm:[2,3,0,1] row_mask:0xf bank_mask:0xf
	v_sqrt_f32_e32 v224, v224
	s_nop 0
	v_max_f32_e32 v224, 0x2b8cbccc, v224
	v_rcp_f32_e32 v224, v224
	s_nop 0
	v_xor_b32_e32 v224, 0x80000000, v224
	v_mov_b32_e32 v225, v224
	v_cvt_pk_bf16_f32 v144, v192, v193
	v_cvt_pk_bf16_f32 v145, v194, v195
	v_cvt_pk_bf16_f32 v146, v196, v197
	v_cvt_pk_bf16_f32 v147, v198, v199
	v_cvt_pk_bf16_f32 v148, v200, v201
	v_cvt_pk_bf16_f32 v149, v202, v203
	v_cvt_pk_bf16_f32 v150, v204, v205
	v_cvt_pk_bf16_f32 v151, v206, v207
	v_pk_mul_f32 v[208:209], v[208:209], v[224:225]
	v_pk_mul_f32 v[210:211], v[210:211], v[224:225]
	v_pk_mul_f32 v[212:213], v[212:213], v[224:225]
	v_pk_mul_f32 v[214:215], v[214:215], v[224:225]
	v_pk_mul_f32 v[216:217], v[216:217], v[224:225]
	v_pk_mul_f32 v[218:219], v[218:219], v[224:225]
	v_pk_mul_f32 v[220:221], v[220:221], v[224:225]
	v_pk_mul_f32 v[222:223], v[222:223], v[224:225]
	buffer_store_dwordx4 v[208:211], v234, s[68:71], s72 offen offset:0
	buffer_store_dwordx4 v[212:215], v234, s[68:71], s72 offen offset:16
	buffer_store_dwordx4 v[216:219], v234, s[68:71], s72 offen offset:32
	buffer_store_dwordx4 v[220:223], v234, s[68:71], s72 offen offset:48
	buffer_store_dwordx4 v[144:147], v236, s[68:71], s73 offen offset:0
	buffer_store_dwordx4 v[148:151], v236, s[68:71], s73 offen offset:16
	s_add_u32 s72, s72, 0x1000
	s_add_u32 s73, s73, 0x800
	s_add_u32 s74, s74, 0x200
	s_add_u32 s75, s75, 0x40
	s_waitcnt vmcnt(40)
; __device__ __forceinline__ void prep_phase(const Params& p) {
;     ...
;             for (int i = 0; i < 16; ++i) {
;                 const bool hn = (tt0 + i) < SEQ - 1; const Z16 kn = hn ? ldz(zc + (size_t)(i + 1) * 3328) : zz();
;                 float k[16], kk[16]; mix16(kp, kc, kn, mpk, mnk, k);
;                 float s2 = 0.f;
; #pragma unroll
;                 for (int q = 0; q < 16; ++q) { kk[q] = k[q] * kkc[q]; s2 += kk[q] * kk[q]; }
;                 s2 += __shfl_xor(s2, 1); s2 += __shfl_xor(s2, 2);
;                 const float inv = -1.0f / fmaxf(sqrtf(s2), 1e-12f);
;                 const size_t o = (size_t)(t0 + i) * RW + c;
; #pragma unroll
;                 for (int j4 = 0; j4 < 4; ++j4) *(f32x4*)(A + o + j4 * 4) = (f32x4){kk[j4 * 4] * inv, kk[j4 * 4 + 1] * inv, kk[j4 * 4 + 2] * inv, kk[j4 * 4 + 3] * inv};
;                 st16bf(Kb + o, k);
;                 kp = kc; kc = kn;
	v_lshlrev_b32_e32 v144, 16, v60
	v_and_b32_e32 v145, 0xffff0000, v60
	v_lshlrev_b32_e32 v146, 16, v61
	v_and_b32_e32 v147, 0xffff0000, v61
	v_lshlrev_b32_e32 v148, 16, v62
	v_and_b32_e32 v149, 0xffff0000, v62
	v_lshlrev_b32_e32 v150, 16, v63
	v_and_b32_e32 v151, 0xffff0000, v63
	v_lshlrev_b32_e32 v152, 16, v64
	v_and_b32_e32 v153, 0xffff0000, v64
	v_lshlrev_b32_e32 v154, 16, v65
	v_and_b32_e32 v155, 0xffff0000, v65
	v_lshlrev_b32_e32 v156, 16, v66
	v_and_b32_e32 v157, 0xffff0000, v66
	v_lshlrev_b32_e32 v158, 16, v67
	v_and_b32_e32 v159, 0xffff0000, v67
	v_lshlrev_b32_e32 v160, 16, v72
	v_and_b32_e32 v161, 0xffff0000, v72
	v_lshlrev_b32_e32 v162, 16, v73
	v_and_b32_e32 v163, 0xffff0000, v73
	v_lshlrev_b32_e32 v164, 16, v74
	v_and_b32_e32 v165, 0xffff0000, v74
	v_lshlrev_b32_e32 v166, 16, v75
	v_and_b32_e32 v167, 0xffff0000, v75
	v_lshlrev_b32_e32 v168, 16, v76
	v_and_b32_e32 v169, 0xffff0000, v76
	v_lshlrev_b32_e32 v170, 16, v77
	v_and_b32_e32 v171, 0xffff0000, v77
	v_lshlrev_b32_e32 v172, 16, v78
	v_and_b32_e32 v173, 0xffff0000, v78
	v_lshlrev_b32_e32 v174, 16, v79
	v_and_b32_e32 v175, 0xffff0000, v79
	v_lshlrev_b32_e32 v176, 16, v84
	v_and_b32_e32 v177, 0xffff0000, v84
	v_lshlrev_b32_e32 v178, 16, v85
	v_and_b32_e32 v179, 0xffff0000, v85
	v_lshlrev_b32_e32 v180, 16, v86
	v_and_b32_e32 v181, 0xffff0000, v86
	v_lshlrev_b32_e32 v182, 16, v87
	v_and_b32_e32 v183, 0xffff0000, v87
	v_lshlrev_b32_e32 v184, 16, v88
	v_and_b32_e32 v185, 0xffff0000, v88
	v_lshlrev_b32_e32 v186, 16, v89
	v_and_b32_e32 v187, 0xffff0000, v89
	v_lshlrev_b32_e32 v188, 16, v90
	v_and_b32_e32 v189, 0xffff0000, v90
	v_lshlrev_b32_e32 v190, 16, v91
	v_and_b32_e32 v191, 0xffff0000, v91
	buffer_load_dwordx4 v[60:63], v232, s[64:67], 0 offen offset:2048 nt
	buffer_load_dwordx4 v[64:67], v232, s[64:67], 0 offen offset:2064 nt
	v_add_u32_e32 v232, 6656, v232
	v_pk_add_f32 v[224:225], v[144:145], v[160:161] neg_lo:[0,1] neg_hi:[0,1]
	v_pk_add_f32 v[226:227], v[176:177], v[160:161] neg_lo:[0,1] neg_hi:[0,1]
	v_pk_fma_f32 v[192:193], v[96:97], v[224:225], v[160:161]
	v_pk_fma_f32 v[192:193], v[112:113], v[226:227], v[192:193]
	v_pk_add_f32 v[224:225], v[146:147], v[162:163] neg_lo:[0,1] neg_hi:[0,1]
	v_pk_add_f32 v[226:227], v[178:179], v[162:163] neg_lo:[0,1] neg_hi:[0,1]
	v_pk_fma_f32 v[194:195], v[98:99], v[224:225], v[162:163]
	v_pk_fma_f32 v[194:195], v[114:115], v[226:227], v[194:195]
	v_pk_add_f32 v[224:225], v[148:149], v[164:165] neg_lo:[0,1] neg_hi:[0,1]
	v_pk_add_f32 v[226:227], v[180:181], v[164:165] neg_lo:[0,1] neg_hi:[0,1]
	v_pk_fma_f32 v[196:197], v[100:101], v[224:225], v[164:165]
	v_pk_fma_f32 v[196:197], v[116:117], v[226:227], v[196:197]
	v_pk_add_f32 v[224:225], v[150:151], v[166:167] neg_lo:[0,1] neg_hi:[0,1]
	v_pk_add_f32 v[226:227], v[182:183], v[166:167] neg_lo:[0,1] neg_hi:[0,1]
	v_pk_fma_f32 v[198:199], v[102:103], v[224:225], v[166:167]
	v_pk_fma_f32 v[198:199], v[118:119], v[226:227], v[198:199]
	v_pk_add_f32 v[224:225], v[152:153], v[168:169] neg_lo:[0,1] neg_hi:[0,1]
	v_pk_add_f32 v[226:227], v[184:185], v[168:169] neg_lo:[0,1] neg_hi:[0,1]
	v_pk_fma_f32 v[200:201], v[104:105], v[224:225], v[168:169]
	v_pk_fma_f32 v[200:201], v[120:121], v[226:227], v[200:201]
	v_pk_add_f32 v[224:225], v[154:155], v[170:171] neg_lo:[0,1] neg_hi:[0,1]
	v_pk_add_f32 v[226:227], v[186:187], v[170:171] neg_lo:[0,1] neg_hi:[0,1]
	v_pk_fma_f32 v[202:203], v[106:107], v[224:225], v[170:171]
	v_pk_fma_f32 v[202:203], v[122:123], v[226:227], v[202:203]
	v_pk_add_f32 v[224:225], v[156:157], v[172:173] neg_lo:[0,1] neg_hi:[0,1]
	v_pk_add_f32 v[226:227], v[188:189], v[172:173] neg_lo:[0,1] neg_hi:[0,1]
	v_pk_fma_f32 v[204:205], v[108:109], v[224:225], v[172:173]
	v_pk_fma_f32 v[204:205], v[124:125], v[226:227], v[204:205]
	v_pk_add_f32 v[224:225], v[158:159], v[174:175] neg_lo:[0,1] neg_hi:[0,1]
	v_pk_add_f32 v[226:227], v[190:191], v[174:175] neg_lo:[0,1] neg_hi:[0,1]
	v_pk_fma_f32 v[206:207], v[110:111], v[224:225], v[174:175]
	v_pk_fma_f32 v[206:207], v[126:127], v[226:227], v[206:207]
	v_pk_mul_f32 v[208:209], v[192:193], v[128:129]
	v_pk_mul_f32 v[210:211], v[194:195], v[130:131]
	v_pk_mul_f32 v[212:213], v[196:197], v[132:133]
	v_pk_mul_f32 v[214:215], v[198:199], v[134:135]
	v_pk_mul_f32 v[216:217], v[200:201], v[136:137]
	v_pk_mul_f32 v[218:219], v[202:203], v[138:139]
	v_pk_mul_f32 v[220:221], v[204:205], v[140:141]
	v_pk_mul_f32 v[222:223], v[206:207], v[142:143]
	v_mul_f32_e32 v224, v208, v208
	v_fmac_f32_e32 v224, v209, v209
	v_fmac_f32_e32 v224, v210, v210
	v_fmac_f32_e32 v224, v211, v211
	v_fmac_f32_e32 v224, v212, v212
	v_fmac_f32_e32 v224, v213, v213
	v_fmac_f32_e32 v224, v214, v214
	v_fmac_f32_e32 v224, v215, v215
	v_fmac_f32_e32 v224, v216, v216
	v_fmac_f32_e32 v224, v217, v217
	v_fmac_f32_e32 v224, v218, v218
	v_fmac_f32_e32 v224, v219, v219
	v_fmac_f32_e32 v224, v220, v220
	v_fmac_f32_e32 v224, v221, v221
	v_fmac_f32_e32 v224, v222, v222
	v_fmac_f32_e32 v224, v223, v223
	s_nop 1
	v_add_f32_dpp v224, v224, v224 quad_perm:[1,0,3,2] row_mask:0xf bank_mask:0xf
	s_nop 1
	v_add_f32_dpp v224, v224, v224 quad_perm:[2,3,0,1] row_mask:0xf bank_mask:0xf
	v_sqrt_f32_e32 v224, v224
	s_nop 0
	v_max_f32_e32 v224, 0x2b8cbccc, v224
	v_rcp_f32_e32 v224, v224
	s_nop 0
	v_xor_b32_e32 v224, 0x80000000, v224
	v_mov_b32_e32 v225, v224
	v_cvt_pk_bf16_f32 v144, v192, v193
	v_cvt_pk_bf16_f32 v145, v194, v195
	v_cvt_pk_bf16_f32 v146, v196, v197
	v_cvt_pk_bf16_f32 v147, v198, v199
	v_cvt_pk_bf16_f32 v148, v200, v201
	v_cvt_pk_bf16_f32 v149, v202, v203
	v_cvt_pk_bf16_f32 v150, v204, v205
	v_cvt_pk_bf16_f32 v151, v206, v207
	v_pk_mul_f32 v[208:209], v[208:209], v[224:225]
	v_pk_mul_f32 v[210:211], v[210:211], v[224:225]
	v_pk_mul_f32 v[212:213], v[212:213], v[224:225]
	v_pk_mul_f32 v[214:215], v[214:215], v[224:225]
	v_pk_mul_f32 v[216:217], v[216:217], v[224:225]
	v_pk_mul_f32 v[218:219], v[218:219], v[224:225]
	v_pk_mul_f32 v[220:221], v[220:221], v[224:225]
	v_pk_mul_f32 v[222:223], v[222:223], v[224:225]
	buffer_store_dwordx4 v[208:211], v234, s[68:71], s72 offen offset:0
	buffer_store_dwordx4 v[212:215], v234, s[68:71], s72 offen offset:16
	buffer_store_dwordx4 v[216:219], v234, s[68:71], s72 offen offset:32
	buffer_store_dwordx4 v[220:223], v234, s[68:71], s72 offen offset:48
	buffer_store_dwordx4 v[144:147], v236, s[68:71], s73 offen offset:0
	buffer_store_dwordx4 v[148:151], v236, s[68:71], s73 offen offset:16
	s_add_u32 s72, s72, 0x1000
	s_add_u32 s73, s73, 0x800
	s_add_u32 s74, s74, 0x200
	s_add_u32 s75, s75, 0x40
	s_waitcnt vmcnt(46)
; __device__ __forceinline__ void prep_phase(const Params& p) {
;     ...
;             for (int i = 0; i < 16; ++i) {
;                 const bool hn = (tt0 + i) < SEQ - 1; const Z16 kn = hn ? ldz(zc + (size_t)(i + 1) * 3328) : zz();
;                 float k[16], kk[16]; mix16(kp, kc, kn, mpk, mnk, k);
;                 float s2 = 0.f;
; #pragma unroll
;                 for (int q = 0; q < 16; ++q) { kk[q] = k[q] * kkc[q]; s2 += kk[q] * kk[q]; }
;                 s2 += __shfl_xor(s2, 1); s2 += __shfl_xor(s2, 2);
;                 const float inv = -1.0f / fmaxf(sqrtf(s2), 1e-12f);
;                 const size_t o = (size_t)(t0 + i) * RW + c;
; #pragma unroll
;                 for (int j4 = 0; j4 < 4; ++j4) *(f32x4*)(A + o + j4 * 4) = (f32x4){kk[j4 * 4] * inv, kk[j4 * 4 + 1] * inv, kk[j4 * 4 + 2] * inv, kk[j4 * 4 + 3] * inv};
;                 st16bf(Kb + o, k);
;                 kp = kc; kc = kn;
	v_lshlrev_b32_e32 v144, 16, v72
	v_and_b32_e32 v145, 0xffff0000, v72
	v_lshlrev_b32_e32 v146, 16, v73
	v_and_b32_e32 v147, 0xffff0000, v73
	v_lshlrev_b32_e32 v148, 16, v74
	v_and_b32_e32 v149, 0xffff0000, v74
	v_lshlrev_b32_e32 v150, 16, v75
	v_and_b32_e32 v151, 0xffff0000, v75
	v_lshlrev_b32_e32 v152, 16, v76
	v_and_b32_e32 v153, 0xffff0000, v76
	v_lshlrev_b32_e32 v154, 16, v77
	v_and_b32_e32 v155, 0xffff0000, v77
	v_lshlrev_b32_e32 v156, 16, v78
	v_and_b32_e32 v157, 0xffff0000, v78
	v_lshlrev_b32_e32 v158, 16, v79
	v_and_b32_e32 v159, 0xffff0000, v79
	v_lshlrev_b32_e32 v160, 16, v84
	v_and_b32_e32 v161, 0xffff0000, v84
	v_lshlrev_b32_e32 v162, 16, v85
	v_and_b32_e32 v163, 0xffff0000, v85
	v_lshlrev_b32_e32 v164, 16, v86
	v_and_b32_e32 v165, 0xffff0000, v86
	v_lshlrev_b32_e32 v166, 16, v87
	v_and_b32_e32 v167, 0xffff0000, v87
	v_lshlrev_b32_e32 v168, 16, v88
	v_and_b32_e32 v169, 0xffff0000, v88
	v_lshlrev_b32_e32 v170, 16, v89
	v_and_b32_e32 v171, 0xffff0000, v89
	v_lshlrev_b32_e32 v172, 16, v90
	v_and_b32_e32 v173, 0xffff0000, v90
	v_lshlrev_b32_e32 v174, 16, v91
	v_and_b32_e32 v175, 0xffff0000, v91
	v_lshlrev_b32_e32 v176, 16, v0
	v_and_b32_e32 v177, 0xffff0000, v0
	v_lshlrev_b32_e32 v178, 16, v1
	v_and_b32_e32 v179, 0xffff0000, v1
	v_lshlrev_b32_e32 v180, 16, v2
	v_and_b32_e32 v181, 0xffff0000, v2
	v_lshlrev_b32_e32 v182, 16, v3
	v_and_b32_e32 v183, 0xffff0000, v3
	v_lshlrev_b32_e32 v184, 16, v4
	v_and_b32_e32 v185, 0xffff0000, v4
	v_lshlrev_b32_e32 v186, 16, v5
	v_and_b32_e32 v187, 0xffff0000, v5
	v_lshlrev_b32_e32 v188, 16, v6
	v_and_b32_e32 v189, 0xffff0000, v6
	v_lshlrev_b32_e32 v190, 16, v7
	v_and_b32_e32 v191, 0xffff0000, v7
	buffer_load_dwordx4 v[72:75], v232, s[64:67], 0 offen offset:2048 nt
	buffer_load_dwordx4 v[76:79], v232, s[64:67], 0 offen offset:2064 nt
	v_add_u32_e32 v232, 6656, v232
	v_pk_add_f32 v[224:225], v[144:145], v[160:161] neg_lo:[0,1] neg_hi:[0,1]
	v_pk_add_f32 v[226:227], v[176:177], v[160:161] neg_lo:[0,1] neg_hi:[0,1]
	v_pk_fma_f32 v[192:193], v[96:97], v[224:225], v[160:161]
	v_pk_fma_f32 v[192:193], v[112:113], v[226:227], v[192:193]
	v_pk_add_f32 v[224:225], v[146:147], v[162:163] neg_lo:[0,1] neg_hi:[0,1]
	v_pk_add_f32 v[226:227], v[178:179], v[162:163] neg_lo:[0,1] neg_hi:[0,1]
	v_pk_fma_f32 v[194:195], v[98:99], v[224:225], v[162:163]
	v_pk_fma_f32 v[194:195], v[114:115], v[226:227], v[194:195]
	v_pk_add_f32 v[224:225], v[148:149], v[164:165] neg_lo:[0,1] neg_hi:[0,1]
	v_pk_add_f32 v[226:227], v[180:181], v[164:165] neg_lo:[0,1] neg_hi:[0,1]
	v_pk_fma_f32 v[196:197], v[100:101], v[224:225], v[164:165]
	v_pk_fma_f32 v[196:197], v[116:117], v[226:227], v[196:197]
	v_pk_add_f32 v[224:225], v[150:151], v[166:167] neg_lo:[0,1] neg_hi:[0,1]
	v_pk_add_f32 v[226:227], v[182:183], v[166:167] neg_lo:[0,1] neg_hi:[0,1]
	v_pk_fma_f32 v[198:199], v[102:103], v[224:225], v[166:167]
	v_pk_fma_f32 v[198:199], v[118:119], v[226:227], v[198:199]
	v_pk_add_f32 v[224:225], v[152:153], v[168:169] neg_lo:[0,1] neg_hi:[0,1]
	v_pk_add_f32 v[226:227], v[184:185], v[168:169] neg_lo:[0,1] neg_hi:[0,1]
	v_pk_fma_f32 v[200:201], v[104:105], v[224:225], v[168:169]
	v_pk_fma_f32 v[200:201], v[120:121], v[226:227], v[200:201]
	v_pk_add_f32 v[224:225], v[154:155], v[170:171] neg_lo:[0,1] neg_hi:[0,1]
	v_pk_add_f32 v[226:227], v[186:187], v[170:171] neg_lo:[0,1] neg_hi:[0,1]
	v_pk_fma_f32 v[202:203], v[106:107], v[224:225], v[170:171]
	v_pk_fma_f32 v[202:203], v[122:123], v[226:227], v[202:203]
	v_pk_add_f32 v[224:225], v[156:157], v[172:173] neg_lo:[0,1] neg_hi:[0,1]
	v_pk_add_f32 v[226:227], v[188:189], v[172:173] neg_lo:[0,1] neg_hi:[0,1]
	v_pk_fma_f32 v[204:205], v[108:109], v[224:225], v[172:173]
	v_pk_fma_f32 v[204:205], v[124:125], v[226:227], v[204:205]
	v_pk_add_f32 v[224:225], v[158:159], v[174:175] neg_lo:[0,1] neg_hi:[0,1]
	v_pk_add_f32 v[226:227], v[190:191], v[174:175] neg_lo:[0,1] neg_hi:[0,1]
	v_pk_fma_f32 v[206:207], v[110:111], v[224:225], v[174:175]
	v_pk_fma_f32 v[206:207], v[126:127], v[226:227], v[206:207]
	v_pk_mul_f32 v[208:209], v[192:193], v[128:129]
	v_pk_mul_f32 v[210:211], v[194:195], v[130:131]
	v_pk_mul_f32 v[212:213], v[196:197], v[132:133]
	v_pk_mul_f32 v[214:215], v[198:199], v[134:135]
	v_pk_mul_f32 v[216:217], v[200:201], v[136:137]
	v_pk_mul_f32 v[218:219], v[202:203], v[138:139]
	v_pk_mul_f32 v[220:221], v[204:205], v[140:141]
	v_pk_mul_f32 v[222:223], v[206:207], v[142:143]
	v_mul_f32_e32 v224, v208, v208
	v_fmac_f32_e32 v224, v209, v209
	v_fmac_f32_e32 v224, v210, v210
	v_fmac_f32_e32 v224, v211, v211
	v_fmac_f32_e32 v224, v212, v212
	v_fmac_f32_e32 v224, v213, v213
	v_fmac_f32_e32 v224, v214, v214
	v_fmac_f32_e32 v224, v215, v215
	v_fmac_f32_e32 v224, v216, v216
	v_fmac_f32_e32 v224, v217, v217
	v_fmac_f32_e32 v224, v218, v218
	v_fmac_f32_e32 v224, v219, v219
	v_fmac_f32_e32 v224, v220, v220
	v_fmac_f32_e32 v224, v221, v221
	v_fmac_f32_e32 v224, v222, v222
	v_fmac_f32_e32 v224, v223, v223
	s_nop 1
	v_add_f32_dpp v224, v224, v224 quad_perm:[1,0,3,2] row_mask:0xf bank_mask:0xf
	s_nop 1
	v_add_f32_dpp v224, v224, v224 quad_perm:[2,3,0,1] row_mask:0xf bank_mask:0xf
	v_sqrt_f32_e32 v224, v224
	s_nop 0
	v_max_f32_e32 v224, 0x2b8cbccc, v224
	v_rcp_f32_e32 v224, v224
	s_nop 0
	v_xor_b32_e32 v224, 0x80000000, v224
	v_mov_b32_e32 v225, v224
	v_cvt_pk_bf16_f32 v144, v192, v193
	v_cvt_pk_bf16_f32 v145, v194, v195
	v_cvt_pk_bf16_f32 v146, v196, v197
	v_cvt_pk_bf16_f32 v147, v198, v199
	v_cvt_pk_bf16_f32 v148, v200, v201
	v_cvt_pk_bf16_f32 v149, v202, v203
	v_cvt_pk_bf16_f32 v150, v204, v205
	v_cvt_pk_bf16_f32 v151, v206, v207
	v_pk_mul_f32 v[208:209], v[208:209], v[224:225]
	v_pk_mul_f32 v[210:211], v[210:211], v[224:225]
	v_pk_mul_f32 v[212:213], v[212:213], v[224:225]
	v_pk_mul_f32 v[214:215], v[214:215], v[224:225]
	v_pk_mul_f32 v[216:217], v[216:217], v[224:225]
	v_pk_mul_f32 v[218:219], v[218:219], v[224:225]
	v_pk_mul_f32 v[220:221], v[220:221], v[224:225]
	v_pk_mul_f32 v[222:223], v[222:223], v[224:225]
	buffer_store_dwordx4 v[208:211], v234, s[68:71], s72 offen offset:0
	buffer_store_dwordx4 v[212:215], v234, s[68:71], s72 offen offset:16
	buffer_store_dwordx4 v[216:219], v234, s[68:71], s72 offen offset:32
	buffer_store_dwordx4 v[220:223], v234, s[68:71], s72 offen offset:48
	buffer_store_dwordx4 v[144:147], v236, s[68:71], s73 offen offset:0
	buffer_store_dwordx4 v[148:151], v236, s[68:71], s73 offen offset:16
	s_add_u32 s72, s72, 0x1000
	s_add_u32 s73, s73, 0x800
	s_add_u32 s74, s74, 0x200
	s_add_u32 s75, s75, 0x40
	s_waitcnt vmcnt(46)
; __device__ __forceinline__ void prep_phase(const Params& p) {
;     ...
;             for (int i = 0; i < 16; ++i) {
;                 const bool hn = (tt0 + i) < SEQ - 1; const Z16 kn = hn ? ldz(zc + (size_t)(i + 1) * 3328) : zz();
;                 float k[16], kk[16]; mix16(kp, kc, kn, mpk, mnk, k);
;                 float s2 = 0.f;
; #pragma unroll
;                 for (int q = 0; q < 16; ++q) { kk[q] = k[q] * kkc[q]; s2 += kk[q] * kk[q]; }
;                 s2 += __shfl_xor(s2, 1); s2 += __shfl_xor(s2, 2);
;                 const float inv = -1.0f / fmaxf(sqrtf(s2), 1e-12f);
;                 const size_t o = (size_t)(t0 + i) * RW + c;
; #pragma unroll
;                 for (int j4 = 0; j4 < 4; ++j4) *(f32x4*)(A + o + j4 * 4) = (f32x4){kk[j4 * 4] * inv, kk[j4 * 4 + 1] * inv, kk[j4 * 4 + 2] * inv, kk[j4 * 4 + 3] * inv};
;                 st16bf(Kb + o, k);
;                 kp = kc; kc = kn;
	v_lshlrev_b32_e32 v144, 16, v84
	v_and_b32_e32 v145, 0xffff0000, v84
	v_lshlrev_b32_e32 v146, 16, v85
	v_and_b32_e32 v147, 0xffff0000, v85
	v_lshlrev_b32_e32 v148, 16, v86
	v_and_b32_e32 v149, 0xffff0000, v86
	v_lshlrev_b32_e32 v150, 16, v87
	v_and_b32_e32 v151, 0xffff0000, v87
	v_lshlrev_b32_e32 v152, 16, v88
	v_and_b32_e32 v153, 0xffff0000, v88
	v_lshlrev_b32_e32 v154, 16, v89
	v_and_b32_e32 v155, 0xffff0000, v89
	v_lshlrev_b32_e32 v156, 16, v90
	v_and_b32_e32 v157, 0xffff0000, v90
	v_lshlrev_b32_e32 v158, 16, v91
	v_and_b32_e32 v159, 0xffff0000, v91
	v_lshlrev_b32_e32 v160, 16, v0
	v_and_b32_e32 v161, 0xffff0000, v0
	v_lshlrev_b32_e32 v162, 16, v1
	v_and_b32_e32 v163, 0xffff0000, v1
	v_lshlrev_b32_e32 v164, 16, v2
	v_and_b32_e32 v165, 0xffff0000, v2
	v_lshlrev_b32_e32 v166, 16, v3
	v_and_b32_e32 v167, 0xffff0000, v3
	v_lshlrev_b32_e32 v168, 16, v4
	v_and_b32_e32 v169, 0xffff0000, v4
	v_lshlrev_b32_e32 v170, 16, v5
	v_and_b32_e32 v171, 0xffff0000, v5
	v_lshlrev_b32_e32 v172, 16, v6
	v_and_b32_e32 v173, 0xffff0000, v6
	v_lshlrev_b32_e32 v174, 16, v7
	v_and_b32_e32 v175, 0xffff0000, v7
	v_lshlrev_b32_e32 v176, 16, v12
	v_and_b32_e32 v177, 0xffff0000, v12
	v_lshlrev_b32_e32 v178, 16, v13
	v_and_b32_e32 v179, 0xffff0000, v13
	v_lshlrev_b32_e32 v180, 16, v14
	v_and_b32_e32 v181, 0xffff0000, v14
	v_lshlrev_b32_e32 v182, 16, v15
	v_and_b32_e32 v183, 0xffff0000, v15
	v_lshlrev_b32_e32 v184, 16, v16
	v_and_b32_e32 v185, 0xffff0000, v16
	v_lshlrev_b32_e32 v186, 16, v17
	v_and_b32_e32 v187, 0xffff0000, v17
	v_lshlrev_b32_e32 v188, 16, v18
	v_and_b32_e32 v189, 0xffff0000, v18
	v_lshlrev_b32_e32 v190, 16, v19
	v_and_b32_e32 v191, 0xffff0000, v19
	buffer_load_dwordx4 v[84:87], v232, s[64:67], 0 offen offset:2048 nt
	buffer_load_dwordx4 v[88:91], v232, s[64:67], 0 offen offset:2064 nt
	v_add_u32_e32 v232, 6656, v232
	v_pk_add_f32 v[224:225], v[144:145], v[160:161] neg_lo:[0,1] neg_hi:[0,1]
	v_pk_add_f32 v[226:227], v[176:177], v[160:161] neg_lo:[0,1] neg_hi:[0,1]
	v_pk_fma_f32 v[192:193], v[96:97], v[224:225], v[160:161]
	v_pk_fma_f32 v[192:193], v[112:113], v[226:227], v[192:193]
	v_pk_add_f32 v[224:225], v[146:147], v[162:163] neg_lo:[0,1] neg_hi:[0,1]
	v_pk_add_f32 v[226:227], v[178:179], v[162:163] neg_lo:[0,1] neg_hi:[0,1]
	v_pk_fma_f32 v[194:195], v[98:99], v[224:225], v[162:163]
	v_pk_fma_f32 v[194:195], v[114:115], v[226:227], v[194:195]
	v_pk_add_f32 v[224:225], v[148:149], v[164:165] neg_lo:[0,1] neg_hi:[0,1]
	v_pk_add_f32 v[226:227], v[180:181], v[164:165] neg_lo:[0,1] neg_hi:[0,1]
	v_pk_fma_f32 v[196:197], v[100:101], v[224:225], v[164:165]
	v_pk_fma_f32 v[196:197], v[116:117], v[226:227], v[196:197]
	v_pk_add_f32 v[224:225], v[150:151], v[166:167] neg_lo:[0,1] neg_hi:[0,1]
	v_pk_add_f32 v[226:227], v[182:183], v[166:167] neg_lo:[0,1] neg_hi:[0,1]
	v_pk_fma_f32 v[198:199], v[102:103], v[224:225], v[166:167]
	v_pk_fma_f32 v[198:199], v[118:119], v[226:227], v[198:199]
	v_pk_add_f32 v[224:225], v[152:153], v[168:169] neg_lo:[0,1] neg_hi:[0,1]
	v_pk_add_f32 v[226:227], v[184:185], v[168:169] neg_lo:[0,1] neg_hi:[0,1]
	v_pk_fma_f32 v[200:201], v[104:105], v[224:225], v[168:169]
	v_pk_fma_f32 v[200:201], v[120:121], v[226:227], v[200:201]
	v_pk_add_f32 v[224:225], v[154:155], v[170:171] neg_lo:[0,1] neg_hi:[0,1]
	v_pk_add_f32 v[226:227], v[186:187], v[170:171] neg_lo:[0,1] neg_hi:[0,1]
	v_pk_fma_f32 v[202:203], v[106:107], v[224:225], v[170:171]
	v_pk_fma_f32 v[202:203], v[122:123], v[226:227], v[202:203]
	v_pk_add_f32 v[224:225], v[156:157], v[172:173] neg_lo:[0,1] neg_hi:[0,1]
	v_pk_add_f32 v[226:227], v[188:189], v[172:173] neg_lo:[0,1] neg_hi:[0,1]
	v_pk_fma_f32 v[204:205], v[108:109], v[224:225], v[172:173]
	v_pk_fma_f32 v[204:205], v[124:125], v[226:227], v[204:205]
	v_pk_add_f32 v[224:225], v[158:159], v[174:175] neg_lo:[0,1] neg_hi:[0,1]
	v_pk_add_f32 v[226:227], v[190:191], v[174:175] neg_lo:[0,1] neg_hi:[0,1]
	v_pk_fma_f32 v[206:207], v[110:111], v[224:225], v[174:175]
	v_pk_fma_f32 v[206:207], v[126:127], v[226:227], v[206:207]
	v_pk_mul_f32 v[208:209], v[192:193], v[128:129]
	v_pk_mul_f32 v[210:211], v[194:195], v[130:131]
	v_pk_mul_f32 v[212:213], v[196:197], v[132:133]
	v_pk_mul_f32 v[214:215], v[198:199], v[134:135]
	v_pk_mul_f32 v[216:217], v[200:201], v[136:137]
	v_pk_mul_f32 v[218:219], v[202:203], v[138:139]
	v_pk_mul_f32 v[220:221], v[204:205], v[140:141]
	v_pk_mul_f32 v[222:223], v[206:207], v[142:143]
	v_mul_f32_e32 v224, v208, v208
	v_fmac_f32_e32 v224, v209, v209
	v_fmac_f32_e32 v224, v210, v210
	v_fmac_f32_e32 v224, v211, v211
	v_fmac_f32_e32 v224, v212, v212
	v_fmac_f32_e32 v224, v213, v213
	v_fmac_f32_e32 v224, v214, v214
	v_fmac_f32_e32 v224, v215, v215
	v_fmac_f32_e32 v224, v216, v216
	v_fmac_f32_e32 v224, v217, v217
	v_fmac_f32_e32 v224, v218, v218
	v_fmac_f32_e32 v224, v219, v219
	v_fmac_f32_e32 v224, v220, v220
	v_fmac_f32_e32 v224, v221, v221
	v_fmac_f32_e32 v224, v222, v222
	v_fmac_f32_e32 v224, v223, v223
	s_nop 1
	v_add_f32_dpp v224, v224, v224 quad_perm:[1,0,3,2] row_mask:0xf bank_mask:0xf
	s_nop 1
	v_add_f32_dpp v224, v224, v224 quad_perm:[2,3,0,1] row_mask:0xf bank_mask:0xf
	v_sqrt_f32_e32 v224, v224
	s_nop 0
	v_max_f32_e32 v224, 0x2b8cbccc, v224
	v_rcp_f32_e32 v224, v224
	s_nop 0
	v_xor_b32_e32 v224, 0x80000000, v224
	v_mov_b32_e32 v225, v224
	v_cvt_pk_bf16_f32 v144, v192, v193
	v_cvt_pk_bf16_f32 v145, v194, v195
	v_cvt_pk_bf16_f32 v146, v196, v197
	v_cvt_pk_bf16_f32 v147, v198, v199
	v_cvt_pk_bf16_f32 v148, v200, v201
	v_cvt_pk_bf16_f32 v149, v202, v203
	v_cvt_pk_bf16_f32 v150, v204, v205
	v_cvt_pk_bf16_f32 v151, v206, v207
	v_pk_mul_f32 v[208:209], v[208:209], v[224:225]
	v_pk_mul_f32 v[210:211], v[210:211], v[224:225]
	v_pk_mul_f32 v[212:213], v[212:213], v[224:225]
	v_pk_mul_f32 v[214:215], v[214:215], v[224:225]
	v_pk_mul_f32 v[216:217], v[216:217], v[224:225]
	v_pk_mul_f32 v[218:219], v[218:219], v[224:225]
	v_pk_mul_f32 v[220:221], v[220:221], v[224:225]
	v_pk_mul_f32 v[222:223], v[222:223], v[224:225]
	buffer_store_dwordx4 v[208:211], v234, s[68:71], s72 offen offset:0
	buffer_store_dwordx4 v[212:215], v234, s[68:71], s72 offen offset:16
	buffer_store_dwordx4 v[216:219], v234, s[68:71], s72 offen offset:32
	buffer_store_dwordx4 v[220:223], v234, s[68:71], s72 offen offset:48
	buffer_store_dwordx4 v[144:147], v236, s[68:71], s73 offen offset:0
	buffer_store_dwordx4 v[148:151], v236, s[68:71], s73 offen offset:16
	s_add_u32 s72, s72, 0x1000
	s_add_u32 s73, s73, 0x800
	s_add_u32 s74, s74, 0x200
	s_add_u32 s75, s75, 0x40
	s_waitcnt vmcnt(46)
; __device__ __forceinline__ void prep_phase(const Params& p) {
;     ...
;             for (int i = 0; i < 16; ++i) {
;                 const bool hn = (tt0 + i) < SEQ - 1; const Z16 kn = hn ? ldz(zc + (size_t)(i + 1) * 3328) : zz();
;                 float k[16], kk[16]; mix16(kp, kc, kn, mpk, mnk, k);
;                 float s2 = 0.f;
; #pragma unroll
;                 for (int q = 0; q < 16; ++q) { kk[q] = k[q] * kkc[q]; s2 += kk[q] * kk[q]; }
;                 s2 += __shfl_xor(s2, 1); s2 += __shfl_xor(s2, 2);
;                 const float inv = -1.0f / fmaxf(sqrtf(s2), 1e-12f);
;                 const size_t o = (size_t)(t0 + i) * RW + c;
; #pragma unroll
;                 for (int j4 = 0; j4 < 4; ++j4) *(f32x4*)(A + o + j4 * 4) = (f32x4){kk[j4 * 4] * inv, kk[j4 * 4 + 1] * inv, kk[j4 * 4 + 2] * inv, kk[j4 * 4 + 3] * inv};
;                 st16bf(Kb + o, k);
;                 kp = kc; kc = kn;
	v_lshlrev_b32_e32 v144, 16, v0
	v_and_b32_e32 v145, 0xffff0000, v0
	v_lshlrev_b32_e32 v146, 16, v1
	v_and_b32_e32 v147, 0xffff0000, v1
	v_lshlrev_b32_e32 v148, 16, v2
	v_and_b32_e32 v149, 0xffff0000, v2
	v_lshlrev_b32_e32 v150, 16, v3
	v_and_b32_e32 v151, 0xffff0000, v3
	v_lshlrev_b32_e32 v152, 16, v4
	v_and_b32_e32 v153, 0xffff0000, v4
	v_lshlrev_b32_e32 v154, 16, v5
	v_and_b32_e32 v155, 0xffff0000, v5
	v_lshlrev_b32_e32 v156, 16, v6
	v_and_b32_e32 v157, 0xffff0000, v6
	v_lshlrev_b32_e32 v158, 16, v7
	v_and_b32_e32 v159, 0xffff0000, v7
	v_lshlrev_b32_e32 v160, 16, v12
	v_and_b32_e32 v161, 0xffff0000, v12
	v_lshlrev_b32_e32 v162, 16, v13
	v_and_b32_e32 v163, 0xffff0000, v13
	v_lshlrev_b32_e32 v164, 16, v14
	v_and_b32_e32 v165, 0xffff0000, v14
	v_lshlrev_b32_e32 v166, 16, v15
	v_and_b32_e32 v167, 0xffff0000, v15
	v_lshlrev_b32_e32 v168, 16, v16
	v_and_b32_e32 v169, 0xffff0000, v16
	v_lshlrev_b32_e32 v170, 16, v17
	v_and_b32_e32 v171, 0xffff0000, v17
	v_lshlrev_b32_e32 v172, 16, v18
	v_and_b32_e32 v173, 0xffff0000, v18
	v_lshlrev_b32_e32 v174, 16, v19
	v_and_b32_e32 v175, 0xffff0000, v19
	v_lshlrev_b32_e32 v176, 16, v24
	v_and_b32_e32 v177, 0xffff0000, v24
	v_lshlrev_b32_e32 v178, 16, v25
	v_and_b32_e32 v179, 0xffff0000, v25
	v_lshlrev_b32_e32 v180, 16, v26
	v_and_b32_e32 v181, 0xffff0000, v26
	v_lshlrev_b32_e32 v182, 16, v27
	v_and_b32_e32 v183, 0xffff0000, v27
	v_lshlrev_b32_e32 v184, 16, v28
	v_and_b32_e32 v185, 0xffff0000, v28
	v_lshlrev_b32_e32 v186, 16, v29
	v_and_b32_e32 v187, 0xffff0000, v29
	v_lshlrev_b32_e32 v188, 16, v30
	v_and_b32_e32 v189, 0xffff0000, v30
	v_lshlrev_b32_e32 v190, 16, v31
	v_and_b32_e32 v191, 0xffff0000, v31
	buffer_load_dwordx4 v[0:3], v232, s[64:67], 0 offen offset:2048 nt
	buffer_load_dwordx4 v[4:7], v232, s[64:67], 0 offen offset:2064 nt
	v_add_u32_e32 v232, 6656, v232
	v_pk_add_f32 v[224:225], v[144:145], v[160:161] neg_lo:[0,1] neg_hi:[0,1]
	v_pk_add_f32 v[226:227], v[176:177], v[160:161] neg_lo:[0,1] neg_hi:[0,1]
	v_pk_fma_f32 v[192:193], v[96:97], v[224:225], v[160:161]
	v_pk_fma_f32 v[192:193], v[112:113], v[226:227], v[192:193]
	v_pk_add_f32 v[224:225], v[146:147], v[162:163] neg_lo:[0,1] neg_hi:[0,1]
	v_pk_add_f32 v[226:227], v[178:179], v[162:163] neg_lo:[0,1] neg_hi:[0,1]
	v_pk_fma_f32 v[194:195], v[98:99], v[224:225], v[162:163]
	v_pk_fma_f32 v[194:195], v[114:115], v[226:227], v[194:195]
	v_pk_add_f32 v[224:225], v[148:149], v[164:165] neg_lo:[0,1] neg_hi:[0,1]
	v_pk_add_f32 v[226:227], v[180:181], v[164:165] neg_lo:[0,1] neg_hi:[0,1]
	v_pk_fma_f32 v[196:197], v[100:101], v[224:225], v[164:165]
	v_pk_fma_f32 v[196:197], v[116:117], v[226:227], v[196:197]
	v_pk_add_f32 v[224:225], v[150:151], v[166:167] neg_lo:[0,1] neg_hi:[0,1]
	v_pk_add_f32 v[226:227], v[182:183], v[166:167] neg_lo:[0,1] neg_hi:[0,1]
	v_pk_fma_f32 v[198:199], v[102:103], v[224:225], v[166:167]
	v_pk_fma_f32 v[198:199], v[118:119], v[226:227], v[198:199]
	v_pk_add_f32 v[224:225], v[152:153], v[168:169] neg_lo:[0,1] neg_hi:[0,1]
	v_pk_add_f32 v[226:227], v[184:185], v[168:169] neg_lo:[0,1] neg_hi:[0,1]
	v_pk_fma_f32 v[200:201], v[104:105], v[224:225], v[168:169]
	v_pk_fma_f32 v[200:201], v[120:121], v[226:227], v[200:201]
	v_pk_add_f32 v[224:225], v[154:155], v[170:171] neg_lo:[0,1] neg_hi:[0,1]
	v_pk_add_f32 v[226:227], v[186:187], v[170:171] neg_lo:[0,1] neg_hi:[0,1]
	v_pk_fma_f32 v[202:203], v[106:107], v[224:225], v[170:171]
	v_pk_fma_f32 v[202:203], v[122:123], v[226:227], v[202:203]
	v_pk_add_f32 v[224:225], v[156:157], v[172:173] neg_lo:[0,1] neg_hi:[0,1]
	v_pk_add_f32 v[226:227], v[188:189], v[172:173] neg_lo:[0,1] neg_hi:[0,1]
	v_pk_fma_f32 v[204:205], v[108:109], v[224:225], v[172:173]
	v_pk_fma_f32 v[204:205], v[124:125], v[226:227], v[204:205]
	v_pk_add_f32 v[224:225], v[158:159], v[174:175] neg_lo:[0,1] neg_hi:[0,1]
	v_pk_add_f32 v[226:227], v[190:191], v[174:175] neg_lo:[0,1] neg_hi:[0,1]
	v_pk_fma_f32 v[206:207], v[110:111], v[224:225], v[174:175]
	v_pk_fma_f32 v[206:207], v[126:127], v[226:227], v[206:207]
	v_pk_mul_f32 v[208:209], v[192:193], v[128:129]
	v_pk_mul_f32 v[210:211], v[194:195], v[130:131]
	v_pk_mul_f32 v[212:213], v[196:197], v[132:133]
	v_pk_mul_f32 v[214:215], v[198:199], v[134:135]
	v_pk_mul_f32 v[216:217], v[200:201], v[136:137]
	v_pk_mul_f32 v[218:219], v[202:203], v[138:139]
	v_pk_mul_f32 v[220:221], v[204:205], v[140:141]
	v_pk_mul_f32 v[222:223], v[206:207], v[142:143]
	v_mul_f32_e32 v224, v208, v208
	v_fmac_f32_e32 v224, v209, v209
	v_fmac_f32_e32 v224, v210, v210
	v_fmac_f32_e32 v224, v211, v211
	v_fmac_f32_e32 v224, v212, v212
	v_fmac_f32_e32 v224, v213, v213
	v_fmac_f32_e32 v224, v214, v214
	v_fmac_f32_e32 v224, v215, v215
	v_fmac_f32_e32 v224, v216, v216
	v_fmac_f32_e32 v224, v217, v217
	v_fmac_f32_e32 v224, v218, v218
	v_fmac_f32_e32 v224, v219, v219
	v_fmac_f32_e32 v224, v220, v220
	v_fmac_f32_e32 v224, v221, v221
	v_fmac_f32_e32 v224, v222, v222
	v_fmac_f32_e32 v224, v223, v223
	s_nop 1
	v_add_f32_dpp v224, v224, v224 quad_perm:[1,0,3,2] row_mask:0xf bank_mask:0xf
	s_nop 1
	v_add_f32_dpp v224, v224, v224 quad_perm:[2,3,0,1] row_mask:0xf bank_mask:0xf
	v_sqrt_f32_e32 v224, v224
	s_nop 0
	v_max_f32_e32 v224, 0x2b8cbccc, v224
	v_rcp_f32_e32 v224, v224
	s_nop 0
	v_xor_b32_e32 v224, 0x80000000, v224
	v_mov_b32_e32 v225, v224
	v_cvt_pk_bf16_f32 v144, v192, v193
	v_cvt_pk_bf16_f32 v145, v194, v195
	v_cvt_pk_bf16_f32 v146, v196, v197
	v_cvt_pk_bf16_f32 v147, v198, v199
	v_cvt_pk_bf16_f32 v148, v200, v201
	v_cvt_pk_bf16_f32 v149, v202, v203
	v_cvt_pk_bf16_f32 v150, v204, v205
	v_cvt_pk_bf16_f32 v151, v206, v207
	v_pk_mul_f32 v[208:209], v[208:209], v[224:225]
	v_pk_mul_f32 v[210:211], v[210:211], v[224:225]
	v_pk_mul_f32 v[212:213], v[212:213], v[224:225]
	v_pk_mul_f32 v[214:215], v[214:215], v[224:225]
	v_pk_mul_f32 v[216:217], v[216:217], v[224:225]
	v_pk_mul_f32 v[218:219], v[218:219], v[224:225]
	v_pk_mul_f32 v[220:221], v[220:221], v[224:225]
	v_pk_mul_f32 v[222:223], v[222:223], v[224:225]
	buffer_store_dwordx4 v[208:211], v234, s[68:71], s72 offen offset:0
	buffer_store_dwordx4 v[212:215], v234, s[68:71], s72 offen offset:16
	buffer_store_dwordx4 v[216:219], v234, s[68:71], s72 offen offset:32
	buffer_store_dwordx4 v[220:223], v234, s[68:71], s72 offen offset:48
	buffer_store_dwordx4 v[144:147], v236, s[68:71], s73 offen offset:0
	buffer_store_dwordx4 v[148:151], v236, s[68:71], s73 offen offset:16
	s_add_u32 s72, s72, 0x1000
	s_add_u32 s73, s73, 0x800
	s_add_u32 s74, s74, 0x200
	s_add_u32 s75, s75, 0x40
	s_waitcnt vmcnt(46)
; __device__ __forceinline__ void prep_phase(const Params& p) {
;     ...
;             for (int i = 0; i < 16; ++i) {
;                 const bool hn = (tt0 + i) < SEQ - 1; const Z16 kn = hn ? ldz(zc + (size_t)(i + 1) * 3328) : zz();
;                 float k[16], kk[16]; mix16(kp, kc, kn, mpk, mnk, k);
;                 float s2 = 0.f;
; #pragma unroll
;                 for (int q = 0; q < 16; ++q) { kk[q] = k[q] * kkc[q]; s2 += kk[q] * kk[q]; }
;                 s2 += __shfl_xor(s2, 1); s2 += __shfl_xor(s2, 2);
;                 const float inv = -1.0f / fmaxf(sqrtf(s2), 1e-12f);
;                 const size_t o = (size_t)(t0 + i) * RW + c;
; #pragma unroll
;                 for (int j4 = 0; j4 < 4; ++j4) *(f32x4*)(A + o + j4 * 4) = (f32x4){kk[j4 * 4] * inv, kk[j4 * 4 + 1] * inv, kk[j4 * 4 + 2] * inv, kk[j4 * 4 + 3] * inv};
;                 st16bf(Kb + o, k);
;                 kp = kc; kc = kn;
	v_lshlrev_b32_e32 v144, 16, v12
	v_and_b32_e32 v145, 0xffff0000, v12
	v_lshlrev_b32_e32 v146, 16, v13
	v_and_b32_e32 v147, 0xffff0000, v13
	v_lshlrev_b32_e32 v148, 16, v14
	v_and_b32_e32 v149, 0xffff0000, v14
	v_lshlrev_b32_e32 v150, 16, v15
	v_and_b32_e32 v151, 0xffff0000, v15
	v_lshlrev_b32_e32 v152, 16, v16
	v_and_b32_e32 v153, 0xffff0000, v16
	v_lshlrev_b32_e32 v154, 16, v17
	v_and_b32_e32 v155, 0xffff0000, v17
	v_lshlrev_b32_e32 v156, 16, v18
	v_and_b32_e32 v157, 0xffff0000, v18
	v_lshlrev_b32_e32 v158, 16, v19
	v_and_b32_e32 v159, 0xffff0000, v19
	v_lshlrev_b32_e32 v160, 16, v24
	v_and_b32_e32 v161, 0xffff0000, v24
	v_lshlrev_b32_e32 v162, 16, v25
	v_and_b32_e32 v163, 0xffff0000, v25
	v_lshlrev_b32_e32 v164, 16, v26
	v_and_b32_e32 v165, 0xffff0000, v26
	v_lshlrev_b32_e32 v166, 16, v27
	v_and_b32_e32 v167, 0xffff0000, v27
	v_lshlrev_b32_e32 v168, 16, v28
	v_and_b32_e32 v169, 0xffff0000, v28
	v_lshlrev_b32_e32 v170, 16, v29
	v_and_b32_e32 v171, 0xffff0000, v29
	v_lshlrev_b32_e32 v172, 16, v30
	v_and_b32_e32 v173, 0xffff0000, v30
	v_lshlrev_b32_e32 v174, 16, v31
	v_and_b32_e32 v175, 0xffff0000, v31
	v_lshlrev_b32_e32 v176, 16, v36
	v_and_b32_e32 v177, 0xffff0000, v36
	v_lshlrev_b32_e32 v178, 16, v37
	v_and_b32_e32 v179, 0xffff0000, v37
	v_lshlrev_b32_e32 v180, 16, v38
	v_and_b32_e32 v181, 0xffff0000, v38
	v_lshlrev_b32_e32 v182, 16, v39
	v_and_b32_e32 v183, 0xffff0000, v39
	v_lshlrev_b32_e32 v184, 16, v40
	v_and_b32_e32 v185, 0xffff0000, v40
	v_lshlrev_b32_e32 v186, 16, v41
	v_and_b32_e32 v187, 0xffff0000, v41
	v_lshlrev_b32_e32 v188, 16, v42
	v_and_b32_e32 v189, 0xffff0000, v42
	v_lshlrev_b32_e32 v190, 16, v43
	v_and_b32_e32 v191, 0xffff0000, v43
	buffer_load_dwordx4 v[12:15], v232, s[64:67], 0 offen offset:2048 nt
	buffer_load_dwordx4 v[16:19], v232, s[64:67], 0 offen offset:2064 nt
	v_add_u32_e32 v232, 6656, v232
	v_pk_add_f32 v[224:225], v[144:145], v[160:161] neg_lo:[0,1] neg_hi:[0,1]
	v_pk_add_f32 v[226:227], v[176:177], v[160:161] neg_lo:[0,1] neg_hi:[0,1]
	v_pk_fma_f32 v[192:193], v[96:97], v[224:225], v[160:161]
	v_pk_fma_f32 v[192:193], v[112:113], v[226:227], v[192:193]
	v_pk_add_f32 v[224:225], v[146:147], v[162:163] neg_lo:[0,1] neg_hi:[0,1]
	v_pk_add_f32 v[226:227], v[178:179], v[162:163] neg_lo:[0,1] neg_hi:[0,1]
	v_pk_fma_f32 v[194:195], v[98:99], v[224:225], v[162:163]
	v_pk_fma_f32 v[194:195], v[114:115], v[226:227], v[194:195]
	v_pk_add_f32 v[224:225], v[148:149], v[164:165] neg_lo:[0,1] neg_hi:[0,1]
	v_pk_add_f32 v[226:227], v[180:181], v[164:165] neg_lo:[0,1] neg_hi:[0,1]
	v_pk_fma_f32 v[196:197], v[100:101], v[224:225], v[164:165]
	v_pk_fma_f32 v[196:197], v[116:117], v[226:227], v[196:197]
	v_pk_add_f32 v[224:225], v[150:151], v[166:167] neg_lo:[0,1] neg_hi:[0,1]
	v_pk_add_f32 v[226:227], v[182:183], v[166:167] neg_lo:[0,1] neg_hi:[0,1]
	v_pk_fma_f32 v[198:199], v[102:103], v[224:225], v[166:167]
	v_pk_fma_f32 v[198:199], v[118:119], v[226:227], v[198:199]
	v_pk_add_f32 v[224:225], v[152:153], v[168:169] neg_lo:[0,1] neg_hi:[0,1]
	v_pk_add_f32 v[226:227], v[184:185], v[168:169] neg_lo:[0,1] neg_hi:[0,1]
	v_pk_fma_f32 v[200:201], v[104:105], v[224:225], v[168:169]
	v_pk_fma_f32 v[200:201], v[120:121], v[226:227], v[200:201]
	v_pk_add_f32 v[224:225], v[154:155], v[170:171] neg_lo:[0,1] neg_hi:[0,1]
	v_pk_add_f32 v[226:227], v[186:187], v[170:171] neg_lo:[0,1] neg_hi:[0,1]
	v_pk_fma_f32 v[202:203], v[106:107], v[224:225], v[170:171]
	v_pk_fma_f32 v[202:203], v[122:123], v[226:227], v[202:203]
	v_pk_add_f32 v[224:225], v[156:157], v[172:173] neg_lo:[0,1] neg_hi:[0,1]
	v_pk_add_f32 v[226:227], v[188:189], v[172:173] neg_lo:[0,1] neg_hi:[0,1]
	v_pk_fma_f32 v[204:205], v[108:109], v[224:225], v[172:173]
	v_pk_fma_f32 v[204:205], v[124:125], v[226:227], v[204:205]
	v_pk_add_f32 v[224:225], v[158:159], v[174:175] neg_lo:[0,1] neg_hi:[0,1]
	v_pk_add_f32 v[226:227], v[190:191], v[174:175] neg_lo:[0,1] neg_hi:[0,1]
	v_pk_fma_f32 v[206:207], v[110:111], v[224:225], v[174:175]
	v_pk_fma_f32 v[206:207], v[126:127], v[226:227], v[206:207]
	v_pk_mul_f32 v[208:209], v[192:193], v[128:129]
	v_pk_mul_f32 v[210:211], v[194:195], v[130:131]
	v_pk_mul_f32 v[212:213], v[196:197], v[132:133]
	v_pk_mul_f32 v[214:215], v[198:199], v[134:135]
	v_pk_mul_f32 v[216:217], v[200:201], v[136:137]
	v_pk_mul_f32 v[218:219], v[202:203], v[138:139]
	v_pk_mul_f32 v[220:221], v[204:205], v[140:141]
	v_pk_mul_f32 v[222:223], v[206:207], v[142:143]
	v_mul_f32_e32 v224, v208, v208
	v_fmac_f32_e32 v224, v209, v209
	v_fmac_f32_e32 v224, v210, v210
	v_fmac_f32_e32 v224, v211, v211
	v_fmac_f32_e32 v224, v212, v212
	v_fmac_f32_e32 v224, v213, v213
	v_fmac_f32_e32 v224, v214, v214
	v_fmac_f32_e32 v224, v215, v215
	v_fmac_f32_e32 v224, v216, v216
	v_fmac_f32_e32 v224, v217, v217
	v_fmac_f32_e32 v224, v218, v218
	v_fmac_f32_e32 v224, v219, v219
	v_fmac_f32_e32 v224, v220, v220
	v_fmac_f32_e32 v224, v221, v221
	v_fmac_f32_e32 v224, v222, v222
	v_fmac_f32_e32 v224, v223, v223
	s_nop 1
	v_add_f32_dpp v224, v224, v224 quad_perm:[1,0,3,2] row_mask:0xf bank_mask:0xf
	s_nop 1
	v_add_f32_dpp v224, v224, v224 quad_perm:[2,3,0,1] row_mask:0xf bank_mask:0xf
	v_sqrt_f32_e32 v224, v224
	s_nop 0
	v_max_f32_e32 v224, 0x2b8cbccc, v224
	v_rcp_f32_e32 v224, v224
	s_nop 0
	v_xor_b32_e32 v224, 0x80000000, v224
	v_mov_b32_e32 v225, v224
	v_cvt_pk_bf16_f32 v144, v192, v193
	v_cvt_pk_bf16_f32 v145, v194, v195
	v_cvt_pk_bf16_f32 v146, v196, v197
	v_cvt_pk_bf16_f32 v147, v198, v199
	v_cvt_pk_bf16_f32 v148, v200, v201
	v_cvt_pk_bf16_f32 v149, v202, v203
	v_cvt_pk_bf16_f32 v150, v204, v205
	v_cvt_pk_bf16_f32 v151, v206, v207
	v_pk_mul_f32 v[208:209], v[208:209], v[224:225]
	v_pk_mul_f32 v[210:211], v[210:211], v[224:225]
	v_pk_mul_f32 v[212:213], v[212:213], v[224:225]
	v_pk_mul_f32 v[214:215], v[214:215], v[224:225]
	v_pk_mul_f32 v[216:217], v[216:217], v[224:225]
	v_pk_mul_f32 v[218:219], v[218:219], v[224:225]
	v_pk_mul_f32 v[220:221], v[220:221], v[224:225]
	v_pk_mul_f32 v[222:223], v[222:223], v[224:225]
	buffer_store_dwordx4 v[208:211], v234, s[68:71], s72 offen offset:0
	buffer_store_dwordx4 v[212:215], v234, s[68:71], s72 offen offset:16
	buffer_store_dwordx4 v[216:219], v234, s[68:71], s72 offen offset:32
	buffer_store_dwordx4 v[220:223], v234, s[68:71], s72 offen offset:48
	buffer_store_dwordx4 v[144:147], v236, s[68:71], s73 offen offset:0
	buffer_store_dwordx4 v[148:151], v236, s[68:71], s73 offen offset:16
	s_add_u32 s72, s72, 0x1000
	s_add_u32 s73, s73, 0x800
	s_add_u32 s74, s74, 0x200
	s_add_u32 s75, s75, 0x40
	s_waitcnt vmcnt(46)
; __device__ __forceinline__ void prep_phase(const Params& p) {
;     ...
;             for (int i = 0; i < 16; ++i) {
;                 const bool hn = (tt0 + i) < SEQ - 1; const Z16 kn = hn ? ldz(zc + (size_t)(i + 1) * 3328) : zz();
;                 float k[16], kk[16]; mix16(kp, kc, kn, mpk, mnk, k);
;                 float s2 = 0.f;
; #pragma unroll
;                 for (int q = 0; q < 16; ++q) { kk[q] = k[q] * kkc[q]; s2 += kk[q] * kk[q]; }
;                 s2 += __shfl_xor(s2, 1); s2 += __shfl_xor(s2, 2);
;                 const float inv = -1.0f / fmaxf(sqrtf(s2), 1e-12f);
;                 const size_t o = (size_t)(t0 + i) * RW + c;
; #pragma unroll
;                 for (int j4 = 0; j4 < 4; ++j4) *(f32x4*)(A + o + j4 * 4) = (f32x4){kk[j4 * 4] * inv, kk[j4 * 4 + 1] * inv, kk[j4 * 4 + 2] * inv, kk[j4 * 4 + 3] * inv};
;                 st16bf(Kb + o, k);
;                 kp = kc; kc = kn;
	v_lshlrev_b32_e32 v144, 16, v24
	v_and_b32_e32 v145, 0xffff0000, v24
	v_lshlrev_b32_e32 v146, 16, v25
	v_and_b32_e32 v147, 0xffff0000, v25
	v_lshlrev_b32_e32 v148, 16, v26
	v_and_b32_e32 v149, 0xffff0000, v26
	v_lshlrev_b32_e32 v150, 16, v27
	v_and_b32_e32 v151, 0xffff0000, v27
	v_lshlrev_b32_e32 v152, 16, v28
	v_and_b32_e32 v153, 0xffff0000, v28
	v_lshlrev_b32_e32 v154, 16, v29
	v_and_b32_e32 v155, 0xffff0000, v29
	v_lshlrev_b32_e32 v156, 16, v30
	v_and_b32_e32 v157, 0xffff0000, v30
	v_lshlrev_b32_e32 v158, 16, v31
	v_and_b32_e32 v159, 0xffff0000, v31
	v_lshlrev_b32_e32 v160, 16, v36
	v_and_b32_e32 v161, 0xffff0000, v36
	v_lshlrev_b32_e32 v162, 16, v37
	v_and_b32_e32 v163, 0xffff0000, v37
	v_lshlrev_b32_e32 v164, 16, v38
	v_and_b32_e32 v165, 0xffff0000, v38
	v_lshlrev_b32_e32 v166, 16, v39
	v_and_b32_e32 v167, 0xffff0000, v39
	v_lshlrev_b32_e32 v168, 16, v40
	v_and_b32_e32 v169, 0xffff0000, v40
	v_lshlrev_b32_e32 v170, 16, v41
	v_and_b32_e32 v171, 0xffff0000, v41
	v_lshlrev_b32_e32 v172, 16, v42
	v_and_b32_e32 v173, 0xffff0000, v42
	v_lshlrev_b32_e32 v174, 16, v43
	v_and_b32_e32 v175, 0xffff0000, v43
	v_lshlrev_b32_e32 v176, 16, v48
	v_and_b32_e32 v177, 0xffff0000, v48
	v_lshlrev_b32_e32 v178, 16, v49
	v_and_b32_e32 v179, 0xffff0000, v49
	v_lshlrev_b32_e32 v180, 16, v50
	v_and_b32_e32 v181, 0xffff0000, v50
	v_lshlrev_b32_e32 v182, 16, v51
	v_and_b32_e32 v183, 0xffff0000, v51
	v_lshlrev_b32_e32 v184, 16, v52
	v_and_b32_e32 v185, 0xffff0000, v52
	v_lshlrev_b32_e32 v186, 16, v53
	v_and_b32_e32 v187, 0xffff0000, v53
	v_lshlrev_b32_e32 v188, 16, v54
	v_and_b32_e32 v189, 0xffff0000, v54
	v_lshlrev_b32_e32 v190, 16, v55
	v_and_b32_e32 v191, 0xffff0000, v55
	v_pk_add_f32 v[224:225], v[144:145], v[160:161] neg_lo:[0,1] neg_hi:[0,1]
	v_pk_add_f32 v[226:227], v[176:177], v[160:161] neg_lo:[0,1] neg_hi:[0,1]
	v_pk_fma_f32 v[192:193], v[96:97], v[224:225], v[160:161]
	v_pk_fma_f32 v[192:193], v[112:113], v[226:227], v[192:193]
	v_pk_add_f32 v[224:225], v[146:147], v[162:163] neg_lo:[0,1] neg_hi:[0,1]
	v_pk_add_f32 v[226:227], v[178:179], v[162:163] neg_lo:[0,1] neg_hi:[0,1]
	v_pk_fma_f32 v[194:195], v[98:99], v[224:225], v[162:163]
	v_pk_fma_f32 v[194:195], v[114:115], v[226:227], v[194:195]
	v_pk_add_f32 v[224:225], v[148:149], v[164:165] neg_lo:[0,1] neg_hi:[0,1]
	v_pk_add_f32 v[226:227], v[180:181], v[164:165] neg_lo:[0,1] neg_hi:[0,1]
	v_pk_fma_f32 v[196:197], v[100:101], v[224:225], v[164:165]
	v_pk_fma_f32 v[196:197], v[116:117], v[226:227], v[196:197]
	v_pk_add_f32 v[224:225], v[150:151], v[166:167] neg_lo:[0,1] neg_hi:[0,1]
	v_pk_add_f32 v[226:227], v[182:183], v[166:167] neg_lo:[0,1] neg_hi:[0,1]
	v_pk_fma_f32 v[198:199], v[102:103], v[224:225], v[166:167]
	v_pk_fma_f32 v[198:199], v[118:119], v[226:227], v[198:199]
	v_pk_add_f32 v[224:225], v[152:153], v[168:169] neg_lo:[0,1] neg_hi:[0,1]
	v_pk_add_f32 v[226:227], v[184:185], v[168:169] neg_lo:[0,1] neg_hi:[0,1]
	v_pk_fma_f32 v[200:201], v[104:105], v[224:225], v[168:169]
	v_pk_fma_f32 v[200:201], v[120:121], v[226:227], v[200:201]
	v_pk_add_f32 v[224:225], v[154:155], v[170:171] neg_lo:[0,1] neg_hi:[0,1]
	v_pk_add_f32 v[226:227], v[186:187], v[170:171] neg_lo:[0,1] neg_hi:[0,1]
	v_pk_fma_f32 v[202:203], v[106:107], v[224:225], v[170:171]
	v_pk_fma_f32 v[202:203], v[122:123], v[226:227], v[202:203]
	v_pk_add_f32 v[224:225], v[156:157], v[172:173] neg_lo:[0,1] neg_hi:[0,1]
	v_pk_add_f32 v[226:227], v[188:189], v[172:173] neg_lo:[0,1] neg_hi:[0,1]
	v_pk_fma_f32 v[204:205], v[108:109], v[224:225], v[172:173]
	v_pk_fma_f32 v[204:205], v[124:125], v[226:227], v[204:205]
	v_pk_add_f32 v[224:225], v[158:159], v[174:175] neg_lo:[0,1] neg_hi:[0,1]
	v_pk_add_f32 v[226:227], v[190:191], v[174:175] neg_lo:[0,1] neg_hi:[0,1]
	v_pk_fma_f32 v[206:207], v[110:111], v[224:225], v[174:175]
	v_pk_fma_f32 v[206:207], v[126:127], v[226:227], v[206:207]
	v_pk_mul_f32 v[208:209], v[192:193], v[128:129]
	v_pk_mul_f32 v[210:211], v[194:195], v[130:131]
	v_pk_mul_f32 v[212:213], v[196:197], v[132:133]
	v_pk_mul_f32 v[214:215], v[198:199], v[134:135]
	v_pk_mul_f32 v[216:217], v[200:201], v[136:137]
	v_pk_mul_f32 v[218:219], v[202:203], v[138:139]
	v_pk_mul_f32 v[220:221], v[204:205], v[140:141]
	v_pk_mul_f32 v[222:223], v[206:207], v[142:143]
	v_mul_f32_e32 v224, v208, v208
	v_fmac_f32_e32 v224, v209, v209
	v_fmac_f32_e32 v224, v210, v210
	v_fmac_f32_e32 v224, v211, v211
	v_fmac_f32_e32 v224, v212, v212
	v_fmac_f32_e32 v224, v213, v213
	v_fmac_f32_e32 v224, v214, v214
	v_fmac_f32_e32 v224, v215, v215
	v_fmac_f32_e32 v224, v216, v216
	v_fmac_f32_e32 v224, v217, v217
	v_fmac_f32_e32 v224, v218, v218
	v_fmac_f32_e32 v224, v219, v219
	v_fmac_f32_e32 v224, v220, v220
	v_fmac_f32_e32 v224, v221, v221
	v_fmac_f32_e32 v224, v222, v222
	v_fmac_f32_e32 v224, v223, v223
	s_nop 1
	v_add_f32_dpp v224, v224, v224 quad_perm:[1,0,3,2] row_mask:0xf bank_mask:0xf
	s_nop 1
	v_add_f32_dpp v224, v224, v224 quad_perm:[2,3,0,1] row_mask:0xf bank_mask:0xf
	v_sqrt_f32_e32 v224, v224
	s_nop 0
	v_max_f32_e32 v224, 0x2b8cbccc, v224
	v_rcp_f32_e32 v224, v224
	s_nop 0
	v_xor_b32_e32 v224, 0x80000000, v224
	v_mov_b32_e32 v225, v224
	v_cvt_pk_bf16_f32 v144, v192, v193
	v_cvt_pk_bf16_f32 v145, v194, v195
	v_cvt_pk_bf16_f32 v146, v196, v197
	v_cvt_pk_bf16_f32 v147, v198, v199
	v_cvt_pk_bf16_f32 v148, v200, v201
	v_cvt_pk_bf16_f32 v149, v202, v203
	v_cvt_pk_bf16_f32 v150, v204, v205
	v_cvt_pk_bf16_f32 v151, v206, v207
	v_pk_mul_f32 v[208:209], v[208:209], v[224:225]
	v_pk_mul_f32 v[210:211], v[210:211], v[224:225]
	v_pk_mul_f32 v[212:213], v[212:213], v[224:225]
	v_pk_mul_f32 v[214:215], v[214:215], v[224:225]
	v_pk_mul_f32 v[216:217], v[216:217], v[224:225]
	v_pk_mul_f32 v[218:219], v[218:219], v[224:225]
	v_pk_mul_f32 v[220:221], v[220:221], v[224:225]
	v_pk_mul_f32 v[222:223], v[222:223], v[224:225]
	buffer_store_dwordx4 v[208:211], v234, s[68:71], s72 offen offset:0
	buffer_store_dwordx4 v[212:215], v234, s[68:71], s72 offen offset:16
	buffer_store_dwordx4 v[216:219], v234, s[68:71], s72 offen offset:32
	buffer_store_dwordx4 v[220:223], v234, s[68:71], s72 offen offset:48
	buffer_store_dwordx4 v[144:147], v236, s[68:71], s73 offen offset:0
	buffer_store_dwordx4 v[148:151], v236, s[68:71], s73 offen offset:16
	s_add_u32 s72, s72, 0x1000
	s_add_u32 s73, s73, 0x800
	s_add_u32 s74, s74, 0x200
	s_add_u32 s75, s75, 0x40
	s_waitcnt vmcnt(44)
; __device__ __forceinline__ void prep_phase(const Params& p) {
;     ...
;             for (int i = 0; i < 16; ++i) {
;                 const bool hn = (tt0 + i) < SEQ - 1; const Z16 kn = hn ? ldz(zc + (size_t)(i + 1) * 3328) : zz();
;                 float k[16], kk[16]; mix16(kp, kc, kn, mpk, mnk, k);
;                 float s2 = 0.f;
; #pragma unroll
;                 for (int q = 0; q < 16; ++q) { kk[q] = k[q] * kkc[q]; s2 += kk[q] * kk[q]; }
;                 s2 += __shfl_xor(s2, 1); s2 += __shfl_xor(s2, 2);
;                 const float inv = -1.0f / fmaxf(sqrtf(s2), 1e-12f);
;                 const size_t o = (size_t)(t0 + i) * RW + c;
; #pragma unroll
;                 for (int j4 = 0; j4 < 4; ++j4) *(f32x4*)(A + o + j4 * 4) = (f32x4){kk[j4 * 4] * inv, kk[j4 * 4 + 1] * inv, kk[j4 * 4 + 2] * inv, kk[j4 * 4 + 3] * inv};
;                 st16bf(Kb + o, k);
;                 kp = kc; kc = kn;
	v_lshlrev_b32_e32 v144, 16, v36
	v_and_b32_e32 v145, 0xffff0000, v36
	v_lshlrev_b32_e32 v146, 16, v37
	v_and_b32_e32 v147, 0xffff0000, v37
	v_lshlrev_b32_e32 v148, 16, v38
	v_and_b32_e32 v149, 0xffff0000, v38
	v_lshlrev_b32_e32 v150, 16, v39
	v_and_b32_e32 v151, 0xffff0000, v39
	v_lshlrev_b32_e32 v152, 16, v40
	v_and_b32_e32 v153, 0xffff0000, v40
	v_lshlrev_b32_e32 v154, 16, v41
	v_and_b32_e32 v155, 0xffff0000, v41
	v_lshlrev_b32_e32 v156, 16, v42
	v_and_b32_e32 v157, 0xffff0000, v42
	v_lshlrev_b32_e32 v158, 16, v43
	v_and_b32_e32 v159, 0xffff0000, v43
	v_lshlrev_b32_e32 v160, 16, v48
	v_and_b32_e32 v161, 0xffff0000, v48
	v_lshlrev_b32_e32 v162, 16, v49
	v_and_b32_e32 v163, 0xffff0000, v49
	v_lshlrev_b32_e32 v164, 16, v50
	v_and_b32_e32 v165, 0xffff0000, v50
	v_lshlrev_b32_e32 v166, 16, v51
	v_and_b32_e32 v167, 0xffff0000, v51
	v_lshlrev_b32_e32 v168, 16, v52
	v_and_b32_e32 v169, 0xffff0000, v52
	v_lshlrev_b32_e32 v170, 16, v53
	v_and_b32_e32 v171, 0xffff0000, v53
	v_lshlrev_b32_e32 v172, 16, v54
	v_and_b32_e32 v173, 0xffff0000, v54
	v_lshlrev_b32_e32 v174, 16, v55
	v_and_b32_e32 v175, 0xffff0000, v55
	v_lshlrev_b32_e32 v176, 16, v60
	v_and_b32_e32 v177, 0xffff0000, v60
	v_lshlrev_b32_e32 v178, 16, v61
	v_and_b32_e32 v179, 0xffff0000, v61
	v_lshlrev_b32_e32 v180, 16, v62
	v_and_b32_e32 v181, 0xffff0000, v62
	v_lshlrev_b32_e32 v182, 16, v63
	v_and_b32_e32 v183, 0xffff0000, v63
	v_lshlrev_b32_e32 v184, 16, v64
	v_and_b32_e32 v185, 0xffff0000, v64
	v_lshlrev_b32_e32 v186, 16, v65
	v_and_b32_e32 v187, 0xffff0000, v65
	v_lshlrev_b32_e32 v188, 16, v66
	v_and_b32_e32 v189, 0xffff0000, v66
	v_lshlrev_b32_e32 v190, 16, v67
	v_and_b32_e32 v191, 0xffff0000, v67
	v_pk_add_f32 v[224:225], v[144:145], v[160:161] neg_lo:[0,1] neg_hi:[0,1]
	v_pk_add_f32 v[226:227], v[176:177], v[160:161] neg_lo:[0,1] neg_hi:[0,1]
	v_pk_fma_f32 v[192:193], v[96:97], v[224:225], v[160:161]
	v_pk_fma_f32 v[192:193], v[112:113], v[226:227], v[192:193]
	v_pk_add_f32 v[224:225], v[146:147], v[162:163] neg_lo:[0,1] neg_hi:[0,1]
	v_pk_add_f32 v[226:227], v[178:179], v[162:163] neg_lo:[0,1] neg_hi:[0,1]
	v_pk_fma_f32 v[194:195], v[98:99], v[224:225], v[162:163]
	v_pk_fma_f32 v[194:195], v[114:115], v[226:227], v[194:195]
	v_pk_add_f32 v[224:225], v[148:149], v[164:165] neg_lo:[0,1] neg_hi:[0,1]
	v_pk_add_f32 v[226:227], v[180:181], v[164:165] neg_lo:[0,1] neg_hi:[0,1]
	v_pk_fma_f32 v[196:197], v[100:101], v[224:225], v[164:165]
	v_pk_fma_f32 v[196:197], v[116:117], v[226:227], v[196:197]
	v_pk_add_f32 v[224:225], v[150:151], v[166:167] neg_lo:[0,1] neg_hi:[0,1]
	v_pk_add_f32 v[226:227], v[182:183], v[166:167] neg_lo:[0,1] neg_hi:[0,1]
	v_pk_fma_f32 v[198:199], v[102:103], v[224:225], v[166:167]
	v_pk_fma_f32 v[198:199], v[118:119], v[226:227], v[198:199]
	v_pk_add_f32 v[224:225], v[152:153], v[168:169] neg_lo:[0,1] neg_hi:[0,1]
	v_pk_add_f32 v[226:227], v[184:185], v[168:169] neg_lo:[0,1] neg_hi:[0,1]
	v_pk_fma_f32 v[200:201], v[104:105], v[224:225], v[168:169]
	v_pk_fma_f32 v[200:201], v[120:121], v[226:227], v[200:201]
	v_pk_add_f32 v[224:225], v[154:155], v[170:171] neg_lo:[0,1] neg_hi:[0,1]
	v_pk_add_f32 v[226:227], v[186:187], v[170:171] neg_lo:[0,1] neg_hi:[0,1]
	v_pk_fma_f32 v[202:203], v[106:107], v[224:225], v[170:171]
	v_pk_fma_f32 v[202:203], v[122:123], v[226:227], v[202:203]
	v_pk_add_f32 v[224:225], v[156:157], v[172:173] neg_lo:[0,1] neg_hi:[0,1]
	v_pk_add_f32 v[226:227], v[188:189], v[172:173] neg_lo:[0,1] neg_hi:[0,1]
	v_pk_fma_f32 v[204:205], v[108:109], v[224:225], v[172:173]
	v_pk_fma_f32 v[204:205], v[124:125], v[226:227], v[204:205]
	v_pk_add_f32 v[224:225], v[158:159], v[174:175] neg_lo:[0,1] neg_hi:[0,1]
	v_pk_add_f32 v[226:227], v[190:191], v[174:175] neg_lo:[0,1] neg_hi:[0,1]
	v_pk_fma_f32 v[206:207], v[110:111], v[224:225], v[174:175]
	v_pk_fma_f32 v[206:207], v[126:127], v[226:227], v[206:207]
	v_pk_mul_f32 v[208:209], v[192:193], v[128:129]
	v_pk_mul_f32 v[210:211], v[194:195], v[130:131]
	v_pk_mul_f32 v[212:213], v[196:197], v[132:133]
	v_pk_mul_f32 v[214:215], v[198:199], v[134:135]
	v_pk_mul_f32 v[216:217], v[200:201], v[136:137]
	v_pk_mul_f32 v[218:219], v[202:203], v[138:139]
	v_pk_mul_f32 v[220:221], v[204:205], v[140:141]
	v_pk_mul_f32 v[222:223], v[206:207], v[142:143]
	v_mul_f32_e32 v224, v208, v208
	v_fmac_f32_e32 v224, v209, v209
	v_fmac_f32_e32 v224, v210, v210
	v_fmac_f32_e32 v224, v211, v211
	v_fmac_f32_e32 v224, v212, v212
	v_fmac_f32_e32 v224, v213, v213
	v_fmac_f32_e32 v224, v214, v214
	v_fmac_f32_e32 v224, v215, v215
	v_fmac_f32_e32 v224, v216, v216
	v_fmac_f32_e32 v224, v217, v217
	v_fmac_f32_e32 v224, v218, v218
	v_fmac_f32_e32 v224, v219, v219
	v_fmac_f32_e32 v224, v220, v220
	v_fmac_f32_e32 v224, v221, v221
	v_fmac_f32_e32 v224, v222, v222
	v_fmac_f32_e32 v224, v223, v223
	s_nop 1
	v_add_f32_dpp v224, v224, v224 quad_perm:[1,0,3,2] row_mask:0xf bank_mask:0xf
	s_nop 1
	v_add_f32_dpp v224, v224, v224 quad_perm:[2,3,0,1] row_mask:0xf bank_mask:0xf
	v_sqrt_f32_e32 v224, v224
	s_nop 0
	v_max_f32_e32 v224, 0x2b8cbccc, v224
	v_rcp_f32_e32 v224, v224
	s_nop 0
	v_xor_b32_e32 v224, 0x80000000, v224
	v_mov_b32_e32 v225, v224
	v_cvt_pk_bf16_f32 v144, v192, v193
	v_cvt_pk_bf16_f32 v145, v194, v195
	v_cvt_pk_bf16_f32 v146, v196, v197
	v_cvt_pk_bf16_f32 v147, v198, v199
	v_cvt_pk_bf16_f32 v148, v200, v201
	v_cvt_pk_bf16_f32 v149, v202, v203
	v_cvt_pk_bf16_f32 v150, v204, v205
	v_cvt_pk_bf16_f32 v151, v206, v207
	v_pk_mul_f32 v[208:209], v[208:209], v[224:225]
	v_pk_mul_f32 v[210:211], v[210:211], v[224:225]
	v_pk_mul_f32 v[212:213], v[212:213], v[224:225]
	v_pk_mul_f32 v[214:215], v[214:215], v[224:225]
	v_pk_mul_f32 v[216:217], v[216:217], v[224:225]
	v_pk_mul_f32 v[218:219], v[218:219], v[224:225]
	v_pk_mul_f32 v[220:221], v[220:221], v[224:225]
	v_pk_mul_f32 v[222:223], v[222:223], v[224:225]
	buffer_store_dwordx4 v[208:211], v234, s[68:71], s72 offen offset:0
	buffer_store_dwordx4 v[212:215], v234, s[68:71], s72 offen offset:16
	buffer_store_dwordx4 v[216:219], v234, s[68:71], s72 offen offset:32
	buffer_store_dwordx4 v[220:223], v234, s[68:71], s72 offen offset:48
	buffer_store_dwordx4 v[144:147], v236, s[68:71], s73 offen offset:0
	buffer_store_dwordx4 v[148:151], v236, s[68:71], s73 offen offset:16
	s_add_u32 s72, s72, 0x1000
	s_add_u32 s73, s73, 0x800
	s_add_u32 s74, s74, 0x200
	s_add_u32 s75, s75, 0x40
	s_waitcnt vmcnt(42)
; __device__ __forceinline__ void prep_phase(const Params& p) {
;     ...
;             for (int i = 0; i < 16; ++i) {
;                 const bool hn = (tt0 + i) < SEQ - 1; const Z16 kn = hn ? ldz(zc + (size_t)(i + 1) * 3328) : zz();
;                 float k[16], kk[16]; mix16(kp, kc, kn, mpk, mnk, k);
;                 float s2 = 0.f;
; #pragma unroll
;                 for (int q = 0; q < 16; ++q) { kk[q] = k[q] * kkc[q]; s2 += kk[q] * kk[q]; }
;                 s2 += __shfl_xor(s2, 1); s2 += __shfl_xor(s2, 2);
;                 const float inv = -1.0f / fmaxf(sqrtf(s2), 1e-12f);
;                 const size_t o = (size_t)(t0 + i) * RW + c;
; #pragma unroll
;                 for (int j4 = 0; j4 < 4; ++j4) *(f32x4*)(A + o + j4 * 4) = (f32x4){kk[j4 * 4] * inv, kk[j4 * 4 + 1] * inv, kk[j4 * 4 + 2] * inv, kk[j4 * 4 + 3] * inv};
;                 st16bf(Kb + o, k);
;                 kp = kc; kc = kn;
	v_lshlrev_b32_e32 v144, 16, v48
	v_and_b32_e32 v145, 0xffff0000, v48
	v_lshlrev_b32_e32 v146, 16, v49
	v_and_b32_e32 v147, 0xffff0000, v49
	v_lshlrev_b32_e32 v148, 16, v50
	v_and_b32_e32 v149, 0xffff0000, v50
	v_lshlrev_b32_e32 v150, 16, v51
	v_and_b32_e32 v151, 0xffff0000, v51
	v_lshlrev_b32_e32 v152, 16, v52
	v_and_b32_e32 v153, 0xffff0000, v52
	v_lshlrev_b32_e32 v154, 16, v53
	v_and_b32_e32 v155, 0xffff0000, v53
	v_lshlrev_b32_e32 v156, 16, v54
	v_and_b32_e32 v157, 0xffff0000, v54
	v_lshlrev_b32_e32 v158, 16, v55
	v_and_b32_e32 v159, 0xffff0000, v55
	v_lshlrev_b32_e32 v160, 16, v60
	v_and_b32_e32 v161, 0xffff0000, v60
	v_lshlrev_b32_e32 v162, 16, v61
	v_and_b32_e32 v163, 0xffff0000, v61
	v_lshlrev_b32_e32 v164, 16, v62
	v_and_b32_e32 v165, 0xffff0000, v62
	v_lshlrev_b32_e32 v166, 16, v63
	v_and_b32_e32 v167, 0xffff0000, v63
	v_lshlrev_b32_e32 v168, 16, v64
	v_and_b32_e32 v169, 0xffff0000, v64
	v_lshlrev_b32_e32 v170, 16, v65
	v_and_b32_e32 v171, 0xffff0000, v65
	v_lshlrev_b32_e32 v172, 16, v66
	v_and_b32_e32 v173, 0xffff0000, v66
	v_lshlrev_b32_e32 v174, 16, v67
	v_and_b32_e32 v175, 0xffff0000, v67
	v_lshlrev_b32_e32 v176, 16, v72
	v_and_b32_e32 v177, 0xffff0000, v72
	v_lshlrev_b32_e32 v178, 16, v73
	v_and_b32_e32 v179, 0xffff0000, v73
	v_lshlrev_b32_e32 v180, 16, v74
	v_and_b32_e32 v181, 0xffff0000, v74
	v_lshlrev_b32_e32 v182, 16, v75
	v_and_b32_e32 v183, 0xffff0000, v75
	v_lshlrev_b32_e32 v184, 16, v76
	v_and_b32_e32 v185, 0xffff0000, v76
	v_lshlrev_b32_e32 v186, 16, v77
	v_and_b32_e32 v187, 0xffff0000, v77
	v_lshlrev_b32_e32 v188, 16, v78
	v_and_b32_e32 v189, 0xffff0000, v78
	v_lshlrev_b32_e32 v190, 16, v79
	v_and_b32_e32 v191, 0xffff0000, v79
	v_pk_add_f32 v[224:225], v[144:145], v[160:161] neg_lo:[0,1] neg_hi:[0,1]
	v_pk_add_f32 v[226:227], v[176:177], v[160:161] neg_lo:[0,1] neg_hi:[0,1]
	v_pk_fma_f32 v[192:193], v[96:97], v[224:225], v[160:161]
	v_pk_fma_f32 v[192:193], v[112:113], v[226:227], v[192:193]
	v_pk_add_f32 v[224:225], v[146:147], v[162:163] neg_lo:[0,1] neg_hi:[0,1]
	v_pk_add_f32 v[226:227], v[178:179], v[162:163] neg_lo:[0,1] neg_hi:[0,1]
	v_pk_fma_f32 v[194:195], v[98:99], v[224:225], v[162:163]
	v_pk_fma_f32 v[194:195], v[114:115], v[226:227], v[194:195]
	v_pk_add_f32 v[224:225], v[148:149], v[164:165] neg_lo:[0,1] neg_hi:[0,1]
	v_pk_add_f32 v[226:227], v[180:181], v[164:165] neg_lo:[0,1] neg_hi:[0,1]
	v_pk_fma_f32 v[196:197], v[100:101], v[224:225], v[164:165]
	v_pk_fma_f32 v[196:197], v[116:117], v[226:227], v[196:197]
	v_pk_add_f32 v[224:225], v[150:151], v[166:167] neg_lo:[0,1] neg_hi:[0,1]
	v_pk_add_f32 v[226:227], v[182:183], v[166:167] neg_lo:[0,1] neg_hi:[0,1]
	v_pk_fma_f32 v[198:199], v[102:103], v[224:225], v[166:167]
	v_pk_fma_f32 v[198:199], v[118:119], v[226:227], v[198:199]
	v_pk_add_f32 v[224:225], v[152:153], v[168:169] neg_lo:[0,1] neg_hi:[0,1]
	v_pk_add_f32 v[226:227], v[184:185], v[168:169] neg_lo:[0,1] neg_hi:[0,1]
	v_pk_fma_f32 v[200:201], v[104:105], v[224:225], v[168:169]
	v_pk_fma_f32 v[200:201], v[120:121], v[226:227], v[200:201]
	v_pk_add_f32 v[224:225], v[154:155], v[170:171] neg_lo:[0,1] neg_hi:[0,1]
	v_pk_add_f32 v[226:227], v[186:187], v[170:171] neg_lo:[0,1] neg_hi:[0,1]
	v_pk_fma_f32 v[202:203], v[106:107], v[224:225], v[170:171]
	v_pk_fma_f32 v[202:203], v[122:123], v[226:227], v[202:203]
	v_pk_add_f32 v[224:225], v[156:157], v[172:173] neg_lo:[0,1] neg_hi:[0,1]
	v_pk_add_f32 v[226:227], v[188:189], v[172:173] neg_lo:[0,1] neg_hi:[0,1]
	v_pk_fma_f32 v[204:205], v[108:109], v[224:225], v[172:173]
	v_pk_fma_f32 v[204:205], v[124:125], v[226:227], v[204:205]
	v_pk_add_f32 v[224:225], v[158:159], v[174:175] neg_lo:[0,1] neg_hi:[0,1]
	v_pk_add_f32 v[226:227], v[190:191], v[174:175] neg_lo:[0,1] neg_hi:[0,1]
	v_pk_fma_f32 v[206:207], v[110:111], v[224:225], v[174:175]
	v_pk_fma_f32 v[206:207], v[126:127], v[226:227], v[206:207]
	v_pk_mul_f32 v[208:209], v[192:193], v[128:129]
	v_pk_mul_f32 v[210:211], v[194:195], v[130:131]
	v_pk_mul_f32 v[212:213], v[196:197], v[132:133]
	v_pk_mul_f32 v[214:215], v[198:199], v[134:135]
	v_pk_mul_f32 v[216:217], v[200:201], v[136:137]
	v_pk_mul_f32 v[218:219], v[202:203], v[138:139]
	v_pk_mul_f32 v[220:221], v[204:205], v[140:141]
	v_pk_mul_f32 v[222:223], v[206:207], v[142:143]
	v_mul_f32_e32 v224, v208, v208
	v_fmac_f32_e32 v224, v209, v209
	v_fmac_f32_e32 v224, v210, v210
	v_fmac_f32_e32 v224, v211, v211
	v_fmac_f32_e32 v224, v212, v212
	v_fmac_f32_e32 v224, v213, v213
	v_fmac_f32_e32 v224, v214, v214
	v_fmac_f32_e32 v224, v215, v215
	v_fmac_f32_e32 v224, v216, v216
	v_fmac_f32_e32 v224, v217, v217
	v_fmac_f32_e32 v224, v218, v218
	v_fmac_f32_e32 v224, v219, v219
	v_fmac_f32_e32 v224, v220, v220
	v_fmac_f32_e32 v224, v221, v221
	v_fmac_f32_e32 v224, v222, v222
	v_fmac_f32_e32 v224, v223, v223
	s_nop 1
	v_add_f32_dpp v224, v224, v224 quad_perm:[1,0,3,2] row_mask:0xf bank_mask:0xf
	s_nop 1
	v_add_f32_dpp v224, v224, v224 quad_perm:[2,3,0,1] row_mask:0xf bank_mask:0xf
	v_sqrt_f32_e32 v224, v224
	s_nop 0
	v_max_f32_e32 v224, 0x2b8cbccc, v224
	v_rcp_f32_e32 v224, v224
	s_nop 0
	v_xor_b32_e32 v224, 0x80000000, v224
	v_mov_b32_e32 v225, v224
	v_cvt_pk_bf16_f32 v144, v192, v193
	v_cvt_pk_bf16_f32 v145, v194, v195
	v_cvt_pk_bf16_f32 v146, v196, v197
	v_cvt_pk_bf16_f32 v147, v198, v199
	v_cvt_pk_bf16_f32 v148, v200, v201
	v_cvt_pk_bf16_f32 v149, v202, v203
	v_cvt_pk_bf16_f32 v150, v204, v205
	v_cvt_pk_bf16_f32 v151, v206, v207
	v_pk_mul_f32 v[208:209], v[208:209], v[224:225]
	v_pk_mul_f32 v[210:211], v[210:211], v[224:225]
	v_pk_mul_f32 v[212:213], v[212:213], v[224:225]
	v_pk_mul_f32 v[214:215], v[214:215], v[224:225]
	v_pk_mul_f32 v[216:217], v[216:217], v[224:225]
	v_pk_mul_f32 v[218:219], v[218:219], v[224:225]
	v_pk_mul_f32 v[220:221], v[220:221], v[224:225]
	v_pk_mul_f32 v[222:223], v[222:223], v[224:225]
	buffer_store_dwordx4 v[208:211], v234, s[68:71], s72 offen offset:0
	buffer_store_dwordx4 v[212:215], v234, s[68:71], s72 offen offset:16
	buffer_store_dwordx4 v[216:219], v234, s[68:71], s72 offen offset:32
	buffer_store_dwordx4 v[220:223], v234, s[68:71], s72 offen offset:48
	buffer_store_dwordx4 v[144:147], v236, s[68:71], s73 offen offset:0
	buffer_store_dwordx4 v[148:151], v236, s[68:71], s73 offen offset:16
	s_add_u32 s72, s72, 0x1000
	s_add_u32 s73, s73, 0x800
	s_add_u32 s74, s74, 0x200
	s_add_u32 s75, s75, 0x40
	s_waitcnt vmcnt(40)
; __device__ __forceinline__ void prep_phase(const Params& p) {
;     ...
;             for (int i = 0; i < 16; ++i) {
;                 const bool hn = (tt0 + i) < SEQ - 1; const Z16 kn = hn ? ldz(zc + (size_t)(i + 1) * 3328) : zz();
;                 float k[16], kk[16]; mix16(kp, kc, kn, mpk, mnk, k);
;                 float s2 = 0.f;
; #pragma unroll
;                 for (int q = 0; q < 16; ++q) { kk[q] = k[q] * kkc[q]; s2 += kk[q] * kk[q]; }
;                 s2 += __shfl_xor(s2, 1); s2 += __shfl_xor(s2, 2);
;                 const float inv = -1.0f / fmaxf(sqrtf(s2), 1e-12f);
;                 const size_t o = (size_t)(t0 + i) * RW + c;
; #pragma unroll
;                 for (int j4 = 0; j4 < 4; ++j4) *(f32x4*)(A + o + j4 * 4) = (f32x4){kk[j4 * 4] * inv, kk[j4 * 4 + 1] * inv, kk[j4 * 4 + 2] * inv, kk[j4 * 4 + 3] * inv};
;                 st16bf(Kb + o, k);
;                 kp = kc; kc = kn;
	v_lshlrev_b32_e32 v144, 16, v60
	v_and_b32_e32 v145, 0xffff0000, v60
	v_lshlrev_b32_e32 v146, 16, v61
	v_and_b32_e32 v147, 0xffff0000, v61
	v_lshlrev_b32_e32 v148, 16, v62
	v_and_b32_e32 v149, 0xffff0000, v62
	v_lshlrev_b32_e32 v150, 16, v63
	v_and_b32_e32 v151, 0xffff0000, v63
	v_lshlrev_b32_e32 v152, 16, v64
	v_and_b32_e32 v153, 0xffff0000, v64
	v_lshlrev_b32_e32 v154, 16, v65
	v_and_b32_e32 v155, 0xffff0000, v65
	v_lshlrev_b32_e32 v156, 16, v66
	v_and_b32_e32 v157, 0xffff0000, v66
	v_lshlrev_b32_e32 v158, 16, v67
	v_and_b32_e32 v159, 0xffff0000, v67
	v_lshlrev_b32_e32 v160, 16, v72
	v_and_b32_e32 v161, 0xffff0000, v72
	v_lshlrev_b32_e32 v162, 16, v73
	v_and_b32_e32 v163, 0xffff0000, v73
	v_lshlrev_b32_e32 v164, 16, v74
	v_and_b32_e32 v165, 0xffff0000, v74
	v_lshlrev_b32_e32 v166, 16, v75
	v_and_b32_e32 v167, 0xffff0000, v75
	v_lshlrev_b32_e32 v168, 16, v76
	v_and_b32_e32 v169, 0xffff0000, v76
	v_lshlrev_b32_e32 v170, 16, v77
	v_and_b32_e32 v171, 0xffff0000, v77
	v_lshlrev_b32_e32 v172, 16, v78
	v_and_b32_e32 v173, 0xffff0000, v78
	v_lshlrev_b32_e32 v174, 16, v79
	v_and_b32_e32 v175, 0xffff0000, v79
	v_lshlrev_b32_e32 v176, 16, v84
	v_and_b32_e32 v177, 0xffff0000, v84
	v_lshlrev_b32_e32 v178, 16, v85
	v_and_b32_e32 v179, 0xffff0000, v85
	v_lshlrev_b32_e32 v180, 16, v86
	v_and_b32_e32 v181, 0xffff0000, v86
	v_lshlrev_b32_e32 v182, 16, v87
	v_and_b32_e32 v183, 0xffff0000, v87
	v_lshlrev_b32_e32 v184, 16, v88
	v_and_b32_e32 v185, 0xffff0000, v88
	v_lshlrev_b32_e32 v186, 16, v89
	v_and_b32_e32 v187, 0xffff0000, v89
	v_lshlrev_b32_e32 v188, 16, v90
	v_and_b32_e32 v189, 0xffff0000, v90
	v_lshlrev_b32_e32 v190, 16, v91
	v_and_b32_e32 v191, 0xffff0000, v91
	v_pk_add_f32 v[224:225], v[144:145], v[160:161] neg_lo:[0,1] neg_hi:[0,1]
	v_pk_add_f32 v[226:227], v[176:177], v[160:161] neg_lo:[0,1] neg_hi:[0,1]
	v_pk_fma_f32 v[192:193], v[96:97], v[224:225], v[160:161]
	v_pk_fma_f32 v[192:193], v[112:113], v[226:227], v[192:193]
	v_pk_add_f32 v[224:225], v[146:147], v[162:163] neg_lo:[0,1] neg_hi:[0,1]
	v_pk_add_f32 v[226:227], v[178:179], v[162:163] neg_lo:[0,1] neg_hi:[0,1]
	v_pk_fma_f32 v[194:195], v[98:99], v[224:225], v[162:163]
	v_pk_fma_f32 v[194:195], v[114:115], v[226:227], v[194:195]
	v_pk_add_f32 v[224:225], v[148:149], v[164:165] neg_lo:[0,1] neg_hi:[0,1]
	v_pk_add_f32 v[226:227], v[180:181], v[164:165] neg_lo:[0,1] neg_hi:[0,1]
	v_pk_fma_f32 v[196:197], v[100:101], v[224:225], v[164:165]
	v_pk_fma_f32 v[196:197], v[116:117], v[226:227], v[196:197]
	v_pk_add_f32 v[224:225], v[150:151], v[166:167] neg_lo:[0,1] neg_hi:[0,1]
	v_pk_add_f32 v[226:227], v[182:183], v[166:167] neg_lo:[0,1] neg_hi:[0,1]
	v_pk_fma_f32 v[198:199], v[102:103], v[224:225], v[166:167]
	v_pk_fma_f32 v[198:199], v[118:119], v[226:227], v[198:199]
	v_pk_add_f32 v[224:225], v[152:153], v[168:169] neg_lo:[0,1] neg_hi:[0,1]
	v_pk_add_f32 v[226:227], v[184:185], v[168:169] neg_lo:[0,1] neg_hi:[0,1]
	v_pk_fma_f32 v[200:201], v[104:105], v[224:225], v[168:169]
	v_pk_fma_f32 v[200:201], v[120:121], v[226:227], v[200:201]
	v_pk_add_f32 v[224:225], v[154:155], v[170:171] neg_lo:[0,1] neg_hi:[0,1]
	v_pk_add_f32 v[226:227], v[186:187], v[170:171] neg_lo:[0,1] neg_hi:[0,1]
	v_pk_fma_f32 v[202:203], v[106:107], v[224:225], v[170:171]
	v_pk_fma_f32 v[202:203], v[122:123], v[226:227], v[202:203]
	v_pk_add_f32 v[224:225], v[156:157], v[172:173] neg_lo:[0,1] neg_hi:[0,1]
	v_pk_add_f32 v[226:227], v[188:189], v[172:173] neg_lo:[0,1] neg_hi:[0,1]
	v_pk_fma_f32 v[204:205], v[108:109], v[224:225], v[172:173]
	v_pk_fma_f32 v[204:205], v[124:125], v[226:227], v[204:205]
	v_pk_add_f32 v[224:225], v[158:159], v[174:175] neg_lo:[0,1] neg_hi:[0,1]
	v_pk_add_f32 v[226:227], v[190:191], v[174:175] neg_lo:[0,1] neg_hi:[0,1]
	v_pk_fma_f32 v[206:207], v[110:111], v[224:225], v[174:175]
	v_pk_fma_f32 v[206:207], v[126:127], v[226:227], v[206:207]
	v_pk_mul_f32 v[208:209], v[192:193], v[128:129]
	v_pk_mul_f32 v[210:211], v[194:195], v[130:131]
	v_pk_mul_f32 v[212:213], v[196:197], v[132:133]
	v_pk_mul_f32 v[214:215], v[198:199], v[134:135]
	v_pk_mul_f32 v[216:217], v[200:201], v[136:137]
	v_pk_mul_f32 v[218:219], v[202:203], v[138:139]
	v_pk_mul_f32 v[220:221], v[204:205], v[140:141]
	v_pk_mul_f32 v[222:223], v[206:207], v[142:143]
	v_mul_f32_e32 v224, v208, v208
	v_fmac_f32_e32 v224, v209, v209
	v_fmac_f32_e32 v224, v210, v210
	v_fmac_f32_e32 v224, v211, v211
	v_fmac_f32_e32 v224, v212, v212
	v_fmac_f32_e32 v224, v213, v213
	v_fmac_f32_e32 v224, v214, v214
	v_fmac_f32_e32 v224, v215, v215
	v_fmac_f32_e32 v224, v216, v216
	v_fmac_f32_e32 v224, v217, v217
	v_fmac_f32_e32 v224, v218, v218
	v_fmac_f32_e32 v224, v219, v219
	v_fmac_f32_e32 v224, v220, v220
	v_fmac_f32_e32 v224, v221, v221
	v_fmac_f32_e32 v224, v222, v222
	v_fmac_f32_e32 v224, v223, v223
	s_nop 1
	v_add_f32_dpp v224, v224, v224 quad_perm:[1,0,3,2] row_mask:0xf bank_mask:0xf
	s_nop 1
	v_add_f32_dpp v224, v224, v224 quad_perm:[2,3,0,1] row_mask:0xf bank_mask:0xf
	v_sqrt_f32_e32 v224, v224
	s_nop 0
	v_max_f32_e32 v224, 0x2b8cbccc, v224
	v_rcp_f32_e32 v224, v224
	s_nop 0
	v_xor_b32_e32 v224, 0x80000000, v224
	v_mov_b32_e32 v225, v224
	v_cvt_pk_bf16_f32 v144, v192, v193
	v_cvt_pk_bf16_f32 v145, v194, v195
	v_cvt_pk_bf16_f32 v146, v196, v197
	v_cvt_pk_bf16_f32 v147, v198, v199
	v_cvt_pk_bf16_f32 v148, v200, v201
	v_cvt_pk_bf16_f32 v149, v202, v203
	v_cvt_pk_bf16_f32 v150, v204, v205
	v_cvt_pk_bf16_f32 v151, v206, v207
	v_pk_mul_f32 v[208:209], v[208:209], v[224:225]
	v_pk_mul_f32 v[210:211], v[210:211], v[224:225]
	v_pk_mul_f32 v[212:213], v[212:213], v[224:225]
	v_pk_mul_f32 v[214:215], v[214:215], v[224:225]
	v_pk_mul_f32 v[216:217], v[216:217], v[224:225]
	v_pk_mul_f32 v[218:219], v[218:219], v[224:225]
	v_pk_mul_f32 v[220:221], v[220:221], v[224:225]
	v_pk_mul_f32 v[222:223], v[222:223], v[224:225]
	buffer_store_dwordx4 v[208:211], v234, s[68:71], s72 offen offset:0
	buffer_store_dwordx4 v[212:215], v234, s[68:71], s72 offen offset:16
	buffer_store_dwordx4 v[216:219], v234, s[68:71], s72 offen offset:32
	buffer_store_dwordx4 v[220:223], v234, s[68:71], s72 offen offset:48
	buffer_store_dwordx4 v[144:147], v236, s[68:71], s73 offen offset:0
	buffer_store_dwordx4 v[148:151], v236, s[68:71], s73 offen offset:16
	s_add_u32 s72, s72, 0x1000
	s_add_u32 s73, s73, 0x800
	s_add_u32 s74, s74, 0x200
	s_add_u32 s75, s75, 0x40
	s_waitcnt vmcnt(38)
; __device__ __forceinline__ void prep_phase(const Params& p) {
;     ...
;             for (int i = 0; i < 16; ++i) {
;                 const bool hn = (tt0 + i) < SEQ - 1; const Z16 kn = hn ? ldz(zc + (size_t)(i + 1) * 3328) : zz();
;                 float k[16], kk[16]; mix16(kp, kc, kn, mpk, mnk, k);
;                 float s2 = 0.f;
; #pragma unroll
;                 for (int q = 0; q < 16; ++q) { kk[q] = k[q] * kkc[q]; s2 += kk[q] * kk[q]; }
;                 s2 += __shfl_xor(s2, 1); s2 += __shfl_xor(s2, 2);
;                 const float inv = -1.0f / fmaxf(sqrtf(s2), 1e-12f);
;                 const size_t o = (size_t)(t0 + i) * RW + c;
; #pragma unroll
;                 for (int j4 = 0; j4 < 4; ++j4) *(f32x4*)(A + o + j4 * 4) = (f32x4){kk[j4 * 4] * inv, kk[j4 * 4 + 1] * inv, kk[j4 * 4 + 2] * inv, kk[j4 * 4 + 3] * inv};
;                 st16bf(Kb + o, k);
;                 kp = kc; kc = kn;
	v_lshlrev_b32_e32 v144, 16, v72
	v_and_b32_e32 v145, 0xffff0000, v72
	v_lshlrev_b32_e32 v146, 16, v73
	v_and_b32_e32 v147, 0xffff0000, v73
	v_lshlrev_b32_e32 v148, 16, v74
	v_and_b32_e32 v149, 0xffff0000, v74
	v_lshlrev_b32_e32 v150, 16, v75
	v_and_b32_e32 v151, 0xffff0000, v75
	v_lshlrev_b32_e32 v152, 16, v76
	v_and_b32_e32 v153, 0xffff0000, v76
	v_lshlrev_b32_e32 v154, 16, v77
	v_and_b32_e32 v155, 0xffff0000, v77
	v_lshlrev_b32_e32 v156, 16, v78
	v_and_b32_e32 v157, 0xffff0000, v78
	v_lshlrev_b32_e32 v158, 16, v79
	v_and_b32_e32 v159, 0xffff0000, v79
	v_lshlrev_b32_e32 v160, 16, v84
	v_and_b32_e32 v161, 0xffff0000, v84
	v_lshlrev_b32_e32 v162, 16, v85
	v_and_b32_e32 v163, 0xffff0000, v85
	v_lshlrev_b32_e32 v164, 16, v86
	v_and_b32_e32 v165, 0xffff0000, v86
	v_lshlrev_b32_e32 v166, 16, v87
	v_and_b32_e32 v167, 0xffff0000, v87
	v_lshlrev_b32_e32 v168, 16, v88
	v_and_b32_e32 v169, 0xffff0000, v88
	v_lshlrev_b32_e32 v170, 16, v89
	v_and_b32_e32 v171, 0xffff0000, v89
	v_lshlrev_b32_e32 v172, 16, v90
	v_and_b32_e32 v173, 0xffff0000, v90
	v_lshlrev_b32_e32 v174, 16, v91
	v_and_b32_e32 v175, 0xffff0000, v91
	v_lshlrev_b32_e32 v176, 16, v0
	v_and_b32_e32 v177, 0xffff0000, v0
	v_lshlrev_b32_e32 v178, 16, v1
	v_and_b32_e32 v179, 0xffff0000, v1
	v_lshlrev_b32_e32 v180, 16, v2
	v_and_b32_e32 v181, 0xffff0000, v2
	v_lshlrev_b32_e32 v182, 16, v3
	v_and_b32_e32 v183, 0xffff0000, v3
	v_lshlrev_b32_e32 v184, 16, v4
	v_and_b32_e32 v185, 0xffff0000, v4
	v_lshlrev_b32_e32 v186, 16, v5
	v_and_b32_e32 v187, 0xffff0000, v5
	v_lshlrev_b32_e32 v188, 16, v6
	v_and_b32_e32 v189, 0xffff0000, v6
	v_lshlrev_b32_e32 v190, 16, v7
	v_and_b32_e32 v191, 0xffff0000, v7
	v_pk_add_f32 v[224:225], v[144:145], v[160:161] neg_lo:[0,1] neg_hi:[0,1]
	v_pk_add_f32 v[226:227], v[176:177], v[160:161] neg_lo:[0,1] neg_hi:[0,1]
	v_pk_fma_f32 v[192:193], v[96:97], v[224:225], v[160:161]
	v_pk_fma_f32 v[192:193], v[112:113], v[226:227], v[192:193]
	v_pk_add_f32 v[224:225], v[146:147], v[162:163] neg_lo:[0,1] neg_hi:[0,1]
	v_pk_add_f32 v[226:227], v[178:179], v[162:163] neg_lo:[0,1] neg_hi:[0,1]
	v_pk_fma_f32 v[194:195], v[98:99], v[224:225], v[162:163]
	v_pk_fma_f32 v[194:195], v[114:115], v[226:227], v[194:195]
	v_pk_add_f32 v[224:225], v[148:149], v[164:165] neg_lo:[0,1] neg_hi:[0,1]
	v_pk_add_f32 v[226:227], v[180:181], v[164:165] neg_lo:[0,1] neg_hi:[0,1]
	v_pk_fma_f32 v[196:197], v[100:101], v[224:225], v[164:165]
	v_pk_fma_f32 v[196:197], v[116:117], v[226:227], v[196:197]
	v_pk_add_f32 v[224:225], v[150:151], v[166:167] neg_lo:[0,1] neg_hi:[0,1]
	v_pk_add_f32 v[226:227], v[182:183], v[166:167] neg_lo:[0,1] neg_hi:[0,1]
	v_pk_fma_f32 v[198:199], v[102:103], v[224:225], v[166:167]
	v_pk_fma_f32 v[198:199], v[118:119], v[226:227], v[198:199]
	v_pk_add_f32 v[224:225], v[152:153], v[168:169] neg_lo:[0,1] neg_hi:[0,1]
	v_pk_add_f32 v[226:227], v[184:185], v[168:169] neg_lo:[0,1] neg_hi:[0,1]
	v_pk_fma_f32 v[200:201], v[104:105], v[224:225], v[168:169]
	v_pk_fma_f32 v[200:201], v[120:121], v[226:227], v[200:201]
	v_pk_add_f32 v[224:225], v[154:155], v[170:171] neg_lo:[0,1] neg_hi:[0,1]
	v_pk_add_f32 v[226:227], v[186:187], v[170:171] neg_lo:[0,1] neg_hi:[0,1]
	v_pk_fma_f32 v[202:203], v[106:107], v[224:225], v[170:171]
	v_pk_fma_f32 v[202:203], v[122:123], v[226:227], v[202:203]
	v_pk_add_f32 v[224:225], v[156:157], v[172:173] neg_lo:[0,1] neg_hi:[0,1]
	v_pk_add_f32 v[226:227], v[188:189], v[172:173] neg_lo:[0,1] neg_hi:[0,1]
	v_pk_fma_f32 v[204:205], v[108:109], v[224:225], v[172:173]
	v_pk_fma_f32 v[204:205], v[124:125], v[226:227], v[204:205]
	v_pk_add_f32 v[224:225], v[158:159], v[174:175] neg_lo:[0,1] neg_hi:[0,1]
	v_pk_add_f32 v[226:227], v[190:191], v[174:175] neg_lo:[0,1] neg_hi:[0,1]
	v_pk_fma_f32 v[206:207], v[110:111], v[224:225], v[174:175]
	v_pk_fma_f32 v[206:207], v[126:127], v[226:227], v[206:207]
	v_pk_mul_f32 v[208:209], v[192:193], v[128:129]
	v_pk_mul_f32 v[210:211], v[194:195], v[130:131]
	v_pk_mul_f32 v[212:213], v[196:197], v[132:133]
	v_pk_mul_f32 v[214:215], v[198:199], v[134:135]
	v_pk_mul_f32 v[216:217], v[200:201], v[136:137]
	v_pk_mul_f32 v[218:219], v[202:203], v[138:139]
	v_pk_mul_f32 v[220:221], v[204:205], v[140:141]
	v_pk_mul_f32 v[222:223], v[206:207], v[142:143]
	v_mul_f32_e32 v224, v208, v208
	v_fmac_f32_e32 v224, v209, v209
	v_fmac_f32_e32 v224, v210, v210
	v_fmac_f32_e32 v224, v211, v211
	v_fmac_f32_e32 v224, v212, v212
	v_fmac_f32_e32 v224, v213, v213
	v_fmac_f32_e32 v224, v214, v214
	v_fmac_f32_e32 v224, v215, v215
	v_fmac_f32_e32 v224, v216, v216
	v_fmac_f32_e32 v224, v217, v217
	v_fmac_f32_e32 v224, v218, v218
	v_fmac_f32_e32 v224, v219, v219
	v_fmac_f32_e32 v224, v220, v220
	v_fmac_f32_e32 v224, v221, v221
	v_fmac_f32_e32 v224, v222, v222
	v_fmac_f32_e32 v224, v223, v223
	s_nop 1
	v_add_f32_dpp v224, v224, v224 quad_perm:[1,0,3,2] row_mask:0xf bank_mask:0xf
	s_nop 1
	v_add_f32_dpp v224, v224, v224 quad_perm:[2,3,0,1] row_mask:0xf bank_mask:0xf
	v_sqrt_f32_e32 v224, v224
	s_nop 0
	v_max_f32_e32 v224, 0x2b8cbccc, v224
	v_rcp_f32_e32 v224, v224
	s_nop 0
	v_xor_b32_e32 v224, 0x80000000, v224
	v_mov_b32_e32 v225, v224
	v_cvt_pk_bf16_f32 v144, v192, v193
	v_cvt_pk_bf16_f32 v145, v194, v195
	v_cvt_pk_bf16_f32 v146, v196, v197
	v_cvt_pk_bf16_f32 v147, v198, v199
	v_cvt_pk_bf16_f32 v148, v200, v201
	v_cvt_pk_bf16_f32 v149, v202, v203
	v_cvt_pk_bf16_f32 v150, v204, v205
	v_cvt_pk_bf16_f32 v151, v206, v207
	v_pk_mul_f32 v[208:209], v[208:209], v[224:225]
	v_pk_mul_f32 v[210:211], v[210:211], v[224:225]
	v_pk_mul_f32 v[212:213], v[212:213], v[224:225]
	v_pk_mul_f32 v[214:215], v[214:215], v[224:225]
	v_pk_mul_f32 v[216:217], v[216:217], v[224:225]
	v_pk_mul_f32 v[218:219], v[218:219], v[224:225]
	v_pk_mul_f32 v[220:221], v[220:221], v[224:225]
	v_pk_mul_f32 v[222:223], v[222:223], v[224:225]
	buffer_store_dwordx4 v[208:211], v234, s[68:71], s72 offen offset:0
	buffer_store_dwordx4 v[212:215], v234, s[68:71], s72 offen offset:16
	buffer_store_dwordx4 v[216:219], v234, s[68:71], s72 offen offset:32
	buffer_store_dwordx4 v[220:223], v234, s[68:71], s72 offen offset:48
	buffer_store_dwordx4 v[144:147], v236, s[68:71], s73 offen offset:0
	buffer_store_dwordx4 v[148:151], v236, s[68:71], s73 offen offset:16
	s_add_u32 s72, s72, 0x1000
	s_add_u32 s73, s73, 0x800
	s_add_u32 s74, s74, 0x200
	s_add_u32 s75, s75, 0x40
	s_waitcnt vmcnt(36)
; __device__ __forceinline__ void prep_phase(const Params& p) {
;     ...
;             for (int i = 0; i < 16; ++i) {
;                 const bool hn = (tt0 + i) < SEQ - 1; const Z16 kn = hn ? ldz(zc + (size_t)(i + 1) * 3328) : zz();
;                 float k[16], kk[16]; mix16(kp, kc, kn, mpk, mnk, k);
;                 float s2 = 0.f;
; #pragma unroll
;                 for (int q = 0; q < 16; ++q) { kk[q] = k[q] * kkc[q]; s2 += kk[q] * kk[q]; }
;                 s2 += __shfl_xor(s2, 1); s2 += __shfl_xor(s2, 2);
;                 const float inv = -1.0f / fmaxf(sqrtf(s2), 1e-12f);
;                 const size_t o = (size_t)(t0 + i) * RW + c;
; #pragma unroll
;                 for (int j4 = 0; j4 < 4; ++j4) *(f32x4*)(A + o + j4 * 4) = (f32x4){kk[j4 * 4] * inv, kk[j4 * 4 + 1] * inv, kk[j4 * 4 + 2] * inv, kk[j4 * 4 + 3] * inv};
;                 st16bf(Kb + o, k);
;                 kp = kc; kc = kn;
	v_lshlrev_b32_e32 v144, 16, v84
	v_and_b32_e32 v145, 0xffff0000, v84
	v_lshlrev_b32_e32 v146, 16, v85
	v_and_b32_e32 v147, 0xffff0000, v85
	v_lshlrev_b32_e32 v148, 16, v86
	v_and_b32_e32 v149, 0xffff0000, v86
	v_lshlrev_b32_e32 v150, 16, v87
	v_and_b32_e32 v151, 0xffff0000, v87
	v_lshlrev_b32_e32 v152, 16, v88
	v_and_b32_e32 v153, 0xffff0000, v88
	v_lshlrev_b32_e32 v154, 16, v89
	v_and_b32_e32 v155, 0xffff0000, v89
	v_lshlrev_b32_e32 v156, 16, v90
	v_and_b32_e32 v157, 0xffff0000, v90
	v_lshlrev_b32_e32 v158, 16, v91
	v_and_b32_e32 v159, 0xffff0000, v91
	v_lshlrev_b32_e32 v160, 16, v0
	v_and_b32_e32 v161, 0xffff0000, v0
	v_lshlrev_b32_e32 v162, 16, v1
	v_and_b32_e32 v163, 0xffff0000, v1
	v_lshlrev_b32_e32 v164, 16, v2
	v_and_b32_e32 v165, 0xffff0000, v2
	v_lshlrev_b32_e32 v166, 16, v3
	v_and_b32_e32 v167, 0xffff0000, v3
	v_lshlrev_b32_e32 v168, 16, v4
	v_and_b32_e32 v169, 0xffff0000, v4
	v_lshlrev_b32_e32 v170, 16, v5
	v_and_b32_e32 v171, 0xffff0000, v5
	v_lshlrev_b32_e32 v172, 16, v6
	v_and_b32_e32 v173, 0xffff0000, v6
	v_lshlrev_b32_e32 v174, 16, v7
	v_and_b32_e32 v175, 0xffff0000, v7
	v_lshlrev_b32_e32 v176, 16, v12
	v_and_b32_e32 v177, 0xffff0000, v12
	v_lshlrev_b32_e32 v178, 16, v13
	v_and_b32_e32 v179, 0xffff0000, v13
	v_lshlrev_b32_e32 v180, 16, v14
	v_and_b32_e32 v181, 0xffff0000, v14
	v_lshlrev_b32_e32 v182, 16, v15
	v_and_b32_e32 v183, 0xffff0000, v15
	v_lshlrev_b32_e32 v184, 16, v16
	v_and_b32_e32 v185, 0xffff0000, v16
	v_lshlrev_b32_e32 v186, 16, v17
	v_and_b32_e32 v187, 0xffff0000, v17
	v_lshlrev_b32_e32 v188, 16, v18
	v_and_b32_e32 v189, 0xffff0000, v18
	v_lshlrev_b32_e32 v190, 16, v19
	v_and_b32_e32 v191, 0xffff0000, v19
	v_pk_add_f32 v[224:225], v[144:145], v[160:161] neg_lo:[0,1] neg_hi:[0,1]
	v_pk_add_f32 v[226:227], v[176:177], v[160:161] neg_lo:[0,1] neg_hi:[0,1]
	v_pk_fma_f32 v[192:193], v[96:97], v[224:225], v[160:161]
	v_pk_fma_f32 v[192:193], v[112:113], v[226:227], v[192:193]
	v_pk_add_f32 v[224:225], v[146:147], v[162:163] neg_lo:[0,1] neg_hi:[0,1]
	v_pk_add_f32 v[226:227], v[178:179], v[162:163] neg_lo:[0,1] neg_hi:[0,1]
	v_pk_fma_f32 v[194:195], v[98:99], v[224:225], v[162:163]
	v_pk_fma_f32 v[194:195], v[114:115], v[226:227], v[194:195]
	v_pk_add_f32 v[224:225], v[148:149], v[164:165] neg_lo:[0,1] neg_hi:[0,1]
	v_pk_add_f32 v[226:227], v[180:181], v[164:165] neg_lo:[0,1] neg_hi:[0,1]
	v_pk_fma_f32 v[196:197], v[100:101], v[224:225], v[164:165]
	v_pk_fma_f32 v[196:197], v[116:117], v[226:227], v[196:197]
	v_pk_add_f32 v[224:225], v[150:151], v[166:167] neg_lo:[0,1] neg_hi:[0,1]
	v_pk_add_f32 v[226:227], v[182:183], v[166:167] neg_lo:[0,1] neg_hi:[0,1]
	v_pk_fma_f32 v[198:199], v[102:103], v[224:225], v[166:167]
	v_pk_fma_f32 v[198:199], v[118:119], v[226:227], v[198:199]
	v_pk_add_f32 v[224:225], v[152:153], v[168:169] neg_lo:[0,1] neg_hi:[0,1]
	v_pk_add_f32 v[226:227], v[184:185], v[168:169] neg_lo:[0,1] neg_hi:[0,1]
	v_pk_fma_f32 v[200:201], v[104:105], v[224:225], v[168:169]
	v_pk_fma_f32 v[200:201], v[120:121], v[226:227], v[200:201]
	v_pk_add_f32 v[224:225], v[154:155], v[170:171] neg_lo:[0,1] neg_hi:[0,1]
	v_pk_add_f32 v[226:227], v[186:187], v[170:171] neg_lo:[0,1] neg_hi:[0,1]
	v_pk_fma_f32 v[202:203], v[106:107], v[224:225], v[170:171]
	v_pk_fma_f32 v[202:203], v[122:123], v[226:227], v[202:203]
	v_pk_add_f32 v[224:225], v[156:157], v[172:173] neg_lo:[0,1] neg_hi:[0,1]
	v_pk_add_f32 v[226:227], v[188:189], v[172:173] neg_lo:[0,1] neg_hi:[0,1]
	v_pk_fma_f32 v[204:205], v[108:109], v[224:225], v[172:173]
	v_pk_fma_f32 v[204:205], v[124:125], v[226:227], v[204:205]
	v_pk_add_f32 v[224:225], v[158:159], v[174:175] neg_lo:[0,1] neg_hi:[0,1]
	v_pk_add_f32 v[226:227], v[190:191], v[174:175] neg_lo:[0,1] neg_hi:[0,1]
	v_pk_fma_f32 v[206:207], v[110:111], v[224:225], v[174:175]
	v_pk_fma_f32 v[206:207], v[126:127], v[226:227], v[206:207]
	v_pk_mul_f32 v[208:209], v[192:193], v[128:129]
	v_pk_mul_f32 v[210:211], v[194:195], v[130:131]
	v_pk_mul_f32 v[212:213], v[196:197], v[132:133]
	v_pk_mul_f32 v[214:215], v[198:199], v[134:135]
	v_pk_mul_f32 v[216:217], v[200:201], v[136:137]
	v_pk_mul_f32 v[218:219], v[202:203], v[138:139]
	v_pk_mul_f32 v[220:221], v[204:205], v[140:141]
	v_pk_mul_f32 v[222:223], v[206:207], v[142:143]
	v_mul_f32_e32 v224, v208, v208
	v_fmac_f32_e32 v224, v209, v209
	v_fmac_f32_e32 v224, v210, v210
	v_fmac_f32_e32 v224, v211, v211
	v_fmac_f32_e32 v224, v212, v212
	v_fmac_f32_e32 v224, v213, v213
	v_fmac_f32_e32 v224, v214, v214
	v_fmac_f32_e32 v224, v215, v215
	v_fmac_f32_e32 v224, v216, v216
	v_fmac_f32_e32 v224, v217, v217
	v_fmac_f32_e32 v224, v218, v218
	v_fmac_f32_e32 v224, v219, v219
	v_fmac_f32_e32 v224, v220, v220
	v_fmac_f32_e32 v224, v221, v221
	v_fmac_f32_e32 v224, v222, v222
	v_fmac_f32_e32 v224, v223, v223
	s_nop 1
	v_add_f32_dpp v224, v224, v224 quad_perm:[1,0,3,2] row_mask:0xf bank_mask:0xf
	s_nop 1
	v_add_f32_dpp v224, v224, v224 quad_perm:[2,3,0,1] row_mask:0xf bank_mask:0xf
	v_sqrt_f32_e32 v224, v224
	s_nop 0
	v_max_f32_e32 v224, 0x2b8cbccc, v224
	v_rcp_f32_e32 v224, v224
	s_nop 0
	v_xor_b32_e32 v224, 0x80000000, v224
	v_mov_b32_e32 v225, v224
	v_cvt_pk_bf16_f32 v144, v192, v193
	v_cvt_pk_bf16_f32 v145, v194, v195
	v_cvt_pk_bf16_f32 v146, v196, v197
	v_cvt_pk_bf16_f32 v147, v198, v199
	v_cvt_pk_bf16_f32 v148, v200, v201
	v_cvt_pk_bf16_f32 v149, v202, v203
	v_cvt_pk_bf16_f32 v150, v204, v205
	v_cvt_pk_bf16_f32 v151, v206, v207
	v_pk_mul_f32 v[208:209], v[208:209], v[224:225]
	v_pk_mul_f32 v[210:211], v[210:211], v[224:225]
	v_pk_mul_f32 v[212:213], v[212:213], v[224:225]
	v_pk_mul_f32 v[214:215], v[214:215], v[224:225]
	v_pk_mul_f32 v[216:217], v[216:217], v[224:225]
	v_pk_mul_f32 v[218:219], v[218:219], v[224:225]
	v_pk_mul_f32 v[220:221], v[220:221], v[224:225]
	v_pk_mul_f32 v[222:223], v[222:223], v[224:225]
	buffer_store_dwordx4 v[208:211], v234, s[68:71], s72 offen offset:0
	buffer_store_dwordx4 v[212:215], v234, s[68:71], s72 offen offset:16
	buffer_store_dwordx4 v[216:219], v234, s[68:71], s72 offen offset:32
	buffer_store_dwordx4 v[220:223], v234, s[68:71], s72 offen offset:48
	buffer_store_dwordx4 v[144:147], v236, s[68:71], s73 offen offset:0
	buffer_store_dwordx4 v[148:151], v236, s[68:71], s73 offen offset:16
	s_waitcnt vmcnt(0)
; __device__ __forceinline__ void prep_phase(const Params& p) {
;     ...
;             float mpr[16], mnr[16], rkc[16]; ld16f(p.mu_prev + c, mpr); ld16f(p.mu_next + c, mnr); ld16f(p.r_k + c, rkc);
;             const u16* zc = ZS + (size_t)t0 * 3328 + c;
;             Z16 rp = tt0 > 0 ? ldz(zc - 3328) : zz(), rc = ldz(zc);
; #pragma unroll 2
;             for (int i = 0; i < 16; ++i) {
;                 const bool hn = (tt0 + i) < SEQ - 1; const Z16 rn = hn ? ldz(zc + (size_t)(i + 1) * 3328) : zz();
;                 const size_t o = (size_t)(t0 + i) * RW + c;
;                 float r[16], k[16]; mix16(rp, rc, rn, mpr, mnr, r); unz(ldz(Kb + o), k);
;                 float bs = 0.f;
; #pragma unroll
;                 for (int q = 0; q < 16; ++q) bs += r[q] * k[q] * rkc[q];
	v_lshl_add_u32 v232, v240, 5, s5
	v_lshlrev_b32_e32 v224, 6, v240
	global_load_dwordx4 v[96:99], v224, s[20:21] offset:0
	global_load_dwordx4 v[100:103], v224, s[20:21] offset:16
	global_load_dwordx4 v[104:107], v224, s[20:21] offset:32
	global_load_dwordx4 v[108:111], v224, s[20:21] offset:48
	global_load_dwordx4 v[112:115], v224, s[22:23] offset:0
	global_load_dwordx4 v[116:119], v224, s[22:23] offset:16
	global_load_dwordx4 v[120:123], v224, s[22:23] offset:32
	global_load_dwordx4 v[124:127], v224, s[22:23] offset:48
	global_load_dwordx4 v[128:131], v224, s[44:45] offset:0
	global_load_dwordx4 v[132:135], v224, s[44:45] offset:16
	global_load_dwordx4 v[136:139], v224, s[44:45] offset:32
	global_load_dwordx4 v[140:143], v224, s[44:45] offset:48
	buffer_load_dwordx4 v[0:3], v232, s[64:67], 0 offen nt
	buffer_load_dwordx4 v[4:7], v232, s[64:67], 0 offen offset:16 nt
	v_add_u32_e32 v232, 6656, v232
	buffer_load_dwordx4 v[12:15], v232, s[64:67], 0 offen nt
	buffer_load_dwordx4 v[16:19], v232, s[64:67], 0 offen offset:16 nt
	v_add_u32_e32 v232, 6656, v232
	buffer_load_dwordx4 v[24:27], v232, s[64:67], 0 offen nt
	buffer_load_dwordx4 v[28:31], v232, s[64:67], 0 offen offset:16 nt
	v_add_u32_e32 v232, 6656, v232
	buffer_load_dwordx4 v[36:39], v232, s[64:67], 0 offen nt
	buffer_load_dwordx4 v[40:43], v232, s[64:67], 0 offen offset:16 nt
	v_add_u32_e32 v232, 6656, v232
	buffer_load_dwordx4 v[48:51], v232, s[64:67], 0 offen nt
	buffer_load_dwordx4 v[52:55], v232, s[64:67], 0 offen offset:16 nt
	v_add_u32_e32 v232, 6656, v232
	buffer_load_dwordx4 v[60:63], v232, s[64:67], 0 offen nt
	buffer_load_dwordx4 v[64:67], v232, s[64:67], 0 offen offset:16 nt
	v_add_u32_e32 v232, 6656, v232
	buffer_load_dwordx4 v[72:75], v232, s[64:67], 0 offen nt
	buffer_load_dwordx4 v[76:79], v232, s[64:67], 0 offen offset:16 nt
	v_add_u32_e32 v232, 6656, v232
	buffer_load_dwordx4 v[84:87], v232, s[64:67], 0 offen nt
	buffer_load_dwordx4 v[88:91], v232, s[64:67], 0 offen offset:16 nt
	v_add_u32_e32 v232, 6656, v232
	s_lshl_b32 s76, s0, 11
	buffer_load_dwordx4 v[208:211], v236, s[68:71], s76 offen
	buffer_load_dwordx4 v[212:215], v236, s[68:71], s76 offen offset:16
	s_lshl_b32 s72, s0, 12
	s_lshl_b32 s73, s0, 11
	s_lshl_b32 s74, s0, 9
	s_lshl_b32 s75, s0, 6
	s_waitcnt vmcnt(12)
	v_lshlrev_b32_e32 v144, 16, v0
	v_and_b32_e32 v145, 0xffff0000, v0
	v_lshlrev_b32_e32 v146, 16, v1
	v_and_b32_e32 v147, 0xffff0000, v1
	v_lshlrev_b32_e32 v148, 16, v2
	v_and_b32_e32 v149, 0xffff0000, v2
	v_lshlrev_b32_e32 v150, 16, v3
	v_and_b32_e32 v151, 0xffff0000, v3
	v_lshlrev_b32_e32 v152, 16, v4
	v_and_b32_e32 v153, 0xffff0000, v4
	v_lshlrev_b32_e32 v154, 16, v5
	v_and_b32_e32 v155, 0xffff0000, v5
	v_lshlrev_b32_e32 v156, 16, v6
	v_and_b32_e32 v157, 0xffff0000, v6
	v_lshlrev_b32_e32 v158, 16, v7
	v_and_b32_e32 v159, 0xffff0000, v7
	v_lshlrev_b32_e32 v160, 16, v12
	v_and_b32_e32 v161, 0xffff0000, v12
	v_lshlrev_b32_e32 v162, 16, v13
	v_and_b32_e32 v163, 0xffff0000, v13
	v_lshlrev_b32_e32 v164, 16, v14
	v_and_b32_e32 v165, 0xffff0000, v14
	v_lshlrev_b32_e32 v166, 16, v15
	v_and_b32_e32 v167, 0xffff0000, v15
	v_lshlrev_b32_e32 v168, 16, v16
	v_and_b32_e32 v169, 0xffff0000, v16
	v_lshlrev_b32_e32 v170, 16, v17
	v_and_b32_e32 v171, 0xffff0000, v17
	v_lshlrev_b32_e32 v172, 16, v18
	v_and_b32_e32 v173, 0xffff0000, v18
	v_lshlrev_b32_e32 v174, 16, v19
	v_and_b32_e32 v175, 0xffff0000, v19
	v_lshlrev_b32_e32 v176, 16, v24
	v_and_b32_e32 v177, 0xffff0000, v24
	v_lshlrev_b32_e32 v178, 16, v25
	v_and_b32_e32 v179, 0xffff0000, v25
	v_lshlrev_b32_e32 v180, 16, v26
	v_and_b32_e32 v181, 0xffff0000, v26
	v_lshlrev_b32_e32 v182, 16, v27
	v_and_b32_e32 v183, 0xffff0000, v27
	v_lshlrev_b32_e32 v184, 16, v28
	v_and_b32_e32 v185, 0xffff0000, v28
	v_lshlrev_b32_e32 v186, 16, v29
	v_and_b32_e32 v187, 0xffff0000, v29
	v_lshlrev_b32_e32 v188, 16, v30
	v_and_b32_e32 v189, 0xffff0000, v30
	v_lshlrev_b32_e32 v190, 16, v31
	v_and_b32_e32 v191, 0xffff0000, v31
	buffer_load_dwordx4 v[0:3], v232, s[64:67], 0 offen nt
	buffer_load_dwordx4 v[4:7], v232, s[64:67], 0 offen offset:16 nt
	v_add_u32_e32 v232, 6656, v232
	v_pk_add_f32 v[224:225], v[144:145], v[160:161] neg_lo:[0,1] neg_hi:[0,1]
	v_pk_add_f32 v[226:227], v[176:177], v[160:161] neg_lo:[0,1] neg_hi:[0,1]
	v_pk_fma_f32 v[192:193], v[96:97], v[224:225], v[160:161]
	v_pk_fma_f32 v[192:193], v[112:113], v[226:227], v[192:193]
	v_pk_add_f32 v[224:225], v[146:147], v[162:163] neg_lo:[0,1] neg_hi:[0,1]
	v_pk_add_f32 v[226:227], v[178:179], v[162:163] neg_lo:[0,1] neg_hi:[0,1]
	v_pk_fma_f32 v[194:195], v[98:99], v[224:225], v[162:163]
	v_pk_fma_f32 v[194:195], v[114:115], v[226:227], v[194:195]
	v_pk_add_f32 v[224:225], v[148:149], v[164:165] neg_lo:[0,1] neg_hi:[0,1]
	v_pk_add_f32 v[226:227], v[180:181], v[164:165] neg_lo:[0,1] neg_hi:[0,1]
	v_pk_fma_f32 v[196:197], v[100:101], v[224:225], v[164:165]
	v_pk_fma_f32 v[196:197], v[116:117], v[226:227], v[196:197]
	v_pk_add_f32 v[224:225], v[150:151], v[166:167] neg_lo:[0,1] neg_hi:[0,1]
	v_pk_add_f32 v[226:227], v[182:183], v[166:167] neg_lo:[0,1] neg_hi:[0,1]
	v_pk_fma_f32 v[198:199], v[102:103], v[224:225], v[166:167]
	v_pk_fma_f32 v[198:199], v[118:119], v[226:227], v[198:199]
	v_pk_add_f32 v[224:225], v[152:153], v[168:169] neg_lo:[0,1] neg_hi:[0,1]
	v_pk_add_f32 v[226:227], v[184:185], v[168:169] neg_lo:[0,1] neg_hi:[0,1]
	v_pk_fma_f32 v[200:201], v[104:105], v[224:225], v[168:169]
	v_pk_fma_f32 v[200:201], v[120:121], v[226:227], v[200:201]
	v_pk_add_f32 v[224:225], v[154:155], v[170:171] neg_lo:[0,1] neg_hi:[0,1]
	v_pk_add_f32 v[226:227], v[186:187], v[170:171] neg_lo:[0,1] neg_hi:[0,1]
	v_pk_fma_f32 v[202:203], v[106:107], v[224:225], v[170:171]
	v_pk_fma_f32 v[202:203], v[122:123], v[226:227], v[202:203]
	v_pk_add_f32 v[224:225], v[156:157], v[172:173] neg_lo:[0,1] neg_hi:[0,1]
	v_pk_add_f32 v[226:227], v[188:189], v[172:173] neg_lo:[0,1] neg_hi:[0,1]
	v_pk_fma_f32 v[204:205], v[108:109], v[224:225], v[172:173]
	v_pk_fma_f32 v[204:205], v[124:125], v[226:227], v[204:205]
	v_pk_add_f32 v[224:225], v[158:159], v[174:175] neg_lo:[0,1] neg_hi:[0,1]
	v_pk_add_f32 v[226:227], v[190:191], v[174:175] neg_lo:[0,1] neg_hi:[0,1]
	v_pk_fma_f32 v[206:207], v[110:111], v[224:225], v[174:175]
	v_pk_fma_f32 v[206:207], v[126:127], v[226:227], v[206:207]
	s_add_u32 s76, s76, 0x800
	buffer_load_dwordx4 v[216:219], v236, s[68:71], s76 offen
	buffer_load_dwordx4 v[220:223], v236, s[68:71], s76 offen offset:16
	buffer_store_dwordx4 v[192:195], v235, s[68:71], s72 offen offset:0
	buffer_store_dwordx4 v[196:199], v235, s[68:71], s72 offen offset:16
	buffer_store_dwordx4 v[200:203], v235, s[68:71], s72 offen offset:32
	buffer_store_dwordx4 v[204:207], v235, s[68:71], s72 offen offset:48
	s_waitcnt vmcnt(8)
; __device__ __forceinline__ void prep_phase(const Params& p) {
;     ...
;             for (int i = 0; i < 16; ++i) {
;                 const bool hn = (tt0 + i) < SEQ - 1; const Z16 rn = hn ? ldz(zc + (size_t)(i + 1) * 3328) : zz();
;                 const size_t o = (size_t)(t0 + i) * RW + c;
;                 float r[16], k[16]; mix16(rp, rc, rn, mpr, mnr, r); unz(ldz(Kb + o), k);
;                 float bs = 0.f;
; #pragma unroll
;                 for (int q = 0; q < 16; ++q) bs += r[q] * k[q] * rkc[q];
;                 bs += __shfl_xor(bs, 1); bs += __shfl_xor(bs, 2);
; #pragma unroll
;                 for (int j4 = 0; j4 < 4; ++j4) *(f32x4*)(R + o + j4 * 4) = (f32x4){r[j4 * 4], r[j4 * 4 + 1], r[j4 * 4 + 2], r[j4 * 4 + 3]};
;                 if ((lane & 3) == 0) BON[(size_t)(t0 + i) * 16 + (lane >> 2)] = bs;
;                 rp = rc; rc = rn;
	v_lshlrev_b32_e32 v144, 16, v208
	v_and_b32_e32 v145, 0xffff0000, v208
	v_lshlrev_b32_e32 v146, 16, v209
	v_and_b32_e32 v147, 0xffff0000, v209
	v_lshlrev_b32_e32 v148, 16, v210
	v_and_b32_e32 v149, 0xffff0000, v210
	v_lshlrev_b32_e32 v150, 16, v211
	v_and_b32_e32 v151, 0xffff0000, v211
	v_lshlrev_b32_e32 v152, 16, v212
	v_and_b32_e32 v153, 0xffff0000, v212
	v_lshlrev_b32_e32 v154, 16, v213
	v_and_b32_e32 v155, 0xffff0000, v213
	v_lshlrev_b32_e32 v156, 16, v214
	v_and_b32_e32 v157, 0xffff0000, v214
	v_lshlrev_b32_e32 v158, 16, v215
	v_and_b32_e32 v159, 0xffff0000, v215
	v_pk_mul_f32 v[144:145], v[192:193], v[144:145]
	v_pk_mul_f32 v[146:147], v[194:195], v[146:147]
	v_pk_mul_f32 v[148:149], v[196:197], v[148:149]
	v_pk_mul_f32 v[150:151], v[198:199], v[150:151]
	v_pk_mul_f32 v[152:153], v[200:201], v[152:153]
	v_pk_mul_f32 v[154:155], v[202:203], v[154:155]
	v_pk_mul_f32 v[156:157], v[204:205], v[156:157]
	v_pk_mul_f32 v[158:159], v[206:207], v[158:159]
	v_mul_f32_e32 v224, v144, v128
	v_fmac_f32_e32 v224, v145, v129
	v_fmac_f32_e32 v224, v146, v130
	v_fmac_f32_e32 v224, v147, v131
	v_fmac_f32_e32 v224, v148, v132
	v_fmac_f32_e32 v224, v149, v133
	v_fmac_f32_e32 v224, v150, v134
	v_fmac_f32_e32 v224, v151, v135
	v_fmac_f32_e32 v224, v152, v136
	v_fmac_f32_e32 v224, v153, v137
	v_fmac_f32_e32 v224, v154, v138
	v_fmac_f32_e32 v224, v155, v139
	v_fmac_f32_e32 v224, v156, v140
	v_fmac_f32_e32 v224, v157, v141
	v_fmac_f32_e32 v224, v158, v142
	v_fmac_f32_e32 v224, v159, v143
	s_nop 1
	v_add_f32_dpp v224, v224, v224 quad_perm:[1,0,3,2] row_mask:0xf bank_mask:0xf
	s_nop 1
	v_add_f32_dpp v224, v224, v224 quad_perm:[2,3,0,1] row_mask:0xf bank_mask:0xf
	buffer_store_dword v224, v239, s[68:71], s75 offen
	s_add_u32 s72, s72, 0x1000
	s_add_u32 s73, s73, 0x800
	s_add_u32 s74, s74, 0x200
	s_add_u32 s75, s75, 0x40
	s_waitcnt vmcnt(19)
	v_lshlrev_b32_e32 v144, 16, v12
	v_and_b32_e32 v145, 0xffff0000, v12
	v_lshlrev_b32_e32 v146, 16, v13
	v_and_b32_e32 v147, 0xffff0000, v13
	v_lshlrev_b32_e32 v148, 16, v14
	v_and_b32_e32 v149, 0xffff0000, v14
	v_lshlrev_b32_e32 v150, 16, v15
	v_and_b32_e32 v151, 0xffff0000, v15
	v_lshlrev_b32_e32 v152, 16, v16
	v_and_b32_e32 v153, 0xffff0000, v16
	v_lshlrev_b32_e32 v154, 16, v17
	v_and_b32_e32 v155, 0xffff0000, v17
	v_lshlrev_b32_e32 v156, 16, v18
	v_and_b32_e32 v157, 0xffff0000, v18
	v_lshlrev_b32_e32 v158, 16, v19
	v_and_b32_e32 v159, 0xffff0000, v19
	v_lshlrev_b32_e32 v160, 16, v24
	v_and_b32_e32 v161, 0xffff0000, v24
	v_lshlrev_b32_e32 v162, 16, v25
	v_and_b32_e32 v163, 0xffff0000, v25
	v_lshlrev_b32_e32 v164, 16, v26
	v_and_b32_e32 v165, 0xffff0000, v26
	v_lshlrev_b32_e32 v166, 16, v27
	v_and_b32_e32 v167, 0xffff0000, v27
	v_lshlrev_b32_e32 v168, 16, v28
	v_and_b32_e32 v169, 0xffff0000, v28
	v_lshlrev_b32_e32 v170, 16, v29
	v_and_b32_e32 v171, 0xffff0000, v29
	v_lshlrev_b32_e32 v172, 16, v30
	v_and_b32_e32 v173, 0xffff0000, v30
	v_lshlrev_b32_e32 v174, 16, v31
	v_and_b32_e32 v175, 0xffff0000, v31
	v_lshlrev_b32_e32 v176, 16, v36
	v_and_b32_e32 v177, 0xffff0000, v36
	v_lshlrev_b32_e32 v178, 16, v37
	v_and_b32_e32 v179, 0xffff0000, v37
	v_lshlrev_b32_e32 v180, 16, v38
	v_and_b32_e32 v181, 0xffff0000, v38
	v_lshlrev_b32_e32 v182, 16, v39
	v_and_b32_e32 v183, 0xffff0000, v39
	v_lshlrev_b32_e32 v184, 16, v40
	v_and_b32_e32 v185, 0xffff0000, v40
	v_lshlrev_b32_e32 v186, 16, v41
	v_and_b32_e32 v187, 0xffff0000, v41
	v_lshlrev_b32_e32 v188, 16, v42
	v_and_b32_e32 v189, 0xffff0000, v42
	v_lshlrev_b32_e32 v190, 16, v43
	v_and_b32_e32 v191, 0xffff0000, v43
	buffer_load_dwordx4 v[12:15], v232, s[64:67], 0 offen nt
	buffer_load_dwordx4 v[16:19], v232, s[64:67], 0 offen offset:16 nt
	v_add_u32_e32 v232, 6656, v232
	v_pk_add_f32 v[224:225], v[144:145], v[160:161] neg_lo:[0,1] neg_hi:[0,1]
	v_pk_add_f32 v[226:227], v[176:177], v[160:161] neg_lo:[0,1] neg_hi:[0,1]
	v_pk_fma_f32 v[192:193], v[96:97], v[224:225], v[160:161]
	v_pk_fma_f32 v[192:193], v[112:113], v[226:227], v[192:193]
	v_pk_add_f32 v[224:225], v[146:147], v[162:163] neg_lo:[0,1] neg_hi:[0,1]
	v_pk_add_f32 v[226:227], v[178:179], v[162:163] neg_lo:[0,1] neg_hi:[0,1]
	v_pk_fma_f32 v[194:195], v[98:99], v[224:225], v[162:163]
	v_pk_fma_f32 v[194:195], v[114:115], v[226:227], v[194:195]
	v_pk_add_f32 v[224:225], v[148:149], v[164:165] neg_lo:[0,1] neg_hi:[0,1]
	v_pk_add_f32 v[226:227], v[180:181], v[164:165] neg_lo:[0,1] neg_hi:[0,1]
	v_pk_fma_f32 v[196:197], v[100:101], v[224:225], v[164:165]
	v_pk_fma_f32 v[196:197], v[116:117], v[226:227], v[196:197]
	v_pk_add_f32 v[224:225], v[150:151], v[166:167] neg_lo:[0,1] neg_hi:[0,1]
	v_pk_add_f32 v[226:227], v[182:183], v[166:167] neg_lo:[0,1] neg_hi:[0,1]
	v_pk_fma_f32 v[198:199], v[102:103], v[224:225], v[166:167]
	v_pk_fma_f32 v[198:199], v[118:119], v[226:227], v[198:199]
	v_pk_add_f32 v[224:225], v[152:153], v[168:169] neg_lo:[0,1] neg_hi:[0,1]
	v_pk_add_f32 v[226:227], v[184:185], v[168:169] neg_lo:[0,1] neg_hi:[0,1]
	v_pk_fma_f32 v[200:201], v[104:105], v[224:225], v[168:169]
	v_pk_fma_f32 v[200:201], v[120:121], v[226:227], v[200:201]
	v_pk_add_f32 v[224:225], v[154:155], v[170:171] neg_lo:[0,1] neg_hi:[0,1]
	v_pk_add_f32 v[226:227], v[186:187], v[170:171] neg_lo:[0,1] neg_hi:[0,1]
	v_pk_fma_f32 v[202:203], v[106:107], v[224:225], v[170:171]
	v_pk_fma_f32 v[202:203], v[122:123], v[226:227], v[202:203]
	v_pk_add_f32 v[224:225], v[156:157], v[172:173] neg_lo:[0,1] neg_hi:[0,1]
	v_pk_add_f32 v[226:227], v[188:189], v[172:173] neg_lo:[0,1] neg_hi:[0,1]
	v_pk_fma_f32 v[204:205], v[108:109], v[224:225], v[172:173]
	v_pk_fma_f32 v[204:205], v[124:125], v[226:227], v[204:205]
	v_pk_add_f32 v[224:225], v[158:159], v[174:175] neg_lo:[0,1] neg_hi:[0,1]
	v_pk_add_f32 v[226:227], v[190:191], v[174:175] neg_lo:[0,1] neg_hi:[0,1]
	v_pk_fma_f32 v[206:207], v[110:111], v[224:225], v[174:175]
	v_pk_fma_f32 v[206:207], v[126:127], v[226:227], v[206:207]
	s_add_u32 s76, s76, 0x800
	buffer_load_dwordx4 v[208:211], v236, s[68:71], s76 offen
	buffer_load_dwordx4 v[212:215], v236, s[68:71], s76 offen offset:16
	buffer_store_dwordx4 v[192:195], v235, s[68:71], s72 offen offset:0
	buffer_store_dwordx4 v[196:199], v235, s[68:71], s72 offen offset:16
	buffer_store_dwordx4 v[200:203], v235, s[68:71], s72 offen offset:32
	buffer_store_dwordx4 v[204:207], v235, s[68:71], s72 offen offset:48
	s_waitcnt vmcnt(13)
; __device__ __forceinline__ void prep_phase(const Params& p) {
;     ...
;             for (int i = 0; i < 16; ++i) {
;                 const bool hn = (tt0 + i) < SEQ - 1; const Z16 rn = hn ? ldz(zc + (size_t)(i + 1) * 3328) : zz();
;                 const size_t o = (size_t)(t0 + i) * RW + c;
;                 float r[16], k[16]; mix16(rp, rc, rn, mpr, mnr, r); unz(ldz(Kb + o), k);
;                 float bs = 0.f;
; #pragma unroll
;                 for (int q = 0; q < 16; ++q) bs += r[q] * k[q] * rkc[q];
;                 bs += __shfl_xor(bs, 1); bs += __shfl_xor(bs, 2);
; #pragma unroll
;                 for (int j4 = 0; j4 < 4; ++j4) *(f32x4*)(R + o + j4 * 4) = (f32x4){r[j4 * 4], r[j4 * 4 + 1], r[j4 * 4 + 2], r[j4 * 4 + 3]};
;                 if ((lane & 3) == 0) BON[(size_t)(t0 + i) * 16 + (lane >> 2)] = bs;
;                 rp = rc; rc = rn;
	v_lshlrev_b32_e32 v144, 16, v216
	v_and_b32_e32 v145, 0xffff0000, v216
	v_lshlrev_b32_e32 v146, 16, v217
	v_and_b32_e32 v147, 0xffff0000, v217
	v_lshlrev_b32_e32 v148, 16, v218
	v_and_b32_e32 v149, 0xffff0000, v218
	v_lshlrev_b32_e32 v150, 16, v219
	v_and_b32_e32 v151, 0xffff0000, v219
	v_lshlrev_b32_e32 v152, 16, v220
	v_and_b32_e32 v153, 0xffff0000, v220
	v_lshlrev_b32_e32 v154, 16, v221
	v_and_b32_e32 v155, 0xffff0000, v221
	v_lshlrev_b32_e32 v156, 16, v222
	v_and_b32_e32 v157, 0xffff0000, v222
	v_lshlrev_b32_e32 v158, 16, v223
	v_and_b32_e32 v159, 0xffff0000, v223
	v_pk_mul_f32 v[144:145], v[192:193], v[144:145]
	v_pk_mul_f32 v[146:147], v[194:195], v[146:147]
	v_pk_mul_f32 v[148:149], v[196:197], v[148:149]
	v_pk_mul_f32 v[150:151], v[198:199], v[150:151]
	v_pk_mul_f32 v[152:153], v[200:201], v[152:153]
	v_pk_mul_f32 v[154:155], v[202:203], v[154:155]
	v_pk_mul_f32 v[156:157], v[204:205], v[156:157]
	v_pk_mul_f32 v[158:159], v[206:207], v[158:159]
	v_mul_f32_e32 v224, v144, v128
	v_fmac_f32_e32 v224, v145, v129
	v_fmac_f32_e32 v224, v146, v130
	v_fmac_f32_e32 v224, v147, v131
	v_fmac_f32_e32 v224, v148, v132
	v_fmac_f32_e32 v224, v149, v133
	v_fmac_f32_e32 v224, v150, v134
	v_fmac_f32_e32 v224, v151, v135
	v_fmac_f32_e32 v224, v152, v136
	v_fmac_f32_e32 v224, v153, v137
	v_fmac_f32_e32 v224, v154, v138
	v_fmac_f32_e32 v224, v155, v139
	v_fmac_f32_e32 v224, v156, v140
	v_fmac_f32_e32 v224, v157, v141
	v_fmac_f32_e32 v224, v158, v142
	v_fmac_f32_e32 v224, v159, v143
	s_nop 1
	v_add_f32_dpp v224, v224, v224 quad_perm:[1,0,3,2] row_mask:0xf bank_mask:0xf
	s_nop 1
	v_add_f32_dpp v224, v224, v224 quad_perm:[2,3,0,1] row_mask:0xf bank_mask:0xf
	buffer_store_dword v224, v239, s[68:71], s75 offen
	s_add_u32 s72, s72, 0x1000
	s_add_u32 s73, s73, 0x800
	s_add_u32 s74, s74, 0x200
	s_add_u32 s75, s75, 0x40
	s_waitcnt vmcnt(26)
	v_lshlrev_b32_e32 v144, 16, v24
	v_and_b32_e32 v145, 0xffff0000, v24
	v_lshlrev_b32_e32 v146, 16, v25
	v_and_b32_e32 v147, 0xffff0000, v25
	v_lshlrev_b32_e32 v148, 16, v26
	v_and_b32_e32 v149, 0xffff0000, v26
	v_lshlrev_b32_e32 v150, 16, v27
	v_and_b32_e32 v151, 0xffff0000, v27
	v_lshlrev_b32_e32 v152, 16, v28
	v_and_b32_e32 v153, 0xffff0000, v28
	v_lshlrev_b32_e32 v154, 16, v29
	v_and_b32_e32 v155, 0xffff0000, v29
	v_lshlrev_b32_e32 v156, 16, v30
	v_and_b32_e32 v157, 0xffff0000, v30
	v_lshlrev_b32_e32 v158, 16, v31
	v_and_b32_e32 v159, 0xffff0000, v31
	v_lshlrev_b32_e32 v160, 16, v36
	v_and_b32_e32 v161, 0xffff0000, v36
	v_lshlrev_b32_e32 v162, 16, v37
	v_and_b32_e32 v163, 0xffff0000, v37
	v_lshlrev_b32_e32 v164, 16, v38
	v_and_b32_e32 v165, 0xffff0000, v38
	v_lshlrev_b32_e32 v166, 16, v39
	v_and_b32_e32 v167, 0xffff0000, v39
	v_lshlrev_b32_e32 v168, 16, v40
	v_and_b32_e32 v169, 0xffff0000, v40
	v_lshlrev_b32_e32 v170, 16, v41
	v_and_b32_e32 v171, 0xffff0000, v41
	v_lshlrev_b32_e32 v172, 16, v42
	v_and_b32_e32 v173, 0xffff0000, v42
	v_lshlrev_b32_e32 v174, 16, v43
	v_and_b32_e32 v175, 0xffff0000, v43
	v_lshlrev_b32_e32 v176, 16, v48
	v_and_b32_e32 v177, 0xffff0000, v48
	v_lshlrev_b32_e32 v178, 16, v49
	v_and_b32_e32 v179, 0xffff0000, v49
	v_lshlrev_b32_e32 v180, 16, v50
	v_and_b32_e32 v181, 0xffff0000, v50
	v_lshlrev_b32_e32 v182, 16, v51
	v_and_b32_e32 v183, 0xffff0000, v51
	v_lshlrev_b32_e32 v184, 16, v52
	v_and_b32_e32 v185, 0xffff0000, v52
	v_lshlrev_b32_e32 v186, 16, v53
	v_and_b32_e32 v187, 0xffff0000, v53
	v_lshlrev_b32_e32 v188, 16, v54
	v_and_b32_e32 v189, 0xffff0000, v54
	v_lshlrev_b32_e32 v190, 16, v55
	v_and_b32_e32 v191, 0xffff0000, v55
	buffer_load_dwordx4 v[24:27], v232, s[64:67], 0 offen nt
	buffer_load_dwordx4 v[28:31], v232, s[64:67], 0 offen offset:16 nt
	v_add_u32_e32 v232, 6656, v232
	v_pk_add_f32 v[224:225], v[144:145], v[160:161] neg_lo:[0,1] neg_hi:[0,1]
	v_pk_add_f32 v[226:227], v[176:177], v[160:161] neg_lo:[0,1] neg_hi:[0,1]
	v_pk_fma_f32 v[192:193], v[96:97], v[224:225], v[160:161]
	v_pk_fma_f32 v[192:193], v[112:113], v[226:227], v[192:193]
	v_pk_add_f32 v[224:225], v[146:147], v[162:163] neg_lo:[0,1] neg_hi:[0,1]
	v_pk_add_f32 v[226:227], v[178:179], v[162:163] neg_lo:[0,1] neg_hi:[0,1]
	v_pk_fma_f32 v[194:195], v[98:99], v[224:225], v[162:163]
	v_pk_fma_f32 v[194:195], v[114:115], v[226:227], v[194:195]
	v_pk_add_f32 v[224:225], v[148:149], v[164:165] neg_lo:[0,1] neg_hi:[0,1]
	v_pk_add_f32 v[226:227], v[180:181], v[164:165] neg_lo:[0,1] neg_hi:[0,1]
	v_pk_fma_f32 v[196:197], v[100:101], v[224:225], v[164:165]
	v_pk_fma_f32 v[196:197], v[116:117], v[226:227], v[196:197]
	v_pk_add_f32 v[224:225], v[150:151], v[166:167] neg_lo:[0,1] neg_hi:[0,1]
	v_pk_add_f32 v[226:227], v[182:183], v[166:167] neg_lo:[0,1] neg_hi:[0,1]
	v_pk_fma_f32 v[198:199], v[102:103], v[224:225], v[166:167]
	v_pk_fma_f32 v[198:199], v[118:119], v[226:227], v[198:199]
	v_pk_add_f32 v[224:225], v[152:153], v[168:169] neg_lo:[0,1] neg_hi:[0,1]
	v_pk_add_f32 v[226:227], v[184:185], v[168:169] neg_lo:[0,1] neg_hi:[0,1]
	v_pk_fma_f32 v[200:201], v[104:105], v[224:225], v[168:169]
	v_pk_fma_f32 v[200:201], v[120:121], v[226:227], v[200:201]
	v_pk_add_f32 v[224:225], v[154:155], v[170:171] neg_lo:[0,1] neg_hi:[0,1]
	v_pk_add_f32 v[226:227], v[186:187], v[170:171] neg_lo:[0,1] neg_hi:[0,1]
	v_pk_fma_f32 v[202:203], v[106:107], v[224:225], v[170:171]
	v_pk_fma_f32 v[202:203], v[122:123], v[226:227], v[202:203]
	v_pk_add_f32 v[224:225], v[156:157], v[172:173] neg_lo:[0,1] neg_hi:[0,1]
	v_pk_add_f32 v[226:227], v[188:189], v[172:173] neg_lo:[0,1] neg_hi:[0,1]
	v_pk_fma_f32 v[204:205], v[108:109], v[224:225], v[172:173]
	v_pk_fma_f32 v[204:205], v[124:125], v[226:227], v[204:205]
	v_pk_add_f32 v[224:225], v[158:159], v[174:175] neg_lo:[0,1] neg_hi:[0,1]
	v_pk_add_f32 v[226:227], v[190:191], v[174:175] neg_lo:[0,1] neg_hi:[0,1]
	v_pk_fma_f32 v[206:207], v[110:111], v[224:225], v[174:175]
	v_pk_fma_f32 v[206:207], v[126:127], v[226:227], v[206:207]
	s_add_u32 s76, s76, 0x800
	buffer_load_dwordx4 v[216:219], v236, s[68:71], s76 offen
	buffer_load_dwordx4 v[220:223], v236, s[68:71], s76 offen offset:16
	buffer_store_dwordx4 v[192:195], v235, s[68:71], s72 offen offset:0
	buffer_store_dwordx4 v[196:199], v235, s[68:71], s72 offen offset:16
	buffer_store_dwordx4 v[200:203], v235, s[68:71], s72 offen offset:32
	buffer_store_dwordx4 v[204:207], v235, s[68:71], s72 offen offset:48
	s_waitcnt vmcnt(13)
; __device__ __forceinline__ void prep_phase(const Params& p) {
;     ...
;             for (int i = 0; i < 16; ++i) {
;                 const bool hn = (tt0 + i) < SEQ - 1; const Z16 rn = hn ? ldz(zc + (size_t)(i + 1) * 3328) : zz();
;                 const size_t o = (size_t)(t0 + i) * RW + c;
;                 float r[16], k[16]; mix16(rp, rc, rn, mpr, mnr, r); unz(ldz(Kb + o), k);
;                 float bs = 0.f;
; #pragma unroll
;                 for (int q = 0; q < 16; ++q) bs += r[q] * k[q] * rkc[q];
;                 bs += __shfl_xor(bs, 1); bs += __shfl_xor(bs, 2);
; #pragma unroll
;                 for (int j4 = 0; j4 < 4; ++j4) *(f32x4*)(R + o + j4 * 4) = (f32x4){r[j4 * 4], r[j4 * 4 + 1], r[j4 * 4 + 2], r[j4 * 4 + 3]};
;                 if ((lane & 3) == 0) BON[(size_t)(t0 + i) * 16 + (lane >> 2)] = bs;
;                 rp = rc; rc = rn;
	v_lshlrev_b32_e32 v144, 16, v208
	v_and_b32_e32 v145, 0xffff0000, v208
	v_lshlrev_b32_e32 v146, 16, v209
	v_and_b32_e32 v147, 0xffff0000, v209
	v_lshlrev_b32_e32 v148, 16, v210
	v_and_b32_e32 v149, 0xffff0000, v210
	v_lshlrev_b32_e32 v150, 16, v211
	v_and_b32_e32 v151, 0xffff0000, v211
	v_lshlrev_b32_e32 v152, 16, v212
	v_and_b32_e32 v153, 0xffff0000, v212
	v_lshlrev_b32_e32 v154, 16, v213
	v_and_b32_e32 v155, 0xffff0000, v213
	v_lshlrev_b32_e32 v156, 16, v214
	v_and_b32_e32 v157, 0xffff0000, v214
	v_lshlrev_b32_e32 v158, 16, v215
	v_and_b32_e32 v159, 0xffff0000, v215
	v_pk_mul_f32 v[144:145], v[192:193], v[144:145]
	v_pk_mul_f32 v[146:147], v[194:195], v[146:147]
	v_pk_mul_f32 v[148:149], v[196:197], v[148:149]
	v_pk_mul_f32 v[150:151], v[198:199], v[150:151]
	v_pk_mul_f32 v[152:153], v[200:201], v[152:153]
	v_pk_mul_f32 v[154:155], v[202:203], v[154:155]
	v_pk_mul_f32 v[156:157], v[204:205], v[156:157]
	v_pk_mul_f32 v[158:159], v[206:207], v[158:159]
	v_mul_f32_e32 v224, v144, v128
	v_fmac_f32_e32 v224, v145, v129
	v_fmac_f32_e32 v224, v146, v130
	v_fmac_f32_e32 v224, v147, v131
	v_fmac_f32_e32 v224, v148, v132
	v_fmac_f32_e32 v224, v149, v133
	v_fmac_f32_e32 v224, v150, v134
	v_fmac_f32_e32 v224, v151, v135
	v_fmac_f32_e32 v224, v152, v136
	v_fmac_f32_e32 v224, v153, v137
	v_fmac_f32_e32 v224, v154, v138
	v_fmac_f32_e32 v224, v155, v139
	v_fmac_f32_e32 v224, v156, v140
	v_fmac_f32_e32 v224, v157, v141
	v_fmac_f32_e32 v224, v158, v142
	v_fmac_f32_e32 v224, v159, v143
	s_nop 1
	v_add_f32_dpp v224, v224, v224 quad_perm:[1,0,3,2] row_mask:0xf bank_mask:0xf
	s_nop 1
	v_add_f32_dpp v224, v224, v224 quad_perm:[2,3,0,1] row_mask:0xf bank_mask:0xf
	buffer_store_dword v224, v239, s[68:71], s75 offen
	s_add_u32 s72, s72, 0x1000
	s_add_u32 s73, s73, 0x800
	s_add_u32 s74, s74, 0x200
	s_add_u32 s75, s75, 0x40
	s_waitcnt vmcnt(33)
	v_lshlrev_b32_e32 v144, 16, v36
	v_and_b32_e32 v145, 0xffff0000, v36
	v_lshlrev_b32_e32 v146, 16, v37
	v_and_b32_e32 v147, 0xffff0000, v37
	v_lshlrev_b32_e32 v148, 16, v38
	v_and_b32_e32 v149, 0xffff0000, v38
	v_lshlrev_b32_e32 v150, 16, v39
	v_and_b32_e32 v151, 0xffff0000, v39
	v_lshlrev_b32_e32 v152, 16, v40
	v_and_b32_e32 v153, 0xffff0000, v40
	v_lshlrev_b32_e32 v154, 16, v41
	v_and_b32_e32 v155, 0xffff0000, v41
	v_lshlrev_b32_e32 v156, 16, v42
	v_and_b32_e32 v157, 0xffff0000, v42
	v_lshlrev_b32_e32 v158, 16, v43
	v_and_b32_e32 v159, 0xffff0000, v43
	v_lshlrev_b32_e32 v160, 16, v48
	v_and_b32_e32 v161, 0xffff0000, v48
	v_lshlrev_b32_e32 v162, 16, v49
	v_and_b32_e32 v163, 0xffff0000, v49
	v_lshlrev_b32_e32 v164, 16, v50
	v_and_b32_e32 v165, 0xffff0000, v50
	v_lshlrev_b32_e32 v166, 16, v51
	v_and_b32_e32 v167, 0xffff0000, v51
	v_lshlrev_b32_e32 v168, 16, v52
	v_and_b32_e32 v169, 0xffff0000, v52
	v_lshlrev_b32_e32 v170, 16, v53
	v_and_b32_e32 v171, 0xffff0000, v53
	v_lshlrev_b32_e32 v172, 16, v54
	v_and_b32_e32 v173, 0xffff0000, v54
	v_lshlrev_b32_e32 v174, 16, v55
	v_and_b32_e32 v175, 0xffff0000, v55
	v_lshlrev_b32_e32 v176, 16, v60
	v_and_b32_e32 v177, 0xffff0000, v60
	v_lshlrev_b32_e32 v178, 16, v61
	v_and_b32_e32 v179, 0xffff0000, v61
	v_lshlrev_b32_e32 v180, 16, v62
	v_and_b32_e32 v181, 0xffff0000, v62
	v_lshlrev_b32_e32 v182, 16, v63
	v_and_b32_e32 v183, 0xffff0000, v63
	v_lshlrev_b32_e32 v184, 16, v64
	v_and_b32_e32 v185, 0xffff0000, v64
	v_lshlrev_b32_e32 v186, 16, v65
	v_and_b32_e32 v187, 0xffff0000, v65
	v_lshlrev_b32_e32 v188, 16, v66
	v_and_b32_e32 v189, 0xffff0000, v66
	v_lshlrev_b32_e32 v190, 16, v67
	v_and_b32_e32 v191, 0xffff0000, v67
	buffer_load_dwordx4 v[36:39], v232, s[64:67], 0 offen nt
	buffer_load_dwordx4 v[40:43], v232, s[64:67], 0 offen offset:16 nt
	v_add_u32_e32 v232, 6656, v232
	v_pk_add_f32 v[224:225], v[144:145], v[160:161] neg_lo:[0,1] neg_hi:[0,1]
	v_pk_add_f32 v[226:227], v[176:177], v[160:161] neg_lo:[0,1] neg_hi:[0,1]
	v_pk_fma_f32 v[192:193], v[96:97], v[224:225], v[160:161]
	v_pk_fma_f32 v[192:193], v[112:113], v[226:227], v[192:193]
	v_pk_add_f32 v[224:225], v[146:147], v[162:163] neg_lo:[0,1] neg_hi:[0,1]
	v_pk_add_f32 v[226:227], v[178:179], v[162:163] neg_lo:[0,1] neg_hi:[0,1]
	v_pk_fma_f32 v[194:195], v[98:99], v[224:225], v[162:163]
	v_pk_fma_f32 v[194:195], v[114:115], v[226:227], v[194:195]
	v_pk_add_f32 v[224:225], v[148:149], v[164:165] neg_lo:[0,1] neg_hi:[0,1]
	v_pk_add_f32 v[226:227], v[180:181], v[164:165] neg_lo:[0,1] neg_hi:[0,1]
	v_pk_fma_f32 v[196:197], v[100:101], v[224:225], v[164:165]
	v_pk_fma_f32 v[196:197], v[116:117], v[226:227], v[196:197]
	v_pk_add_f32 v[224:225], v[150:151], v[166:167] neg_lo:[0,1] neg_hi:[0,1]
	v_pk_add_f32 v[226:227], v[182:183], v[166:167] neg_lo:[0,1] neg_hi:[0,1]
	v_pk_fma_f32 v[198:199], v[102:103], v[224:225], v[166:167]
	v_pk_fma_f32 v[198:199], v[118:119], v[226:227], v[198:199]
	v_pk_add_f32 v[224:225], v[152:153], v[168:169] neg_lo:[0,1] neg_hi:[0,1]
	v_pk_add_f32 v[226:227], v[184:185], v[168:169] neg_lo:[0,1] neg_hi:[0,1]
	v_pk_fma_f32 v[200:201], v[104:105], v[224:225], v[168:169]
	v_pk_fma_f32 v[200:201], v[120:121], v[226:227], v[200:201]
	v_pk_add_f32 v[224:225], v[154:155], v[170:171] neg_lo:[0,1] neg_hi:[0,1]
	v_pk_add_f32 v[226:227], v[186:187], v[170:171] neg_lo:[0,1] neg_hi:[0,1]
	v_pk_fma_f32 v[202:203], v[106:107], v[224:225], v[170:171]
	v_pk_fma_f32 v[202:203], v[122:123], v[226:227], v[202:203]
	v_pk_add_f32 v[224:225], v[156:157], v[172:173] neg_lo:[0,1] neg_hi:[0,1]
	v_pk_add_f32 v[226:227], v[188:189], v[172:173] neg_lo:[0,1] neg_hi:[0,1]
	v_pk_fma_f32 v[204:205], v[108:109], v[224:225], v[172:173]
	v_pk_fma_f32 v[204:205], v[124:125], v[226:227], v[204:205]
	v_pk_add_f32 v[224:225], v[158:159], v[174:175] neg_lo:[0,1] neg_hi:[0,1]
	v_pk_add_f32 v[226:227], v[190:191], v[174:175] neg_lo:[0,1] neg_hi:[0,1]
	v_pk_fma_f32 v[206:207], v[110:111], v[224:225], v[174:175]
	v_pk_fma_f32 v[206:207], v[126:127], v[226:227], v[206:207]
	s_add_u32 s76, s76, 0x800
	buffer_load_dwordx4 v[208:211], v236, s[68:71], s76 offen
	buffer_load_dwordx4 v[212:215], v236, s[68:71], s76 offen offset:16
	buffer_store_dwordx4 v[192:195], v235, s[68:71], s72 offen offset:0
	buffer_store_dwordx4 v[196:199], v235, s[68:71], s72 offen offset:16
	buffer_store_dwordx4 v[200:203], v235, s[68:71], s72 offen offset:32
	buffer_store_dwordx4 v[204:207], v235, s[68:71], s72 offen offset:48
	s_waitcnt vmcnt(13)
; __device__ __forceinline__ void prep_phase(const Params& p) {
;     ...
;             for (int i = 0; i < 16; ++i) {
;                 const bool hn = (tt0 + i) < SEQ - 1; const Z16 rn = hn ? ldz(zc + (size_t)(i + 1) * 3328) : zz();
;                 const size_t o = (size_t)(t0 + i) * RW + c;
;                 float r[16], k[16]; mix16(rp, rc, rn, mpr, mnr, r); unz(ldz(Kb + o), k);
;                 float bs = 0.f;
; #pragma unroll
;                 for (int q = 0; q < 16; ++q) bs += r[q] * k[q] * rkc[q];
;                 bs += __shfl_xor(bs, 1); bs += __shfl_xor(bs, 2);
; #pragma unroll
;                 for (int j4 = 0; j4 < 4; ++j4) *(f32x4*)(R + o + j4 * 4) = (f32x4){r[j4 * 4], r[j4 * 4 + 1], r[j4 * 4 + 2], r[j4 * 4 + 3]};
;                 if ((lane & 3) == 0) BON[(size_t)(t0 + i) * 16 + (lane >> 2)] = bs;
;                 rp = rc; rc = rn;
	v_lshlrev_b32_e32 v144, 16, v216
	v_and_b32_e32 v145, 0xffff0000, v216
	v_lshlrev_b32_e32 v146, 16, v217
	v_and_b32_e32 v147, 0xffff0000, v217
	v_lshlrev_b32_e32 v148, 16, v218
	v_and_b32_e32 v149, 0xffff0000, v218
	v_lshlrev_b32_e32 v150, 16, v219
	v_and_b32_e32 v151, 0xffff0000, v219
	v_lshlrev_b32_e32 v152, 16, v220
	v_and_b32_e32 v153, 0xffff0000, v220
	v_lshlrev_b32_e32 v154, 16, v221
	v_and_b32_e32 v155, 0xffff0000, v221
	v_lshlrev_b32_e32 v156, 16, v222
	v_and_b32_e32 v157, 0xffff0000, v222
	v_lshlrev_b32_e32 v158, 16, v223
	v_and_b32_e32 v159, 0xffff0000, v223
	v_pk_mul_f32 v[144:145], v[192:193], v[144:145]
	v_pk_mul_f32 v[146:147], v[194:195], v[146:147]
	v_pk_mul_f32 v[148:149], v[196:197], v[148:149]
	v_pk_mul_f32 v[150:151], v[198:199], v[150:151]
	v_pk_mul_f32 v[152:153], v[200:201], v[152:153]
	v_pk_mul_f32 v[154:155], v[202:203], v[154:155]
	v_pk_mul_f32 v[156:157], v[204:205], v[156:157]
	v_pk_mul_f32 v[158:159], v[206:207], v[158:159]
	v_mul_f32_e32 v224, v144, v128
	v_fmac_f32_e32 v224, v145, v129
	v_fmac_f32_e32 v224, v146, v130
	v_fmac_f32_e32 v224, v147, v131
	v_fmac_f32_e32 v224, v148, v132
	v_fmac_f32_e32 v224, v149, v133
	v_fmac_f32_e32 v224, v150, v134
	v_fmac_f32_e32 v224, v151, v135
	v_fmac_f32_e32 v224, v152, v136
	v_fmac_f32_e32 v224, v153, v137
	v_fmac_f32_e32 v224, v154, v138
	v_fmac_f32_e32 v224, v155, v139
	v_fmac_f32_e32 v224, v156, v140
	v_fmac_f32_e32 v224, v157, v141
	v_fmac_f32_e32 v224, v158, v142
	v_fmac_f32_e32 v224, v159, v143
	s_nop 1
	v_add_f32_dpp v224, v224, v224 quad_perm:[1,0,3,2] row_mask:0xf bank_mask:0xf
	s_nop 1
	v_add_f32_dpp v224, v224, v224 quad_perm:[2,3,0,1] row_mask:0xf bank_mask:0xf
	buffer_store_dword v224, v239, s[68:71], s75 offen
	s_add_u32 s72, s72, 0x1000
	s_add_u32 s73, s73, 0x800
	s_add_u32 s74, s74, 0x200
	s_add_u32 s75, s75, 0x40
	s_waitcnt vmcnt(40)
	v_lshlrev_b32_e32 v144, 16, v48
	v_and_b32_e32 v145, 0xffff0000, v48
	v_lshlrev_b32_e32 v146, 16, v49
	v_and_b32_e32 v147, 0xffff0000, v49
	v_lshlrev_b32_e32 v148, 16, v50
	v_and_b32_e32 v149, 0xffff0000, v50
	v_lshlrev_b32_e32 v150, 16, v51
	v_and_b32_e32 v151, 0xffff0000, v51
	v_lshlrev_b32_e32 v152, 16, v52
	v_and_b32_e32 v153, 0xffff0000, v52
	v_lshlrev_b32_e32 v154, 16, v53
	v_and_b32_e32 v155, 0xffff0000, v53
	v_lshlrev_b32_e32 v156, 16, v54
	v_and_b32_e32 v157, 0xffff0000, v54
	v_lshlrev_b32_e32 v158, 16, v55
	v_and_b32_e32 v159, 0xffff0000, v55
	v_lshlrev_b32_e32 v160, 16, v60
	v_and_b32_e32 v161, 0xffff0000, v60
	v_lshlrev_b32_e32 v162, 16, v61
	v_and_b32_e32 v163, 0xffff0000, v61
	v_lshlrev_b32_e32 v164, 16, v62
	v_and_b32_e32 v165, 0xffff0000, v62
	v_lshlrev_b32_e32 v166, 16, v63
	v_and_b32_e32 v167, 0xffff0000, v63
	v_lshlrev_b32_e32 v168, 16, v64
	v_and_b32_e32 v169, 0xffff0000, v64
	v_lshlrev_b32_e32 v170, 16, v65
	v_and_b32_e32 v171, 0xffff0000, v65
	v_lshlrev_b32_e32 v172, 16, v66
	v_and_b32_e32 v173, 0xffff0000, v66
	v_lshlrev_b32_e32 v174, 16, v67
	v_and_b32_e32 v175, 0xffff0000, v67
	v_lshlrev_b32_e32 v176, 16, v72
	v_and_b32_e32 v177, 0xffff0000, v72
	v_lshlrev_b32_e32 v178, 16, v73
	v_and_b32_e32 v179, 0xffff0000, v73
	v_lshlrev_b32_e32 v180, 16, v74
	v_and_b32_e32 v181, 0xffff0000, v74
	v_lshlrev_b32_e32 v182, 16, v75
	v_and_b32_e32 v183, 0xffff0000, v75
	v_lshlrev_b32_e32 v184, 16, v76
	v_and_b32_e32 v185, 0xffff0000, v76
	v_lshlrev_b32_e32 v186, 16, v77
	v_and_b32_e32 v187, 0xffff0000, v77
	v_lshlrev_b32_e32 v188, 16, v78
	v_and_b32_e32 v189, 0xffff0000, v78
	v_lshlrev_b32_e32 v190, 16, v79
	v_and_b32_e32 v191, 0xffff0000, v79
	buffer_load_dwordx4 v[48:51], v232, s[64:67], 0 offen nt
	buffer_load_dwordx4 v[52:55], v232, s[64:67], 0 offen offset:16 nt
	v_add_u32_e32 v232, 6656, v232
	v_pk_add_f32 v[224:225], v[144:145], v[160:161] neg_lo:[0,1] neg_hi:[0,1]
	v_pk_add_f32 v[226:227], v[176:177], v[160:161] neg_lo:[0,1] neg_hi:[0,1]
	v_pk_fma_f32 v[192:193], v[96:97], v[224:225], v[160:161]
	v_pk_fma_f32 v[192:193], v[112:113], v[226:227], v[192:193]
	v_pk_add_f32 v[224:225], v[146:147], v[162:163] neg_lo:[0,1] neg_hi:[0,1]
	v_pk_add_f32 v[226:227], v[178:179], v[162:163] neg_lo:[0,1] neg_hi:[0,1]
	v_pk_fma_f32 v[194:195], v[98:99], v[224:225], v[162:163]
	v_pk_fma_f32 v[194:195], v[114:115], v[226:227], v[194:195]
	v_pk_add_f32 v[224:225], v[148:149], v[164:165] neg_lo:[0,1] neg_hi:[0,1]
	v_pk_add_f32 v[226:227], v[180:181], v[164:165] neg_lo:[0,1] neg_hi:[0,1]
	v_pk_fma_f32 v[196:197], v[100:101], v[224:225], v[164:165]
	v_pk_fma_f32 v[196:197], v[116:117], v[226:227], v[196:197]
	v_pk_add_f32 v[224:225], v[150:151], v[166:167] neg_lo:[0,1] neg_hi:[0,1]
	v_pk_add_f32 v[226:227], v[182:183], v[166:167] neg_lo:[0,1] neg_hi:[0,1]
	v_pk_fma_f32 v[198:199], v[102:103], v[224:225], v[166:167]
	v_pk_fma_f32 v[198:199], v[118:119], v[226:227], v[198:199]
	v_pk_add_f32 v[224:225], v[152:153], v[168:169] neg_lo:[0,1] neg_hi:[0,1]
	v_pk_add_f32 v[226:227], v[184:185], v[168:169] neg_lo:[0,1] neg_hi:[0,1]
	v_pk_fma_f32 v[200:201], v[104:105], v[224:225], v[168:169]
	v_pk_fma_f32 v[200:201], v[120:121], v[226:227], v[200:201]
	v_pk_add_f32 v[224:225], v[154:155], v[170:171] neg_lo:[0,1] neg_hi:[0,1]
	v_pk_add_f32 v[226:227], v[186:187], v[170:171] neg_lo:[0,1] neg_hi:[0,1]
	v_pk_fma_f32 v[202:203], v[106:107], v[224:225], v[170:171]
	v_pk_fma_f32 v[202:203], v[122:123], v[226:227], v[202:203]
	v_pk_add_f32 v[224:225], v[156:157], v[172:173] neg_lo:[0,1] neg_hi:[0,1]
	v_pk_add_f32 v[226:227], v[188:189], v[172:173] neg_lo:[0,1] neg_hi:[0,1]
	v_pk_fma_f32 v[204:205], v[108:109], v[224:225], v[172:173]
	v_pk_fma_f32 v[204:205], v[124:125], v[226:227], v[204:205]
	v_pk_add_f32 v[224:225], v[158:159], v[174:175] neg_lo:[0,1] neg_hi:[0,1]
	v_pk_add_f32 v[226:227], v[190:191], v[174:175] neg_lo:[0,1] neg_hi:[0,1]
	v_pk_fma_f32 v[206:207], v[110:111], v[224:225], v[174:175]
	v_pk_fma_f32 v[206:207], v[126:127], v[226:227], v[206:207]
	s_add_u32 s76, s76, 0x800
	buffer_load_dwordx4 v[216:219], v236, s[68:71], s76 offen
	buffer_load_dwordx4 v[220:223], v236, s[68:71], s76 offen offset:16
	buffer_store_dwordx4 v[192:195], v235, s[68:71], s72 offen offset:0
	buffer_store_dwordx4 v[196:199], v235, s[68:71], s72 offen offset:16
	buffer_store_dwordx4 v[200:203], v235, s[68:71], s72 offen offset:32
	buffer_store_dwordx4 v[204:207], v235, s[68:71], s72 offen offset:48
	s_waitcnt vmcnt(13)
; __device__ __forceinline__ void prep_phase(const Params& p) {
;     ...
;             for (int i = 0; i < 16; ++i) {
;                 const bool hn = (tt0 + i) < SEQ - 1; const Z16 rn = hn ? ldz(zc + (size_t)(i + 1) * 3328) : zz();
;                 const size_t o = (size_t)(t0 + i) * RW + c;
;                 float r[16], k[16]; mix16(rp, rc, rn, mpr, mnr, r); unz(ldz(Kb + o), k);
;                 float bs = 0.f;
; #pragma unroll
;                 for (int q = 0; q < 16; ++q) bs += r[q] * k[q] * rkc[q];
;                 bs += __shfl_xor(bs, 1); bs += __shfl_xor(bs, 2);
; #pragma unroll
;                 for (int j4 = 0; j4 < 4; ++j4) *(f32x4*)(R + o + j4 * 4) = (f32x4){r[j4 * 4], r[j4 * 4 + 1], r[j4 * 4 + 2], r[j4 * 4 + 3]};
;                 if ((lane & 3) == 0) BON[(size_t)(t0 + i) * 16 + (lane >> 2)] = bs;
;                 rp = rc; rc = rn;
	v_lshlrev_b32_e32 v144, 16, v208
	v_and_b32_e32 v145, 0xffff0000, v208
	v_lshlrev_b32_e32 v146, 16, v209
	v_and_b32_e32 v147, 0xffff0000, v209
	v_lshlrev_b32_e32 v148, 16, v210
	v_and_b32_e32 v149, 0xffff0000, v210
	v_lshlrev_b32_e32 v150, 16, v211
	v_and_b32_e32 v151, 0xffff0000, v211
	v_lshlrev_b32_e32 v152, 16, v212
	v_and_b32_e32 v153, 0xffff0000, v212
	v_lshlrev_b32_e32 v154, 16, v213
	v_and_b32_e32 v155, 0xffff0000, v213
	v_lshlrev_b32_e32 v156, 16, v214
	v_and_b32_e32 v157, 0xffff0000, v214
	v_lshlrev_b32_e32 v158, 16, v215
	v_and_b32_e32 v159, 0xffff0000, v215
	v_pk_mul_f32 v[144:145], v[192:193], v[144:145]
	v_pk_mul_f32 v[146:147], v[194:195], v[146:147]
	v_pk_mul_f32 v[148:149], v[196:197], v[148:149]
	v_pk_mul_f32 v[150:151], v[198:199], v[150:151]
	v_pk_mul_f32 v[152:153], v[200:201], v[152:153]
	v_pk_mul_f32 v[154:155], v[202:203], v[154:155]
	v_pk_mul_f32 v[156:157], v[204:205], v[156:157]
	v_pk_mul_f32 v[158:159], v[206:207], v[158:159]
	v_mul_f32_e32 v224, v144, v128
	v_fmac_f32_e32 v224, v145, v129
	v_fmac_f32_e32 v224, v146, v130
	v_fmac_f32_e32 v224, v147, v131
	v_fmac_f32_e32 v224, v148, v132
	v_fmac_f32_e32 v224, v149, v133
	v_fmac_f32_e32 v224, v150, v134
	v_fmac_f32_e32 v224, v151, v135
	v_fmac_f32_e32 v224, v152, v136
	v_fmac_f32_e32 v224, v153, v137
	v_fmac_f32_e32 v224, v154, v138
	v_fmac_f32_e32 v224, v155, v139
	v_fmac_f32_e32 v224, v156, v140
	v_fmac_f32_e32 v224, v157, v141
	v_fmac_f32_e32 v224, v158, v142
	v_fmac_f32_e32 v224, v159, v143
	s_nop 1
	v_add_f32_dpp v224, v224, v224 quad_perm:[1,0,3,2] row_mask:0xf bank_mask:0xf
	s_nop 1
	v_add_f32_dpp v224, v224, v224 quad_perm:[2,3,0,1] row_mask:0xf bank_mask:0xf
	buffer_store_dword v224, v239, s[68:71], s75 offen
	s_add_u32 s72, s72, 0x1000
	s_add_u32 s73, s73, 0x800
	s_add_u32 s74, s74, 0x200
	s_add_u32 s75, s75, 0x40
	s_waitcnt vmcnt(47)
	v_lshlrev_b32_e32 v144, 16, v60
	v_and_b32_e32 v145, 0xffff0000, v60
	v_lshlrev_b32_e32 v146, 16, v61
	v_and_b32_e32 v147, 0xffff0000, v61
	v_lshlrev_b32_e32 v148, 16, v62
	v_and_b32_e32 v149, 0xffff0000, v62
	v_lshlrev_b32_e32 v150, 16, v63
	v_and_b32_e32 v151, 0xffff0000, v63
	v_lshlrev_b32_e32 v152, 16, v64
	v_and_b32_e32 v153, 0xffff0000, v64
	v_lshlrev_b32_e32 v154, 16, v65
	v_and_b32_e32 v155, 0xffff0000, v65
	v_lshlrev_b32_e32 v156, 16, v66
	v_and_b32_e32 v157, 0xffff0000, v66
	v_lshlrev_b32_e32 v158, 16, v67
	v_and_b32_e32 v159, 0xffff0000, v67
	v_lshlrev_b32_e32 v160, 16, v72
	v_and_b32_e32 v161, 0xffff0000, v72
	v_lshlrev_b32_e32 v162, 16, v73
	v_and_b32_e32 v163, 0xffff0000, v73
	v_lshlrev_b32_e32 v164, 16, v74
	v_and_b32_e32 v165, 0xffff0000, v74
	v_lshlrev_b32_e32 v166, 16, v75
	v_and_b32_e32 v167, 0xffff0000, v75
	v_lshlrev_b32_e32 v168, 16, v76
	v_and_b32_e32 v169, 0xffff0000, v76
	v_lshlrev_b32_e32 v170, 16, v77
	v_and_b32_e32 v171, 0xffff0000, v77
	v_lshlrev_b32_e32 v172, 16, v78
	v_and_b32_e32 v173, 0xffff0000, v78
	v_lshlrev_b32_e32 v174, 16, v79
	v_and_b32_e32 v175, 0xffff0000, v79
	v_lshlrev_b32_e32 v176, 16, v84
	v_and_b32_e32 v177, 0xffff0000, v84
	v_lshlrev_b32_e32 v178, 16, v85
	v_and_b32_e32 v179, 0xffff0000, v85
	v_lshlrev_b32_e32 v180, 16, v86
	v_and_b32_e32 v181, 0xffff0000, v86
	v_lshlrev_b32_e32 v182, 16, v87
	v_and_b32_e32 v183, 0xffff0000, v87
	v_lshlrev_b32_e32 v184, 16, v88
	v_and_b32_e32 v185, 0xffff0000, v88
	v_lshlrev_b32_e32 v186, 16, v89
	v_and_b32_e32 v187, 0xffff0000, v89
	v_lshlrev_b32_e32 v188, 16, v90
	v_and_b32_e32 v189, 0xffff0000, v90
	v_lshlrev_b32_e32 v190, 16, v91
	v_and_b32_e32 v191, 0xffff0000, v91
	buffer_load_dwordx4 v[60:63], v232, s[64:67], 0 offen nt
	buffer_load_dwordx4 v[64:67], v232, s[64:67], 0 offen offset:16 nt
	v_add_u32_e32 v232, 6656, v232
	v_pk_add_f32 v[224:225], v[144:145], v[160:161] neg_lo:[0,1] neg_hi:[0,1]
	v_pk_add_f32 v[226:227], v[176:177], v[160:161] neg_lo:[0,1] neg_hi:[0,1]
	v_pk_fma_f32 v[192:193], v[96:97], v[224:225], v[160:161]
	v_pk_fma_f32 v[192:193], v[112:113], v[226:227], v[192:193]
	v_pk_add_f32 v[224:225], v[146:147], v[162:163] neg_lo:[0,1] neg_hi:[0,1]
	v_pk_add_f32 v[226:227], v[178:179], v[162:163] neg_lo:[0,1] neg_hi:[0,1]
	v_pk_fma_f32 v[194:195], v[98:99], v[224:225], v[162:163]
	v_pk_fma_f32 v[194:195], v[114:115], v[226:227], v[194:195]
	v_pk_add_f32 v[224:225], v[148:149], v[164:165] neg_lo:[0,1] neg_hi:[0,1]
	v_pk_add_f32 v[226:227], v[180:181], v[164:165] neg_lo:[0,1] neg_hi:[0,1]
	v_pk_fma_f32 v[196:197], v[100:101], v[224:225], v[164:165]
	v_pk_fma_f32 v[196:197], v[116:117], v[226:227], v[196:197]
	v_pk_add_f32 v[224:225], v[150:151], v[166:167] neg_lo:[0,1] neg_hi:[0,1]
	v_pk_add_f32 v[226:227], v[182:183], v[166:167] neg_lo:[0,1] neg_hi:[0,1]
	v_pk_fma_f32 v[198:199], v[102:103], v[224:225], v[166:167]
	v_pk_fma_f32 v[198:199], v[118:119], v[226:227], v[198:199]
	v_pk_add_f32 v[224:225], v[152:153], v[168:169] neg_lo:[0,1] neg_hi:[0,1]
	v_pk_add_f32 v[226:227], v[184:185], v[168:169] neg_lo:[0,1] neg_hi:[0,1]
	v_pk_fma_f32 v[200:201], v[104:105], v[224:225], v[168:169]
	v_pk_fma_f32 v[200:201], v[120:121], v[226:227], v[200:201]
	v_pk_add_f32 v[224:225], v[154:155], v[170:171] neg_lo:[0,1] neg_hi:[0,1]
	v_pk_add_f32 v[226:227], v[186:187], v[170:171] neg_lo:[0,1] neg_hi:[0,1]
	v_pk_fma_f32 v[202:203], v[106:107], v[224:225], v[170:171]
	v_pk_fma_f32 v[202:203], v[122:123], v[226:227], v[202:203]
	v_pk_add_f32 v[224:225], v[156:157], v[172:173] neg_lo:[0,1] neg_hi:[0,1]
	v_pk_add_f32 v[226:227], v[188:189], v[172:173] neg_lo:[0,1] neg_hi:[0,1]
	v_pk_fma_f32 v[204:205], v[108:109], v[224:225], v[172:173]
	v_pk_fma_f32 v[204:205], v[124:125], v[226:227], v[204:205]
	v_pk_add_f32 v[224:225], v[158:159], v[174:175] neg_lo:[0,1] neg_hi:[0,1]
	v_pk_add_f32 v[226:227], v[190:191], v[174:175] neg_lo:[0,1] neg_hi:[0,1]
	v_pk_fma_f32 v[206:207], v[110:111], v[224:225], v[174:175]
	v_pk_fma_f32 v[206:207], v[126:127], v[226:227], v[206:207]
	s_add_u32 s76, s76, 0x800
	buffer_load_dwordx4 v[208:211], v236, s[68:71], s76 offen
	buffer_load_dwordx4 v[212:215], v236, s[68:71], s76 offen offset:16
	buffer_store_dwordx4 v[192:195], v235, s[68:71], s72 offen offset:0
	buffer_store_dwordx4 v[196:199], v235, s[68:71], s72 offen offset:16
	buffer_store_dwordx4 v[200:203], v235, s[68:71], s72 offen offset:32
	buffer_store_dwordx4 v[204:207], v235, s[68:71], s72 offen offset:48
	s_waitcnt vmcnt(13)
; __device__ __forceinline__ void prep_phase(const Params& p) {
;     ...
;             for (int i = 0; i < 16; ++i) {
;                 const bool hn = (tt0 + i) < SEQ - 1; const Z16 rn = hn ? ldz(zc + (size_t)(i + 1) * 3328) : zz();
;                 const size_t o = (size_t)(t0 + i) * RW + c;
;                 float r[16], k[16]; mix16(rp, rc, rn, mpr, mnr, r); unz(ldz(Kb + o), k);
;                 float bs = 0.f;
; #pragma unroll
;                 for (int q = 0; q < 16; ++q) bs += r[q] * k[q] * rkc[q];
;                 bs += __shfl_xor(bs, 1); bs += __shfl_xor(bs, 2);
; #pragma unroll
;                 for (int j4 = 0; j4 < 4; ++j4) *(f32x4*)(R + o + j4 * 4) = (f32x4){r[j4 * 4], r[j4 * 4 + 1], r[j4 * 4 + 2], r[j4 * 4 + 3]};
;                 if ((lane & 3) == 0) BON[(size_t)(t0 + i) * 16 + (lane >> 2)] = bs;
;                 rp = rc; rc = rn;
	v_lshlrev_b32_e32 v144, 16, v216
	v_and_b32_e32 v145, 0xffff0000, v216
	v_lshlrev_b32_e32 v146, 16, v217
	v_and_b32_e32 v147, 0xffff0000, v217
	v_lshlrev_b32_e32 v148, 16, v218
	v_and_b32_e32 v149, 0xffff0000, v218
	v_lshlrev_b32_e32 v150, 16, v219
	v_and_b32_e32 v151, 0xffff0000, v219
	v_lshlrev_b32_e32 v152, 16, v220
	v_and_b32_e32 v153, 0xffff0000, v220
	v_lshlrev_b32_e32 v154, 16, v221
	v_and_b32_e32 v155, 0xffff0000, v221
	v_lshlrev_b32_e32 v156, 16, v222
	v_and_b32_e32 v157, 0xffff0000, v222
	v_lshlrev_b32_e32 v158, 16, v223
	v_and_b32_e32 v159, 0xffff0000, v223
	v_pk_mul_f32 v[144:145], v[192:193], v[144:145]
	v_pk_mul_f32 v[146:147], v[194:195], v[146:147]
	v_pk_mul_f32 v[148:149], v[196:197], v[148:149]
	v_pk_mul_f32 v[150:151], v[198:199], v[150:151]
	v_pk_mul_f32 v[152:153], v[200:201], v[152:153]
	v_pk_mul_f32 v[154:155], v[202:203], v[154:155]
	v_pk_mul_f32 v[156:157], v[204:205], v[156:157]
	v_pk_mul_f32 v[158:159], v[206:207], v[158:159]
	v_mul_f32_e32 v224, v144, v128
	v_fmac_f32_e32 v224, v145, v129
	v_fmac_f32_e32 v224, v146, v130
	v_fmac_f32_e32 v224, v147, v131
	v_fmac_f32_e32 v224, v148, v132
	v_fmac_f32_e32 v224, v149, v133
	v_fmac_f32_e32 v224, v150, v134
	v_fmac_f32_e32 v224, v151, v135
	v_fmac_f32_e32 v224, v152, v136
	v_fmac_f32_e32 v224, v153, v137
	v_fmac_f32_e32 v224, v154, v138
	v_fmac_f32_e32 v224, v155, v139
	v_fmac_f32_e32 v224, v156, v140
	v_fmac_f32_e32 v224, v157, v141
	v_fmac_f32_e32 v224, v158, v142
	v_fmac_f32_e32 v224, v159, v143
	s_nop 1
	v_add_f32_dpp v224, v224, v224 quad_perm:[1,0,3,2] row_mask:0xf bank_mask:0xf
	s_nop 1
	v_add_f32_dpp v224, v224, v224 quad_perm:[2,3,0,1] row_mask:0xf bank_mask:0xf
	buffer_store_dword v224, v239, s[68:71], s75 offen
	s_add_u32 s72, s72, 0x1000
	s_add_u32 s73, s73, 0x800
	s_add_u32 s74, s74, 0x200
	s_add_u32 s75, s75, 0x40
	s_waitcnt vmcnt(52)
	v_lshlrev_b32_e32 v144, 16, v72
	v_and_b32_e32 v145, 0xffff0000, v72
	v_lshlrev_b32_e32 v146, 16, v73
	v_and_b32_e32 v147, 0xffff0000, v73
	v_lshlrev_b32_e32 v148, 16, v74
	v_and_b32_e32 v149, 0xffff0000, v74
	v_lshlrev_b32_e32 v150, 16, v75
	v_and_b32_e32 v151, 0xffff0000, v75
	v_lshlrev_b32_e32 v152, 16, v76
	v_and_b32_e32 v153, 0xffff0000, v76
	v_lshlrev_b32_e32 v154, 16, v77
	v_and_b32_e32 v155, 0xffff0000, v77
	v_lshlrev_b32_e32 v156, 16, v78
	v_and_b32_e32 v157, 0xffff0000, v78
	v_lshlrev_b32_e32 v158, 16, v79
	v_and_b32_e32 v159, 0xffff0000, v79
	v_lshlrev_b32_e32 v160, 16, v84
	v_and_b32_e32 v161, 0xffff0000, v84
	v_lshlrev_b32_e32 v162, 16, v85
	v_and_b32_e32 v163, 0xffff0000, v85
	v_lshlrev_b32_e32 v164, 16, v86
	v_and_b32_e32 v165, 0xffff0000, v86
	v_lshlrev_b32_e32 v166, 16, v87
	v_and_b32_e32 v167, 0xffff0000, v87
	v_lshlrev_b32_e32 v168, 16, v88
	v_and_b32_e32 v169, 0xffff0000, v88
	v_lshlrev_b32_e32 v170, 16, v89
	v_and_b32_e32 v171, 0xffff0000, v89
	v_lshlrev_b32_e32 v172, 16, v90
	v_and_b32_e32 v173, 0xffff0000, v90
	v_lshlrev_b32_e32 v174, 16, v91
	v_and_b32_e32 v175, 0xffff0000, v91
	v_lshlrev_b32_e32 v176, 16, v0
	v_and_b32_e32 v177, 0xffff0000, v0
	v_lshlrev_b32_e32 v178, 16, v1
	v_and_b32_e32 v179, 0xffff0000, v1
	v_lshlrev_b32_e32 v180, 16, v2
	v_and_b32_e32 v181, 0xffff0000, v2
	v_lshlrev_b32_e32 v182, 16, v3
	v_and_b32_e32 v183, 0xffff0000, v3
	v_lshlrev_b32_e32 v184, 16, v4
	v_and_b32_e32 v185, 0xffff0000, v4
	v_lshlrev_b32_e32 v186, 16, v5
	v_and_b32_e32 v187, 0xffff0000, v5
	v_lshlrev_b32_e32 v188, 16, v6
	v_and_b32_e32 v189, 0xffff0000, v6
	v_lshlrev_b32_e32 v190, 16, v7
	v_and_b32_e32 v191, 0xffff0000, v7
	buffer_load_dwordx4 v[72:75], v232, s[64:67], 0 offen nt
	buffer_load_dwordx4 v[76:79], v232, s[64:67], 0 offen offset:16 nt
	v_add_u32_e32 v232, 6656, v232
	v_pk_add_f32 v[224:225], v[144:145], v[160:161] neg_lo:[0,1] neg_hi:[0,1]
	v_pk_add_f32 v[226:227], v[176:177], v[160:161] neg_lo:[0,1] neg_hi:[0,1]
	v_pk_fma_f32 v[192:193], v[96:97], v[224:225], v[160:161]
	v_pk_fma_f32 v[192:193], v[112:113], v[226:227], v[192:193]
	v_pk_add_f32 v[224:225], v[146:147], v[162:163] neg_lo:[0,1] neg_hi:[0,1]
	v_pk_add_f32 v[226:227], v[178:179], v[162:163] neg_lo:[0,1] neg_hi:[0,1]
	v_pk_fma_f32 v[194:195], v[98:99], v[224:225], v[162:163]
	v_pk_fma_f32 v[194:195], v[114:115], v[226:227], v[194:195]
	v_pk_add_f32 v[224:225], v[148:149], v[164:165] neg_lo:[0,1] neg_hi:[0,1]
	v_pk_add_f32 v[226:227], v[180:181], v[164:165] neg_lo:[0,1] neg_hi:[0,1]
	v_pk_fma_f32 v[196:197], v[100:101], v[224:225], v[164:165]
	v_pk_fma_f32 v[196:197], v[116:117], v[226:227], v[196:197]
	v_pk_add_f32 v[224:225], v[150:151], v[166:167] neg_lo:[0,1] neg_hi:[0,1]
	v_pk_add_f32 v[226:227], v[182:183], v[166:167] neg_lo:[0,1] neg_hi:[0,1]
	v_pk_fma_f32 v[198:199], v[102:103], v[224:225], v[166:167]
	v_pk_fma_f32 v[198:199], v[118:119], v[226:227], v[198:199]
	v_pk_add_f32 v[224:225], v[152:153], v[168:169] neg_lo:[0,1] neg_hi:[0,1]
	v_pk_add_f32 v[226:227], v[184:185], v[168:169] neg_lo:[0,1] neg_hi:[0,1]
	v_pk_fma_f32 v[200:201], v[104:105], v[224:225], v[168:169]
	v_pk_fma_f32 v[200:201], v[120:121], v[226:227], v[200:201]
	v_pk_add_f32 v[224:225], v[154:155], v[170:171] neg_lo:[0,1] neg_hi:[0,1]
	v_pk_add_f32 v[226:227], v[186:187], v[170:171] neg_lo:[0,1] neg_hi:[0,1]
	v_pk_fma_f32 v[202:203], v[106:107], v[224:225], v[170:171]
	v_pk_fma_f32 v[202:203], v[122:123], v[226:227], v[202:203]
	v_pk_add_f32 v[224:225], v[156:157], v[172:173] neg_lo:[0,1] neg_hi:[0,1]
	v_pk_add_f32 v[226:227], v[188:189], v[172:173] neg_lo:[0,1] neg_hi:[0,1]
	v_pk_fma_f32 v[204:205], v[108:109], v[224:225], v[172:173]
	v_pk_fma_f32 v[204:205], v[124:125], v[226:227], v[204:205]
	v_pk_add_f32 v[224:225], v[158:159], v[174:175] neg_lo:[0,1] neg_hi:[0,1]
	v_pk_add_f32 v[226:227], v[190:191], v[174:175] neg_lo:[0,1] neg_hi:[0,1]
	v_pk_fma_f32 v[206:207], v[110:111], v[224:225], v[174:175]
	v_pk_fma_f32 v[206:207], v[126:127], v[226:227], v[206:207]
	s_add_u32 s76, s76, 0x800
	buffer_load_dwordx4 v[216:219], v236, s[68:71], s76 offen
	buffer_load_dwordx4 v[220:223], v236, s[68:71], s76 offen offset:16
	buffer_store_dwordx4 v[192:195], v235, s[68:71], s72 offen offset:0
	buffer_store_dwordx4 v[196:199], v235, s[68:71], s72 offen offset:16
	buffer_store_dwordx4 v[200:203], v235, s[68:71], s72 offen offset:32
	buffer_store_dwordx4 v[204:207], v235, s[68:71], s72 offen offset:48
	s_waitcnt vmcnt(13)
; __device__ __forceinline__ void prep_phase(const Params& p) {
;     ...
;             for (int i = 0; i < 16; ++i) {
;                 const bool hn = (tt0 + i) < SEQ - 1; const Z16 rn = hn ? ldz(zc + (size_t)(i + 1) * 3328) : zz();
;                 const size_t o = (size_t)(t0 + i) * RW + c;
;                 float r[16], k[16]; mix16(rp, rc, rn, mpr, mnr, r); unz(ldz(Kb + o), k);
;                 float bs = 0.f;
; #pragma unroll
;                 for (int q = 0; q < 16; ++q) bs += r[q] * k[q] * rkc[q];
;                 bs += __shfl_xor(bs, 1); bs += __shfl_xor(bs, 2);
; #pragma unroll
;                 for (int j4 = 0; j4 < 4; ++j4) *(f32x4*)(R + o + j4 * 4) = (f32x4){r[j4 * 4], r[j4 * 4 + 1], r[j4 * 4 + 2], r[j4 * 4 + 3]};
;                 if ((lane & 3) == 0) BON[(size_t)(t0 + i) * 16 + (lane >> 2)] = bs;
;                 rp = rc; rc = rn;
	v_lshlrev_b32_e32 v144, 16, v208
	v_and_b32_e32 v145, 0xffff0000, v208
	v_lshlrev_b32_e32 v146, 16, v209
	v_and_b32_e32 v147, 0xffff0000, v209
	v_lshlrev_b32_e32 v148, 16, v210
	v_and_b32_e32 v149, 0xffff0000, v210
	v_lshlrev_b32_e32 v150, 16, v211
	v_and_b32_e32 v151, 0xffff0000, v211
	v_lshlrev_b32_e32 v152, 16, v212
	v_and_b32_e32 v153, 0xffff0000, v212
	v_lshlrev_b32_e32 v154, 16, v213
	v_and_b32_e32 v155, 0xffff0000, v213
	v_lshlrev_b32_e32 v156, 16, v214
	v_and_b32_e32 v157, 0xffff0000, v214
	v_lshlrev_b32_e32 v158, 16, v215
	v_and_b32_e32 v159, 0xffff0000, v215
	v_pk_mul_f32 v[144:145], v[192:193], v[144:145]
	v_pk_mul_f32 v[146:147], v[194:195], v[146:147]
	v_pk_mul_f32 v[148:149], v[196:197], v[148:149]
	v_pk_mul_f32 v[150:151], v[198:199], v[150:151]
	v_pk_mul_f32 v[152:153], v[200:201], v[152:153]
	v_pk_mul_f32 v[154:155], v[202:203], v[154:155]
	v_pk_mul_f32 v[156:157], v[204:205], v[156:157]
	v_pk_mul_f32 v[158:159], v[206:207], v[158:159]
	v_mul_f32_e32 v224, v144, v128
	v_fmac_f32_e32 v224, v145, v129
	v_fmac_f32_e32 v224, v146, v130
	v_fmac_f32_e32 v224, v147, v131
	v_fmac_f32_e32 v224, v148, v132
	v_fmac_f32_e32 v224, v149, v133
	v_fmac_f32_e32 v224, v150, v134
	v_fmac_f32_e32 v224, v151, v135
	v_fmac_f32_e32 v224, v152, v136
	v_fmac_f32_e32 v224, v153, v137
	v_fmac_f32_e32 v224, v154, v138
	v_fmac_f32_e32 v224, v155, v139
	v_fmac_f32_e32 v224, v156, v140
	v_fmac_f32_e32 v224, v157, v141
	v_fmac_f32_e32 v224, v158, v142
	v_fmac_f32_e32 v224, v159, v143
	s_nop 1
	v_add_f32_dpp v224, v224, v224 quad_perm:[1,0,3,2] row_mask:0xf bank_mask:0xf
	s_nop 1
	v_add_f32_dpp v224, v224, v224 quad_perm:[2,3,0,1] row_mask:0xf bank_mask:0xf
	buffer_store_dword v224, v239, s[68:71], s75 offen
	s_add_u32 s72, s72, 0x1000
	s_add_u32 s73, s73, 0x800
	s_add_u32 s74, s74, 0x200
	s_add_u32 s75, s75, 0x40
	s_waitcnt vmcnt(52)
	v_lshlrev_b32_e32 v144, 16, v84
	v_and_b32_e32 v145, 0xffff0000, v84
	v_lshlrev_b32_e32 v146, 16, v85
	v_and_b32_e32 v147, 0xffff0000, v85
	v_lshlrev_b32_e32 v148, 16, v86
	v_and_b32_e32 v149, 0xffff0000, v86
	v_lshlrev_b32_e32 v150, 16, v87
	v_and_b32_e32 v151, 0xffff0000, v87
	v_lshlrev_b32_e32 v152, 16, v88
	v_and_b32_e32 v153, 0xffff0000, v88
	v_lshlrev_b32_e32 v154, 16, v89
	v_and_b32_e32 v155, 0xffff0000, v89
	v_lshlrev_b32_e32 v156, 16, v90
	v_and_b32_e32 v157, 0xffff0000, v90
	v_lshlrev_b32_e32 v158, 16, v91
	v_and_b32_e32 v159, 0xffff0000, v91
	v_lshlrev_b32_e32 v160, 16, v0
	v_and_b32_e32 v161, 0xffff0000, v0
	v_lshlrev_b32_e32 v162, 16, v1
	v_and_b32_e32 v163, 0xffff0000, v1
	v_lshlrev_b32_e32 v164, 16, v2
	v_and_b32_e32 v165, 0xffff0000, v2
	v_lshlrev_b32_e32 v166, 16, v3
	v_and_b32_e32 v167, 0xffff0000, v3
	v_lshlrev_b32_e32 v168, 16, v4
	v_and_b32_e32 v169, 0xffff0000, v4
	v_lshlrev_b32_e32 v170, 16, v5
	v_and_b32_e32 v171, 0xffff0000, v5
	v_lshlrev_b32_e32 v172, 16, v6
	v_and_b32_e32 v173, 0xffff0000, v6
	v_lshlrev_b32_e32 v174, 16, v7
	v_and_b32_e32 v175, 0xffff0000, v7
	v_lshlrev_b32_e32 v176, 16, v12
	v_and_b32_e32 v177, 0xffff0000, v12
	v_lshlrev_b32_e32 v178, 16, v13
	v_and_b32_e32 v179, 0xffff0000, v13
	v_lshlrev_b32_e32 v180, 16, v14
	v_and_b32_e32 v181, 0xffff0000, v14
	v_lshlrev_b32_e32 v182, 16, v15
	v_and_b32_e32 v183, 0xffff0000, v15
	v_lshlrev_b32_e32 v184, 16, v16
	v_and_b32_e32 v185, 0xffff0000, v16
	v_lshlrev_b32_e32 v186, 16, v17
	v_and_b32_e32 v187, 0xffff0000, v17
	v_lshlrev_b32_e32 v188, 16, v18
	v_and_b32_e32 v189, 0xffff0000, v18
	v_lshlrev_b32_e32 v190, 16, v19
	v_and_b32_e32 v191, 0xffff0000, v19
	buffer_load_dwordx4 v[84:87], v232, s[64:67], 0 offen nt
	buffer_load_dwordx4 v[88:91], v232, s[64:67], 0 offen offset:16 nt
	v_add_u32_e32 v232, 6656, v232
	v_pk_add_f32 v[224:225], v[144:145], v[160:161] neg_lo:[0,1] neg_hi:[0,1]
	v_pk_add_f32 v[226:227], v[176:177], v[160:161] neg_lo:[0,1] neg_hi:[0,1]
	v_pk_fma_f32 v[192:193], v[96:97], v[224:225], v[160:161]
	v_pk_fma_f32 v[192:193], v[112:113], v[226:227], v[192:193]
	v_pk_add_f32 v[224:225], v[146:147], v[162:163] neg_lo:[0,1] neg_hi:[0,1]
	v_pk_add_f32 v[226:227], v[178:179], v[162:163] neg_lo:[0,1] neg_hi:[0,1]
	v_pk_fma_f32 v[194:195], v[98:99], v[224:225], v[162:163]
	v_pk_fma_f32 v[194:195], v[114:115], v[226:227], v[194:195]
	v_pk_add_f32 v[224:225], v[148:149], v[164:165] neg_lo:[0,1] neg_hi:[0,1]
	v_pk_add_f32 v[226:227], v[180:181], v[164:165] neg_lo:[0,1] neg_hi:[0,1]
	v_pk_fma_f32 v[196:197], v[100:101], v[224:225], v[164:165]
	v_pk_fma_f32 v[196:197], v[116:117], v[226:227], v[196:197]
	v_pk_add_f32 v[224:225], v[150:151], v[166:167] neg_lo:[0,1] neg_hi:[0,1]
	v_pk_add_f32 v[226:227], v[182:183], v[166:167] neg_lo:[0,1] neg_hi:[0,1]
	v_pk_fma_f32 v[198:199], v[102:103], v[224:225], v[166:167]
	v_pk_fma_f32 v[198:199], v[118:119], v[226:227], v[198:199]
	v_pk_add_f32 v[224:225], v[152:153], v[168:169] neg_lo:[0,1] neg_hi:[0,1]
	v_pk_add_f32 v[226:227], v[184:185], v[168:169] neg_lo:[0,1] neg_hi:[0,1]
	v_pk_fma_f32 v[200:201], v[104:105], v[224:225], v[168:169]
	v_pk_fma_f32 v[200:201], v[120:121], v[226:227], v[200:201]
	v_pk_add_f32 v[224:225], v[154:155], v[170:171] neg_lo:[0,1] neg_hi:[0,1]
	v_pk_add_f32 v[226:227], v[186:187], v[170:171] neg_lo:[0,1] neg_hi:[0,1]
	v_pk_fma_f32 v[202:203], v[106:107], v[224:225], v[170:171]
	v_pk_fma_f32 v[202:203], v[122:123], v[226:227], v[202:203]
	v_pk_add_f32 v[224:225], v[156:157], v[172:173] neg_lo:[0,1] neg_hi:[0,1]
	v_pk_add_f32 v[226:227], v[188:189], v[172:173] neg_lo:[0,1] neg_hi:[0,1]
	v_pk_fma_f32 v[204:205], v[108:109], v[224:225], v[172:173]
	v_pk_fma_f32 v[204:205], v[124:125], v[226:227], v[204:205]
	v_pk_add_f32 v[224:225], v[158:159], v[174:175] neg_lo:[0,1] neg_hi:[0,1]
	v_pk_add_f32 v[226:227], v[190:191], v[174:175] neg_lo:[0,1] neg_hi:[0,1]
	v_pk_fma_f32 v[206:207], v[110:111], v[224:225], v[174:175]
	v_pk_fma_f32 v[206:207], v[126:127], v[226:227], v[206:207]
	s_add_u32 s76, s76, 0x800
	buffer_load_dwordx4 v[208:211], v236, s[68:71], s76 offen
	buffer_load_dwordx4 v[212:215], v236, s[68:71], s76 offen offset:16
	buffer_store_dwordx4 v[192:195], v235, s[68:71], s72 offen offset:0
	buffer_store_dwordx4 v[196:199], v235, s[68:71], s72 offen offset:16
	buffer_store_dwordx4 v[200:203], v235, s[68:71], s72 offen offset:32
	buffer_store_dwordx4 v[204:207], v235, s[68:71], s72 offen offset:48
	s_waitcnt vmcnt(13)
; __device__ __forceinline__ void prep_phase(const Params& p) {
;     ...
;             for (int i = 0; i < 16; ++i) {
;                 const bool hn = (tt0 + i) < SEQ - 1; const Z16 rn = hn ? ldz(zc + (size_t)(i + 1) * 3328) : zz();
;                 const size_t o = (size_t)(t0 + i) * RW + c;
;                 float r[16], k[16]; mix16(rp, rc, rn, mpr, mnr, r); unz(ldz(Kb + o), k);
;                 float bs = 0.f;
; #pragma unroll
;                 for (int q = 0; q < 16; ++q) bs += r[q] * k[q] * rkc[q];
;                 bs += __shfl_xor(bs, 1); bs += __shfl_xor(bs, 2);
; #pragma unroll
;                 for (int j4 = 0; j4 < 4; ++j4) *(f32x4*)(R + o + j4 * 4) = (f32x4){r[j4 * 4], r[j4 * 4 + 1], r[j4 * 4 + 2], r[j4 * 4 + 3]};
;                 if ((lane & 3) == 0) BON[(size_t)(t0 + i) * 16 + (lane >> 2)] = bs;
;                 rp = rc; rc = rn;
	v_lshlrev_b32_e32 v144, 16, v216
	v_and_b32_e32 v145, 0xffff0000, v216
	v_lshlrev_b32_e32 v146, 16, v217
	v_and_b32_e32 v147, 0xffff0000, v217
	v_lshlrev_b32_e32 v148, 16, v218
	v_and_b32_e32 v149, 0xffff0000, v218
	v_lshlrev_b32_e32 v150, 16, v219
	v_and_b32_e32 v151, 0xffff0000, v219
	v_lshlrev_b32_e32 v152, 16, v220
	v_and_b32_e32 v153, 0xffff0000, v220
	v_lshlrev_b32_e32 v154, 16, v221
	v_and_b32_e32 v155, 0xffff0000, v221
	v_lshlrev_b32_e32 v156, 16, v222
	v_and_b32_e32 v157, 0xffff0000, v222
	v_lshlrev_b32_e32 v158, 16, v223
	v_and_b32_e32 v159, 0xffff0000, v223
	v_pk_mul_f32 v[144:145], v[192:193], v[144:145]
	v_pk_mul_f32 v[146:147], v[194:195], v[146:147]
	v_pk_mul_f32 v[148:149], v[196:197], v[148:149]
	v_pk_mul_f32 v[150:151], v[198:199], v[150:151]
	v_pk_mul_f32 v[152:153], v[200:201], v[152:153]
	v_pk_mul_f32 v[154:155], v[202:203], v[154:155]
	v_pk_mul_f32 v[156:157], v[204:205], v[156:157]
	v_pk_mul_f32 v[158:159], v[206:207], v[158:159]
	v_mul_f32_e32 v224, v144, v128
	v_fmac_f32_e32 v224, v145, v129
	v_fmac_f32_e32 v224, v146, v130
	v_fmac_f32_e32 v224, v147, v131
	v_fmac_f32_e32 v224, v148, v132
	v_fmac_f32_e32 v224, v149, v133
	v_fmac_f32_e32 v224, v150, v134
	v_fmac_f32_e32 v224, v151, v135
	v_fmac_f32_e32 v224, v152, v136
	v_fmac_f32_e32 v224, v153, v137
	v_fmac_f32_e32 v224, v154, v138
	v_fmac_f32_e32 v224, v155, v139
	v_fmac_f32_e32 v224, v156, v140
	v_fmac_f32_e32 v224, v157, v141
	v_fmac_f32_e32 v224, v158, v142
	v_fmac_f32_e32 v224, v159, v143
	s_nop 1
	v_add_f32_dpp v224, v224, v224 quad_perm:[1,0,3,2] row_mask:0xf bank_mask:0xf
	s_nop 1
	v_add_f32_dpp v224, v224, v224 quad_perm:[2,3,0,1] row_mask:0xf bank_mask:0xf
	buffer_store_dword v224, v239, s[68:71], s75 offen
	s_add_u32 s72, s72, 0x1000
	s_add_u32 s73, s73, 0x800
	s_add_u32 s74, s74, 0x200
	s_add_u32 s75, s75, 0x40
	s_waitcnt vmcnt(52)
	v_lshlrev_b32_e32 v144, 16, v0
	v_and_b32_e32 v145, 0xffff0000, v0
	v_lshlrev_b32_e32 v146, 16, v1
	v_and_b32_e32 v147, 0xffff0000, v1
	v_lshlrev_b32_e32 v148, 16, v2
	v_and_b32_e32 v149, 0xffff0000, v2
	v_lshlrev_b32_e32 v150, 16, v3
	v_and_b32_e32 v151, 0xffff0000, v3
	v_lshlrev_b32_e32 v152, 16, v4
	v_and_b32_e32 v153, 0xffff0000, v4
	v_lshlrev_b32_e32 v154, 16, v5
	v_and_b32_e32 v155, 0xffff0000, v5
	v_lshlrev_b32_e32 v156, 16, v6
	v_and_b32_e32 v157, 0xffff0000, v6
	v_lshlrev_b32_e32 v158, 16, v7
	v_and_b32_e32 v159, 0xffff0000, v7
	v_lshlrev_b32_e32 v160, 16, v12
	v_and_b32_e32 v161, 0xffff0000, v12
	v_lshlrev_b32_e32 v162, 16, v13
	v_and_b32_e32 v163, 0xffff0000, v13
	v_lshlrev_b32_e32 v164, 16, v14
	v_and_b32_e32 v165, 0xffff0000, v14
	v_lshlrev_b32_e32 v166, 16, v15
	v_and_b32_e32 v167, 0xffff0000, v15
	v_lshlrev_b32_e32 v168, 16, v16
	v_and_b32_e32 v169, 0xffff0000, v16
	v_lshlrev_b32_e32 v170, 16, v17
	v_and_b32_e32 v171, 0xffff0000, v17
	v_lshlrev_b32_e32 v172, 16, v18
	v_and_b32_e32 v173, 0xffff0000, v18
	v_lshlrev_b32_e32 v174, 16, v19
	v_and_b32_e32 v175, 0xffff0000, v19
	v_lshlrev_b32_e32 v176, 16, v24
	v_and_b32_e32 v177, 0xffff0000, v24
	v_lshlrev_b32_e32 v178, 16, v25
	v_and_b32_e32 v179, 0xffff0000, v25
	v_lshlrev_b32_e32 v180, 16, v26
	v_and_b32_e32 v181, 0xffff0000, v26
	v_lshlrev_b32_e32 v182, 16, v27
	v_and_b32_e32 v183, 0xffff0000, v27
	v_lshlrev_b32_e32 v184, 16, v28
	v_and_b32_e32 v185, 0xffff0000, v28
	v_lshlrev_b32_e32 v186, 16, v29
	v_and_b32_e32 v187, 0xffff0000, v29
	v_lshlrev_b32_e32 v188, 16, v30
	v_and_b32_e32 v189, 0xffff0000, v30
	v_lshlrev_b32_e32 v190, 16, v31
	v_and_b32_e32 v191, 0xffff0000, v31
	buffer_load_dwordx4 v[0:3], v232, s[64:67], 0 offen nt
	buffer_load_dwordx4 v[4:7], v232, s[64:67], 0 offen offset:16 nt
	v_add_u32_e32 v232, 6656, v232
	v_pk_add_f32 v[224:225], v[144:145], v[160:161] neg_lo:[0,1] neg_hi:[0,1]
	v_pk_add_f32 v[226:227], v[176:177], v[160:161] neg_lo:[0,1] neg_hi:[0,1]
	v_pk_fma_f32 v[192:193], v[96:97], v[224:225], v[160:161]
	v_pk_fma_f32 v[192:193], v[112:113], v[226:227], v[192:193]
	v_pk_add_f32 v[224:225], v[146:147], v[162:163] neg_lo:[0,1] neg_hi:[0,1]
	v_pk_add_f32 v[226:227], v[178:179], v[162:163] neg_lo:[0,1] neg_hi:[0,1]
	v_pk_fma_f32 v[194:195], v[98:99], v[224:225], v[162:163]
	v_pk_fma_f32 v[194:195], v[114:115], v[226:227], v[194:195]
	v_pk_add_f32 v[224:225], v[148:149], v[164:165] neg_lo:[0,1] neg_hi:[0,1]
	v_pk_add_f32 v[226:227], v[180:181], v[164:165] neg_lo:[0,1] neg_hi:[0,1]
	v_pk_fma_f32 v[196:197], v[100:101], v[224:225], v[164:165]
	v_pk_fma_f32 v[196:197], v[116:117], v[226:227], v[196:197]
	v_pk_add_f32 v[224:225], v[150:151], v[166:167] neg_lo:[0,1] neg_hi:[0,1]
	v_pk_add_f32 v[226:227], v[182:183], v[166:167] neg_lo:[0,1] neg_hi:[0,1]
	v_pk_fma_f32 v[198:199], v[102:103], v[224:225], v[166:167]
	v_pk_fma_f32 v[198:199], v[118:119], v[226:227], v[198:199]
	v_pk_add_f32 v[224:225], v[152:153], v[168:169] neg_lo:[0,1] neg_hi:[0,1]
	v_pk_add_f32 v[226:227], v[184:185], v[168:169] neg_lo:[0,1] neg_hi:[0,1]
	v_pk_fma_f32 v[200:201], v[104:105], v[224:225], v[168:169]
	v_pk_fma_f32 v[200:201], v[120:121], v[226:227], v[200:201]
	v_pk_add_f32 v[224:225], v[154:155], v[170:171] neg_lo:[0,1] neg_hi:[0,1]
	v_pk_add_f32 v[226:227], v[186:187], v[170:171] neg_lo:[0,1] neg_hi:[0,1]
	v_pk_fma_f32 v[202:203], v[106:107], v[224:225], v[170:171]
	v_pk_fma_f32 v[202:203], v[122:123], v[226:227], v[202:203]
	v_pk_add_f32 v[224:225], v[156:157], v[172:173] neg_lo:[0,1] neg_hi:[0,1]
	v_pk_add_f32 v[226:227], v[188:189], v[172:173] neg_lo:[0,1] neg_hi:[0,1]
	v_pk_fma_f32 v[204:205], v[108:109], v[224:225], v[172:173]
	v_pk_fma_f32 v[204:205], v[124:125], v[226:227], v[204:205]
	v_pk_add_f32 v[224:225], v[158:159], v[174:175] neg_lo:[0,1] neg_hi:[0,1]
	v_pk_add_f32 v[226:227], v[190:191], v[174:175] neg_lo:[0,1] neg_hi:[0,1]
	v_pk_fma_f32 v[206:207], v[110:111], v[224:225], v[174:175]
	v_pk_fma_f32 v[206:207], v[126:127], v[226:227], v[206:207]
	s_add_u32 s76, s76, 0x800
	buffer_load_dwordx4 v[216:219], v236, s[68:71], s76 offen
	buffer_load_dwordx4 v[220:223], v236, s[68:71], s76 offen offset:16
	buffer_store_dwordx4 v[192:195], v235, s[68:71], s72 offen offset:0
	buffer_store_dwordx4 v[196:199], v235, s[68:71], s72 offen offset:16
	buffer_store_dwordx4 v[200:203], v235, s[68:71], s72 offen offset:32
	buffer_store_dwordx4 v[204:207], v235, s[68:71], s72 offen offset:48
	s_waitcnt vmcnt(13)
; __device__ __forceinline__ void mix16(const Z16& zp, const Z16& zc, const Z16& zn, const float* mp, const float* mn, float* o) {
;     float p_[16], c_[16], n_[16]; unz(zp, p_); unz(zc, c_); unz(zn, n_);
; #pragma unroll
;     for (int q = 0; q < 16; ++q) o[q] = c_[q] + mp[q] * (p_[q] - c_[q]) + mn[q] * (n_[q] - c_[q]);
; }
; __device__ __forceinline__ void prep_phase(const Params& p) {
;     ...
;             for (int i = 0; i < 16; ++i) {
;                 const bool hn = (tt0 + i) < SEQ - 1; const Z16 rn = hn ? ldz(zc + (size_t)(i + 1) * 3328) : zz();
;                 const size_t o = (size_t)(t0 + i) * RW + c;
;                 float r[16], k[16]; mix16(rp, rc, rn, mpr, mnr, r); unz(ldz(Kb + o), k);
;                 float bs = 0.f;
; #pragma unroll
;                 for (int q = 0; q < 16; ++q) bs += r[q] * k[q] * rkc[q];
;                 bs += __shfl_xor(bs, 1); bs += __shfl_xor(bs, 2);
; #pragma unroll
;                 for (int j4 = 0; j4 < 4; ++j4) *(f32x4*)(R + o + j4 * 4) = (f32x4){r[j4 * 4], r[j4 * 4 + 1], r[j4 * 4 + 2], r[j4 * 4 + 3]};
;                 if ((lane & 3) == 0) BON[(size_t)(t0 + i) * 16 + (lane >> 2)] = bs;
;                 rp = rc; rc = rn;
;             }
	v_lshlrev_b32_e32 v144, 16, v208
	v_and_b32_e32 v145, 0xffff0000, v208
	v_lshlrev_b32_e32 v146, 16, v209
	v_and_b32_e32 v147, 0xffff0000, v209
	v_lshlrev_b32_e32 v148, 16, v210
	v_and_b32_e32 v149, 0xffff0000, v210
	v_lshlrev_b32_e32 v150, 16, v211
	v_and_b32_e32 v151, 0xffff0000, v211
	v_lshlrev_b32_e32 v152, 16, v212
	v_and_b32_e32 v153, 0xffff0000, v212
	v_lshlrev_b32_e32 v154, 16, v213
	v_and_b32_e32 v155, 0xffff0000, v213
	v_lshlrev_b32_e32 v156, 16, v214
	v_and_b32_e32 v157, 0xffff0000, v214
	v_lshlrev_b32_e32 v158, 16, v215
	v_and_b32_e32 v159, 0xffff0000, v215
	v_pk_mul_f32 v[144:145], v[192:193], v[144:145]
	v_pk_mul_f32 v[146:147], v[194:195], v[146:147]
	v_pk_mul_f32 v[148:149], v[196:197], v[148:149]
	v_pk_mul_f32 v[150:151], v[198:199], v[150:151]
	v_pk_mul_f32 v[152:153], v[200:201], v[152:153]
	v_pk_mul_f32 v[154:155], v[202:203], v[154:155]
	v_pk_mul_f32 v[156:157], v[204:205], v[156:157]
	v_pk_mul_f32 v[158:159], v[206:207], v[158:159]
	v_mul_f32_e32 v224, v144, v128
	v_fmac_f32_e32 v224, v145, v129
	v_fmac_f32_e32 v224, v146, v130
	v_fmac_f32_e32 v224, v147, v131
	v_fmac_f32_e32 v224, v148, v132
	v_fmac_f32_e32 v224, v149, v133
	v_fmac_f32_e32 v224, v150, v134
	v_fmac_f32_e32 v224, v151, v135
	v_fmac_f32_e32 v224, v152, v136
	v_fmac_f32_e32 v224, v153, v137
	v_fmac_f32_e32 v224, v154, v138
	v_fmac_f32_e32 v224, v155, v139
	v_fmac_f32_e32 v224, v156, v140
	v_fmac_f32_e32 v224, v157, v141
	v_fmac_f32_e32 v224, v158, v142
	v_fmac_f32_e32 v224, v159, v143
	s_nop 1
	v_add_f32_dpp v224, v224, v224 quad_perm:[1,0,3,2] row_mask:0xf bank_mask:0xf
	s_nop 1
	v_add_f32_dpp v224, v224, v224 quad_perm:[2,3,0,1] row_mask:0xf bank_mask:0xf
	buffer_store_dword v224, v239, s[68:71], s75 offen
	s_add_u32 s72, s72, 0x1000
	s_add_u32 s73, s73, 0x800
	s_add_u32 s74, s74, 0x200
	s_add_u32 s75, s75, 0x40
	s_waitcnt vmcnt(52)
	v_lshlrev_b32_e32 v144, 16, v12
	v_and_b32_e32 v145, 0xffff0000, v12
	v_lshlrev_b32_e32 v146, 16, v13
	v_and_b32_e32 v147, 0xffff0000, v13
	v_lshlrev_b32_e32 v148, 16, v14
	v_and_b32_e32 v149, 0xffff0000, v14
	v_lshlrev_b32_e32 v150, 16, v15
	v_and_b32_e32 v151, 0xffff0000, v15
	v_lshlrev_b32_e32 v152, 16, v16
	v_and_b32_e32 v153, 0xffff0000, v16
	v_lshlrev_b32_e32 v154, 16, v17
	v_and_b32_e32 v155, 0xffff0000, v17
	v_lshlrev_b32_e32 v156, 16, v18
	v_and_b32_e32 v157, 0xffff0000, v18
	v_lshlrev_b32_e32 v158, 16, v19
	v_and_b32_e32 v159, 0xffff0000, v19
	v_lshlrev_b32_e32 v160, 16, v24
	v_and_b32_e32 v161, 0xffff0000, v24
	v_lshlrev_b32_e32 v162, 16, v25
	v_and_b32_e32 v163, 0xffff0000, v25
	v_lshlrev_b32_e32 v164, 16, v26
	v_and_b32_e32 v165, 0xffff0000, v26
	v_lshlrev_b32_e32 v166, 16, v27
	v_and_b32_e32 v167, 0xffff0000, v27
	v_lshlrev_b32_e32 v168, 16, v28
	v_and_b32_e32 v169, 0xffff0000, v28
	v_lshlrev_b32_e32 v170, 16, v29
	v_and_b32_e32 v171, 0xffff0000, v29
	v_lshlrev_b32_e32 v172, 16, v30
	v_and_b32_e32 v173, 0xffff0000, v30
	v_lshlrev_b32_e32 v174, 16, v31
	v_and_b32_e32 v175, 0xffff0000, v31
	v_lshlrev_b32_e32 v176, 16, v36
	v_and_b32_e32 v177, 0xffff0000, v36
	v_lshlrev_b32_e32 v178, 16, v37
	v_and_b32_e32 v179, 0xffff0000, v37
	v_lshlrev_b32_e32 v180, 16, v38
	v_and_b32_e32 v181, 0xffff0000, v38
	v_lshlrev_b32_e32 v182, 16, v39
	v_and_b32_e32 v183, 0xffff0000, v39
	v_lshlrev_b32_e32 v184, 16, v40
	v_and_b32_e32 v185, 0xffff0000, v40
	v_lshlrev_b32_e32 v186, 16, v41
	v_and_b32_e32 v187, 0xffff0000, v41
	v_lshlrev_b32_e32 v188, 16, v42
	v_and_b32_e32 v189, 0xffff0000, v42
	v_lshlrev_b32_e32 v190, 16, v43
	v_and_b32_e32 v191, 0xffff0000, v43
	buffer_load_dwordx4 v[12:15], v232, s[64:67], 0 offen nt
	buffer_load_dwordx4 v[16:19], v232, s[64:67], 0 offen offset:16 nt
	v_add_u32_e32 v232, 6656, v232
	v_pk_add_f32 v[224:225], v[144:145], v[160:161] neg_lo:[0,1] neg_hi:[0,1]
	v_pk_add_f32 v[226:227], v[176:177], v[160:161] neg_lo:[0,1] neg_hi:[0,1]
	v_pk_fma_f32 v[192:193], v[96:97], v[224:225], v[160:161]
	v_pk_fma_f32 v[192:193], v[112:113], v[226:227], v[192:193]
	v_pk_add_f32 v[224:225], v[146:147], v[162:163] neg_lo:[0,1] neg_hi:[0,1]
	v_pk_add_f32 v[226:227], v[178:179], v[162:163] neg_lo:[0,1] neg_hi:[0,1]
	v_pk_fma_f32 v[194:195], v[98:99], v[224:225], v[162:163]
	v_pk_fma_f32 v[194:195], v[114:115], v[226:227], v[194:195]
	v_pk_add_f32 v[224:225], v[148:149], v[164:165] neg_lo:[0,1] neg_hi:[0,1]
	v_pk_add_f32 v[226:227], v[180:181], v[164:165] neg_lo:[0,1] neg_hi:[0,1]
	v_pk_fma_f32 v[196:197], v[100:101], v[224:225], v[164:165]
	v_pk_fma_f32 v[196:197], v[116:117], v[226:227], v[196:197]
	v_pk_add_f32 v[224:225], v[150:151], v[166:167] neg_lo:[0,1] neg_hi:[0,1]
	v_pk_add_f32 v[226:227], v[182:183], v[166:167] neg_lo:[0,1] neg_hi:[0,1]
	v_pk_fma_f32 v[198:199], v[102:103], v[224:225], v[166:167]
	v_pk_fma_f32 v[198:199], v[118:119], v[226:227], v[198:199]
	v_pk_add_f32 v[224:225], v[152:153], v[168:169] neg_lo:[0,1] neg_hi:[0,1]
	v_pk_add_f32 v[226:227], v[184:185], v[168:169] neg_lo:[0,1] neg_hi:[0,1]
	v_pk_fma_f32 v[200:201], v[104:105], v[224:225], v[168:169]
	v_pk_fma_f32 v[200:201], v[120:121], v[226:227], v[200:201]
	v_pk_add_f32 v[224:225], v[154:155], v[170:171] neg_lo:[0,1] neg_hi:[0,1]
	v_pk_add_f32 v[226:227], v[186:187], v[170:171] neg_lo:[0,1] neg_hi:[0,1]
	v_pk_fma_f32 v[202:203], v[106:107], v[224:225], v[170:171]
	v_pk_fma_f32 v[202:203], v[122:123], v[226:227], v[202:203]
	v_pk_add_f32 v[224:225], v[156:157], v[172:173] neg_lo:[0,1] neg_hi:[0,1]
	v_pk_add_f32 v[226:227], v[188:189], v[172:173] neg_lo:[0,1] neg_hi:[0,1]
	v_pk_fma_f32 v[204:205], v[108:109], v[224:225], v[172:173]
	v_pk_fma_f32 v[204:205], v[124:125], v[226:227], v[204:205]
	v_pk_add_f32 v[224:225], v[158:159], v[174:175] neg_lo:[0,1] neg_hi:[0,1]
	v_pk_add_f32 v[226:227], v[190:191], v[174:175] neg_lo:[0,1] neg_hi:[0,1]
	v_pk_fma_f32 v[206:207], v[110:111], v[224:225], v[174:175]
	v_pk_fma_f32 v[206:207], v[126:127], v[226:227], v[206:207]
	s_add_u32 s76, s76, 0x800
	buffer_load_dwordx4 v[208:211], v236, s[68:71], s76 offen
	buffer_load_dwordx4 v[212:215], v236, s[68:71], s76 offen offset:16
	buffer_store_dwordx4 v[192:195], v235, s[68:71], s72 offen offset:0
	buffer_store_dwordx4 v[196:199], v235, s[68:71], s72 offen offset:16
	buffer_store_dwordx4 v[200:203], v235, s[68:71], s72 offen offset:32
	buffer_store_dwordx4 v[204:207], v235, s[68:71], s72 offen offset:48
	s_waitcnt vmcnt(13)
; __device__ __forceinline__ void prep_phase(const Params& p) {
;     ...
;             for (int i = 0; i < 16; ++i) {
;                 const bool hn = (tt0 + i) < SEQ - 1; const Z16 rn = hn ? ldz(zc + (size_t)(i + 1) * 3328) : zz();
;                 const size_t o = (size_t)(t0 + i) * RW + c;
;                 float r[16], k[16]; mix16(rp, rc, rn, mpr, mnr, r); unz(ldz(Kb + o), k);
;                 float bs = 0.f;
; #pragma unroll
;                 for (int q = 0; q < 16; ++q) bs += r[q] * k[q] * rkc[q];
;                 bs += __shfl_xor(bs, 1); bs += __shfl_xor(bs, 2);
; #pragma unroll
;                 for (int j4 = 0; j4 < 4; ++j4) *(f32x4*)(R + o + j4 * 4) = (f32x4){r[j4 * 4], r[j4 * 4 + 1], r[j4 * 4 + 2], r[j4 * 4 + 3]};
;                 if ((lane & 3) == 0) BON[(size_t)(t0 + i) * 16 + (lane >> 2)] = bs;
;                 rp = rc; rc = rn;
;             }
	v_lshlrev_b32_e32 v144, 16, v216
	v_and_b32_e32 v145, 0xffff0000, v216
	v_lshlrev_b32_e32 v146, 16, v217
	v_and_b32_e32 v147, 0xffff0000, v217
	v_lshlrev_b32_e32 v148, 16, v218
	v_and_b32_e32 v149, 0xffff0000, v218
	v_lshlrev_b32_e32 v150, 16, v219
	v_and_b32_e32 v151, 0xffff0000, v219
	v_lshlrev_b32_e32 v152, 16, v220
	v_and_b32_e32 v153, 0xffff0000, v220
	v_lshlrev_b32_e32 v154, 16, v221
	v_and_b32_e32 v155, 0xffff0000, v221
	v_lshlrev_b32_e32 v156, 16, v222
	v_and_b32_e32 v157, 0xffff0000, v222
	v_lshlrev_b32_e32 v158, 16, v223
	v_and_b32_e32 v159, 0xffff0000, v223
	v_pk_mul_f32 v[144:145], v[192:193], v[144:145]
	v_pk_mul_f32 v[146:147], v[194:195], v[146:147]
	v_pk_mul_f32 v[148:149], v[196:197], v[148:149]
	v_pk_mul_f32 v[150:151], v[198:199], v[150:151]
	v_pk_mul_f32 v[152:153], v[200:201], v[152:153]
	v_pk_mul_f32 v[154:155], v[202:203], v[154:155]
	v_pk_mul_f32 v[156:157], v[204:205], v[156:157]
	v_pk_mul_f32 v[158:159], v[206:207], v[158:159]
	v_mul_f32_e32 v224, v144, v128
	v_fmac_f32_e32 v224, v145, v129
	v_fmac_f32_e32 v224, v146, v130
	v_fmac_f32_e32 v224, v147, v131
	v_fmac_f32_e32 v224, v148, v132
	v_fmac_f32_e32 v224, v149, v133
	v_fmac_f32_e32 v224, v150, v134
	v_fmac_f32_e32 v224, v151, v135
	v_fmac_f32_e32 v224, v152, v136
	v_fmac_f32_e32 v224, v153, v137
	v_fmac_f32_e32 v224, v154, v138
	v_fmac_f32_e32 v224, v155, v139
	v_fmac_f32_e32 v224, v156, v140
	v_fmac_f32_e32 v224, v157, v141
	v_fmac_f32_e32 v224, v158, v142
	v_fmac_f32_e32 v224, v159, v143
	s_nop 1
	v_add_f32_dpp v224, v224, v224 quad_perm:[1,0,3,2] row_mask:0xf bank_mask:0xf
	s_nop 1
	v_add_f32_dpp v224, v224, v224 quad_perm:[2,3,0,1] row_mask:0xf bank_mask:0xf
	buffer_store_dword v224, v239, s[68:71], s75 offen
	s_add_u32 s72, s72, 0x1000
	s_add_u32 s73, s73, 0x800
	s_add_u32 s74, s74, 0x200
	s_add_u32 s75, s75, 0x40
	s_waitcnt vmcnt(52)
	v_lshlrev_b32_e32 v144, 16, v24
	v_and_b32_e32 v145, 0xffff0000, v24
	v_lshlrev_b32_e32 v146, 16, v25
	v_and_b32_e32 v147, 0xffff0000, v25
	v_lshlrev_b32_e32 v148, 16, v26
	v_and_b32_e32 v149, 0xffff0000, v26
	v_lshlrev_b32_e32 v150, 16, v27
	v_and_b32_e32 v151, 0xffff0000, v27
	v_lshlrev_b32_e32 v152, 16, v28
	v_and_b32_e32 v153, 0xffff0000, v28
	v_lshlrev_b32_e32 v154, 16, v29
	v_and_b32_e32 v155, 0xffff0000, v29
	v_lshlrev_b32_e32 v156, 16, v30
	v_and_b32_e32 v157, 0xffff0000, v30
	v_lshlrev_b32_e32 v158, 16, v31
	v_and_b32_e32 v159, 0xffff0000, v31
	v_lshlrev_b32_e32 v160, 16, v36
	v_and_b32_e32 v161, 0xffff0000, v36
	v_lshlrev_b32_e32 v162, 16, v37
	v_and_b32_e32 v163, 0xffff0000, v37
	v_lshlrev_b32_e32 v164, 16, v38
	v_and_b32_e32 v165, 0xffff0000, v38
	v_lshlrev_b32_e32 v166, 16, v39
	v_and_b32_e32 v167, 0xffff0000, v39
	v_lshlrev_b32_e32 v168, 16, v40
	v_and_b32_e32 v169, 0xffff0000, v40
	v_lshlrev_b32_e32 v170, 16, v41
	v_and_b32_e32 v171, 0xffff0000, v41
	v_lshlrev_b32_e32 v172, 16, v42
	v_and_b32_e32 v173, 0xffff0000, v42
	v_lshlrev_b32_e32 v174, 16, v43
	v_and_b32_e32 v175, 0xffff0000, v43
	v_lshlrev_b32_e32 v176, 16, v48
	v_and_b32_e32 v177, 0xffff0000, v48
	v_lshlrev_b32_e32 v178, 16, v49
	v_and_b32_e32 v179, 0xffff0000, v49
	v_lshlrev_b32_e32 v180, 16, v50
	v_and_b32_e32 v181, 0xffff0000, v50
	v_lshlrev_b32_e32 v182, 16, v51
	v_and_b32_e32 v183, 0xffff0000, v51
	v_lshlrev_b32_e32 v184, 16, v52
	v_and_b32_e32 v185, 0xffff0000, v52
	v_lshlrev_b32_e32 v186, 16, v53
	v_and_b32_e32 v187, 0xffff0000, v53
	v_lshlrev_b32_e32 v188, 16, v54
	v_and_b32_e32 v189, 0xffff0000, v54
	v_lshlrev_b32_e32 v190, 16, v55
	v_and_b32_e32 v191, 0xffff0000, v55
	v_pk_add_f32 v[224:225], v[144:145], v[160:161] neg_lo:[0,1] neg_hi:[0,1]
	v_pk_add_f32 v[226:227], v[176:177], v[160:161] neg_lo:[0,1] neg_hi:[0,1]
	v_pk_fma_f32 v[192:193], v[96:97], v[224:225], v[160:161]
	v_pk_fma_f32 v[192:193], v[112:113], v[226:227], v[192:193]
	v_pk_add_f32 v[224:225], v[146:147], v[162:163] neg_lo:[0,1] neg_hi:[0,1]
	v_pk_add_f32 v[226:227], v[178:179], v[162:163] neg_lo:[0,1] neg_hi:[0,1]
	v_pk_fma_f32 v[194:195], v[98:99], v[224:225], v[162:163]
	v_pk_fma_f32 v[194:195], v[114:115], v[226:227], v[194:195]
	v_pk_add_f32 v[224:225], v[148:149], v[164:165] neg_lo:[0,1] neg_hi:[0,1]
	v_pk_add_f32 v[226:227], v[180:181], v[164:165] neg_lo:[0,1] neg_hi:[0,1]
	v_pk_fma_f32 v[196:197], v[100:101], v[224:225], v[164:165]
	v_pk_fma_f32 v[196:197], v[116:117], v[226:227], v[196:197]
	v_pk_add_f32 v[224:225], v[150:151], v[166:167] neg_lo:[0,1] neg_hi:[0,1]
	v_pk_add_f32 v[226:227], v[182:183], v[166:167] neg_lo:[0,1] neg_hi:[0,1]
	v_pk_fma_f32 v[198:199], v[102:103], v[224:225], v[166:167]
	v_pk_fma_f32 v[198:199], v[118:119], v[226:227], v[198:199]
	v_pk_add_f32 v[224:225], v[152:153], v[168:169] neg_lo:[0,1] neg_hi:[0,1]
	v_pk_add_f32 v[226:227], v[184:185], v[168:169] neg_lo:[0,1] neg_hi:[0,1]
	v_pk_fma_f32 v[200:201], v[104:105], v[224:225], v[168:169]
	v_pk_fma_f32 v[200:201], v[120:121], v[226:227], v[200:201]
	v_pk_add_f32 v[224:225], v[154:155], v[170:171] neg_lo:[0,1] neg_hi:[0,1]
	v_pk_add_f32 v[226:227], v[186:187], v[170:171] neg_lo:[0,1] neg_hi:[0,1]
	v_pk_fma_f32 v[202:203], v[106:107], v[224:225], v[170:171]
	v_pk_fma_f32 v[202:203], v[122:123], v[226:227], v[202:203]
	v_pk_add_f32 v[224:225], v[156:157], v[172:173] neg_lo:[0,1] neg_hi:[0,1]
	v_pk_add_f32 v[226:227], v[188:189], v[172:173] neg_lo:[0,1] neg_hi:[0,1]
	v_pk_fma_f32 v[204:205], v[108:109], v[224:225], v[172:173]
	v_pk_fma_f32 v[204:205], v[124:125], v[226:227], v[204:205]
	v_pk_add_f32 v[224:225], v[158:159], v[174:175] neg_lo:[0,1] neg_hi:[0,1]
	v_pk_add_f32 v[226:227], v[190:191], v[174:175] neg_lo:[0,1] neg_hi:[0,1]
	v_pk_fma_f32 v[206:207], v[110:111], v[224:225], v[174:175]
	v_pk_fma_f32 v[206:207], v[126:127], v[226:227], v[206:207]
	s_add_u32 s76, s76, 0x800
	buffer_load_dwordx4 v[216:219], v236, s[68:71], s76 offen
	buffer_load_dwordx4 v[220:223], v236, s[68:71], s76 offen offset:16
	buffer_store_dwordx4 v[192:195], v235, s[68:71], s72 offen offset:0
	buffer_store_dwordx4 v[196:199], v235, s[68:71], s72 offen offset:16
	buffer_store_dwordx4 v[200:203], v235, s[68:71], s72 offen offset:32
	buffer_store_dwordx4 v[204:207], v235, s[68:71], s72 offen offset:48
	s_waitcnt vmcnt(11)
; __device__ __forceinline__ void prep_phase(const Params& p) {
;     ...
;             for (int i = 0; i < 16; ++i) {
;                 const bool hn = (tt0 + i) < SEQ - 1; const Z16 rn = hn ? ldz(zc + (size_t)(i + 1) * 3328) : zz();
;                 const size_t o = (size_t)(t0 + i) * RW + c;
;                 float r[16], k[16]; mix16(rp, rc, rn, mpr, mnr, r); unz(ldz(Kb + o), k);
;                 float bs = 0.f;
; #pragma unroll
;                 for (int q = 0; q < 16; ++q) bs += r[q] * k[q] * rkc[q];
;                 bs += __shfl_xor(bs, 1); bs += __shfl_xor(bs, 2);
; #pragma unroll
;                 for (int j4 = 0; j4 < 4; ++j4) *(f32x4*)(R + o + j4 * 4) = (f32x4){r[j4 * 4], r[j4 * 4 + 1], r[j4 * 4 + 2], r[j4 * 4 + 3]};
;                 if ((lane & 3) == 0) BON[(size_t)(t0 + i) * 16 + (lane >> 2)] = bs;
;                 rp = rc; rc = rn;
;             }
	v_lshlrev_b32_e32 v144, 16, v208
	v_and_b32_e32 v145, 0xffff0000, v208
	v_lshlrev_b32_e32 v146, 16, v209
	v_and_b32_e32 v147, 0xffff0000, v209
	v_lshlrev_b32_e32 v148, 16, v210
	v_and_b32_e32 v149, 0xffff0000, v210
	v_lshlrev_b32_e32 v150, 16, v211
	v_and_b32_e32 v151, 0xffff0000, v211
	v_lshlrev_b32_e32 v152, 16, v212
	v_and_b32_e32 v153, 0xffff0000, v212
	v_lshlrev_b32_e32 v154, 16, v213
	v_and_b32_e32 v155, 0xffff0000, v213
	v_lshlrev_b32_e32 v156, 16, v214
	v_and_b32_e32 v157, 0xffff0000, v214
	v_lshlrev_b32_e32 v158, 16, v215
	v_and_b32_e32 v159, 0xffff0000, v215
	v_pk_mul_f32 v[144:145], v[192:193], v[144:145]
	v_pk_mul_f32 v[146:147], v[194:195], v[146:147]
	v_pk_mul_f32 v[148:149], v[196:197], v[148:149]
	v_pk_mul_f32 v[150:151], v[198:199], v[150:151]
	v_pk_mul_f32 v[152:153], v[200:201], v[152:153]
	v_pk_mul_f32 v[154:155], v[202:203], v[154:155]
	v_pk_mul_f32 v[156:157], v[204:205], v[156:157]
	v_pk_mul_f32 v[158:159], v[206:207], v[158:159]
	v_mul_f32_e32 v224, v144, v128
	v_fmac_f32_e32 v224, v145, v129
	v_fmac_f32_e32 v224, v146, v130
	v_fmac_f32_e32 v224, v147, v131
	v_fmac_f32_e32 v224, v148, v132
	v_fmac_f32_e32 v224, v149, v133
	v_fmac_f32_e32 v224, v150, v134
	v_fmac_f32_e32 v224, v151, v135
	v_fmac_f32_e32 v224, v152, v136
	v_fmac_f32_e32 v224, v153, v137
	v_fmac_f32_e32 v224, v154, v138
	v_fmac_f32_e32 v224, v155, v139
	v_fmac_f32_e32 v224, v156, v140
	v_fmac_f32_e32 v224, v157, v141
	v_fmac_f32_e32 v224, v158, v142
	v_fmac_f32_e32 v224, v159, v143
	s_nop 1
	v_add_f32_dpp v224, v224, v224 quad_perm:[1,0,3,2] row_mask:0xf bank_mask:0xf
	s_nop 1
	v_add_f32_dpp v224, v224, v224 quad_perm:[2,3,0,1] row_mask:0xf bank_mask:0xf
	buffer_store_dword v224, v239, s[68:71], s75 offen
	s_add_u32 s72, s72, 0x1000
	s_add_u32 s73, s73, 0x800
	s_add_u32 s74, s74, 0x200
	s_add_u32 s75, s75, 0x40
	s_waitcnt vmcnt(50)
	v_lshlrev_b32_e32 v144, 16, v36
	v_and_b32_e32 v145, 0xffff0000, v36
	v_lshlrev_b32_e32 v146, 16, v37
	v_and_b32_e32 v147, 0xffff0000, v37
	v_lshlrev_b32_e32 v148, 16, v38
	v_and_b32_e32 v149, 0xffff0000, v38
	v_lshlrev_b32_e32 v150, 16, v39
	v_and_b32_e32 v151, 0xffff0000, v39
	v_lshlrev_b32_e32 v152, 16, v40
	v_and_b32_e32 v153, 0xffff0000, v40
	v_lshlrev_b32_e32 v154, 16, v41
	v_and_b32_e32 v155, 0xffff0000, v41
	v_lshlrev_b32_e32 v156, 16, v42
	v_and_b32_e32 v157, 0xffff0000, v42
	v_lshlrev_b32_e32 v158, 16, v43
	v_and_b32_e32 v159, 0xffff0000, v43
	v_lshlrev_b32_e32 v160, 16, v48
	v_and_b32_e32 v161, 0xffff0000, v48
	v_lshlrev_b32_e32 v162, 16, v49
	v_and_b32_e32 v163, 0xffff0000, v49
	v_lshlrev_b32_e32 v164, 16, v50
	v_and_b32_e32 v165, 0xffff0000, v50
	v_lshlrev_b32_e32 v166, 16, v51
	v_and_b32_e32 v167, 0xffff0000, v51
	v_lshlrev_b32_e32 v168, 16, v52
	v_and_b32_e32 v169, 0xffff0000, v52
	v_lshlrev_b32_e32 v170, 16, v53
	v_and_b32_e32 v171, 0xffff0000, v53
	v_lshlrev_b32_e32 v172, 16, v54
	v_and_b32_e32 v173, 0xffff0000, v54
	v_lshlrev_b32_e32 v174, 16, v55
	v_and_b32_e32 v175, 0xffff0000, v55
	v_lshlrev_b32_e32 v176, 16, v60
	v_and_b32_e32 v177, 0xffff0000, v60
	v_lshlrev_b32_e32 v178, 16, v61
	v_and_b32_e32 v179, 0xffff0000, v61
	v_lshlrev_b32_e32 v180, 16, v62
	v_and_b32_e32 v181, 0xffff0000, v62
	v_lshlrev_b32_e32 v182, 16, v63
	v_and_b32_e32 v183, 0xffff0000, v63
	v_lshlrev_b32_e32 v184, 16, v64
	v_and_b32_e32 v185, 0xffff0000, v64
	v_lshlrev_b32_e32 v186, 16, v65
	v_and_b32_e32 v187, 0xffff0000, v65
	v_lshlrev_b32_e32 v188, 16, v66
	v_and_b32_e32 v189, 0xffff0000, v66
	v_lshlrev_b32_e32 v190, 16, v67
	v_and_b32_e32 v191, 0xffff0000, v67
	v_pk_add_f32 v[224:225], v[144:145], v[160:161] neg_lo:[0,1] neg_hi:[0,1]
	v_pk_add_f32 v[226:227], v[176:177], v[160:161] neg_lo:[0,1] neg_hi:[0,1]
	v_pk_fma_f32 v[192:193], v[96:97], v[224:225], v[160:161]
	v_pk_fma_f32 v[192:193], v[112:113], v[226:227], v[192:193]
	v_pk_add_f32 v[224:225], v[146:147], v[162:163] neg_lo:[0,1] neg_hi:[0,1]
	v_pk_add_f32 v[226:227], v[178:179], v[162:163] neg_lo:[0,1] neg_hi:[0,1]
	v_pk_fma_f32 v[194:195], v[98:99], v[224:225], v[162:163]
	v_pk_fma_f32 v[194:195], v[114:115], v[226:227], v[194:195]
	v_pk_add_f32 v[224:225], v[148:149], v[164:165] neg_lo:[0,1] neg_hi:[0,1]
	v_pk_add_f32 v[226:227], v[180:181], v[164:165] neg_lo:[0,1] neg_hi:[0,1]
	v_pk_fma_f32 v[196:197], v[100:101], v[224:225], v[164:165]
	v_pk_fma_f32 v[196:197], v[116:117], v[226:227], v[196:197]
	v_pk_add_f32 v[224:225], v[150:151], v[166:167] neg_lo:[0,1] neg_hi:[0,1]
	v_pk_add_f32 v[226:227], v[182:183], v[166:167] neg_lo:[0,1] neg_hi:[0,1]
	v_pk_fma_f32 v[198:199], v[102:103], v[224:225], v[166:167]
	v_pk_fma_f32 v[198:199], v[118:119], v[226:227], v[198:199]
	v_pk_add_f32 v[224:225], v[152:153], v[168:169] neg_lo:[0,1] neg_hi:[0,1]
	v_pk_add_f32 v[226:227], v[184:185], v[168:169] neg_lo:[0,1] neg_hi:[0,1]
	v_pk_fma_f32 v[200:201], v[104:105], v[224:225], v[168:169]
	v_pk_fma_f32 v[200:201], v[120:121], v[226:227], v[200:201]
	v_pk_add_f32 v[224:225], v[154:155], v[170:171] neg_lo:[0,1] neg_hi:[0,1]
	v_pk_add_f32 v[226:227], v[186:187], v[170:171] neg_lo:[0,1] neg_hi:[0,1]
	v_pk_fma_f32 v[202:203], v[106:107], v[224:225], v[170:171]
	v_pk_fma_f32 v[202:203], v[122:123], v[226:227], v[202:203]
	v_pk_add_f32 v[224:225], v[156:157], v[172:173] neg_lo:[0,1] neg_hi:[0,1]
	v_pk_add_f32 v[226:227], v[188:189], v[172:173] neg_lo:[0,1] neg_hi:[0,1]
	v_pk_fma_f32 v[204:205], v[108:109], v[224:225], v[172:173]
	v_pk_fma_f32 v[204:205], v[124:125], v[226:227], v[204:205]
	v_pk_add_f32 v[224:225], v[158:159], v[174:175] neg_lo:[0,1] neg_hi:[0,1]
	v_pk_add_f32 v[226:227], v[190:191], v[174:175] neg_lo:[0,1] neg_hi:[0,1]
	v_pk_fma_f32 v[206:207], v[110:111], v[224:225], v[174:175]
	v_pk_fma_f32 v[206:207], v[126:127], v[226:227], v[206:207]
	s_add_u32 s76, s76, 0x800
	buffer_load_dwordx4 v[208:211], v236, s[68:71], s76 offen
	buffer_load_dwordx4 v[212:215], v236, s[68:71], s76 offen offset:16
	buffer_store_dwordx4 v[192:195], v235, s[68:71], s72 offen offset:0
	buffer_store_dwordx4 v[196:199], v235, s[68:71], s72 offen offset:16
	buffer_store_dwordx4 v[200:203], v235, s[68:71], s72 offen offset:32
	buffer_store_dwordx4 v[204:207], v235, s[68:71], s72 offen offset:48
	s_waitcnt vmcnt(11)
; __device__ __forceinline__ void prep_phase(const Params& p) {
;     ...
;             for (int i = 0; i < 16; ++i) {
;                 const bool hn = (tt0 + i) < SEQ - 1; const Z16 rn = hn ? ldz(zc + (size_t)(i + 1) * 3328) : zz();
;                 const size_t o = (size_t)(t0 + i) * RW + c;
;                 float r[16], k[16]; mix16(rp, rc, rn, mpr, mnr, r); unz(ldz(Kb + o), k);
;                 float bs = 0.f;
; #pragma unroll
;                 for (int q = 0; q < 16; ++q) bs += r[q] * k[q] * rkc[q];
;                 bs += __shfl_xor(bs, 1); bs += __shfl_xor(bs, 2);
; #pragma unroll
;                 for (int j4 = 0; j4 < 4; ++j4) *(f32x4*)(R + o + j4 * 4) = (f32x4){r[j4 * 4], r[j4 * 4 + 1], r[j4 * 4 + 2], r[j4 * 4 + 3]};
;                 if ((lane & 3) == 0) BON[(size_t)(t0 + i) * 16 + (lane >> 2)] = bs;
;                 rp = rc; rc = rn;
;             }
	v_lshlrev_b32_e32 v144, 16, v216
	v_and_b32_e32 v145, 0xffff0000, v216
	v_lshlrev_b32_e32 v146, 16, v217
	v_and_b32_e32 v147, 0xffff0000, v217
	v_lshlrev_b32_e32 v148, 16, v218
	v_and_b32_e32 v149, 0xffff0000, v218
	v_lshlrev_b32_e32 v150, 16, v219
	v_and_b32_e32 v151, 0xffff0000, v219
	v_lshlrev_b32_e32 v152, 16, v220
	v_and_b32_e32 v153, 0xffff0000, v220
	v_lshlrev_b32_e32 v154, 16, v221
	v_and_b32_e32 v155, 0xffff0000, v221
	v_lshlrev_b32_e32 v156, 16, v222
	v_and_b32_e32 v157, 0xffff0000, v222
	v_lshlrev_b32_e32 v158, 16, v223
	v_and_b32_e32 v159, 0xffff0000, v223
	v_pk_mul_f32 v[144:145], v[192:193], v[144:145]
	v_pk_mul_f32 v[146:147], v[194:195], v[146:147]
	v_pk_mul_f32 v[148:149], v[196:197], v[148:149]
	v_pk_mul_f32 v[150:151], v[198:199], v[150:151]
	v_pk_mul_f32 v[152:153], v[200:201], v[152:153]
	v_pk_mul_f32 v[154:155], v[202:203], v[154:155]
	v_pk_mul_f32 v[156:157], v[204:205], v[156:157]
	v_pk_mul_f32 v[158:159], v[206:207], v[158:159]
	v_mul_f32_e32 v224, v144, v128
	v_fmac_f32_e32 v224, v145, v129
	v_fmac_f32_e32 v224, v146, v130
	v_fmac_f32_e32 v224, v147, v131
	v_fmac_f32_e32 v224, v148, v132
	v_fmac_f32_e32 v224, v149, v133
	v_fmac_f32_e32 v224, v150, v134
	v_fmac_f32_e32 v224, v151, v135
	v_fmac_f32_e32 v224, v152, v136
	v_fmac_f32_e32 v224, v153, v137
	v_fmac_f32_e32 v224, v154, v138
	v_fmac_f32_e32 v224, v155, v139
	v_fmac_f32_e32 v224, v156, v140
	v_fmac_f32_e32 v224, v157, v141
	v_fmac_f32_e32 v224, v158, v142
	v_fmac_f32_e32 v224, v159, v143
	s_nop 1
	v_add_f32_dpp v224, v224, v224 quad_perm:[1,0,3,2] row_mask:0xf bank_mask:0xf
	s_nop 1
	v_add_f32_dpp v224, v224, v224 quad_perm:[2,3,0,1] row_mask:0xf bank_mask:0xf
	buffer_store_dword v224, v239, s[68:71], s75 offen
	s_add_u32 s72, s72, 0x1000
	s_add_u32 s73, s73, 0x800
	s_add_u32 s74, s74, 0x200
	s_add_u32 s75, s75, 0x40
	s_waitcnt vmcnt(48)
	v_lshlrev_b32_e32 v144, 16, v48
	v_and_b32_e32 v145, 0xffff0000, v48
	v_lshlrev_b32_e32 v146, 16, v49
	v_and_b32_e32 v147, 0xffff0000, v49
	v_lshlrev_b32_e32 v148, 16, v50
	v_and_b32_e32 v149, 0xffff0000, v50
	v_lshlrev_b32_e32 v150, 16, v51
	v_and_b32_e32 v151, 0xffff0000, v51
	v_lshlrev_b32_e32 v152, 16, v52
	v_and_b32_e32 v153, 0xffff0000, v52
	v_lshlrev_b32_e32 v154, 16, v53
	v_and_b32_e32 v155, 0xffff0000, v53
	v_lshlrev_b32_e32 v156, 16, v54
	v_and_b32_e32 v157, 0xffff0000, v54
	v_lshlrev_b32_e32 v158, 16, v55
	v_and_b32_e32 v159, 0xffff0000, v55
	v_lshlrev_b32_e32 v160, 16, v60
	v_and_b32_e32 v161, 0xffff0000, v60
	v_lshlrev_b32_e32 v162, 16, v61
	v_and_b32_e32 v163, 0xffff0000, v61
	v_lshlrev_b32_e32 v164, 16, v62
	v_and_b32_e32 v165, 0xffff0000, v62
	v_lshlrev_b32_e32 v166, 16, v63
	v_and_b32_e32 v167, 0xffff0000, v63
	v_lshlrev_b32_e32 v168, 16, v64
	v_and_b32_e32 v169, 0xffff0000, v64
	v_lshlrev_b32_e32 v170, 16, v65
	v_and_b32_e32 v171, 0xffff0000, v65
	v_lshlrev_b32_e32 v172, 16, v66
	v_and_b32_e32 v173, 0xffff0000, v66
	v_lshlrev_b32_e32 v174, 16, v67
	v_and_b32_e32 v175, 0xffff0000, v67
	v_lshlrev_b32_e32 v176, 16, v72
	v_and_b32_e32 v177, 0xffff0000, v72
	v_lshlrev_b32_e32 v178, 16, v73
	v_and_b32_e32 v179, 0xffff0000, v73
	v_lshlrev_b32_e32 v180, 16, v74
	v_and_b32_e32 v181, 0xffff0000, v74
	v_lshlrev_b32_e32 v182, 16, v75
	v_and_b32_e32 v183, 0xffff0000, v75
	v_lshlrev_b32_e32 v184, 16, v76
	v_and_b32_e32 v185, 0xffff0000, v76
	v_lshlrev_b32_e32 v186, 16, v77
	v_and_b32_e32 v187, 0xffff0000, v77
	v_lshlrev_b32_e32 v188, 16, v78
	v_and_b32_e32 v189, 0xffff0000, v78
	v_lshlrev_b32_e32 v190, 16, v79
	v_and_b32_e32 v191, 0xffff0000, v79
	v_pk_add_f32 v[224:225], v[144:145], v[160:161] neg_lo:[0,1] neg_hi:[0,1]
	v_pk_add_f32 v[226:227], v[176:177], v[160:161] neg_lo:[0,1] neg_hi:[0,1]
	v_pk_fma_f32 v[192:193], v[96:97], v[224:225], v[160:161]
	v_pk_fma_f32 v[192:193], v[112:113], v[226:227], v[192:193]
	v_pk_add_f32 v[224:225], v[146:147], v[162:163] neg_lo:[0,1] neg_hi:[0,1]
	v_pk_add_f32 v[226:227], v[178:179], v[162:163] neg_lo:[0,1] neg_hi:[0,1]
	v_pk_fma_f32 v[194:195], v[98:99], v[224:225], v[162:163]
	v_pk_fma_f32 v[194:195], v[114:115], v[226:227], v[194:195]
	v_pk_add_f32 v[224:225], v[148:149], v[164:165] neg_lo:[0,1] neg_hi:[0,1]
	v_pk_add_f32 v[226:227], v[180:181], v[164:165] neg_lo:[0,1] neg_hi:[0,1]
	v_pk_fma_f32 v[196:197], v[100:101], v[224:225], v[164:165]
	v_pk_fma_f32 v[196:197], v[116:117], v[226:227], v[196:197]
	v_pk_add_f32 v[224:225], v[150:151], v[166:167] neg_lo:[0,1] neg_hi:[0,1]
	v_pk_add_f32 v[226:227], v[182:183], v[166:167] neg_lo:[0,1] neg_hi:[0,1]
	v_pk_fma_f32 v[198:199], v[102:103], v[224:225], v[166:167]
	v_pk_fma_f32 v[198:199], v[118:119], v[226:227], v[198:199]
	v_pk_add_f32 v[224:225], v[152:153], v[168:169] neg_lo:[0,1] neg_hi:[0,1]
	v_pk_add_f32 v[226:227], v[184:185], v[168:169] neg_lo:[0,1] neg_hi:[0,1]
	v_pk_fma_f32 v[200:201], v[104:105], v[224:225], v[168:169]
	v_pk_fma_f32 v[200:201], v[120:121], v[226:227], v[200:201]
	v_pk_add_f32 v[224:225], v[154:155], v[170:171] neg_lo:[0,1] neg_hi:[0,1]
	v_pk_add_f32 v[226:227], v[186:187], v[170:171] neg_lo:[0,1] neg_hi:[0,1]
	v_pk_fma_f32 v[202:203], v[106:107], v[224:225], v[170:171]
	v_pk_fma_f32 v[202:203], v[122:123], v[226:227], v[202:203]
	v_pk_add_f32 v[224:225], v[156:157], v[172:173] neg_lo:[0,1] neg_hi:[0,1]
	v_pk_add_f32 v[226:227], v[188:189], v[172:173] neg_lo:[0,1] neg_hi:[0,1]
	v_pk_fma_f32 v[204:205], v[108:109], v[224:225], v[172:173]
	v_pk_fma_f32 v[204:205], v[124:125], v[226:227], v[204:205]
	v_pk_add_f32 v[224:225], v[158:159], v[174:175] neg_lo:[0,1] neg_hi:[0,1]
	v_pk_add_f32 v[226:227], v[190:191], v[174:175] neg_lo:[0,1] neg_hi:[0,1]
	v_pk_fma_f32 v[206:207], v[110:111], v[224:225], v[174:175]
	v_pk_fma_f32 v[206:207], v[126:127], v[226:227], v[206:207]
	s_add_u32 s76, s76, 0x800
	buffer_load_dwordx4 v[216:219], v236, s[68:71], s76 offen
	buffer_load_dwordx4 v[220:223], v236, s[68:71], s76 offen offset:16
	buffer_store_dwordx4 v[192:195], v235, s[68:71], s72 offen offset:0
	buffer_store_dwordx4 v[196:199], v235, s[68:71], s72 offen offset:16
	buffer_store_dwordx4 v[200:203], v235, s[68:71], s72 offen offset:32
	buffer_store_dwordx4 v[204:207], v235, s[68:71], s72 offen offset:48
	s_waitcnt vmcnt(11)
; __device__ __forceinline__ void prep_phase(const Params& p) {
;     ...
;             for (int i = 0; i < 16; ++i) {
;                 const bool hn = (tt0 + i) < SEQ - 1; const Z16 rn = hn ? ldz(zc + (size_t)(i + 1) * 3328) : zz();
;                 const size_t o = (size_t)(t0 + i) * RW + c;
;                 float r[16], k[16]; mix16(rp, rc, rn, mpr, mnr, r); unz(ldz(Kb + o), k);
;                 float bs = 0.f;
; #pragma unroll
;                 for (int q = 0; q < 16; ++q) bs += r[q] * k[q] * rkc[q];
;                 bs += __shfl_xor(bs, 1); bs += __shfl_xor(bs, 2);
; #pragma unroll
;                 for (int j4 = 0; j4 < 4; ++j4) *(f32x4*)(R + o + j4 * 4) = (f32x4){r[j4 * 4], r[j4 * 4 + 1], r[j4 * 4 + 2], r[j4 * 4 + 3]};
;                 if ((lane & 3) == 0) BON[(size_t)(t0 + i) * 16 + (lane >> 2)] = bs;
;                 rp = rc; rc = rn;
;             }
	v_lshlrev_b32_e32 v144, 16, v208
	v_and_b32_e32 v145, 0xffff0000, v208
	v_lshlrev_b32_e32 v146, 16, v209
	v_and_b32_e32 v147, 0xffff0000, v209
	v_lshlrev_b32_e32 v148, 16, v210
	v_and_b32_e32 v149, 0xffff0000, v210
	v_lshlrev_b32_e32 v150, 16, v211
	v_and_b32_e32 v151, 0xffff0000, v211
	v_lshlrev_b32_e32 v152, 16, v212
	v_and_b32_e32 v153, 0xffff0000, v212
	v_lshlrev_b32_e32 v154, 16, v213
	v_and_b32_e32 v155, 0xffff0000, v213
	v_lshlrev_b32_e32 v156, 16, v214
	v_and_b32_e32 v157, 0xffff0000, v214
	v_lshlrev_b32_e32 v158, 16, v215
	v_and_b32_e32 v159, 0xffff0000, v215
	v_pk_mul_f32 v[144:145], v[192:193], v[144:145]
	v_pk_mul_f32 v[146:147], v[194:195], v[146:147]
	v_pk_mul_f32 v[148:149], v[196:197], v[148:149]
	v_pk_mul_f32 v[150:151], v[198:199], v[150:151]
	v_pk_mul_f32 v[152:153], v[200:201], v[152:153]
	v_pk_mul_f32 v[154:155], v[202:203], v[154:155]
	v_pk_mul_f32 v[156:157], v[204:205], v[156:157]
	v_pk_mul_f32 v[158:159], v[206:207], v[158:159]
	v_mul_f32_e32 v224, v144, v128
	v_fmac_f32_e32 v224, v145, v129
	v_fmac_f32_e32 v224, v146, v130
	v_fmac_f32_e32 v224, v147, v131
	v_fmac_f32_e32 v224, v148, v132
	v_fmac_f32_e32 v224, v149, v133
	v_fmac_f32_e32 v224, v150, v134
	v_fmac_f32_e32 v224, v151, v135
	v_fmac_f32_e32 v224, v152, v136
	v_fmac_f32_e32 v224, v153, v137
	v_fmac_f32_e32 v224, v154, v138
	v_fmac_f32_e32 v224, v155, v139
	v_fmac_f32_e32 v224, v156, v140
	v_fmac_f32_e32 v224, v157, v141
	v_fmac_f32_e32 v224, v158, v142
	v_fmac_f32_e32 v224, v159, v143
	s_nop 1
	v_add_f32_dpp v224, v224, v224 quad_perm:[1,0,3,2] row_mask:0xf bank_mask:0xf
	s_nop 1
	v_add_f32_dpp v224, v224, v224 quad_perm:[2,3,0,1] row_mask:0xf bank_mask:0xf
	buffer_store_dword v224, v239, s[68:71], s75 offen
	s_add_u32 s72, s72, 0x1000
	s_add_u32 s73, s73, 0x800
	s_add_u32 s74, s74, 0x200
	s_add_u32 s75, s75, 0x40
	s_waitcnt vmcnt(46)
	v_lshlrev_b32_e32 v144, 16, v60
	v_and_b32_e32 v145, 0xffff0000, v60
	v_lshlrev_b32_e32 v146, 16, v61
	v_and_b32_e32 v147, 0xffff0000, v61
	v_lshlrev_b32_e32 v148, 16, v62
	v_and_b32_e32 v149, 0xffff0000, v62
	v_lshlrev_b32_e32 v150, 16, v63
	v_and_b32_e32 v151, 0xffff0000, v63
	v_lshlrev_b32_e32 v152, 16, v64
	v_and_b32_e32 v153, 0xffff0000, v64
	v_lshlrev_b32_e32 v154, 16, v65
	v_and_b32_e32 v155, 0xffff0000, v65
	v_lshlrev_b32_e32 v156, 16, v66
	v_and_b32_e32 v157, 0xffff0000, v66
	v_lshlrev_b32_e32 v158, 16, v67
	v_and_b32_e32 v159, 0xffff0000, v67
	v_lshlrev_b32_e32 v160, 16, v72
	v_and_b32_e32 v161, 0xffff0000, v72
	v_lshlrev_b32_e32 v162, 16, v73
	v_and_b32_e32 v163, 0xffff0000, v73
	v_lshlrev_b32_e32 v164, 16, v74
	v_and_b32_e32 v165, 0xffff0000, v74
	v_lshlrev_b32_e32 v166, 16, v75
	v_and_b32_e32 v167, 0xffff0000, v75
	v_lshlrev_b32_e32 v168, 16, v76
	v_and_b32_e32 v169, 0xffff0000, v76
	v_lshlrev_b32_e32 v170, 16, v77
	v_and_b32_e32 v171, 0xffff0000, v77
	v_lshlrev_b32_e32 v172, 16, v78
	v_and_b32_e32 v173, 0xffff0000, v78
	v_lshlrev_b32_e32 v174, 16, v79
	v_and_b32_e32 v175, 0xffff0000, v79
	v_lshlrev_b32_e32 v176, 16, v84
	v_and_b32_e32 v177, 0xffff0000, v84
	v_lshlrev_b32_e32 v178, 16, v85
	v_and_b32_e32 v179, 0xffff0000, v85
	v_lshlrev_b32_e32 v180, 16, v86
	v_and_b32_e32 v181, 0xffff0000, v86
	v_lshlrev_b32_e32 v182, 16, v87
	v_and_b32_e32 v183, 0xffff0000, v87
	v_lshlrev_b32_e32 v184, 16, v88
	v_and_b32_e32 v185, 0xffff0000, v88
	v_lshlrev_b32_e32 v186, 16, v89
	v_and_b32_e32 v187, 0xffff0000, v89
	v_lshlrev_b32_e32 v188, 16, v90
	v_and_b32_e32 v189, 0xffff0000, v90
	v_lshlrev_b32_e32 v190, 16, v91
	v_and_b32_e32 v191, 0xffff0000, v91
	v_pk_add_f32 v[224:225], v[144:145], v[160:161] neg_lo:[0,1] neg_hi:[0,1]
	v_pk_add_f32 v[226:227], v[176:177], v[160:161] neg_lo:[0,1] neg_hi:[0,1]
	v_pk_fma_f32 v[192:193], v[96:97], v[224:225], v[160:161]
	v_pk_fma_f32 v[192:193], v[112:113], v[226:227], v[192:193]
	v_pk_add_f32 v[224:225], v[146:147], v[162:163] neg_lo:[0,1] neg_hi:[0,1]
	v_pk_add_f32 v[226:227], v[178:179], v[162:163] neg_lo:[0,1] neg_hi:[0,1]
	v_pk_fma_f32 v[194:195], v[98:99], v[224:225], v[162:163]
	v_pk_fma_f32 v[194:195], v[114:115], v[226:227], v[194:195]
	v_pk_add_f32 v[224:225], v[148:149], v[164:165] neg_lo:[0,1] neg_hi:[0,1]
	v_pk_add_f32 v[226:227], v[180:181], v[164:165] neg_lo:[0,1] neg_hi:[0,1]
	v_pk_fma_f32 v[196:197], v[100:101], v[224:225], v[164:165]
	v_pk_fma_f32 v[196:197], v[116:117], v[226:227], v[196:197]
	v_pk_add_f32 v[224:225], v[150:151], v[166:167] neg_lo:[0,1] neg_hi:[0,1]
	v_pk_add_f32 v[226:227], v[182:183], v[166:167] neg_lo:[0,1] neg_hi:[0,1]
	v_pk_fma_f32 v[198:199], v[102:103], v[224:225], v[166:167]
	v_pk_fma_f32 v[198:199], v[118:119], v[226:227], v[198:199]
	v_pk_add_f32 v[224:225], v[152:153], v[168:169] neg_lo:[0,1] neg_hi:[0,1]
	v_pk_add_f32 v[226:227], v[184:185], v[168:169] neg_lo:[0,1] neg_hi:[0,1]
	v_pk_fma_f32 v[200:201], v[104:105], v[224:225], v[168:169]
	v_pk_fma_f32 v[200:201], v[120:121], v[226:227], v[200:201]
	v_pk_add_f32 v[224:225], v[154:155], v[170:171] neg_lo:[0,1] neg_hi:[0,1]
	v_pk_add_f32 v[226:227], v[186:187], v[170:171] neg_lo:[0,1] neg_hi:[0,1]
	v_pk_fma_f32 v[202:203], v[106:107], v[224:225], v[170:171]
	v_pk_fma_f32 v[202:203], v[122:123], v[226:227], v[202:203]
	v_pk_add_f32 v[224:225], v[156:157], v[172:173] neg_lo:[0,1] neg_hi:[0,1]
	v_pk_add_f32 v[226:227], v[188:189], v[172:173] neg_lo:[0,1] neg_hi:[0,1]
	v_pk_fma_f32 v[204:205], v[108:109], v[224:225], v[172:173]
	v_pk_fma_f32 v[204:205], v[124:125], v[226:227], v[204:205]
	v_pk_add_f32 v[224:225], v[158:159], v[174:175] neg_lo:[0,1] neg_hi:[0,1]
	v_pk_add_f32 v[226:227], v[190:191], v[174:175] neg_lo:[0,1] neg_hi:[0,1]
	v_pk_fma_f32 v[206:207], v[110:111], v[224:225], v[174:175]
	v_pk_fma_f32 v[206:207], v[126:127], v[226:227], v[206:207]
	s_add_u32 s76, s76, 0x800
	buffer_load_dwordx4 v[208:211], v236, s[68:71], s76 offen
	buffer_load_dwordx4 v[212:215], v236, s[68:71], s76 offen offset:16
	buffer_store_dwordx4 v[192:195], v235, s[68:71], s72 offen offset:0
	buffer_store_dwordx4 v[196:199], v235, s[68:71], s72 offen offset:16
	buffer_store_dwordx4 v[200:203], v235, s[68:71], s72 offen offset:32
	buffer_store_dwordx4 v[204:207], v235, s[68:71], s72 offen offset:48
	s_waitcnt vmcnt(11)
; __device__ __forceinline__ void prep_phase(const Params& p) {
;     ...
;             for (int i = 0; i < 16; ++i) {
;                 const bool hn = (tt0 + i) < SEQ - 1; const Z16 rn = hn ? ldz(zc + (size_t)(i + 1) * 3328) : zz();
;                 const size_t o = (size_t)(t0 + i) * RW + c;
;                 float r[16], k[16]; mix16(rp, rc, rn, mpr, mnr, r); unz(ldz(Kb + o), k);
;                 float bs = 0.f;
; #pragma unroll
;                 for (int q = 0; q < 16; ++q) bs += r[q] * k[q] * rkc[q];
;                 bs += __shfl_xor(bs, 1); bs += __shfl_xor(bs, 2);
; #pragma unroll
;                 for (int j4 = 0; j4 < 4; ++j4) *(f32x4*)(R + o + j4 * 4) = (f32x4){r[j4 * 4], r[j4 * 4 + 1], r[j4 * 4 + 2], r[j4 * 4 + 3]};
;                 if ((lane & 3) == 0) BON[(size_t)(t0 + i) * 16 + (lane >> 2)] = bs;
;                 rp = rc; rc = rn;
;             }
	v_lshlrev_b32_e32 v144, 16, v216
	v_and_b32_e32 v145, 0xffff0000, v216
	v_lshlrev_b32_e32 v146, 16, v217
	v_and_b32_e32 v147, 0xffff0000, v217
	v_lshlrev_b32_e32 v148, 16, v218
	v_and_b32_e32 v149, 0xffff0000, v218
	v_lshlrev_b32_e32 v150, 16, v219
	v_and_b32_e32 v151, 0xffff0000, v219
	v_lshlrev_b32_e32 v152, 16, v220
	v_and_b32_e32 v153, 0xffff0000, v220
	v_lshlrev_b32_e32 v154, 16, v221
	v_and_b32_e32 v155, 0xffff0000, v221
	v_lshlrev_b32_e32 v156, 16, v222
	v_and_b32_e32 v157, 0xffff0000, v222
	v_lshlrev_b32_e32 v158, 16, v223
	v_and_b32_e32 v159, 0xffff0000, v223
	v_pk_mul_f32 v[144:145], v[192:193], v[144:145]
	v_pk_mul_f32 v[146:147], v[194:195], v[146:147]
	v_pk_mul_f32 v[148:149], v[196:197], v[148:149]
	v_pk_mul_f32 v[150:151], v[198:199], v[150:151]
	v_pk_mul_f32 v[152:153], v[200:201], v[152:153]
	v_pk_mul_f32 v[154:155], v[202:203], v[154:155]
	v_pk_mul_f32 v[156:157], v[204:205], v[156:157]
	v_pk_mul_f32 v[158:159], v[206:207], v[158:159]
	v_mul_f32_e32 v224, v144, v128
	v_fmac_f32_e32 v224, v145, v129
	v_fmac_f32_e32 v224, v146, v130
	v_fmac_f32_e32 v224, v147, v131
	v_fmac_f32_e32 v224, v148, v132
	v_fmac_f32_e32 v224, v149, v133
	v_fmac_f32_e32 v224, v150, v134
	v_fmac_f32_e32 v224, v151, v135
	v_fmac_f32_e32 v224, v152, v136
	v_fmac_f32_e32 v224, v153, v137
	v_fmac_f32_e32 v224, v154, v138
	v_fmac_f32_e32 v224, v155, v139
	v_fmac_f32_e32 v224, v156, v140
	v_fmac_f32_e32 v224, v157, v141
	v_fmac_f32_e32 v224, v158, v142
	v_fmac_f32_e32 v224, v159, v143
	s_nop 1
	v_add_f32_dpp v224, v224, v224 quad_perm:[1,0,3,2] row_mask:0xf bank_mask:0xf
	s_nop 1
	v_add_f32_dpp v224, v224, v224 quad_perm:[2,3,0,1] row_mask:0xf bank_mask:0xf
	buffer_store_dword v224, v239, s[68:71], s75 offen
	s_add_u32 s72, s72, 0x1000
	s_add_u32 s73, s73, 0x800
	s_add_u32 s74, s74, 0x200
	s_add_u32 s75, s75, 0x40
	s_waitcnt vmcnt(44)
	v_lshlrev_b32_e32 v144, 16, v72
	v_and_b32_e32 v145, 0xffff0000, v72
	v_lshlrev_b32_e32 v146, 16, v73
	v_and_b32_e32 v147, 0xffff0000, v73
	v_lshlrev_b32_e32 v148, 16, v74
	v_and_b32_e32 v149, 0xffff0000, v74
	v_lshlrev_b32_e32 v150, 16, v75
	v_and_b32_e32 v151, 0xffff0000, v75
	v_lshlrev_b32_e32 v152, 16, v76
	v_and_b32_e32 v153, 0xffff0000, v76
	v_lshlrev_b32_e32 v154, 16, v77
	v_and_b32_e32 v155, 0xffff0000, v77
	v_lshlrev_b32_e32 v156, 16, v78
	v_and_b32_e32 v157, 0xffff0000, v78
	v_lshlrev_b32_e32 v158, 16, v79
	v_and_b32_e32 v159, 0xffff0000, v79
	v_lshlrev_b32_e32 v160, 16, v84
	v_and_b32_e32 v161, 0xffff0000, v84
	v_lshlrev_b32_e32 v162, 16, v85
	v_and_b32_e32 v163, 0xffff0000, v85
	v_lshlrev_b32_e32 v164, 16, v86
	v_and_b32_e32 v165, 0xffff0000, v86
	v_lshlrev_b32_e32 v166, 16, v87
	v_and_b32_e32 v167, 0xffff0000, v87
	v_lshlrev_b32_e32 v168, 16, v88
	v_and_b32_e32 v169, 0xffff0000, v88
	v_lshlrev_b32_e32 v170, 16, v89
	v_and_b32_e32 v171, 0xffff0000, v89
	v_lshlrev_b32_e32 v172, 16, v90
	v_and_b32_e32 v173, 0xffff0000, v90
	v_lshlrev_b32_e32 v174, 16, v91
	v_and_b32_e32 v175, 0xffff0000, v91
	v_lshlrev_b32_e32 v176, 16, v0
	v_and_b32_e32 v177, 0xffff0000, v0
	v_lshlrev_b32_e32 v178, 16, v1
	v_and_b32_e32 v179, 0xffff0000, v1
	v_lshlrev_b32_e32 v180, 16, v2
	v_and_b32_e32 v181, 0xffff0000, v2
	v_lshlrev_b32_e32 v182, 16, v3
	v_and_b32_e32 v183, 0xffff0000, v3
	v_lshlrev_b32_e32 v184, 16, v4
	v_and_b32_e32 v185, 0xffff0000, v4
	v_lshlrev_b32_e32 v186, 16, v5
	v_and_b32_e32 v187, 0xffff0000, v5
	v_lshlrev_b32_e32 v188, 16, v6
	v_and_b32_e32 v189, 0xffff0000, v6
	v_lshlrev_b32_e32 v190, 16, v7
	v_and_b32_e32 v191, 0xffff0000, v7
	v_pk_add_f32 v[224:225], v[144:145], v[160:161] neg_lo:[0,1] neg_hi:[0,1]
	v_pk_add_f32 v[226:227], v[176:177], v[160:161] neg_lo:[0,1] neg_hi:[0,1]
	v_pk_fma_f32 v[192:193], v[96:97], v[224:225], v[160:161]
	v_pk_fma_f32 v[192:193], v[112:113], v[226:227], v[192:193]
	v_pk_add_f32 v[224:225], v[146:147], v[162:163] neg_lo:[0,1] neg_hi:[0,1]
	v_pk_add_f32 v[226:227], v[178:179], v[162:163] neg_lo:[0,1] neg_hi:[0,1]
	v_pk_fma_f32 v[194:195], v[98:99], v[224:225], v[162:163]
	v_pk_fma_f32 v[194:195], v[114:115], v[226:227], v[194:195]
	v_pk_add_f32 v[224:225], v[148:149], v[164:165] neg_lo:[0,1] neg_hi:[0,1]
	v_pk_add_f32 v[226:227], v[180:181], v[164:165] neg_lo:[0,1] neg_hi:[0,1]
	v_pk_fma_f32 v[196:197], v[100:101], v[224:225], v[164:165]
	v_pk_fma_f32 v[196:197], v[116:117], v[226:227], v[196:197]
	v_pk_add_f32 v[224:225], v[150:151], v[166:167] neg_lo:[0,1] neg_hi:[0,1]
	v_pk_add_f32 v[226:227], v[182:183], v[166:167] neg_lo:[0,1] neg_hi:[0,1]
	v_pk_fma_f32 v[198:199], v[102:103], v[224:225], v[166:167]
	v_pk_fma_f32 v[198:199], v[118:119], v[226:227], v[198:199]
	v_pk_add_f32 v[224:225], v[152:153], v[168:169] neg_lo:[0,1] neg_hi:[0,1]
	v_pk_add_f32 v[226:227], v[184:185], v[168:169] neg_lo:[0,1] neg_hi:[0,1]
	v_pk_fma_f32 v[200:201], v[104:105], v[224:225], v[168:169]
	v_pk_fma_f32 v[200:201], v[120:121], v[226:227], v[200:201]
	v_pk_add_f32 v[224:225], v[154:155], v[170:171] neg_lo:[0,1] neg_hi:[0,1]
	v_pk_add_f32 v[226:227], v[186:187], v[170:171] neg_lo:[0,1] neg_hi:[0,1]
	v_pk_fma_f32 v[202:203], v[106:107], v[224:225], v[170:171]
	v_pk_fma_f32 v[202:203], v[122:123], v[226:227], v[202:203]
	v_pk_add_f32 v[224:225], v[156:157], v[172:173] neg_lo:[0,1] neg_hi:[0,1]
	v_pk_add_f32 v[226:227], v[188:189], v[172:173] neg_lo:[0,1] neg_hi:[0,1]
	v_pk_fma_f32 v[204:205], v[108:109], v[224:225], v[172:173]
	v_pk_fma_f32 v[204:205], v[124:125], v[226:227], v[204:205]
	v_pk_add_f32 v[224:225], v[158:159], v[174:175] neg_lo:[0,1] neg_hi:[0,1]
	v_pk_add_f32 v[226:227], v[190:191], v[174:175] neg_lo:[0,1] neg_hi:[0,1]
	v_pk_fma_f32 v[206:207], v[110:111], v[224:225], v[174:175]
	v_pk_fma_f32 v[206:207], v[126:127], v[226:227], v[206:207]
	s_add_u32 s76, s76, 0x800
	buffer_load_dwordx4 v[216:219], v236, s[68:71], s76 offen
	buffer_load_dwordx4 v[220:223], v236, s[68:71], s76 offen offset:16
	buffer_store_dwordx4 v[192:195], v235, s[68:71], s72 offen offset:0
	buffer_store_dwordx4 v[196:199], v235, s[68:71], s72 offen offset:16
	buffer_store_dwordx4 v[200:203], v235, s[68:71], s72 offen offset:32
	buffer_store_dwordx4 v[204:207], v235, s[68:71], s72 offen offset:48
	s_waitcnt vmcnt(11)
; __device__ __forceinline__ void prep_phase(const Params& p) {
;     ...
;             for (int i = 0; i < 16; ++i) {
;                 const bool hn = (tt0 + i) < SEQ - 1; const Z16 rn = hn ? ldz(zc + (size_t)(i + 1) * 3328) : zz();
;                 const size_t o = (size_t)(t0 + i) * RW + c;
;                 float r[16], k[16]; mix16(rp, rc, rn, mpr, mnr, r); unz(ldz(Kb + o), k);
;                 float bs = 0.f;
; #pragma unroll
;                 for (int q = 0; q < 16; ++q) bs += r[q] * k[q] * rkc[q];
;                 bs += __shfl_xor(bs, 1); bs += __shfl_xor(bs, 2);
; #pragma unroll
;                 for (int j4 = 0; j4 < 4; ++j4) *(f32x4*)(R + o + j4 * 4) = (f32x4){r[j4 * 4], r[j4 * 4 + 1], r[j4 * 4 + 2], r[j4 * 4 + 3]};
;                 if ((lane & 3) == 0) BON[(size_t)(t0 + i) * 16 + (lane >> 2)] = bs;
;                 rp = rc; rc = rn;
;             }
	v_lshlrev_b32_e32 v144, 16, v208
	v_and_b32_e32 v145, 0xffff0000, v208
	v_lshlrev_b32_e32 v146, 16, v209
	v_and_b32_e32 v147, 0xffff0000, v209
	v_lshlrev_b32_e32 v148, 16, v210
	v_and_b32_e32 v149, 0xffff0000, v210
	v_lshlrev_b32_e32 v150, 16, v211
	v_and_b32_e32 v151, 0xffff0000, v211
	v_lshlrev_b32_e32 v152, 16, v212
	v_and_b32_e32 v153, 0xffff0000, v212
	v_lshlrev_b32_e32 v154, 16, v213
	v_and_b32_e32 v155, 0xffff0000, v213
	v_lshlrev_b32_e32 v156, 16, v214
	v_and_b32_e32 v157, 0xffff0000, v214
	v_lshlrev_b32_e32 v158, 16, v215
	v_and_b32_e32 v159, 0xffff0000, v215
	v_pk_mul_f32 v[144:145], v[192:193], v[144:145]
	v_pk_mul_f32 v[146:147], v[194:195], v[146:147]
	v_pk_mul_f32 v[148:149], v[196:197], v[148:149]
	v_pk_mul_f32 v[150:151], v[198:199], v[150:151]
	v_pk_mul_f32 v[152:153], v[200:201], v[152:153]
	v_pk_mul_f32 v[154:155], v[202:203], v[154:155]
	v_pk_mul_f32 v[156:157], v[204:205], v[156:157]
	v_pk_mul_f32 v[158:159], v[206:207], v[158:159]
	v_mul_f32_e32 v224, v144, v128
	v_fmac_f32_e32 v224, v145, v129
	v_fmac_f32_e32 v224, v146, v130
	v_fmac_f32_e32 v224, v147, v131
	v_fmac_f32_e32 v224, v148, v132
	v_fmac_f32_e32 v224, v149, v133
	v_fmac_f32_e32 v224, v150, v134
	v_fmac_f32_e32 v224, v151, v135
	v_fmac_f32_e32 v224, v152, v136
	v_fmac_f32_e32 v224, v153, v137
	v_fmac_f32_e32 v224, v154, v138
	v_fmac_f32_e32 v224, v155, v139
	v_fmac_f32_e32 v224, v156, v140
	v_fmac_f32_e32 v224, v157, v141
	v_fmac_f32_e32 v224, v158, v142
	v_fmac_f32_e32 v224, v159, v143
	s_nop 1
	v_add_f32_dpp v224, v224, v224 quad_perm:[1,0,3,2] row_mask:0xf bank_mask:0xf
	s_nop 1
	v_add_f32_dpp v224, v224, v224 quad_perm:[2,3,0,1] row_mask:0xf bank_mask:0xf
	buffer_store_dword v224, v239, s[68:71], s75 offen
	s_add_u32 s72, s72, 0x1000
	s_add_u32 s73, s73, 0x800
	s_add_u32 s74, s74, 0x200
	s_add_u32 s75, s75, 0x40
	s_waitcnt vmcnt(42)
	v_lshlrev_b32_e32 v144, 16, v84
	v_and_b32_e32 v145, 0xffff0000, v84
	v_lshlrev_b32_e32 v146, 16, v85
	v_and_b32_e32 v147, 0xffff0000, v85
	v_lshlrev_b32_e32 v148, 16, v86
	v_and_b32_e32 v149, 0xffff0000, v86
	v_lshlrev_b32_e32 v150, 16, v87
	v_and_b32_e32 v151, 0xffff0000, v87
	v_lshlrev_b32_e32 v152, 16, v88
	v_and_b32_e32 v153, 0xffff0000, v88
	v_lshlrev_b32_e32 v154, 16, v89
	v_and_b32_e32 v155, 0xffff0000, v89
	v_lshlrev_b32_e32 v156, 16, v90
	v_and_b32_e32 v157, 0xffff0000, v90
	v_lshlrev_b32_e32 v158, 16, v91
	v_and_b32_e32 v159, 0xffff0000, v91
	v_lshlrev_b32_e32 v160, 16, v0
	v_and_b32_e32 v161, 0xffff0000, v0
	v_lshlrev_b32_e32 v162, 16, v1
	v_and_b32_e32 v163, 0xffff0000, v1
	v_lshlrev_b32_e32 v164, 16, v2
	v_and_b32_e32 v165, 0xffff0000, v2
	v_lshlrev_b32_e32 v166, 16, v3
	v_and_b32_e32 v167, 0xffff0000, v3
	v_lshlrev_b32_e32 v168, 16, v4
	v_and_b32_e32 v169, 0xffff0000, v4
	v_lshlrev_b32_e32 v170, 16, v5
	v_and_b32_e32 v171, 0xffff0000, v5
	v_lshlrev_b32_e32 v172, 16, v6
	v_and_b32_e32 v173, 0xffff0000, v6
	v_lshlrev_b32_e32 v174, 16, v7
	v_and_b32_e32 v175, 0xffff0000, v7
	v_lshlrev_b32_e32 v176, 16, v12
	v_and_b32_e32 v177, 0xffff0000, v12
	v_lshlrev_b32_e32 v178, 16, v13
	v_and_b32_e32 v179, 0xffff0000, v13
	v_lshlrev_b32_e32 v180, 16, v14
	v_and_b32_e32 v181, 0xffff0000, v14
	v_lshlrev_b32_e32 v182, 16, v15
	v_and_b32_e32 v183, 0xffff0000, v15
	v_lshlrev_b32_e32 v184, 16, v16
	v_and_b32_e32 v185, 0xffff0000, v16
	v_lshlrev_b32_e32 v186, 16, v17
	v_and_b32_e32 v187, 0xffff0000, v17
	v_lshlrev_b32_e32 v188, 16, v18
	v_and_b32_e32 v189, 0xffff0000, v18
	v_lshlrev_b32_e32 v190, 16, v19
	v_and_b32_e32 v191, 0xffff0000, v19
	v_pk_add_f32 v[224:225], v[144:145], v[160:161] neg_lo:[0,1] neg_hi:[0,1]
	v_pk_add_f32 v[226:227], v[176:177], v[160:161] neg_lo:[0,1] neg_hi:[0,1]
	v_pk_fma_f32 v[192:193], v[96:97], v[224:225], v[160:161]
	v_pk_fma_f32 v[192:193], v[112:113], v[226:227], v[192:193]
	v_pk_add_f32 v[224:225], v[146:147], v[162:163] neg_lo:[0,1] neg_hi:[0,1]
	v_pk_add_f32 v[226:227], v[178:179], v[162:163] neg_lo:[0,1] neg_hi:[0,1]
	v_pk_fma_f32 v[194:195], v[98:99], v[224:225], v[162:163]
	v_pk_fma_f32 v[194:195], v[114:115], v[226:227], v[194:195]
	v_pk_add_f32 v[224:225], v[148:149], v[164:165] neg_lo:[0,1] neg_hi:[0,1]
	v_pk_add_f32 v[226:227], v[180:181], v[164:165] neg_lo:[0,1] neg_hi:[0,1]
	v_pk_fma_f32 v[196:197], v[100:101], v[224:225], v[164:165]
	v_pk_fma_f32 v[196:197], v[116:117], v[226:227], v[196:197]
	v_pk_add_f32 v[224:225], v[150:151], v[166:167] neg_lo:[0,1] neg_hi:[0,1]
	v_pk_add_f32 v[226:227], v[182:183], v[166:167] neg_lo:[0,1] neg_hi:[0,1]
	v_pk_fma_f32 v[198:199], v[102:103], v[224:225], v[166:167]
	v_pk_fma_f32 v[198:199], v[118:119], v[226:227], v[198:199]
	v_pk_add_f32 v[224:225], v[152:153], v[168:169] neg_lo:[0,1] neg_hi:[0,1]
	v_pk_add_f32 v[226:227], v[184:185], v[168:169] neg_lo:[0,1] neg_hi:[0,1]
	v_pk_fma_f32 v[200:201], v[104:105], v[224:225], v[168:169]
	v_pk_fma_f32 v[200:201], v[120:121], v[226:227], v[200:201]
	v_pk_add_f32 v[224:225], v[154:155], v[170:171] neg_lo:[0,1] neg_hi:[0,1]
	v_pk_add_f32 v[226:227], v[186:187], v[170:171] neg_lo:[0,1] neg_hi:[0,1]
	v_pk_fma_f32 v[202:203], v[106:107], v[224:225], v[170:171]
	v_pk_fma_f32 v[202:203], v[122:123], v[226:227], v[202:203]
	v_pk_add_f32 v[224:225], v[156:157], v[172:173] neg_lo:[0,1] neg_hi:[0,1]
	v_pk_add_f32 v[226:227], v[188:189], v[172:173] neg_lo:[0,1] neg_hi:[0,1]
	v_pk_fma_f32 v[204:205], v[108:109], v[224:225], v[172:173]
	v_pk_fma_f32 v[204:205], v[124:125], v[226:227], v[204:205]
	v_pk_add_f32 v[224:225], v[158:159], v[174:175] neg_lo:[0,1] neg_hi:[0,1]
	v_pk_add_f32 v[226:227], v[190:191], v[174:175] neg_lo:[0,1] neg_hi:[0,1]
	v_pk_fma_f32 v[206:207], v[110:111], v[224:225], v[174:175]
	v_pk_fma_f32 v[206:207], v[126:127], v[226:227], v[206:207]
	buffer_store_dwordx4 v[192:195], v235, s[68:71], s72 offen offset:0
	buffer_store_dwordx4 v[196:199], v235, s[68:71], s72 offen offset:16
	buffer_store_dwordx4 v[200:203], v235, s[68:71], s72 offen offset:32
	buffer_store_dwordx4 v[204:207], v235, s[68:71], s72 offen offset:48
	s_waitcnt vmcnt(9)
; __device__ __forceinline__ void prep_phase(const Params& p) {
;     ...
;                 float r[16], k[16]; mix16(rp, rc, rn, mpr, mnr, r); unz(ldz(Kb + o), k);
;                 float bs = 0.f;
; #pragma unroll
;                 for (int q = 0; q < 16; ++q) bs += r[q] * k[q] * rkc[q];
;                 bs += __shfl_xor(bs, 1); bs += __shfl_xor(bs, 2);
; #pragma unroll
;                 for (int j4 = 0; j4 < 4; ++j4) *(f32x4*)(R + o + j4 * 4) = (f32x4){r[j4 * 4], r[j4 * 4 + 1], r[j4 * 4 + 2], r[j4 * 4 + 3]};
;                 if ((lane & 3) == 0) BON[(size_t)(t0 + i) * 16 + (lane >> 2)] = bs;
;                 rp = rc; rc = rn;
;             }
;     ...
;             float mpv[16], mnv[16]; ld16f(p.mu_prev + 2048 + c, mpv); ld16f(p.mu_next + 2048 + c, mnv);
;             const int cl = 3072 + lane * 4; const f32x4 la = *(const f32x4*)(p.mu_prev + cl), lb = *(const f32x4*)(p.mu_next + cl);
;             const int alc = ((lane >> 4) & 1) * 128 + (lane >> 5) * 64 + (lane & 15) * 4;
;             const u16* zc = ZS + (size_t)t0 * 3328;
;             Z16 vp = tt0 > 0 ? ldz(zc - 3328 + 2048 + c) : zz(), vc = ldz(zc + 2048 + c);
;             u32x2 lp = tt0 > 0 ? *(const u32x2*)(zc - 3328 + cl) : (u32x2){0u, 0u}, lc = *(const u32x2*)(zc + cl);
	v_lshlrev_b32_e32 v144, 16, v216
	v_and_b32_e32 v145, 0xffff0000, v216
	v_lshlrev_b32_e32 v146, 16, v217
	v_and_b32_e32 v147, 0xffff0000, v217
	v_lshlrev_b32_e32 v148, 16, v218
	v_and_b32_e32 v149, 0xffff0000, v218
	v_lshlrev_b32_e32 v150, 16, v219
	v_and_b32_e32 v151, 0xffff0000, v219
	v_lshlrev_b32_e32 v152, 16, v220
	v_and_b32_e32 v153, 0xffff0000, v220
	v_lshlrev_b32_e32 v154, 16, v221
	v_and_b32_e32 v155, 0xffff0000, v221
	v_lshlrev_b32_e32 v156, 16, v222
	v_and_b32_e32 v157, 0xffff0000, v222
	v_lshlrev_b32_e32 v158, 16, v223
	v_and_b32_e32 v159, 0xffff0000, v223
	v_pk_mul_f32 v[144:145], v[192:193], v[144:145]
	v_pk_mul_f32 v[146:147], v[194:195], v[146:147]
	v_pk_mul_f32 v[148:149], v[196:197], v[148:149]
	v_pk_mul_f32 v[150:151], v[198:199], v[150:151]
	v_pk_mul_f32 v[152:153], v[200:201], v[152:153]
	v_pk_mul_f32 v[154:155], v[202:203], v[154:155]
	v_pk_mul_f32 v[156:157], v[204:205], v[156:157]
	v_pk_mul_f32 v[158:159], v[206:207], v[158:159]
	v_mul_f32_e32 v224, v144, v128
	v_fmac_f32_e32 v224, v145, v129
	v_fmac_f32_e32 v224, v146, v130
	v_fmac_f32_e32 v224, v147, v131
	v_fmac_f32_e32 v224, v148, v132
	v_fmac_f32_e32 v224, v149, v133
	v_fmac_f32_e32 v224, v150, v134
	v_fmac_f32_e32 v224, v151, v135
	v_fmac_f32_e32 v224, v152, v136
	v_fmac_f32_e32 v224, v153, v137
	v_fmac_f32_e32 v224, v154, v138
	v_fmac_f32_e32 v224, v155, v139
	v_fmac_f32_e32 v224, v156, v140
	v_fmac_f32_e32 v224, v157, v141
	v_fmac_f32_e32 v224, v158, v142
	v_fmac_f32_e32 v224, v159, v143
	s_nop 1
	v_add_f32_dpp v224, v224, v224 quad_perm:[1,0,3,2] row_mask:0xf bank_mask:0xf
	s_nop 1
	v_add_f32_dpp v224, v224, v224 quad_perm:[2,3,0,1] row_mask:0xf bank_mask:0xf
	buffer_store_dword v224, v239, s[68:71], s75 offen
	s_waitcnt vmcnt(0)
	v_lshl_add_u32 v232, v240, 5, s5
	v_add_u32_e32 v232, 32, v232
	v_lshl_add_u32 v233, v240, 3, s5
	v_add_u32_e32 v233, 6144, v233
	v_lshlrev_b32_e32 v224, 6, v240
	v_lshlrev_b32_e32 v225, 4, v240
	v_add_u32_e32 v226, 0x2000, v224
	v_add_u32_e32 v225, 0x3000, v225
	global_load_dwordx4 v[96:99], v226, s[20:21] offset:0
	global_load_dwordx4 v[100:103], v226, s[20:21] offset:16
	global_load_dwordx4 v[104:107], v226, s[20:21] offset:32
	global_load_dwordx4 v[108:111], v226, s[20:21] offset:48
	global_load_dwordx4 v[112:115], v226, s[22:23] offset:0
	global_load_dwordx4 v[116:119], v226, s[22:23] offset:16
	global_load_dwordx4 v[120:123], v226, s[22:23] offset:32
	global_load_dwordx4 v[124:127], v226, s[22:23] offset:48
	global_load_dwordx4 v[128:131], v225, s[20:21] offset:0
	global_load_dwordx4 v[132:135], v225, s[22:23] offset:0
	buffer_load_dwordx4 v[0:3], v232, s[64:67], 0 offen offset:4064 nt
	buffer_load_dwordx4 v[4:7], v232, s[64:67], 0 offen offset:4080 nt
	buffer_load_dwordx2 v[8:9], v233, s[64:67], 0 offen nt
	v_add_u32_e32 v233, 6656, v233
	v_add_u32_e32 v232, 6656, v232
	buffer_load_dwordx4 v[12:15], v232, s[64:67], 0 offen offset:4064 nt
	buffer_load_dwordx4 v[16:19], v232, s[64:67], 0 offen offset:4080 nt
	buffer_load_dwordx2 v[20:21], v233, s[64:67], 0 offen nt
	v_add_u32_e32 v233, 6656, v233
	v_add_u32_e32 v232, 6656, v232
	buffer_load_dwordx4 v[24:27], v232, s[64:67], 0 offen offset:4064 nt
	buffer_load_dwordx4 v[28:31], v232, s[64:67], 0 offen offset:4080 nt
	buffer_load_dwordx2 v[32:33], v233, s[64:67], 0 offen nt
	v_add_u32_e32 v233, 6656, v233
	v_add_u32_e32 v232, 6656, v232
	buffer_load_dwordx4 v[36:39], v232, s[64:67], 0 offen offset:4064 nt
	buffer_load_dwordx4 v[40:43], v232, s[64:67], 0 offen offset:4080 nt
	buffer_load_dwordx2 v[44:45], v233, s[64:67], 0 offen nt
	v_add_u32_e32 v233, 6656, v233
	v_add_u32_e32 v232, 6656, v232
	buffer_load_dwordx4 v[48:51], v232, s[64:67], 0 offen offset:4064 nt
	buffer_load_dwordx4 v[52:55], v232, s[64:67], 0 offen offset:4080 nt
	buffer_load_dwordx2 v[56:57], v233, s[64:67], 0 offen nt
	v_add_u32_e32 v233, 6656, v233
	v_add_u32_e32 v232, 6656, v232
	buffer_load_dwordx4 v[60:63], v232, s[64:67], 0 offen offset:4064 nt
	buffer_load_dwordx4 v[64:67], v232, s[64:67], 0 offen offset:4080 nt
	buffer_load_dwordx2 v[68:69], v233, s[64:67], 0 offen nt
	v_add_u32_e32 v233, 6656, v233
	v_add_u32_e32 v232, 6656, v232
	buffer_load_dwordx4 v[72:75], v232, s[64:67], 0 offen offset:4064 nt
	buffer_load_dwordx4 v[76:79], v232, s[64:67], 0 offen offset:4080 nt
	buffer_load_dwordx2 v[80:81], v233, s[64:67], 0 offen nt
	v_add_u32_e32 v233, 6656, v233
	v_add_u32_e32 v232, 6656, v232
	buffer_load_dwordx4 v[84:87], v232, s[64:67], 0 offen offset:4064 nt
	buffer_load_dwordx4 v[88:91], v232, s[64:67], 0 offen offset:4080 nt
	buffer_load_dwordx2 v[92:93], v233, s[64:67], 0 offen nt
	v_add_u32_e32 v233, 6656, v233
	v_add_u32_e32 v232, 6656, v232
	s_lshl_b32 s72, s0, 12
	s_lshl_b32 s73, s0, 11
	s_lshl_b32 s74, s0, 9
	s_lshl_b32 s75, s0, 6
	s_waitcnt vmcnt(15)
; __device__ __forceinline__ float bflo(unsigned w) { return __uint_as_float(w << 16); }
; __device__ __forceinline__ float bfhi(unsigned w) { return __uint_as_float(w & 0xffff0000u); }
; __device__ __forceinline__ unsigned cvt_pk_bf16(float lo, float hi) { unsigned r; asm volatile("v_cvt_pk_bf16_f32 %0, %1, %2" : "=v"(r) : "v"(lo), "v"(hi)); return r; }
; __device__ __forceinline__ void prep_phase(const Params& p) {
;     ...
;             for (int i = 0; i < 16; ++i) {
;                 const bool hn = (tt0 + i) < SEQ - 1; const u16* zn = zc + (size_t)(i + 1) * 3328;
;                 const Z16 vn = hn ? ldz(zn + 2048 + c) : zz(); const u32x2 ln = hn ? *(const u32x2*)(zn + cl) : (u32x2){0u, 0u};
;                 float v[16]; mix16(vp, vc, vn, mpv, mnv, v);
;                 st16bf(V + (size_t)(t0 + i) * RW + c, v);
;                 const float z4[4] = {bflo(lc.x), bfhi(lc.x), bflo(lc.y), bfhi(lc.y)}, p4[4] = {bflo(lp.x), bfhi(lp.x), bflo(lp.y), bfhi(lp.y)}, n4[4] = {bflo(ln.x), bfhi(ln.x), bflo(ln.y), bfhi(ln.y)};
;                 float o4[4];
; #pragma unroll
;                 for (int j = 0; j < 4; ++j) { const float sft = z4[j] + la[j] * (p4[j] - z4[j]) + lb[j] * (n4[j] - z4[j]); o4[j] = (lane < 32) ? tanhf(sft) : sft; }
;                 u32x2 w; w.x = cvt_pk_bf16(o4[0], o4[1]); w.y = cvt_pk_bf16(o4[2], o4[3]); *(u32x2*)(AL + (size_t)(t0 + i) * 256 + alc) = w;
;                 vp = vc; vc = vn; lp = lc; lc = ln;
	v_lshlrev_b32_e32 v144, 16, v0
	v_and_b32_e32 v145, 0xffff0000, v0
	v_lshlrev_b32_e32 v146, 16, v1
	v_and_b32_e32 v147, 0xffff0000, v1
	v_lshlrev_b32_e32 v148, 16, v2
	v_and_b32_e32 v149, 0xffff0000, v2
	v_lshlrev_b32_e32 v150, 16, v3
	v_and_b32_e32 v151, 0xffff0000, v3
	v_lshlrev_b32_e32 v152, 16, v4
	v_and_b32_e32 v153, 0xffff0000, v4
	v_lshlrev_b32_e32 v154, 16, v5
	v_and_b32_e32 v155, 0xffff0000, v5
	v_lshlrev_b32_e32 v156, 16, v6
	v_and_b32_e32 v157, 0xffff0000, v6
	v_lshlrev_b32_e32 v158, 16, v7
	v_and_b32_e32 v159, 0xffff0000, v7
	v_lshlrev_b32_e32 v160, 16, v12
	v_and_b32_e32 v161, 0xffff0000, v12
	v_lshlrev_b32_e32 v162, 16, v13
	v_and_b32_e32 v163, 0xffff0000, v13
	v_lshlrev_b32_e32 v164, 16, v14
	v_and_b32_e32 v165, 0xffff0000, v14
	v_lshlrev_b32_e32 v166, 16, v15
	v_and_b32_e32 v167, 0xffff0000, v15
	v_lshlrev_b32_e32 v168, 16, v16
	v_and_b32_e32 v169, 0xffff0000, v16
	v_lshlrev_b32_e32 v170, 16, v17
	v_and_b32_e32 v171, 0xffff0000, v17
	v_lshlrev_b32_e32 v172, 16, v18
	v_and_b32_e32 v173, 0xffff0000, v18
	v_lshlrev_b32_e32 v174, 16, v19
	v_and_b32_e32 v175, 0xffff0000, v19
	v_lshlrev_b32_e32 v176, 16, v24
	v_and_b32_e32 v177, 0xffff0000, v24
	v_lshlrev_b32_e32 v178, 16, v25
	v_and_b32_e32 v179, 0xffff0000, v25
	v_lshlrev_b32_e32 v180, 16, v26
	v_and_b32_e32 v181, 0xffff0000, v26
	v_lshlrev_b32_e32 v182, 16, v27
	v_and_b32_e32 v183, 0xffff0000, v27
	v_lshlrev_b32_e32 v184, 16, v28
	v_and_b32_e32 v185, 0xffff0000, v28
	v_lshlrev_b32_e32 v186, 16, v29
	v_and_b32_e32 v187, 0xffff0000, v29
	v_lshlrev_b32_e32 v188, 16, v30
	v_and_b32_e32 v189, 0xffff0000, v30
	v_lshlrev_b32_e32 v190, 16, v31
	v_and_b32_e32 v191, 0xffff0000, v31
	v_lshlrev_b32_e32 v136, 16, v8
	v_and_b32_e32 v137, 0xffff0000, v8
	v_lshlrev_b32_e32 v138, 16, v9
	v_and_b32_e32 v139, 0xffff0000, v9
	v_lshlrev_b32_e32 v140, 16, v20
	v_and_b32_e32 v141, 0xffff0000, v20
	v_lshlrev_b32_e32 v142, 16, v21
	v_and_b32_e32 v143, 0xffff0000, v21
	v_lshlrev_b32_e32 v216, 16, v32
	v_and_b32_e32 v217, 0xffff0000, v32
	v_lshlrev_b32_e32 v218, 16, v33
	v_and_b32_e32 v219, 0xffff0000, v33
	buffer_load_dwordx4 v[0:3], v232, s[64:67], 0 offen offset:4064 nt
	buffer_load_dwordx4 v[4:7], v232, s[64:67], 0 offen offset:4080 nt
	buffer_load_dwordx2 v[8:9], v233, s[64:67], 0 offen nt
	v_add_u32_e32 v233, 6656, v233
	v_add_u32_e32 v232, 6656, v232
	v_pk_add_f32 v[224:225], v[144:145], v[160:161] neg_lo:[0,1] neg_hi:[0,1]
	v_pk_add_f32 v[226:227], v[176:177], v[160:161] neg_lo:[0,1] neg_hi:[0,1]
	v_pk_fma_f32 v[192:193], v[96:97], v[224:225], v[160:161]
	v_pk_fma_f32 v[192:193], v[112:113], v[226:227], v[192:193]
	v_pk_add_f32 v[224:225], v[146:147], v[162:163] neg_lo:[0,1] neg_hi:[0,1]
	v_pk_add_f32 v[226:227], v[178:179], v[162:163] neg_lo:[0,1] neg_hi:[0,1]
	v_pk_fma_f32 v[194:195], v[98:99], v[224:225], v[162:163]
	v_pk_fma_f32 v[194:195], v[114:115], v[226:227], v[194:195]
	v_pk_add_f32 v[224:225], v[148:149], v[164:165] neg_lo:[0,1] neg_hi:[0,1]
	v_pk_add_f32 v[226:227], v[180:181], v[164:165] neg_lo:[0,1] neg_hi:[0,1]
	v_pk_fma_f32 v[196:197], v[100:101], v[224:225], v[164:165]
	v_pk_fma_f32 v[196:197], v[116:117], v[226:227], v[196:197]
	v_pk_add_f32 v[224:225], v[150:151], v[166:167] neg_lo:[0,1] neg_hi:[0,1]
	v_pk_add_f32 v[226:227], v[182:183], v[166:167] neg_lo:[0,1] neg_hi:[0,1]
	v_pk_fma_f32 v[198:199], v[102:103], v[224:225], v[166:167]
	v_pk_fma_f32 v[198:199], v[118:119], v[226:227], v[198:199]
	v_pk_add_f32 v[224:225], v[152:153], v[168:169] neg_lo:[0,1] neg_hi:[0,1]
	v_pk_add_f32 v[226:227], v[184:185], v[168:169] neg_lo:[0,1] neg_hi:[0,1]
	v_pk_fma_f32 v[200:201], v[104:105], v[224:225], v[168:169]
	v_pk_fma_f32 v[200:201], v[120:121], v[226:227], v[200:201]
	v_pk_add_f32 v[224:225], v[154:155], v[170:171] neg_lo:[0,1] neg_hi:[0,1]
	v_pk_add_f32 v[226:227], v[186:187], v[170:171] neg_lo:[0,1] neg_hi:[0,1]
	v_pk_fma_f32 v[202:203], v[106:107], v[224:225], v[170:171]
	v_pk_fma_f32 v[202:203], v[122:123], v[226:227], v[202:203]
	v_pk_add_f32 v[224:225], v[156:157], v[172:173] neg_lo:[0,1] neg_hi:[0,1]
	v_pk_add_f32 v[226:227], v[188:189], v[172:173] neg_lo:[0,1] neg_hi:[0,1]
	v_pk_fma_f32 v[204:205], v[108:109], v[224:225], v[172:173]
	v_pk_fma_f32 v[204:205], v[124:125], v[226:227], v[204:205]
	v_pk_add_f32 v[224:225], v[158:159], v[174:175] neg_lo:[0,1] neg_hi:[0,1]
	v_pk_add_f32 v[226:227], v[190:191], v[174:175] neg_lo:[0,1] neg_hi:[0,1]
	v_pk_fma_f32 v[206:207], v[110:111], v[224:225], v[174:175]
	v_pk_fma_f32 v[206:207], v[126:127], v[226:227], v[206:207]
	v_cvt_pk_bf16_f32 v208, v192, v193
	v_cvt_pk_bf16_f32 v209, v194, v195
	v_cvt_pk_bf16_f32 v210, v196, v197
	v_cvt_pk_bf16_f32 v211, v198, v199
	v_cvt_pk_bf16_f32 v212, v200, v201
	v_cvt_pk_bf16_f32 v213, v202, v203
	v_cvt_pk_bf16_f32 v214, v204, v205
	v_cvt_pk_bf16_f32 v215, v206, v207
	buffer_store_dwordx4 v[208:211], v237, s[68:71], s73 offen offset:0
	buffer_store_dwordx4 v[212:215], v237, s[68:71], s73 offen offset:16
	v_sub_f32_e32 v224, v136, v140
	v_sub_f32_e32 v225, v216, v140
	v_fma_f32 v220, v128, v224, v140
	v_fma_f32 v220, v132, v225, v220
	v_sub_f32_e32 v224, v137, v141
	v_sub_f32_e32 v225, v217, v141
	v_fma_f32 v221, v129, v224, v141
	v_fma_f32 v221, v133, v225, v221
	v_sub_f32_e32 v224, v138, v142
	v_sub_f32_e32 v225, v218, v142
	v_fma_f32 v222, v130, v224, v142
	v_fma_f32 v222, v134, v225, v222
	v_sub_f32_e32 v224, v139, v143
	v_sub_f32_e32 v225, v219, v143
	v_fma_f32 v223, v131, v224, v143
	v_fma_f32 v223, v135, v225, v223
	v_and_b32_e32 v224, 0x7fffffff, v220
	v_mul_f32_e32 v225, 0x4038aa3b, v224
	v_exp_f32_e32 v225, v225
	v_mul_f32_e32 v226, v220, v220
	v_add_f32_e32 v225, 1.0, v225
; __device__ __forceinline__ float bflo(unsigned w) { return __uint_as_float(w << 16); }
; __device__ __forceinline__ float bfhi(unsigned w) { return __uint_as_float(w & 0xffff0000u); }
; __device__ __forceinline__ unsigned cvt_pk_bf16(float lo, float hi) { unsigned r; asm volatile("v_cvt_pk_bf16_f32 %0, %1, %2" : "=v"(r) : "v"(lo), "v"(hi)); return r; }
; __device__ __forceinline__ void prep_phase(const Params& p) {
;     ...
;             for (int i = 0; i < 16; ++i) {
;                 const bool hn = (tt0 + i) < SEQ - 1; const u16* zn = zc + (size_t)(i + 1) * 3328;
;                 const Z16 vn = hn ? ldz(zn + 2048 + c) : zz(); const u32x2 ln = hn ? *(const u32x2*)(zn + cl) : (u32x2){0u, 0u};
;                 float v[16]; mix16(vp, vc, vn, mpv, mnv, v);
;                 st16bf(V + (size_t)(t0 + i) * RW + c, v);
;                 const float z4[4] = {bflo(lc.x), bfhi(lc.x), bflo(lc.y), bfhi(lc.y)}, p4[4] = {bflo(lp.x), bfhi(lp.x), bflo(lp.y), bfhi(lp.y)}, n4[4] = {bflo(ln.x), bfhi(ln.x), bflo(ln.y), bfhi(ln.y)};
;                 float o4[4];
; #pragma unroll
;                 for (int j = 0; j < 4; ++j) { const float sft = z4[j] + la[j] * (p4[j] - z4[j]) + lb[j] * (n4[j] - z4[j]); o4[j] = (lane < 32) ? tanhf(sft) : sft; }
;                 u32x2 w; w.x = cvt_pk_bf16(o4[0], o4[1]); w.y = cvt_pk_bf16(o4[2], o4[3]); *(u32x2*)(AL + (size_t)(t0 + i) * 256 + alc) = w;
;                 vp = vc; vc = vn; lp = lc; lc = ln;
	v_rcp_f32_e32 v225, v225
	v_mul_f32_e32 v227, 0xbeaaaaab, v226
	v_fma_f32 v225, v225, -2.0, 1.0
	v_fma_f32 v227, v227, v220, v220
	v_bfi_b32 v225, v241, v225, v220
	v_cmp_gt_f32_e32 vcc, 0x3d000000, v224
	s_nop 1
	v_cndmask_b32_e32 v225, v225, v227, vcc
	v_cmp_gt_u32_e32 vcc, 32, v240
	s_nop 1
	v_cndmask_b32_e32 v220, v220, v225, vcc
	v_and_b32_e32 v224, 0x7fffffff, v221
	v_mul_f32_e32 v225, 0x4038aa3b, v224
	v_exp_f32_e32 v225, v225
	v_mul_f32_e32 v226, v221, v221
	v_add_f32_e32 v225, 1.0, v225
	v_rcp_f32_e32 v225, v225
	v_mul_f32_e32 v227, 0xbeaaaaab, v226
	v_fma_f32 v225, v225, -2.0, 1.0
	v_fma_f32 v227, v227, v221, v221
	v_bfi_b32 v225, v241, v225, v221
	v_cmp_gt_f32_e32 vcc, 0x3d000000, v224
	s_nop 1
	v_cndmask_b32_e32 v225, v225, v227, vcc
	v_cmp_gt_u32_e32 vcc, 32, v240
	s_nop 1
	v_cndmask_b32_e32 v221, v221, v225, vcc
	v_and_b32_e32 v224, 0x7fffffff, v222
	v_mul_f32_e32 v225, 0x4038aa3b, v224
	v_exp_f32_e32 v225, v225
	v_mul_f32_e32 v226, v222, v222
	v_add_f32_e32 v225, 1.0, v225
	v_rcp_f32_e32 v225, v225
	v_mul_f32_e32 v227, 0xbeaaaaab, v226
	v_fma_f32 v225, v225, -2.0, 1.0
	v_fma_f32 v227, v227, v222, v222
	v_bfi_b32 v225, v241, v225, v222
	v_cmp_gt_f32_e32 vcc, 0x3d000000, v224
	s_nop 1
	v_cndmask_b32_e32 v225, v225, v227, vcc
	v_cmp_gt_u32_e32 vcc, 32, v240
	s_nop 1
	v_cndmask_b32_e32 v222, v222, v225, vcc
	v_and_b32_e32 v224, 0x7fffffff, v223
	v_mul_f32_e32 v225, 0x4038aa3b, v224
	v_exp_f32_e32 v225, v225
	v_mul_f32_e32 v226, v223, v223
	v_add_f32_e32 v225, 1.0, v225
	v_rcp_f32_e32 v225, v225
	v_mul_f32_e32 v227, 0xbeaaaaab, v226
	v_fma_f32 v225, v225, -2.0, 1.0
	v_fma_f32 v227, v227, v223, v223
	v_bfi_b32 v225, v241, v225, v223
	v_cmp_gt_f32_e32 vcc, 0x3d000000, v224
	s_nop 1
	v_cndmask_b32_e32 v225, v225, v227, vcc
	v_cmp_gt_u32_e32 vcc, 32, v240
	s_nop 1
	v_cndmask_b32_e32 v223, v223, v225, vcc
	v_cvt_pk_bf16_f32 v224, v220, v221
	v_cvt_pk_bf16_f32 v225, v222, v223
	buffer_store_dwordx2 v[224:225], v238, s[68:71], s74 offen
	s_add_u32 s72, s72, 0x1000
	s_add_u32 s73, s73, 0x800
	s_add_u32 s74, s74, 0x200
	s_add_u32 s75, s75, 0x40
	s_waitcnt vmcnt(18)
	v_lshlrev_b32_e32 v144, 16, v12
	v_and_b32_e32 v145, 0xffff0000, v12
	v_lshlrev_b32_e32 v146, 16, v13
	v_and_b32_e32 v147, 0xffff0000, v13
	v_lshlrev_b32_e32 v148, 16, v14
	v_and_b32_e32 v149, 0xffff0000, v14
	v_lshlrev_b32_e32 v150, 16, v15
	v_and_b32_e32 v151, 0xffff0000, v15
	v_lshlrev_b32_e32 v152, 16, v16
	v_and_b32_e32 v153, 0xffff0000, v16
	v_lshlrev_b32_e32 v154, 16, v17
	v_and_b32_e32 v155, 0xffff0000, v17
	v_lshlrev_b32_e32 v156, 16, v18
	v_and_b32_e32 v157, 0xffff0000, v18
	v_lshlrev_b32_e32 v158, 16, v19
	v_and_b32_e32 v159, 0xffff0000, v19
	v_lshlrev_b32_e32 v160, 16, v24
	v_and_b32_e32 v161, 0xffff0000, v24
	v_lshlrev_b32_e32 v162, 16, v25
	v_and_b32_e32 v163, 0xffff0000, v25
	v_lshlrev_b32_e32 v164, 16, v26
	v_and_b32_e32 v165, 0xffff0000, v26
	v_lshlrev_b32_e32 v166, 16, v27
	v_and_b32_e32 v167, 0xffff0000, v27
	v_lshlrev_b32_e32 v168, 16, v28
	v_and_b32_e32 v169, 0xffff0000, v28
	v_lshlrev_b32_e32 v170, 16, v29
	v_and_b32_e32 v171, 0xffff0000, v29
	v_lshlrev_b32_e32 v172, 16, v30
	v_and_b32_e32 v173, 0xffff0000, v30
	v_lshlrev_b32_e32 v174, 16, v31
	v_and_b32_e32 v175, 0xffff0000, v31
	v_lshlrev_b32_e32 v176, 16, v36
	v_and_b32_e32 v177, 0xffff0000, v36
	v_lshlrev_b32_e32 v178, 16, v37
	v_and_b32_e32 v179, 0xffff0000, v37
	v_lshlrev_b32_e32 v180, 16, v38
	v_and_b32_e32 v181, 0xffff0000, v38
	v_lshlrev_b32_e32 v182, 16, v39
	v_and_b32_e32 v183, 0xffff0000, v39
	v_lshlrev_b32_e32 v184, 16, v40
	v_and_b32_e32 v185, 0xffff0000, v40
	v_lshlrev_b32_e32 v186, 16, v41
	v_and_b32_e32 v187, 0xffff0000, v41
	v_lshlrev_b32_e32 v188, 16, v42
	v_and_b32_e32 v189, 0xffff0000, v42
	v_lshlrev_b32_e32 v190, 16, v43
	v_and_b32_e32 v191, 0xffff0000, v43
	v_lshlrev_b32_e32 v136, 16, v20
	v_and_b32_e32 v137, 0xffff0000, v20
	v_lshlrev_b32_e32 v138, 16, v21
	v_and_b32_e32 v139, 0xffff0000, v21
	v_lshlrev_b32_e32 v140, 16, v32
	v_and_b32_e32 v141, 0xffff0000, v32
	v_lshlrev_b32_e32 v142, 16, v33
	v_and_b32_e32 v143, 0xffff0000, v33
	v_lshlrev_b32_e32 v216, 16, v44
	v_and_b32_e32 v217, 0xffff0000, v44
	v_lshlrev_b32_e32 v218, 16, v45
	v_and_b32_e32 v219, 0xffff0000, v45
	buffer_load_dwordx4 v[12:15], v232, s[64:67], 0 offen offset:4064 nt
	buffer_load_dwordx4 v[16:19], v232, s[64:67], 0 offen offset:4080 nt
	buffer_load_dwordx2 v[20:21], v233, s[64:67], 0 offen nt
	v_add_u32_e32 v233, 6656, v233
	v_add_u32_e32 v232, 6656, v232
	v_pk_add_f32 v[224:225], v[144:145], v[160:161] neg_lo:[0,1] neg_hi:[0,1]
	v_pk_add_f32 v[226:227], v[176:177], v[160:161] neg_lo:[0,1] neg_hi:[0,1]
	v_pk_fma_f32 v[192:193], v[96:97], v[224:225], v[160:161]
	v_pk_fma_f32 v[192:193], v[112:113], v[226:227], v[192:193]
	v_pk_add_f32 v[224:225], v[146:147], v[162:163] neg_lo:[0,1] neg_hi:[0,1]
	v_pk_add_f32 v[226:227], v[178:179], v[162:163] neg_lo:[0,1] neg_hi:[0,1]
	v_pk_fma_f32 v[194:195], v[98:99], v[224:225], v[162:163]
	v_pk_fma_f32 v[194:195], v[114:115], v[226:227], v[194:195]
	v_pk_add_f32 v[224:225], v[148:149], v[164:165] neg_lo:[0,1] neg_hi:[0,1]
	v_pk_add_f32 v[226:227], v[180:181], v[164:165] neg_lo:[0,1] neg_hi:[0,1]
	v_pk_fma_f32 v[196:197], v[100:101], v[224:225], v[164:165]
	v_pk_fma_f32 v[196:197], v[116:117], v[226:227], v[196:197]
	v_pk_add_f32 v[224:225], v[150:151], v[166:167] neg_lo:[0,1] neg_hi:[0,1]
	v_pk_add_f32 v[226:227], v[182:183], v[166:167] neg_lo:[0,1] neg_hi:[0,1]
	v_pk_fma_f32 v[198:199], v[102:103], v[224:225], v[166:167]
	v_pk_fma_f32 v[198:199], v[118:119], v[226:227], v[198:199]
	v_pk_add_f32 v[224:225], v[152:153], v[168:169] neg_lo:[0,1] neg_hi:[0,1]
; __device__ __forceinline__ float bflo(unsigned w) { return __uint_as_float(w << 16); }
; __device__ __forceinline__ float bfhi(unsigned w) { return __uint_as_float(w & 0xffff0000u); }
; __device__ __forceinline__ unsigned cvt_pk_bf16(float lo, float hi) { unsigned r; asm volatile("v_cvt_pk_bf16_f32 %0, %1, %2" : "=v"(r) : "v"(lo), "v"(hi)); return r; }
; __device__ __forceinline__ void prep_phase(const Params& p) {
;     ...
;                 float v[16]; mix16(vp, vc, vn, mpv, mnv, v);
;                 st16bf(V + (size_t)(t0 + i) * RW + c, v);
;                 const float z4[4] = {bflo(lc.x), bfhi(lc.x), bflo(lc.y), bfhi(lc.y)}, p4[4] = {bflo(lp.x), bfhi(lp.x), bflo(lp.y), bfhi(lp.y)}, n4[4] = {bflo(ln.x), bfhi(ln.x), bflo(ln.y), bfhi(ln.y)};
;                 float o4[4];
; #pragma unroll
;                 for (int j = 0; j < 4; ++j) { const float sft = z4[j] + la[j] * (p4[j] - z4[j]) + lb[j] * (n4[j] - z4[j]); o4[j] = (lane < 32) ? tanhf(sft) : sft; }
;                 u32x2 w; w.x = cvt_pk_bf16(o4[0], o4[1]); w.y = cvt_pk_bf16(o4[2], o4[3]); *(u32x2*)(AL + (size_t)(t0 + i) * 256 + alc) = w;
;                 vp = vc; vc = vn; lp = lc; lc = ln;
	v_pk_add_f32 v[226:227], v[184:185], v[168:169] neg_lo:[0,1] neg_hi:[0,1]
	v_pk_fma_f32 v[200:201], v[104:105], v[224:225], v[168:169]
	v_pk_fma_f32 v[200:201], v[120:121], v[226:227], v[200:201]
	v_pk_add_f32 v[224:225], v[154:155], v[170:171] neg_lo:[0,1] neg_hi:[0,1]
	v_pk_add_f32 v[226:227], v[186:187], v[170:171] neg_lo:[0,1] neg_hi:[0,1]
	v_pk_fma_f32 v[202:203], v[106:107], v[224:225], v[170:171]
	v_pk_fma_f32 v[202:203], v[122:123], v[226:227], v[202:203]
	v_pk_add_f32 v[224:225], v[156:157], v[172:173] neg_lo:[0,1] neg_hi:[0,1]
	v_pk_add_f32 v[226:227], v[188:189], v[172:173] neg_lo:[0,1] neg_hi:[0,1]
	v_pk_fma_f32 v[204:205], v[108:109], v[224:225], v[172:173]
	v_pk_fma_f32 v[204:205], v[124:125], v[226:227], v[204:205]
	v_pk_add_f32 v[224:225], v[158:159], v[174:175] neg_lo:[0,1] neg_hi:[0,1]
	v_pk_add_f32 v[226:227], v[190:191], v[174:175] neg_lo:[0,1] neg_hi:[0,1]
	v_pk_fma_f32 v[206:207], v[110:111], v[224:225], v[174:175]
	v_pk_fma_f32 v[206:207], v[126:127], v[226:227], v[206:207]
	v_cvt_pk_bf16_f32 v208, v192, v193
	v_cvt_pk_bf16_f32 v209, v194, v195
	v_cvt_pk_bf16_f32 v210, v196, v197
	v_cvt_pk_bf16_f32 v211, v198, v199
	v_cvt_pk_bf16_f32 v212, v200, v201
	v_cvt_pk_bf16_f32 v213, v202, v203
	v_cvt_pk_bf16_f32 v214, v204, v205
	v_cvt_pk_bf16_f32 v215, v206, v207
	buffer_store_dwordx4 v[208:211], v237, s[68:71], s73 offen offset:0
	buffer_store_dwordx4 v[212:215], v237, s[68:71], s73 offen offset:16
	v_sub_f32_e32 v224, v136, v140
	v_sub_f32_e32 v225, v216, v140
	v_fma_f32 v220, v128, v224, v140
	v_fma_f32 v220, v132, v225, v220
	v_sub_f32_e32 v224, v137, v141
	v_sub_f32_e32 v225, v217, v141
	v_fma_f32 v221, v129, v224, v141
	v_fma_f32 v221, v133, v225, v221
	v_sub_f32_e32 v224, v138, v142
	v_sub_f32_e32 v225, v218, v142
	v_fma_f32 v222, v130, v224, v142
	v_fma_f32 v222, v134, v225, v222
	v_sub_f32_e32 v224, v139, v143
	v_sub_f32_e32 v225, v219, v143
	v_fma_f32 v223, v131, v224, v143
	v_fma_f32 v223, v135, v225, v223
	v_and_b32_e32 v224, 0x7fffffff, v220
	v_mul_f32_e32 v225, 0x4038aa3b, v224
	v_exp_f32_e32 v225, v225
	v_mul_f32_e32 v226, v220, v220
	v_add_f32_e32 v225, 1.0, v225
	v_rcp_f32_e32 v225, v225
	v_mul_f32_e32 v227, 0xbeaaaaab, v226
	v_fma_f32 v225, v225, -2.0, 1.0
	v_fma_f32 v227, v227, v220, v220
	v_bfi_b32 v225, v241, v225, v220
	v_cmp_gt_f32_e32 vcc, 0x3d000000, v224
	s_nop 1
	v_cndmask_b32_e32 v225, v225, v227, vcc
	v_cmp_gt_u32_e32 vcc, 32, v240
	s_nop 1
	v_cndmask_b32_e32 v220, v220, v225, vcc
	v_and_b32_e32 v224, 0x7fffffff, v221
	v_mul_f32_e32 v225, 0x4038aa3b, v224
	v_exp_f32_e32 v225, v225
	v_mul_f32_e32 v226, v221, v221
	v_add_f32_e32 v225, 1.0, v225
	v_rcp_f32_e32 v225, v225
	v_mul_f32_e32 v227, 0xbeaaaaab, v226
	v_fma_f32 v225, v225, -2.0, 1.0
	v_fma_f32 v227, v227, v221, v221
	v_bfi_b32 v225, v241, v225, v221
	v_cmp_gt_f32_e32 vcc, 0x3d000000, v224
	s_nop 1
	v_cndmask_b32_e32 v225, v225, v227, vcc
	v_cmp_gt_u32_e32 vcc, 32, v240
	s_nop 1
	v_cndmask_b32_e32 v221, v221, v225, vcc
	v_and_b32_e32 v224, 0x7fffffff, v222
	v_mul_f32_e32 v225, 0x4038aa3b, v224
	v_exp_f32_e32 v225, v225
	v_mul_f32_e32 v226, v222, v222
	v_add_f32_e32 v225, 1.0, v225
	v_rcp_f32_e32 v225, v225
	v_mul_f32_e32 v227, 0xbeaaaaab, v226
	v_fma_f32 v225, v225, -2.0, 1.0
	v_fma_f32 v227, v227, v222, v222
	v_bfi_b32 v225, v241, v225, v222
	v_cmp_gt_f32_e32 vcc, 0x3d000000, v224
	s_nop 1
	v_cndmask_b32_e32 v225, v225, v227, vcc
	v_cmp_gt_u32_e32 vcc, 32, v240
	s_nop 1
	v_cndmask_b32_e32 v222, v222, v225, vcc
	v_and_b32_e32 v224, 0x7fffffff, v223
	v_mul_f32_e32 v225, 0x4038aa3b, v224
	v_exp_f32_e32 v225, v225
	v_mul_f32_e32 v226, v223, v223
	v_add_f32_e32 v225, 1.0, v225
	v_rcp_f32_e32 v225, v225
	v_mul_f32_e32 v227, 0xbeaaaaab, v226
	v_fma_f32 v225, v225, -2.0, 1.0
	v_fma_f32 v227, v227, v223, v223
	v_bfi_b32 v225, v241, v225, v223
	v_cmp_gt_f32_e32 vcc, 0x3d000000, v224
	s_nop 1
	v_cndmask_b32_e32 v225, v225, v227, vcc
	v_cmp_gt_u32_e32 vcc, 32, v240
	s_nop 1
	v_cndmask_b32_e32 v223, v223, v225, vcc
	v_cvt_pk_bf16_f32 v224, v220, v221
	v_cvt_pk_bf16_f32 v225, v222, v223
	buffer_store_dwordx2 v[224:225], v238, s[68:71], s74 offen
	s_add_u32 s72, s72, 0x1000
	s_add_u32 s73, s73, 0x800
	s_add_u32 s74, s74, 0x200
	s_add_u32 s75, s75, 0x40
	s_waitcnt vmcnt(21)
; __device__ __forceinline__ float bflo(unsigned w) { return __uint_as_float(w << 16); }
; __device__ __forceinline__ float bfhi(unsigned w) { return __uint_as_float(w & 0xffff0000u); }
; __device__ __forceinline__ unsigned cvt_pk_bf16(float lo, float hi) { unsigned r; asm volatile("v_cvt_pk_bf16_f32 %0, %1, %2" : "=v"(r) : "v"(lo), "v"(hi)); return r; }
; __device__ __forceinline__ void prep_phase(const Params& p) {
;     ...
;             for (int i = 0; i < 16; ++i) {
;                 const bool hn = (tt0 + i) < SEQ - 1; const u16* zn = zc + (size_t)(i + 1) * 3328;
;                 const Z16 vn = hn ? ldz(zn + 2048 + c) : zz(); const u32x2 ln = hn ? *(const u32x2*)(zn + cl) : (u32x2){0u, 0u};
;                 float v[16]; mix16(vp, vc, vn, mpv, mnv, v);
;                 st16bf(V + (size_t)(t0 + i) * RW + c, v);
;                 const float z4[4] = {bflo(lc.x), bfhi(lc.x), bflo(lc.y), bfhi(lc.y)}, p4[4] = {bflo(lp.x), bfhi(lp.x), bflo(lp.y), bfhi(lp.y)}, n4[4] = {bflo(ln.x), bfhi(ln.x), bflo(ln.y), bfhi(ln.y)};
;                 float o4[4];
; #pragma unroll
;                 for (int j = 0; j < 4; ++j) { const float sft = z4[j] + la[j] * (p4[j] - z4[j]) + lb[j] * (n4[j] - z4[j]); o4[j] = (lane < 32) ? tanhf(sft) : sft; }
;                 u32x2 w; w.x = cvt_pk_bf16(o4[0], o4[1]); w.y = cvt_pk_bf16(o4[2], o4[3]); *(u32x2*)(AL + (size_t)(t0 + i) * 256 + alc) = w;
;                 vp = vc; vc = vn; lp = lc; lc = ln;
	v_lshlrev_b32_e32 v144, 16, v24
	v_and_b32_e32 v145, 0xffff0000, v24
	v_lshlrev_b32_e32 v146, 16, v25
	v_and_b32_e32 v147, 0xffff0000, v25
	v_lshlrev_b32_e32 v148, 16, v26
	v_and_b32_e32 v149, 0xffff0000, v26
	v_lshlrev_b32_e32 v150, 16, v27
	v_and_b32_e32 v151, 0xffff0000, v27
	v_lshlrev_b32_e32 v152, 16, v28
	v_and_b32_e32 v153, 0xffff0000, v28
	v_lshlrev_b32_e32 v154, 16, v29
	v_and_b32_e32 v155, 0xffff0000, v29
	v_lshlrev_b32_e32 v156, 16, v30
	v_and_b32_e32 v157, 0xffff0000, v30
	v_lshlrev_b32_e32 v158, 16, v31
	v_and_b32_e32 v159, 0xffff0000, v31
	v_lshlrev_b32_e32 v160, 16, v36
	v_and_b32_e32 v161, 0xffff0000, v36
	v_lshlrev_b32_e32 v162, 16, v37
	v_and_b32_e32 v163, 0xffff0000, v37
	v_lshlrev_b32_e32 v164, 16, v38
	v_and_b32_e32 v165, 0xffff0000, v38
	v_lshlrev_b32_e32 v166, 16, v39
	v_and_b32_e32 v167, 0xffff0000, v39
	v_lshlrev_b32_e32 v168, 16, v40
	v_and_b32_e32 v169, 0xffff0000, v40
	v_lshlrev_b32_e32 v170, 16, v41
	v_and_b32_e32 v171, 0xffff0000, v41
	v_lshlrev_b32_e32 v172, 16, v42
	v_and_b32_e32 v173, 0xffff0000, v42
	v_lshlrev_b32_e32 v174, 16, v43
	v_and_b32_e32 v175, 0xffff0000, v43
	v_lshlrev_b32_e32 v176, 16, v48
	v_and_b32_e32 v177, 0xffff0000, v48
	v_lshlrev_b32_e32 v178, 16, v49
	v_and_b32_e32 v179, 0xffff0000, v49
	v_lshlrev_b32_e32 v180, 16, v50
	v_and_b32_e32 v181, 0xffff0000, v50
	v_lshlrev_b32_e32 v182, 16, v51
	v_and_b32_e32 v183, 0xffff0000, v51
	v_lshlrev_b32_e32 v184, 16, v52
	v_and_b32_e32 v185, 0xffff0000, v52
	v_lshlrev_b32_e32 v186, 16, v53
	v_and_b32_e32 v187, 0xffff0000, v53
	v_lshlrev_b32_e32 v188, 16, v54
	v_and_b32_e32 v189, 0xffff0000, v54
	v_lshlrev_b32_e32 v190, 16, v55
	v_and_b32_e32 v191, 0xffff0000, v55
	v_lshlrev_b32_e32 v136, 16, v32
	v_and_b32_e32 v137, 0xffff0000, v32
	v_lshlrev_b32_e32 v138, 16, v33
	v_and_b32_e32 v139, 0xffff0000, v33
	v_lshlrev_b32_e32 v140, 16, v44
	v_and_b32_e32 v141, 0xffff0000, v44
	v_lshlrev_b32_e32 v142, 16, v45
	v_and_b32_e32 v143, 0xffff0000, v45
	v_lshlrev_b32_e32 v216, 16, v56
	v_and_b32_e32 v217, 0xffff0000, v56
	v_lshlrev_b32_e32 v218, 16, v57
	v_and_b32_e32 v219, 0xffff0000, v57
	buffer_load_dwordx4 v[24:27], v232, s[64:67], 0 offen offset:4064 nt
	buffer_load_dwordx4 v[28:31], v232, s[64:67], 0 offen offset:4080 nt
	buffer_load_dwordx2 v[32:33], v233, s[64:67], 0 offen nt
	v_add_u32_e32 v233, 6656, v233
	v_add_u32_e32 v232, 6656, v232
	v_pk_add_f32 v[224:225], v[144:145], v[160:161] neg_lo:[0,1] neg_hi:[0,1]
	v_pk_add_f32 v[226:227], v[176:177], v[160:161] neg_lo:[0,1] neg_hi:[0,1]
	v_pk_fma_f32 v[192:193], v[96:97], v[224:225], v[160:161]
	v_pk_fma_f32 v[192:193], v[112:113], v[226:227], v[192:193]
	v_pk_add_f32 v[224:225], v[146:147], v[162:163] neg_lo:[0,1] neg_hi:[0,1]
	v_pk_add_f32 v[226:227], v[178:179], v[162:163] neg_lo:[0,1] neg_hi:[0,1]
	v_pk_fma_f32 v[194:195], v[98:99], v[224:225], v[162:163]
	v_pk_fma_f32 v[194:195], v[114:115], v[226:227], v[194:195]
	v_pk_add_f32 v[224:225], v[148:149], v[164:165] neg_lo:[0,1] neg_hi:[0,1]
	v_pk_add_f32 v[226:227], v[180:181], v[164:165] neg_lo:[0,1] neg_hi:[0,1]
	v_pk_fma_f32 v[196:197], v[100:101], v[224:225], v[164:165]
	v_pk_fma_f32 v[196:197], v[116:117], v[226:227], v[196:197]
	v_pk_add_f32 v[224:225], v[150:151], v[166:167] neg_lo:[0,1] neg_hi:[0,1]
	v_pk_add_f32 v[226:227], v[182:183], v[166:167] neg_lo:[0,1] neg_hi:[0,1]
	v_pk_fma_f32 v[198:199], v[102:103], v[224:225], v[166:167]
	v_pk_fma_f32 v[198:199], v[118:119], v[226:227], v[198:199]
	v_pk_add_f32 v[224:225], v[152:153], v[168:169] neg_lo:[0,1] neg_hi:[0,1]
	v_pk_add_f32 v[226:227], v[184:185], v[168:169] neg_lo:[0,1] neg_hi:[0,1]
	v_pk_fma_f32 v[200:201], v[104:105], v[224:225], v[168:169]
	v_pk_fma_f32 v[200:201], v[120:121], v[226:227], v[200:201]
	v_pk_add_f32 v[224:225], v[154:155], v[170:171] neg_lo:[0,1] neg_hi:[0,1]
	v_pk_add_f32 v[226:227], v[186:187], v[170:171] neg_lo:[0,1] neg_hi:[0,1]
	v_pk_fma_f32 v[202:203], v[106:107], v[224:225], v[170:171]
	v_pk_fma_f32 v[202:203], v[122:123], v[226:227], v[202:203]
	v_pk_add_f32 v[224:225], v[156:157], v[172:173] neg_lo:[0,1] neg_hi:[0,1]
	v_pk_add_f32 v[226:227], v[188:189], v[172:173] neg_lo:[0,1] neg_hi:[0,1]
	v_pk_fma_f32 v[204:205], v[108:109], v[224:225], v[172:173]
	v_pk_fma_f32 v[204:205], v[124:125], v[226:227], v[204:205]
	v_pk_add_f32 v[224:225], v[158:159], v[174:175] neg_lo:[0,1] neg_hi:[0,1]
	v_pk_add_f32 v[226:227], v[190:191], v[174:175] neg_lo:[0,1] neg_hi:[0,1]
	v_pk_fma_f32 v[206:207], v[110:111], v[224:225], v[174:175]
	v_pk_fma_f32 v[206:207], v[126:127], v[226:227], v[206:207]
	v_cvt_pk_bf16_f32 v208, v192, v193
	v_cvt_pk_bf16_f32 v209, v194, v195
	v_cvt_pk_bf16_f32 v210, v196, v197
	v_cvt_pk_bf16_f32 v211, v198, v199
	v_cvt_pk_bf16_f32 v212, v200, v201
	v_cvt_pk_bf16_f32 v213, v202, v203
	v_cvt_pk_bf16_f32 v214, v204, v205
	v_cvt_pk_bf16_f32 v215, v206, v207
	buffer_store_dwordx4 v[208:211], v237, s[68:71], s73 offen offset:0
	buffer_store_dwordx4 v[212:215], v237, s[68:71], s73 offen offset:16
	v_sub_f32_e32 v224, v136, v140
	v_sub_f32_e32 v225, v216, v140
	v_fma_f32 v220, v128, v224, v140
	v_fma_f32 v220, v132, v225, v220
	v_sub_f32_e32 v224, v137, v141
	v_sub_f32_e32 v225, v217, v141
	v_fma_f32 v221, v129, v224, v141
	v_fma_f32 v221, v133, v225, v221
	v_sub_f32_e32 v224, v138, v142
	v_sub_f32_e32 v225, v218, v142
	v_fma_f32 v222, v130, v224, v142
	v_fma_f32 v222, v134, v225, v222
	v_sub_f32_e32 v224, v139, v143
	v_sub_f32_e32 v225, v219, v143
	v_fma_f32 v223, v131, v224, v143
	v_fma_f32 v223, v135, v225, v223
	v_and_b32_e32 v224, 0x7fffffff, v220
	v_mul_f32_e32 v225, 0x4038aa3b, v224
	v_exp_f32_e32 v225, v225
	v_mul_f32_e32 v226, v220, v220
	v_add_f32_e32 v225, 1.0, v225
; __device__ __forceinline__ float bflo(unsigned w) { return __uint_as_float(w << 16); }
; __device__ __forceinline__ float bfhi(unsigned w) { return __uint_as_float(w & 0xffff0000u); }
; __device__ __forceinline__ unsigned cvt_pk_bf16(float lo, float hi) { unsigned r; asm volatile("v_cvt_pk_bf16_f32 %0, %1, %2" : "=v"(r) : "v"(lo), "v"(hi)); return r; }
; __device__ __forceinline__ void prep_phase(const Params& p) {
;     ...
;             for (int i = 0; i < 16; ++i) {
;                 const bool hn = (tt0 + i) < SEQ - 1; const u16* zn = zc + (size_t)(i + 1) * 3328;
;                 const Z16 vn = hn ? ldz(zn + 2048 + c) : zz(); const u32x2 ln = hn ? *(const u32x2*)(zn + cl) : (u32x2){0u, 0u};
;                 float v[16]; mix16(vp, vc, vn, mpv, mnv, v);
;                 st16bf(V + (size_t)(t0 + i) * RW + c, v);
;                 const float z4[4] = {bflo(lc.x), bfhi(lc.x), bflo(lc.y), bfhi(lc.y)}, p4[4] = {bflo(lp.x), bfhi(lp.x), bflo(lp.y), bfhi(lp.y)}, n4[4] = {bflo(ln.x), bfhi(ln.x), bflo(ln.y), bfhi(ln.y)};
;                 float o4[4];
; #pragma unroll
;                 for (int j = 0; j < 4; ++j) { const float sft = z4[j] + la[j] * (p4[j] - z4[j]) + lb[j] * (n4[j] - z4[j]); o4[j] = (lane < 32) ? tanhf(sft) : sft; }
;                 u32x2 w; w.x = cvt_pk_bf16(o4[0], o4[1]); w.y = cvt_pk_bf16(o4[2], o4[3]); *(u32x2*)(AL + (size_t)(t0 + i) * 256 + alc) = w;
;                 vp = vc; vc = vn; lp = lc; lc = ln;
	v_rcp_f32_e32 v225, v225
	v_mul_f32_e32 v227, 0xbeaaaaab, v226
	v_fma_f32 v225, v225, -2.0, 1.0
	v_fma_f32 v227, v227, v220, v220
	v_bfi_b32 v225, v241, v225, v220
	v_cmp_gt_f32_e32 vcc, 0x3d000000, v224
	s_nop 1
	v_cndmask_b32_e32 v225, v225, v227, vcc
	v_cmp_gt_u32_e32 vcc, 32, v240
	s_nop 1
	v_cndmask_b32_e32 v220, v220, v225, vcc
	v_and_b32_e32 v224, 0x7fffffff, v221
	v_mul_f32_e32 v225, 0x4038aa3b, v224
	v_exp_f32_e32 v225, v225
	v_mul_f32_e32 v226, v221, v221
	v_add_f32_e32 v225, 1.0, v225
	v_rcp_f32_e32 v225, v225
	v_mul_f32_e32 v227, 0xbeaaaaab, v226
	v_fma_f32 v225, v225, -2.0, 1.0
	v_fma_f32 v227, v227, v221, v221
	v_bfi_b32 v225, v241, v225, v221
	v_cmp_gt_f32_e32 vcc, 0x3d000000, v224
	s_nop 1
	v_cndmask_b32_e32 v225, v225, v227, vcc
	v_cmp_gt_u32_e32 vcc, 32, v240
	s_nop 1
	v_cndmask_b32_e32 v221, v221, v225, vcc
	v_and_b32_e32 v224, 0x7fffffff, v222
	v_mul_f32_e32 v225, 0x4038aa3b, v224
	v_exp_f32_e32 v225, v225
	v_mul_f32_e32 v226, v222, v222
	v_add_f32_e32 v225, 1.0, v225
	v_rcp_f32_e32 v225, v225
	v_mul_f32_e32 v227, 0xbeaaaaab, v226
	v_fma_f32 v225, v225, -2.0, 1.0
	v_fma_f32 v227, v227, v222, v222
	v_bfi_b32 v225, v241, v225, v222
	v_cmp_gt_f32_e32 vcc, 0x3d000000, v224
	s_nop 1
	v_cndmask_b32_e32 v225, v225, v227, vcc
	v_cmp_gt_u32_e32 vcc, 32, v240
	s_nop 1
	v_cndmask_b32_e32 v222, v222, v225, vcc
	v_and_b32_e32 v224, 0x7fffffff, v223
	v_mul_f32_e32 v225, 0x4038aa3b, v224
	v_exp_f32_e32 v225, v225
	v_mul_f32_e32 v226, v223, v223
	v_add_f32_e32 v225, 1.0, v225
	v_rcp_f32_e32 v225, v225
	v_mul_f32_e32 v227, 0xbeaaaaab, v226
	v_fma_f32 v225, v225, -2.0, 1.0
	v_fma_f32 v227, v227, v223, v223
	v_bfi_b32 v225, v241, v225, v223
	v_cmp_gt_f32_e32 vcc, 0x3d000000, v224
	s_nop 1
	v_cndmask_b32_e32 v225, v225, v227, vcc
	v_cmp_gt_u32_e32 vcc, 32, v240
	s_nop 1
	v_cndmask_b32_e32 v223, v223, v225, vcc
	v_cvt_pk_bf16_f32 v224, v220, v221
	v_cvt_pk_bf16_f32 v225, v222, v223
	buffer_store_dwordx2 v[224:225], v238, s[68:71], s74 offen
	s_add_u32 s72, s72, 0x1000
	s_add_u32 s73, s73, 0x800
	s_add_u32 s74, s74, 0x200
	s_add_u32 s75, s75, 0x40
	s_waitcnt vmcnt(24)
	v_lshlrev_b32_e32 v144, 16, v36
	v_and_b32_e32 v145, 0xffff0000, v36
	v_lshlrev_b32_e32 v146, 16, v37
	v_and_b32_e32 v147, 0xffff0000, v37
	v_lshlrev_b32_e32 v148, 16, v38
	v_and_b32_e32 v149, 0xffff0000, v38
	v_lshlrev_b32_e32 v150, 16, v39
	v_and_b32_e32 v151, 0xffff0000, v39
	v_lshlrev_b32_e32 v152, 16, v40
	v_and_b32_e32 v153, 0xffff0000, v40
	v_lshlrev_b32_e32 v154, 16, v41
	v_and_b32_e32 v155, 0xffff0000, v41
	v_lshlrev_b32_e32 v156, 16, v42
	v_and_b32_e32 v157, 0xffff0000, v42
	v_lshlrev_b32_e32 v158, 16, v43
	v_and_b32_e32 v159, 0xffff0000, v43
	v_lshlrev_b32_e32 v160, 16, v48
	v_and_b32_e32 v161, 0xffff0000, v48
	v_lshlrev_b32_e32 v162, 16, v49
	v_and_b32_e32 v163, 0xffff0000, v49
	v_lshlrev_b32_e32 v164, 16, v50
	v_and_b32_e32 v165, 0xffff0000, v50
	v_lshlrev_b32_e32 v166, 16, v51
	v_and_b32_e32 v167, 0xffff0000, v51
	v_lshlrev_b32_e32 v168, 16, v52
	v_and_b32_e32 v169, 0xffff0000, v52
	v_lshlrev_b32_e32 v170, 16, v53
	v_and_b32_e32 v171, 0xffff0000, v53
	v_lshlrev_b32_e32 v172, 16, v54
	v_and_b32_e32 v173, 0xffff0000, v54
	v_lshlrev_b32_e32 v174, 16, v55
	v_and_b32_e32 v175, 0xffff0000, v55
	v_lshlrev_b32_e32 v176, 16, v60
	v_and_b32_e32 v177, 0xffff0000, v60
	v_lshlrev_b32_e32 v178, 16, v61
	v_and_b32_e32 v179, 0xffff0000, v61
	v_lshlrev_b32_e32 v180, 16, v62
	v_and_b32_e32 v181, 0xffff0000, v62
	v_lshlrev_b32_e32 v182, 16, v63
	v_and_b32_e32 v183, 0xffff0000, v63
	v_lshlrev_b32_e32 v184, 16, v64
	v_and_b32_e32 v185, 0xffff0000, v64
	v_lshlrev_b32_e32 v186, 16, v65
	v_and_b32_e32 v187, 0xffff0000, v65
	v_lshlrev_b32_e32 v188, 16, v66
	v_and_b32_e32 v189, 0xffff0000, v66
	v_lshlrev_b32_e32 v190, 16, v67
	v_and_b32_e32 v191, 0xffff0000, v67
	v_lshlrev_b32_e32 v136, 16, v44
	v_and_b32_e32 v137, 0xffff0000, v44
	v_lshlrev_b32_e32 v138, 16, v45
	v_and_b32_e32 v139, 0xffff0000, v45
	v_lshlrev_b32_e32 v140, 16, v56
	v_and_b32_e32 v141, 0xffff0000, v56
	v_lshlrev_b32_e32 v142, 16, v57
	v_and_b32_e32 v143, 0xffff0000, v57
	v_lshlrev_b32_e32 v216, 16, v68
	v_and_b32_e32 v217, 0xffff0000, v68
	v_lshlrev_b32_e32 v218, 16, v69
	v_and_b32_e32 v219, 0xffff0000, v69
	buffer_load_dwordx4 v[36:39], v232, s[64:67], 0 offen offset:4064 nt
	buffer_load_dwordx4 v[40:43], v232, s[64:67], 0 offen offset:4080 nt
	buffer_load_dwordx2 v[44:45], v233, s[64:67], 0 offen nt
	v_add_u32_e32 v233, 6656, v233
	v_add_u32_e32 v232, 6656, v232
	v_pk_add_f32 v[224:225], v[144:145], v[160:161] neg_lo:[0,1] neg_hi:[0,1]
	v_pk_add_f32 v[226:227], v[176:177], v[160:161] neg_lo:[0,1] neg_hi:[0,1]
	v_pk_fma_f32 v[192:193], v[96:97], v[224:225], v[160:161]
	v_pk_fma_f32 v[192:193], v[112:113], v[226:227], v[192:193]
	v_pk_add_f32 v[224:225], v[146:147], v[162:163] neg_lo:[0,1] neg_hi:[0,1]
	v_pk_add_f32 v[226:227], v[178:179], v[162:163] neg_lo:[0,1] neg_hi:[0,1]
	v_pk_fma_f32 v[194:195], v[98:99], v[224:225], v[162:163]
	v_pk_fma_f32 v[194:195], v[114:115], v[226:227], v[194:195]
	v_pk_add_f32 v[224:225], v[148:149], v[164:165] neg_lo:[0,1] neg_hi:[0,1]
	v_pk_add_f32 v[226:227], v[180:181], v[164:165] neg_lo:[0,1] neg_hi:[0,1]
	v_pk_fma_f32 v[196:197], v[100:101], v[224:225], v[164:165]
	v_pk_fma_f32 v[196:197], v[116:117], v[226:227], v[196:197]
	v_pk_add_f32 v[224:225], v[150:151], v[166:167] neg_lo:[0,1] neg_hi:[0,1]
	v_pk_add_f32 v[226:227], v[182:183], v[166:167] neg_lo:[0,1] neg_hi:[0,1]
	v_pk_fma_f32 v[198:199], v[102:103], v[224:225], v[166:167]
	v_pk_fma_f32 v[198:199], v[118:119], v[226:227], v[198:199]
	v_pk_add_f32 v[224:225], v[152:153], v[168:169] neg_lo:[0,1] neg_hi:[0,1]
; __device__ __forceinline__ float bflo(unsigned w) { return __uint_as_float(w << 16); }
; __device__ __forceinline__ float bfhi(unsigned w) { return __uint_as_float(w & 0xffff0000u); }
; __device__ __forceinline__ unsigned cvt_pk_bf16(float lo, float hi) { unsigned r; asm volatile("v_cvt_pk_bf16_f32 %0, %1, %2" : "=v"(r) : "v"(lo), "v"(hi)); return r; }
; __device__ __forceinline__ void prep_phase(const Params& p) {
;     ...
;                 float v[16]; mix16(vp, vc, vn, mpv, mnv, v);
;                 st16bf(V + (size_t)(t0 + i) * RW + c, v);
;                 const float z4[4] = {bflo(lc.x), bfhi(lc.x), bflo(lc.y), bfhi(lc.y)}, p4[4] = {bflo(lp.x), bfhi(lp.x), bflo(lp.y), bfhi(lp.y)}, n4[4] = {bflo(ln.x), bfhi(ln.x), bflo(ln.y), bfhi(ln.y)};
;                 float o4[4];
; #pragma unroll
;                 for (int j = 0; j < 4; ++j) { const float sft = z4[j] + la[j] * (p4[j] - z4[j]) + lb[j] * (n4[j] - z4[j]); o4[j] = (lane < 32) ? tanhf(sft) : sft; }
;                 u32x2 w; w.x = cvt_pk_bf16(o4[0], o4[1]); w.y = cvt_pk_bf16(o4[2], o4[3]); *(u32x2*)(AL + (size_t)(t0 + i) * 256 + alc) = w;
;                 vp = vc; vc = vn; lp = lc; lc = ln;
	v_pk_add_f32 v[226:227], v[184:185], v[168:169] neg_lo:[0,1] neg_hi:[0,1]
	v_pk_fma_f32 v[200:201], v[104:105], v[224:225], v[168:169]
	v_pk_fma_f32 v[200:201], v[120:121], v[226:227], v[200:201]
	v_pk_add_f32 v[224:225], v[154:155], v[170:171] neg_lo:[0,1] neg_hi:[0,1]
	v_pk_add_f32 v[226:227], v[186:187], v[170:171] neg_lo:[0,1] neg_hi:[0,1]
	v_pk_fma_f32 v[202:203], v[106:107], v[224:225], v[170:171]
	v_pk_fma_f32 v[202:203], v[122:123], v[226:227], v[202:203]
	v_pk_add_f32 v[224:225], v[156:157], v[172:173] neg_lo:[0,1] neg_hi:[0,1]
	v_pk_add_f32 v[226:227], v[188:189], v[172:173] neg_lo:[0,1] neg_hi:[0,1]
	v_pk_fma_f32 v[204:205], v[108:109], v[224:225], v[172:173]
	v_pk_fma_f32 v[204:205], v[124:125], v[226:227], v[204:205]
	v_pk_add_f32 v[224:225], v[158:159], v[174:175] neg_lo:[0,1] neg_hi:[0,1]
	v_pk_add_f32 v[226:227], v[190:191], v[174:175] neg_lo:[0,1] neg_hi:[0,1]
	v_pk_fma_f32 v[206:207], v[110:111], v[224:225], v[174:175]
	v_pk_fma_f32 v[206:207], v[126:127], v[226:227], v[206:207]
	v_cvt_pk_bf16_f32 v208, v192, v193
	v_cvt_pk_bf16_f32 v209, v194, v195
	v_cvt_pk_bf16_f32 v210, v196, v197
	v_cvt_pk_bf16_f32 v211, v198, v199
	v_cvt_pk_bf16_f32 v212, v200, v201
	v_cvt_pk_bf16_f32 v213, v202, v203
	v_cvt_pk_bf16_f32 v214, v204, v205
	v_cvt_pk_bf16_f32 v215, v206, v207
	buffer_store_dwordx4 v[208:211], v237, s[68:71], s73 offen offset:0
	buffer_store_dwordx4 v[212:215], v237, s[68:71], s73 offen offset:16
	v_sub_f32_e32 v224, v136, v140
	v_sub_f32_e32 v225, v216, v140
	v_fma_f32 v220, v128, v224, v140
	v_fma_f32 v220, v132, v225, v220
	v_sub_f32_e32 v224, v137, v141
	v_sub_f32_e32 v225, v217, v141
	v_fma_f32 v221, v129, v224, v141
	v_fma_f32 v221, v133, v225, v221
	v_sub_f32_e32 v224, v138, v142
	v_sub_f32_e32 v225, v218, v142
	v_fma_f32 v222, v130, v224, v142
	v_fma_f32 v222, v134, v225, v222
	v_sub_f32_e32 v224, v139, v143
	v_sub_f32_e32 v225, v219, v143
	v_fma_f32 v223, v131, v224, v143
	v_fma_f32 v223, v135, v225, v223
	v_and_b32_e32 v224, 0x7fffffff, v220
	v_mul_f32_e32 v225, 0x4038aa3b, v224
	v_exp_f32_e32 v225, v225
	v_mul_f32_e32 v226, v220, v220
	v_add_f32_e32 v225, 1.0, v225
	v_rcp_f32_e32 v225, v225
	v_mul_f32_e32 v227, 0xbeaaaaab, v226
	v_fma_f32 v225, v225, -2.0, 1.0
	v_fma_f32 v227, v227, v220, v220
	v_bfi_b32 v225, v241, v225, v220
	v_cmp_gt_f32_e32 vcc, 0x3d000000, v224
	s_nop 1
	v_cndmask_b32_e32 v225, v225, v227, vcc
	v_cmp_gt_u32_e32 vcc, 32, v240
	s_nop 1
	v_cndmask_b32_e32 v220, v220, v225, vcc
	v_and_b32_e32 v224, 0x7fffffff, v221
	v_mul_f32_e32 v225, 0x4038aa3b, v224
	v_exp_f32_e32 v225, v225
	v_mul_f32_e32 v226, v221, v221
	v_add_f32_e32 v225, 1.0, v225
	v_rcp_f32_e32 v225, v225
	v_mul_f32_e32 v227, 0xbeaaaaab, v226
	v_fma_f32 v225, v225, -2.0, 1.0
	v_fma_f32 v227, v227, v221, v221
	v_bfi_b32 v225, v241, v225, v221
	v_cmp_gt_f32_e32 vcc, 0x3d000000, v224
	s_nop 1
	v_cndmask_b32_e32 v225, v225, v227, vcc
	v_cmp_gt_u32_e32 vcc, 32, v240
	s_nop 1
	v_cndmask_b32_e32 v221, v221, v225, vcc
	v_and_b32_e32 v224, 0x7fffffff, v222
	v_mul_f32_e32 v225, 0x4038aa3b, v224
	v_exp_f32_e32 v225, v225
	v_mul_f32_e32 v226, v222, v222
	v_add_f32_e32 v225, 1.0, v225
	v_rcp_f32_e32 v225, v225
	v_mul_f32_e32 v227, 0xbeaaaaab, v226
	v_fma_f32 v225, v225, -2.0, 1.0
	v_fma_f32 v227, v227, v222, v222
	v_bfi_b32 v225, v241, v225, v222
	v_cmp_gt_f32_e32 vcc, 0x3d000000, v224
	s_nop 1
	v_cndmask_b32_e32 v225, v225, v227, vcc
	v_cmp_gt_u32_e32 vcc, 32, v240
	s_nop 1
	v_cndmask_b32_e32 v222, v222, v225, vcc
	v_and_b32_e32 v224, 0x7fffffff, v223
	v_mul_f32_e32 v225, 0x4038aa3b, v224
	v_exp_f32_e32 v225, v225
	v_mul_f32_e32 v226, v223, v223
	v_add_f32_e32 v225, 1.0, v225
	v_rcp_f32_e32 v225, v225
	v_mul_f32_e32 v227, 0xbeaaaaab, v226
	v_fma_f32 v225, v225, -2.0, 1.0
	v_fma_f32 v227, v227, v223, v223
	v_bfi_b32 v225, v241, v225, v223
	v_cmp_gt_f32_e32 vcc, 0x3d000000, v224
	s_nop 1
	v_cndmask_b32_e32 v225, v225, v227, vcc
	v_cmp_gt_u32_e32 vcc, 32, v240
	s_nop 1
	v_cndmask_b32_e32 v223, v223, v225, vcc
	v_cvt_pk_bf16_f32 v224, v220, v221
	v_cvt_pk_bf16_f32 v225, v222, v223
	buffer_store_dwordx2 v[224:225], v238, s[68:71], s74 offen
	s_add_u32 s72, s72, 0x1000
	s_add_u32 s73, s73, 0x800
	s_add_u32 s74, s74, 0x200
	s_add_u32 s75, s75, 0x40
	s_waitcnt vmcnt(27)
; __device__ __forceinline__ float bflo(unsigned w) { return __uint_as_float(w << 16); }
; __device__ __forceinline__ float bfhi(unsigned w) { return __uint_as_float(w & 0xffff0000u); }
; __device__ __forceinline__ unsigned cvt_pk_bf16(float lo, float hi) { unsigned r; asm volatile("v_cvt_pk_bf16_f32 %0, %1, %2" : "=v"(r) : "v"(lo), "v"(hi)); return r; }
; __device__ __forceinline__ void prep_phase(const Params& p) {
;     ...
;             for (int i = 0; i < 16; ++i) {
;                 const bool hn = (tt0 + i) < SEQ - 1; const u16* zn = zc + (size_t)(i + 1) * 3328;
;                 const Z16 vn = hn ? ldz(zn + 2048 + c) : zz(); const u32x2 ln = hn ? *(const u32x2*)(zn + cl) : (u32x2){0u, 0u};
;                 float v[16]; mix16(vp, vc, vn, mpv, mnv, v);
;                 st16bf(V + (size_t)(t0 + i) * RW + c, v);
;                 const float z4[4] = {bflo(lc.x), bfhi(lc.x), bflo(lc.y), bfhi(lc.y)}, p4[4] = {bflo(lp.x), bfhi(lp.x), bflo(lp.y), bfhi(lp.y)}, n4[4] = {bflo(ln.x), bfhi(ln.x), bflo(ln.y), bfhi(ln.y)};
;                 float o4[4];
; #pragma unroll
;                 for (int j = 0; j < 4; ++j) { const float sft = z4[j] + la[j] * (p4[j] - z4[j]) + lb[j] * (n4[j] - z4[j]); o4[j] = (lane < 32) ? tanhf(sft) : sft; }
;                 u32x2 w; w.x = cvt_pk_bf16(o4[0], o4[1]); w.y = cvt_pk_bf16(o4[2], o4[3]); *(u32x2*)(AL + (size_t)(t0 + i) * 256 + alc) = w;
;                 vp = vc; vc = vn; lp = lc; lc = ln;
	v_lshlrev_b32_e32 v144, 16, v48
	v_and_b32_e32 v145, 0xffff0000, v48
	v_lshlrev_b32_e32 v146, 16, v49
	v_and_b32_e32 v147, 0xffff0000, v49
	v_lshlrev_b32_e32 v148, 16, v50
	v_and_b32_e32 v149, 0xffff0000, v50
	v_lshlrev_b32_e32 v150, 16, v51
	v_and_b32_e32 v151, 0xffff0000, v51
	v_lshlrev_b32_e32 v152, 16, v52
	v_and_b32_e32 v153, 0xffff0000, v52
	v_lshlrev_b32_e32 v154, 16, v53
	v_and_b32_e32 v155, 0xffff0000, v53
	v_lshlrev_b32_e32 v156, 16, v54
	v_and_b32_e32 v157, 0xffff0000, v54
	v_lshlrev_b32_e32 v158, 16, v55
	v_and_b32_e32 v159, 0xffff0000, v55
	v_lshlrev_b32_e32 v160, 16, v60
	v_and_b32_e32 v161, 0xffff0000, v60
	v_lshlrev_b32_e32 v162, 16, v61
	v_and_b32_e32 v163, 0xffff0000, v61
	v_lshlrev_b32_e32 v164, 16, v62
	v_and_b32_e32 v165, 0xffff0000, v62
	v_lshlrev_b32_e32 v166, 16, v63
	v_and_b32_e32 v167, 0xffff0000, v63
	v_lshlrev_b32_e32 v168, 16, v64
	v_and_b32_e32 v169, 0xffff0000, v64
	v_lshlrev_b32_e32 v170, 16, v65
	v_and_b32_e32 v171, 0xffff0000, v65
	v_lshlrev_b32_e32 v172, 16, v66
	v_and_b32_e32 v173, 0xffff0000, v66
	v_lshlrev_b32_e32 v174, 16, v67
	v_and_b32_e32 v175, 0xffff0000, v67
	v_lshlrev_b32_e32 v176, 16, v72
	v_and_b32_e32 v177, 0xffff0000, v72
	v_lshlrev_b32_e32 v178, 16, v73
	v_and_b32_e32 v179, 0xffff0000, v73
	v_lshlrev_b32_e32 v180, 16, v74
	v_and_b32_e32 v181, 0xffff0000, v74
	v_lshlrev_b32_e32 v182, 16, v75
	v_and_b32_e32 v183, 0xffff0000, v75
	v_lshlrev_b32_e32 v184, 16, v76
	v_and_b32_e32 v185, 0xffff0000, v76
	v_lshlrev_b32_e32 v186, 16, v77
	v_and_b32_e32 v187, 0xffff0000, v77
	v_lshlrev_b32_e32 v188, 16, v78
	v_and_b32_e32 v189, 0xffff0000, v78
	v_lshlrev_b32_e32 v190, 16, v79
	v_and_b32_e32 v191, 0xffff0000, v79
	v_lshlrev_b32_e32 v136, 16, v56
	v_and_b32_e32 v137, 0xffff0000, v56
	v_lshlrev_b32_e32 v138, 16, v57
	v_and_b32_e32 v139, 0xffff0000, v57
	v_lshlrev_b32_e32 v140, 16, v68
	v_and_b32_e32 v141, 0xffff0000, v68
	v_lshlrev_b32_e32 v142, 16, v69
	v_and_b32_e32 v143, 0xffff0000, v69
	v_lshlrev_b32_e32 v216, 16, v80
	v_and_b32_e32 v217, 0xffff0000, v80
	v_lshlrev_b32_e32 v218, 16, v81
	v_and_b32_e32 v219, 0xffff0000, v81
	buffer_load_dwordx4 v[48:51], v232, s[64:67], 0 offen offset:4064 nt
	buffer_load_dwordx4 v[52:55], v232, s[64:67], 0 offen offset:4080 nt
	buffer_load_dwordx2 v[56:57], v233, s[64:67], 0 offen nt
	v_add_u32_e32 v233, 6656, v233
	v_add_u32_e32 v232, 6656, v232
	v_pk_add_f32 v[224:225], v[144:145], v[160:161] neg_lo:[0,1] neg_hi:[0,1]
	v_pk_add_f32 v[226:227], v[176:177], v[160:161] neg_lo:[0,1] neg_hi:[0,1]
	v_pk_fma_f32 v[192:193], v[96:97], v[224:225], v[160:161]
	v_pk_fma_f32 v[192:193], v[112:113], v[226:227], v[192:193]
	v_pk_add_f32 v[224:225], v[146:147], v[162:163] neg_lo:[0,1] neg_hi:[0,1]
	v_pk_add_f32 v[226:227], v[178:179], v[162:163] neg_lo:[0,1] neg_hi:[0,1]
	v_pk_fma_f32 v[194:195], v[98:99], v[224:225], v[162:163]
	v_pk_fma_f32 v[194:195], v[114:115], v[226:227], v[194:195]
	v_pk_add_f32 v[224:225], v[148:149], v[164:165] neg_lo:[0,1] neg_hi:[0,1]
	v_pk_add_f32 v[226:227], v[180:181], v[164:165] neg_lo:[0,1] neg_hi:[0,1]
	v_pk_fma_f32 v[196:197], v[100:101], v[224:225], v[164:165]
	v_pk_fma_f32 v[196:197], v[116:117], v[226:227], v[196:197]
	v_pk_add_f32 v[224:225], v[150:151], v[166:167] neg_lo:[0,1] neg_hi:[0,1]
	v_pk_add_f32 v[226:227], v[182:183], v[166:167] neg_lo:[0,1] neg_hi:[0,1]
	v_pk_fma_f32 v[198:199], v[102:103], v[224:225], v[166:167]
	v_pk_fma_f32 v[198:199], v[118:119], v[226:227], v[198:199]
	v_pk_add_f32 v[224:225], v[152:153], v[168:169] neg_lo:[0,1] neg_hi:[0,1]
	v_pk_add_f32 v[226:227], v[184:185], v[168:169] neg_lo:[0,1] neg_hi:[0,1]
	v_pk_fma_f32 v[200:201], v[104:105], v[224:225], v[168:169]
	v_pk_fma_f32 v[200:201], v[120:121], v[226:227], v[200:201]
	v_pk_add_f32 v[224:225], v[154:155], v[170:171] neg_lo:[0,1] neg_hi:[0,1]
	v_pk_add_f32 v[226:227], v[186:187], v[170:171] neg_lo:[0,1] neg_hi:[0,1]
	v_pk_fma_f32 v[202:203], v[106:107], v[224:225], v[170:171]
	v_pk_fma_f32 v[202:203], v[122:123], v[226:227], v[202:203]
	v_pk_add_f32 v[224:225], v[156:157], v[172:173] neg_lo:[0,1] neg_hi:[0,1]
	v_pk_add_f32 v[226:227], v[188:189], v[172:173] neg_lo:[0,1] neg_hi:[0,1]
	v_pk_fma_f32 v[204:205], v[108:109], v[224:225], v[172:173]
	v_pk_fma_f32 v[204:205], v[124:125], v[226:227], v[204:205]
	v_pk_add_f32 v[224:225], v[158:159], v[174:175] neg_lo:[0,1] neg_hi:[0,1]
	v_pk_add_f32 v[226:227], v[190:191], v[174:175] neg_lo:[0,1] neg_hi:[0,1]
	v_pk_fma_f32 v[206:207], v[110:111], v[224:225], v[174:175]
	v_pk_fma_f32 v[206:207], v[126:127], v[226:227], v[206:207]
	v_cvt_pk_bf16_f32 v208, v192, v193
	v_cvt_pk_bf16_f32 v209, v194, v195
	v_cvt_pk_bf16_f32 v210, v196, v197
	v_cvt_pk_bf16_f32 v211, v198, v199
	v_cvt_pk_bf16_f32 v212, v200, v201
	v_cvt_pk_bf16_f32 v213, v202, v203
	v_cvt_pk_bf16_f32 v214, v204, v205
	v_cvt_pk_bf16_f32 v215, v206, v207
	buffer_store_dwordx4 v[208:211], v237, s[68:71], s73 offen offset:0
	buffer_store_dwordx4 v[212:215], v237, s[68:71], s73 offen offset:16
	v_sub_f32_e32 v224, v136, v140
	v_sub_f32_e32 v225, v216, v140
	v_fma_f32 v220, v128, v224, v140
	v_fma_f32 v220, v132, v225, v220
	v_sub_f32_e32 v224, v137, v141
	v_sub_f32_e32 v225, v217, v141
	v_fma_f32 v221, v129, v224, v141
	v_fma_f32 v221, v133, v225, v221
	v_sub_f32_e32 v224, v138, v142
	v_sub_f32_e32 v225, v218, v142
	v_fma_f32 v222, v130, v224, v142
	v_fma_f32 v222, v134, v225, v222
	v_sub_f32_e32 v224, v139, v143
	v_sub_f32_e32 v225, v219, v143
	v_fma_f32 v223, v131, v224, v143
	v_fma_f32 v223, v135, v225, v223
	v_and_b32_e32 v224, 0x7fffffff, v220
	v_mul_f32_e32 v225, 0x4038aa3b, v224
	v_exp_f32_e32 v225, v225
	v_mul_f32_e32 v226, v220, v220
	v_add_f32_e32 v225, 1.0, v225
; __device__ __forceinline__ float bflo(unsigned w) { return __uint_as_float(w << 16); }
; __device__ __forceinline__ float bfhi(unsigned w) { return __uint_as_float(w & 0xffff0000u); }
; __device__ __forceinline__ unsigned cvt_pk_bf16(float lo, float hi) { unsigned r; asm volatile("v_cvt_pk_bf16_f32 %0, %1, %2" : "=v"(r) : "v"(lo), "v"(hi)); return r; }
; __device__ __forceinline__ void prep_phase(const Params& p) {
;     ...
;             for (int i = 0; i < 16; ++i) {
;                 const bool hn = (tt0 + i) < SEQ - 1; const u16* zn = zc + (size_t)(i + 1) * 3328;
;                 const Z16 vn = hn ? ldz(zn + 2048 + c) : zz(); const u32x2 ln = hn ? *(const u32x2*)(zn + cl) : (u32x2){0u, 0u};
;                 float v[16]; mix16(vp, vc, vn, mpv, mnv, v);
;                 st16bf(V + (size_t)(t0 + i) * RW + c, v);
;                 const float z4[4] = {bflo(lc.x), bfhi(lc.x), bflo(lc.y), bfhi(lc.y)}, p4[4] = {bflo(lp.x), bfhi(lp.x), bflo(lp.y), bfhi(lp.y)}, n4[4] = {bflo(ln.x), bfhi(ln.x), bflo(ln.y), bfhi(ln.y)};
;                 float o4[4];
; #pragma unroll
;                 for (int j = 0; j < 4; ++j) { const float sft = z4[j] + la[j] * (p4[j] - z4[j]) + lb[j] * (n4[j] - z4[j]); o4[j] = (lane < 32) ? tanhf(sft) : sft; }
;                 u32x2 w; w.x = cvt_pk_bf16(o4[0], o4[1]); w.y = cvt_pk_bf16(o4[2], o4[3]); *(u32x2*)(AL + (size_t)(t0 + i) * 256 + alc) = w;
;                 vp = vc; vc = vn; lp = lc; lc = ln;
	v_rcp_f32_e32 v225, v225
	v_mul_f32_e32 v227, 0xbeaaaaab, v226
	v_fma_f32 v225, v225, -2.0, 1.0
	v_fma_f32 v227, v227, v220, v220
	v_bfi_b32 v225, v241, v225, v220
	v_cmp_gt_f32_e32 vcc, 0x3d000000, v224
	s_nop 1
	v_cndmask_b32_e32 v225, v225, v227, vcc
	v_cmp_gt_u32_e32 vcc, 32, v240
	s_nop 1
	v_cndmask_b32_e32 v220, v220, v225, vcc
	v_and_b32_e32 v224, 0x7fffffff, v221
	v_mul_f32_e32 v225, 0x4038aa3b, v224
	v_exp_f32_e32 v225, v225
	v_mul_f32_e32 v226, v221, v221
	v_add_f32_e32 v225, 1.0, v225
	v_rcp_f32_e32 v225, v225
	v_mul_f32_e32 v227, 0xbeaaaaab, v226
	v_fma_f32 v225, v225, -2.0, 1.0
	v_fma_f32 v227, v227, v221, v221
	v_bfi_b32 v225, v241, v225, v221
	v_cmp_gt_f32_e32 vcc, 0x3d000000, v224
	s_nop 1
	v_cndmask_b32_e32 v225, v225, v227, vcc
	v_cmp_gt_u32_e32 vcc, 32, v240
	s_nop 1
	v_cndmask_b32_e32 v221, v221, v225, vcc
	v_and_b32_e32 v224, 0x7fffffff, v222
	v_mul_f32_e32 v225, 0x4038aa3b, v224
	v_exp_f32_e32 v225, v225
	v_mul_f32_e32 v226, v222, v222
	v_add_f32_e32 v225, 1.0, v225
	v_rcp_f32_e32 v225, v225
	v_mul_f32_e32 v227, 0xbeaaaaab, v226
	v_fma_f32 v225, v225, -2.0, 1.0
	v_fma_f32 v227, v227, v222, v222
	v_bfi_b32 v225, v241, v225, v222
	v_cmp_gt_f32_e32 vcc, 0x3d000000, v224
	s_nop 1
	v_cndmask_b32_e32 v225, v225, v227, vcc
	v_cmp_gt_u32_e32 vcc, 32, v240
	s_nop 1
	v_cndmask_b32_e32 v222, v222, v225, vcc
	v_and_b32_e32 v224, 0x7fffffff, v223
	v_mul_f32_e32 v225, 0x4038aa3b, v224
	v_exp_f32_e32 v225, v225
	v_mul_f32_e32 v226, v223, v223
	v_add_f32_e32 v225, 1.0, v225
	v_rcp_f32_e32 v225, v225
	v_mul_f32_e32 v227, 0xbeaaaaab, v226
	v_fma_f32 v225, v225, -2.0, 1.0
	v_fma_f32 v227, v227, v223, v223
	v_bfi_b32 v225, v241, v225, v223
	v_cmp_gt_f32_e32 vcc, 0x3d000000, v224
	s_nop 1
	v_cndmask_b32_e32 v225, v225, v227, vcc
	v_cmp_gt_u32_e32 vcc, 32, v240
	s_nop 1
	v_cndmask_b32_e32 v223, v223, v225, vcc
	v_cvt_pk_bf16_f32 v224, v220, v221
	v_cvt_pk_bf16_f32 v225, v222, v223
	buffer_store_dwordx2 v[224:225], v238, s[68:71], s74 offen
	s_add_u32 s72, s72, 0x1000
	s_add_u32 s73, s73, 0x800
	s_add_u32 s74, s74, 0x200
	s_add_u32 s75, s75, 0x40
	s_waitcnt vmcnt(30)
	v_lshlrev_b32_e32 v144, 16, v60
	v_and_b32_e32 v145, 0xffff0000, v60
	v_lshlrev_b32_e32 v146, 16, v61
	v_and_b32_e32 v147, 0xffff0000, v61
	v_lshlrev_b32_e32 v148, 16, v62
	v_and_b32_e32 v149, 0xffff0000, v62
	v_lshlrev_b32_e32 v150, 16, v63
	v_and_b32_e32 v151, 0xffff0000, v63
	v_lshlrev_b32_e32 v152, 16, v64
	v_and_b32_e32 v153, 0xffff0000, v64
	v_lshlrev_b32_e32 v154, 16, v65
	v_and_b32_e32 v155, 0xffff0000, v65
	v_lshlrev_b32_e32 v156, 16, v66
	v_and_b32_e32 v157, 0xffff0000, v66
	v_lshlrev_b32_e32 v158, 16, v67
	v_and_b32_e32 v159, 0xffff0000, v67
	v_lshlrev_b32_e32 v160, 16, v72
	v_and_b32_e32 v161, 0xffff0000, v72
	v_lshlrev_b32_e32 v162, 16, v73
	v_and_b32_e32 v163, 0xffff0000, v73
	v_lshlrev_b32_e32 v164, 16, v74
	v_and_b32_e32 v165, 0xffff0000, v74
	v_lshlrev_b32_e32 v166, 16, v75
	v_and_b32_e32 v167, 0xffff0000, v75
	v_lshlrev_b32_e32 v168, 16, v76
	v_and_b32_e32 v169, 0xffff0000, v76
	v_lshlrev_b32_e32 v170, 16, v77
	v_and_b32_e32 v171, 0xffff0000, v77
	v_lshlrev_b32_e32 v172, 16, v78
	v_and_b32_e32 v173, 0xffff0000, v78
	v_lshlrev_b32_e32 v174, 16, v79
	v_and_b32_e32 v175, 0xffff0000, v79
	v_lshlrev_b32_e32 v176, 16, v84
	v_and_b32_e32 v177, 0xffff0000, v84
	v_lshlrev_b32_e32 v178, 16, v85
	v_and_b32_e32 v179, 0xffff0000, v85
	v_lshlrev_b32_e32 v180, 16, v86
	v_and_b32_e32 v181, 0xffff0000, v86
	v_lshlrev_b32_e32 v182, 16, v87
	v_and_b32_e32 v183, 0xffff0000, v87
	v_lshlrev_b32_e32 v184, 16, v88
	v_and_b32_e32 v185, 0xffff0000, v88
	v_lshlrev_b32_e32 v186, 16, v89
	v_and_b32_e32 v187, 0xffff0000, v89
	v_lshlrev_b32_e32 v188, 16, v90
	v_and_b32_e32 v189, 0xffff0000, v90
	v_lshlrev_b32_e32 v190, 16, v91
	v_and_b32_e32 v191, 0xffff0000, v91
	v_lshlrev_b32_e32 v136, 16, v68
	v_and_b32_e32 v137, 0xffff0000, v68
	v_lshlrev_b32_e32 v138, 16, v69
	v_and_b32_e32 v139, 0xffff0000, v69
	v_lshlrev_b32_e32 v140, 16, v80
	v_and_b32_e32 v141, 0xffff0000, v80
	v_lshlrev_b32_e32 v142, 16, v81
	v_and_b32_e32 v143, 0xffff0000, v81
	v_lshlrev_b32_e32 v216, 16, v92
	v_and_b32_e32 v217, 0xffff0000, v92
	v_lshlrev_b32_e32 v218, 16, v93
	v_and_b32_e32 v219, 0xffff0000, v93
	buffer_load_dwordx4 v[60:63], v232, s[64:67], 0 offen offset:4064 nt
	buffer_load_dwordx4 v[64:67], v232, s[64:67], 0 offen offset:4080 nt
	buffer_load_dwordx2 v[68:69], v233, s[64:67], 0 offen nt
	v_add_u32_e32 v233, 6656, v233
	v_add_u32_e32 v232, 6656, v232
	v_pk_add_f32 v[224:225], v[144:145], v[160:161] neg_lo:[0,1] neg_hi:[0,1]
	v_pk_add_f32 v[226:227], v[176:177], v[160:161] neg_lo:[0,1] neg_hi:[0,1]
	v_pk_fma_f32 v[192:193], v[96:97], v[224:225], v[160:161]
	v_pk_fma_f32 v[192:193], v[112:113], v[226:227], v[192:193]
	v_pk_add_f32 v[224:225], v[146:147], v[162:163] neg_lo:[0,1] neg_hi:[0,1]
	v_pk_add_f32 v[226:227], v[178:179], v[162:163] neg_lo:[0,1] neg_hi:[0,1]
	v_pk_fma_f32 v[194:195], v[98:99], v[224:225], v[162:163]
	v_pk_fma_f32 v[194:195], v[114:115], v[226:227], v[194:195]
	v_pk_add_f32 v[224:225], v[148:149], v[164:165] neg_lo:[0,1] neg_hi:[0,1]
	v_pk_add_f32 v[226:227], v[180:181], v[164:165] neg_lo:[0,1] neg_hi:[0,1]
	v_pk_fma_f32 v[196:197], v[100:101], v[224:225], v[164:165]
	v_pk_fma_f32 v[196:197], v[116:117], v[226:227], v[196:197]
	v_pk_add_f32 v[224:225], v[150:151], v[166:167] neg_lo:[0,1] neg_hi:[0,1]
	v_pk_add_f32 v[226:227], v[182:183], v[166:167] neg_lo:[0,1] neg_hi:[0,1]
	v_pk_fma_f32 v[198:199], v[102:103], v[224:225], v[166:167]
	v_pk_fma_f32 v[198:199], v[118:119], v[226:227], v[198:199]
	v_pk_add_f32 v[224:225], v[152:153], v[168:169] neg_lo:[0,1] neg_hi:[0,1]
; __device__ __forceinline__ float bflo(unsigned w) { return __uint_as_float(w << 16); }
; __device__ __forceinline__ float bfhi(unsigned w) { return __uint_as_float(w & 0xffff0000u); }
; __device__ __forceinline__ unsigned cvt_pk_bf16(float lo, float hi) { unsigned r; asm volatile("v_cvt_pk_bf16_f32 %0, %1, %2" : "=v"(r) : "v"(lo), "v"(hi)); return r; }
; __device__ __forceinline__ void prep_phase(const Params& p) {
;     ...
;                 float v[16]; mix16(vp, vc, vn, mpv, mnv, v);
;                 st16bf(V + (size_t)(t0 + i) * RW + c, v);
;                 const float z4[4] = {bflo(lc.x), bfhi(lc.x), bflo(lc.y), bfhi(lc.y)}, p4[4] = {bflo(lp.x), bfhi(lp.x), bflo(lp.y), bfhi(lp.y)}, n4[4] = {bflo(ln.x), bfhi(ln.x), bflo(ln.y), bfhi(ln.y)};
;                 float o4[4];
; #pragma unroll
;                 for (int j = 0; j < 4; ++j) { const float sft = z4[j] + la[j] * (p4[j] - z4[j]) + lb[j] * (n4[j] - z4[j]); o4[j] = (lane < 32) ? tanhf(sft) : sft; }
;                 u32x2 w; w.x = cvt_pk_bf16(o4[0], o4[1]); w.y = cvt_pk_bf16(o4[2], o4[3]); *(u32x2*)(AL + (size_t)(t0 + i) * 256 + alc) = w;
;                 vp = vc; vc = vn; lp = lc; lc = ln;
	v_pk_add_f32 v[226:227], v[184:185], v[168:169] neg_lo:[0,1] neg_hi:[0,1]
	v_pk_fma_f32 v[200:201], v[104:105], v[224:225], v[168:169]
	v_pk_fma_f32 v[200:201], v[120:121], v[226:227], v[200:201]
	v_pk_add_f32 v[224:225], v[154:155], v[170:171] neg_lo:[0,1] neg_hi:[0,1]
	v_pk_add_f32 v[226:227], v[186:187], v[170:171] neg_lo:[0,1] neg_hi:[0,1]
	v_pk_fma_f32 v[202:203], v[106:107], v[224:225], v[170:171]
	v_pk_fma_f32 v[202:203], v[122:123], v[226:227], v[202:203]
	v_pk_add_f32 v[224:225], v[156:157], v[172:173] neg_lo:[0,1] neg_hi:[0,1]
	v_pk_add_f32 v[226:227], v[188:189], v[172:173] neg_lo:[0,1] neg_hi:[0,1]
	v_pk_fma_f32 v[204:205], v[108:109], v[224:225], v[172:173]
	v_pk_fma_f32 v[204:205], v[124:125], v[226:227], v[204:205]
	v_pk_add_f32 v[224:225], v[158:159], v[174:175] neg_lo:[0,1] neg_hi:[0,1]
	v_pk_add_f32 v[226:227], v[190:191], v[174:175] neg_lo:[0,1] neg_hi:[0,1]
	v_pk_fma_f32 v[206:207], v[110:111], v[224:225], v[174:175]
	v_pk_fma_f32 v[206:207], v[126:127], v[226:227], v[206:207]
	v_cvt_pk_bf16_f32 v208, v192, v193
	v_cvt_pk_bf16_f32 v209, v194, v195
	v_cvt_pk_bf16_f32 v210, v196, v197
	v_cvt_pk_bf16_f32 v211, v198, v199
	v_cvt_pk_bf16_f32 v212, v200, v201
	v_cvt_pk_bf16_f32 v213, v202, v203
	v_cvt_pk_bf16_f32 v214, v204, v205
	v_cvt_pk_bf16_f32 v215, v206, v207
	buffer_store_dwordx4 v[208:211], v237, s[68:71], s73 offen offset:0
	buffer_store_dwordx4 v[212:215], v237, s[68:71], s73 offen offset:16
	v_sub_f32_e32 v224, v136, v140
	v_sub_f32_e32 v225, v216, v140
	v_fma_f32 v220, v128, v224, v140
	v_fma_f32 v220, v132, v225, v220
	v_sub_f32_e32 v224, v137, v141
	v_sub_f32_e32 v225, v217, v141
	v_fma_f32 v221, v129, v224, v141
	v_fma_f32 v221, v133, v225, v221
	v_sub_f32_e32 v224, v138, v142
	v_sub_f32_e32 v225, v218, v142
	v_fma_f32 v222, v130, v224, v142
	v_fma_f32 v222, v134, v225, v222
	v_sub_f32_e32 v224, v139, v143
	v_sub_f32_e32 v225, v219, v143
	v_fma_f32 v223, v131, v224, v143
	v_fma_f32 v223, v135, v225, v223
	v_and_b32_e32 v224, 0x7fffffff, v220
	v_mul_f32_e32 v225, 0x4038aa3b, v224
	v_exp_f32_e32 v225, v225
	v_mul_f32_e32 v226, v220, v220
	v_add_f32_e32 v225, 1.0, v225
	v_rcp_f32_e32 v225, v225
	v_mul_f32_e32 v227, 0xbeaaaaab, v226
	v_fma_f32 v225, v225, -2.0, 1.0
	v_fma_f32 v227, v227, v220, v220
	v_bfi_b32 v225, v241, v225, v220
	v_cmp_gt_f32_e32 vcc, 0x3d000000, v224
	s_nop 1
	v_cndmask_b32_e32 v225, v225, v227, vcc
	v_cmp_gt_u32_e32 vcc, 32, v240
	s_nop 1
	v_cndmask_b32_e32 v220, v220, v225, vcc
	v_and_b32_e32 v224, 0x7fffffff, v221
	v_mul_f32_e32 v225, 0x4038aa3b, v224
	v_exp_f32_e32 v225, v225
	v_mul_f32_e32 v226, v221, v221
	v_add_f32_e32 v225, 1.0, v225
	v_rcp_f32_e32 v225, v225
	v_mul_f32_e32 v227, 0xbeaaaaab, v226
	v_fma_f32 v225, v225, -2.0, 1.0
	v_fma_f32 v227, v227, v221, v221
	v_bfi_b32 v225, v241, v225, v221
	v_cmp_gt_f32_e32 vcc, 0x3d000000, v224
	s_nop 1
	v_cndmask_b32_e32 v225, v225, v227, vcc
	v_cmp_gt_u32_e32 vcc, 32, v240
	s_nop 1
	v_cndmask_b32_e32 v221, v221, v225, vcc
	v_and_b32_e32 v224, 0x7fffffff, v222
	v_mul_f32_e32 v225, 0x4038aa3b, v224
	v_exp_f32_e32 v225, v225
	v_mul_f32_e32 v226, v222, v222
	v_add_f32_e32 v225, 1.0, v225
	v_rcp_f32_e32 v225, v225
	v_mul_f32_e32 v227, 0xbeaaaaab, v226
	v_fma_f32 v225, v225, -2.0, 1.0
	v_fma_f32 v227, v227, v222, v222
	v_bfi_b32 v225, v241, v225, v222
	v_cmp_gt_f32_e32 vcc, 0x3d000000, v224
	s_nop 1
	v_cndmask_b32_e32 v225, v225, v227, vcc
	v_cmp_gt_u32_e32 vcc, 32, v240
	s_nop 1
	v_cndmask_b32_e32 v222, v222, v225, vcc
	v_and_b32_e32 v224, 0x7fffffff, v223
	v_mul_f32_e32 v225, 0x4038aa3b, v224
	v_exp_f32_e32 v225, v225
	v_mul_f32_e32 v226, v223, v223
	v_add_f32_e32 v225, 1.0, v225
	v_rcp_f32_e32 v225, v225
	v_mul_f32_e32 v227, 0xbeaaaaab, v226
	v_fma_f32 v225, v225, -2.0, 1.0
	v_fma_f32 v227, v227, v223, v223
	v_bfi_b32 v225, v241, v225, v223
	v_cmp_gt_f32_e32 vcc, 0x3d000000, v224
	s_nop 1
	v_cndmask_b32_e32 v225, v225, v227, vcc
	v_cmp_gt_u32_e32 vcc, 32, v240
	s_nop 1
	v_cndmask_b32_e32 v223, v223, v225, vcc
	v_cvt_pk_bf16_f32 v224, v220, v221
	v_cvt_pk_bf16_f32 v225, v222, v223
	buffer_store_dwordx2 v[224:225], v238, s[68:71], s74 offen
	s_add_u32 s72, s72, 0x1000
	s_add_u32 s73, s73, 0x800
	s_add_u32 s74, s74, 0x200
	s_add_u32 s75, s75, 0x40
	s_waitcnt vmcnt(33)
; __device__ __forceinline__ float bflo(unsigned w) { return __uint_as_float(w << 16); }
; __device__ __forceinline__ float bfhi(unsigned w) { return __uint_as_float(w & 0xffff0000u); }
; __device__ __forceinline__ unsigned cvt_pk_bf16(float lo, float hi) { unsigned r; asm volatile("v_cvt_pk_bf16_f32 %0, %1, %2" : "=v"(r) : "v"(lo), "v"(hi)); return r; }
; __device__ __forceinline__ void prep_phase(const Params& p) {
;     ...
;             for (int i = 0; i < 16; ++i) {
;                 const bool hn = (tt0 + i) < SEQ - 1; const u16* zn = zc + (size_t)(i + 1) * 3328;
;                 const Z16 vn = hn ? ldz(zn + 2048 + c) : zz(); const u32x2 ln = hn ? *(const u32x2*)(zn + cl) : (u32x2){0u, 0u};
;                 float v[16]; mix16(vp, vc, vn, mpv, mnv, v);
;                 st16bf(V + (size_t)(t0 + i) * RW + c, v);
;                 const float z4[4] = {bflo(lc.x), bfhi(lc.x), bflo(lc.y), bfhi(lc.y)}, p4[4] = {bflo(lp.x), bfhi(lp.x), bflo(lp.y), bfhi(lp.y)}, n4[4] = {bflo(ln.x), bfhi(ln.x), bflo(ln.y), bfhi(ln.y)};
;                 float o4[4];
; #pragma unroll
;                 for (int j = 0; j < 4; ++j) { const float sft = z4[j] + la[j] * (p4[j] - z4[j]) + lb[j] * (n4[j] - z4[j]); o4[j] = (lane < 32) ? tanhf(sft) : sft; }
;                 u32x2 w; w.x = cvt_pk_bf16(o4[0], o4[1]); w.y = cvt_pk_bf16(o4[2], o4[3]); *(u32x2*)(AL + (size_t)(t0 + i) * 256 + alc) = w;
;                 vp = vc; vc = vn; lp = lc; lc = ln;
	v_lshlrev_b32_e32 v144, 16, v72
	v_and_b32_e32 v145, 0xffff0000, v72
	v_lshlrev_b32_e32 v146, 16, v73
	v_and_b32_e32 v147, 0xffff0000, v73
	v_lshlrev_b32_e32 v148, 16, v74
	v_and_b32_e32 v149, 0xffff0000, v74
	v_lshlrev_b32_e32 v150, 16, v75
	v_and_b32_e32 v151, 0xffff0000, v75
	v_lshlrev_b32_e32 v152, 16, v76
	v_and_b32_e32 v153, 0xffff0000, v76
	v_lshlrev_b32_e32 v154, 16, v77
	v_and_b32_e32 v155, 0xffff0000, v77
	v_lshlrev_b32_e32 v156, 16, v78
	v_and_b32_e32 v157, 0xffff0000, v78
	v_lshlrev_b32_e32 v158, 16, v79
	v_and_b32_e32 v159, 0xffff0000, v79
	v_lshlrev_b32_e32 v160, 16, v84
	v_and_b32_e32 v161, 0xffff0000, v84
	v_lshlrev_b32_e32 v162, 16, v85
	v_and_b32_e32 v163, 0xffff0000, v85
	v_lshlrev_b32_e32 v164, 16, v86
	v_and_b32_e32 v165, 0xffff0000, v86
	v_lshlrev_b32_e32 v166, 16, v87
	v_and_b32_e32 v167, 0xffff0000, v87
	v_lshlrev_b32_e32 v168, 16, v88
	v_and_b32_e32 v169, 0xffff0000, v88
	v_lshlrev_b32_e32 v170, 16, v89
	v_and_b32_e32 v171, 0xffff0000, v89
	v_lshlrev_b32_e32 v172, 16, v90
	v_and_b32_e32 v173, 0xffff0000, v90
	v_lshlrev_b32_e32 v174, 16, v91
	v_and_b32_e32 v175, 0xffff0000, v91
	v_lshlrev_b32_e32 v176, 16, v0
	v_and_b32_e32 v177, 0xffff0000, v0
	v_lshlrev_b32_e32 v178, 16, v1
	v_and_b32_e32 v179, 0xffff0000, v1
	v_lshlrev_b32_e32 v180, 16, v2
	v_and_b32_e32 v181, 0xffff0000, v2
	v_lshlrev_b32_e32 v182, 16, v3
	v_and_b32_e32 v183, 0xffff0000, v3
	v_lshlrev_b32_e32 v184, 16, v4
	v_and_b32_e32 v185, 0xffff0000, v4
	v_lshlrev_b32_e32 v186, 16, v5
	v_and_b32_e32 v187, 0xffff0000, v5
	v_lshlrev_b32_e32 v188, 16, v6
	v_and_b32_e32 v189, 0xffff0000, v6
	v_lshlrev_b32_e32 v190, 16, v7
	v_and_b32_e32 v191, 0xffff0000, v7
	v_lshlrev_b32_e32 v136, 16, v80
	v_and_b32_e32 v137, 0xffff0000, v80
	v_lshlrev_b32_e32 v138, 16, v81
	v_and_b32_e32 v139, 0xffff0000, v81
	v_lshlrev_b32_e32 v140, 16, v92
	v_and_b32_e32 v141, 0xffff0000, v92
	v_lshlrev_b32_e32 v142, 16, v93
	v_and_b32_e32 v143, 0xffff0000, v93
	v_lshlrev_b32_e32 v216, 16, v8
	v_and_b32_e32 v217, 0xffff0000, v8
	v_lshlrev_b32_e32 v218, 16, v9
	v_and_b32_e32 v219, 0xffff0000, v9
	buffer_load_dwordx4 v[72:75], v232, s[64:67], 0 offen offset:4064 nt
	buffer_load_dwordx4 v[76:79], v232, s[64:67], 0 offen offset:4080 nt
	buffer_load_dwordx2 v[80:81], v233, s[64:67], 0 offen nt
	v_add_u32_e32 v233, 6656, v233
	v_add_u32_e32 v232, 6656, v232
	v_pk_add_f32 v[224:225], v[144:145], v[160:161] neg_lo:[0,1] neg_hi:[0,1]
	v_pk_add_f32 v[226:227], v[176:177], v[160:161] neg_lo:[0,1] neg_hi:[0,1]
	v_pk_fma_f32 v[192:193], v[96:97], v[224:225], v[160:161]
	v_pk_fma_f32 v[192:193], v[112:113], v[226:227], v[192:193]
	v_pk_add_f32 v[224:225], v[146:147], v[162:163] neg_lo:[0,1] neg_hi:[0,1]
	v_pk_add_f32 v[226:227], v[178:179], v[162:163] neg_lo:[0,1] neg_hi:[0,1]
	v_pk_fma_f32 v[194:195], v[98:99], v[224:225], v[162:163]
	v_pk_fma_f32 v[194:195], v[114:115], v[226:227], v[194:195]
	v_pk_add_f32 v[224:225], v[148:149], v[164:165] neg_lo:[0,1] neg_hi:[0,1]
	v_pk_add_f32 v[226:227], v[180:181], v[164:165] neg_lo:[0,1] neg_hi:[0,1]
	v_pk_fma_f32 v[196:197], v[100:101], v[224:225], v[164:165]
	v_pk_fma_f32 v[196:197], v[116:117], v[226:227], v[196:197]
	v_pk_add_f32 v[224:225], v[150:151], v[166:167] neg_lo:[0,1] neg_hi:[0,1]
	v_pk_add_f32 v[226:227], v[182:183], v[166:167] neg_lo:[0,1] neg_hi:[0,1]
	v_pk_fma_f32 v[198:199], v[102:103], v[224:225], v[166:167]
	v_pk_fma_f32 v[198:199], v[118:119], v[226:227], v[198:199]
	v_pk_add_f32 v[224:225], v[152:153], v[168:169] neg_lo:[0,1] neg_hi:[0,1]
	v_pk_add_f32 v[226:227], v[184:185], v[168:169] neg_lo:[0,1] neg_hi:[0,1]
	v_pk_fma_f32 v[200:201], v[104:105], v[224:225], v[168:169]
	v_pk_fma_f32 v[200:201], v[120:121], v[226:227], v[200:201]
	v_pk_add_f32 v[224:225], v[154:155], v[170:171] neg_lo:[0,1] neg_hi:[0,1]
	v_pk_add_f32 v[226:227], v[186:187], v[170:171] neg_lo:[0,1] neg_hi:[0,1]
	v_pk_fma_f32 v[202:203], v[106:107], v[224:225], v[170:171]
	v_pk_fma_f32 v[202:203], v[122:123], v[226:227], v[202:203]
	v_pk_add_f32 v[224:225], v[156:157], v[172:173] neg_lo:[0,1] neg_hi:[0,1]
	v_pk_add_f32 v[226:227], v[188:189], v[172:173] neg_lo:[0,1] neg_hi:[0,1]
	v_pk_fma_f32 v[204:205], v[108:109], v[224:225], v[172:173]
	v_pk_fma_f32 v[204:205], v[124:125], v[226:227], v[204:205]
	v_pk_add_f32 v[224:225], v[158:159], v[174:175] neg_lo:[0,1] neg_hi:[0,1]
	v_pk_add_f32 v[226:227], v[190:191], v[174:175] neg_lo:[0,1] neg_hi:[0,1]
	v_pk_fma_f32 v[206:207], v[110:111], v[224:225], v[174:175]
	v_pk_fma_f32 v[206:207], v[126:127], v[226:227], v[206:207]
	v_cvt_pk_bf16_f32 v208, v192, v193
	v_cvt_pk_bf16_f32 v209, v194, v195
	v_cvt_pk_bf16_f32 v210, v196, v197
	v_cvt_pk_bf16_f32 v211, v198, v199
	v_cvt_pk_bf16_f32 v212, v200, v201
	v_cvt_pk_bf16_f32 v213, v202, v203
	v_cvt_pk_bf16_f32 v214, v204, v205
	v_cvt_pk_bf16_f32 v215, v206, v207
	buffer_store_dwordx4 v[208:211], v237, s[68:71], s73 offen offset:0
	buffer_store_dwordx4 v[212:215], v237, s[68:71], s73 offen offset:16
	v_sub_f32_e32 v224, v136, v140
	v_sub_f32_e32 v225, v216, v140
	v_fma_f32 v220, v128, v224, v140
	v_fma_f32 v220, v132, v225, v220
	v_sub_f32_e32 v224, v137, v141
	v_sub_f32_e32 v225, v217, v141
	v_fma_f32 v221, v129, v224, v141
	v_fma_f32 v221, v133, v225, v221
	v_sub_f32_e32 v224, v138, v142
	v_sub_f32_e32 v225, v218, v142
	v_fma_f32 v222, v130, v224, v142
	v_fma_f32 v222, v134, v225, v222
	v_sub_f32_e32 v224, v139, v143
	v_sub_f32_e32 v225, v219, v143
	v_fma_f32 v223, v131, v224, v143
	v_fma_f32 v223, v135, v225, v223
	v_and_b32_e32 v224, 0x7fffffff, v220
	v_mul_f32_e32 v225, 0x4038aa3b, v224
	v_exp_f32_e32 v225, v225
	v_mul_f32_e32 v226, v220, v220
	v_add_f32_e32 v225, 1.0, v225
; __device__ __forceinline__ float bflo(unsigned w) { return __uint_as_float(w << 16); }
; __device__ __forceinline__ float bfhi(unsigned w) { return __uint_as_float(w & 0xffff0000u); }
; __device__ __forceinline__ unsigned cvt_pk_bf16(float lo, float hi) { unsigned r; asm volatile("v_cvt_pk_bf16_f32 %0, %1, %2" : "=v"(r) : "v"(lo), "v"(hi)); return r; }
; __device__ __forceinline__ void prep_phase(const Params& p) {
;     ...
;             for (int i = 0; i < 16; ++i) {
;                 const bool hn = (tt0 + i) < SEQ - 1; const u16* zn = zc + (size_t)(i + 1) * 3328;
;                 const Z16 vn = hn ? ldz(zn + 2048 + c) : zz(); const u32x2 ln = hn ? *(const u32x2*)(zn + cl) : (u32x2){0u, 0u};
;                 float v[16]; mix16(vp, vc, vn, mpv, mnv, v);
;                 st16bf(V + (size_t)(t0 + i) * RW + c, v);
;                 const float z4[4] = {bflo(lc.x), bfhi(lc.x), bflo(lc.y), bfhi(lc.y)}, p4[4] = {bflo(lp.x), bfhi(lp.x), bflo(lp.y), bfhi(lp.y)}, n4[4] = {bflo(ln.x), bfhi(ln.x), bflo(ln.y), bfhi(ln.y)};
;                 float o4[4];
; #pragma unroll
;                 for (int j = 0; j < 4; ++j) { const float sft = z4[j] + la[j] * (p4[j] - z4[j]) + lb[j] * (n4[j] - z4[j]); o4[j] = (lane < 32) ? tanhf(sft) : sft; }
;                 u32x2 w; w.x = cvt_pk_bf16(o4[0], o4[1]); w.y = cvt_pk_bf16(o4[2], o4[3]); *(u32x2*)(AL + (size_t)(t0 + i) * 256 + alc) = w;
;                 vp = vc; vc = vn; lp = lc; lc = ln;
	v_rcp_f32_e32 v225, v225
	v_mul_f32_e32 v227, 0xbeaaaaab, v226
	v_fma_f32 v225, v225, -2.0, 1.0
	v_fma_f32 v227, v227, v220, v220
	v_bfi_b32 v225, v241, v225, v220
	v_cmp_gt_f32_e32 vcc, 0x3d000000, v224
	s_nop 1
	v_cndmask_b32_e32 v225, v225, v227, vcc
	v_cmp_gt_u32_e32 vcc, 32, v240
	s_nop 1
	v_cndmask_b32_e32 v220, v220, v225, vcc
	v_and_b32_e32 v224, 0x7fffffff, v221
	v_mul_f32_e32 v225, 0x4038aa3b, v224
	v_exp_f32_e32 v225, v225
	v_mul_f32_e32 v226, v221, v221
	v_add_f32_e32 v225, 1.0, v225
	v_rcp_f32_e32 v225, v225
	v_mul_f32_e32 v227, 0xbeaaaaab, v226
	v_fma_f32 v225, v225, -2.0, 1.0
	v_fma_f32 v227, v227, v221, v221
	v_bfi_b32 v225, v241, v225, v221
	v_cmp_gt_f32_e32 vcc, 0x3d000000, v224
	s_nop 1
	v_cndmask_b32_e32 v225, v225, v227, vcc
	v_cmp_gt_u32_e32 vcc, 32, v240
	s_nop 1
	v_cndmask_b32_e32 v221, v221, v225, vcc
	v_and_b32_e32 v224, 0x7fffffff, v222
	v_mul_f32_e32 v225, 0x4038aa3b, v224
	v_exp_f32_e32 v225, v225
	v_mul_f32_e32 v226, v222, v222
	v_add_f32_e32 v225, 1.0, v225
	v_rcp_f32_e32 v225, v225
	v_mul_f32_e32 v227, 0xbeaaaaab, v226
	v_fma_f32 v225, v225, -2.0, 1.0
	v_fma_f32 v227, v227, v222, v222
	v_bfi_b32 v225, v241, v225, v222
	v_cmp_gt_f32_e32 vcc, 0x3d000000, v224
	s_nop 1
	v_cndmask_b32_e32 v225, v225, v227, vcc
	v_cmp_gt_u32_e32 vcc, 32, v240
	s_nop 1
	v_cndmask_b32_e32 v222, v222, v225, vcc
	v_and_b32_e32 v224, 0x7fffffff, v223
	v_mul_f32_e32 v225, 0x4038aa3b, v224
	v_exp_f32_e32 v225, v225
	v_mul_f32_e32 v226, v223, v223
	v_add_f32_e32 v225, 1.0, v225
	v_rcp_f32_e32 v225, v225
	v_mul_f32_e32 v227, 0xbeaaaaab, v226
	v_fma_f32 v225, v225, -2.0, 1.0
	v_fma_f32 v227, v227, v223, v223
	v_bfi_b32 v225, v241, v225, v223
	v_cmp_gt_f32_e32 vcc, 0x3d000000, v224
	s_nop 1
	v_cndmask_b32_e32 v225, v225, v227, vcc
	v_cmp_gt_u32_e32 vcc, 32, v240
	s_nop 1
	v_cndmask_b32_e32 v223, v223, v225, vcc
	v_cvt_pk_bf16_f32 v224, v220, v221
	v_cvt_pk_bf16_f32 v225, v222, v223
	buffer_store_dwordx2 v[224:225], v238, s[68:71], s74 offen
	s_add_u32 s72, s72, 0x1000
	s_add_u32 s73, s73, 0x800
	s_add_u32 s74, s74, 0x200
	s_add_u32 s75, s75, 0x40
	s_waitcnt vmcnt(33)
	v_lshlrev_b32_e32 v144, 16, v84
	v_and_b32_e32 v145, 0xffff0000, v84
	v_lshlrev_b32_e32 v146, 16, v85
	v_and_b32_e32 v147, 0xffff0000, v85
	v_lshlrev_b32_e32 v148, 16, v86
	v_and_b32_e32 v149, 0xffff0000, v86
	v_lshlrev_b32_e32 v150, 16, v87
	v_and_b32_e32 v151, 0xffff0000, v87
	v_lshlrev_b32_e32 v152, 16, v88
	v_and_b32_e32 v153, 0xffff0000, v88
	v_lshlrev_b32_e32 v154, 16, v89
	v_and_b32_e32 v155, 0xffff0000, v89
	v_lshlrev_b32_e32 v156, 16, v90
	v_and_b32_e32 v157, 0xffff0000, v90
	v_lshlrev_b32_e32 v158, 16, v91
	v_and_b32_e32 v159, 0xffff0000, v91
	v_lshlrev_b32_e32 v160, 16, v0
	v_and_b32_e32 v161, 0xffff0000, v0
	v_lshlrev_b32_e32 v162, 16, v1
	v_and_b32_e32 v163, 0xffff0000, v1
	v_lshlrev_b32_e32 v164, 16, v2
	v_and_b32_e32 v165, 0xffff0000, v2
	v_lshlrev_b32_e32 v166, 16, v3
	v_and_b32_e32 v167, 0xffff0000, v3
	v_lshlrev_b32_e32 v168, 16, v4
	v_and_b32_e32 v169, 0xffff0000, v4
	v_lshlrev_b32_e32 v170, 16, v5
	v_and_b32_e32 v171, 0xffff0000, v5
	v_lshlrev_b32_e32 v172, 16, v6
	v_and_b32_e32 v173, 0xffff0000, v6
	v_lshlrev_b32_e32 v174, 16, v7
	v_and_b32_e32 v175, 0xffff0000, v7
	v_lshlrev_b32_e32 v176, 16, v12
	v_and_b32_e32 v177, 0xffff0000, v12
	v_lshlrev_b32_e32 v178, 16, v13
	v_and_b32_e32 v179, 0xffff0000, v13
	v_lshlrev_b32_e32 v180, 16, v14
	v_and_b32_e32 v181, 0xffff0000, v14
	v_lshlrev_b32_e32 v182, 16, v15
	v_and_b32_e32 v183, 0xffff0000, v15
	v_lshlrev_b32_e32 v184, 16, v16
	v_and_b32_e32 v185, 0xffff0000, v16
	v_lshlrev_b32_e32 v186, 16, v17
	v_and_b32_e32 v187, 0xffff0000, v17
	v_lshlrev_b32_e32 v188, 16, v18
	v_and_b32_e32 v189, 0xffff0000, v18
	v_lshlrev_b32_e32 v190, 16, v19
	v_and_b32_e32 v191, 0xffff0000, v19
	v_lshlrev_b32_e32 v136, 16, v92
	v_and_b32_e32 v137, 0xffff0000, v92
	v_lshlrev_b32_e32 v138, 16, v93
	v_and_b32_e32 v139, 0xffff0000, v93
	v_lshlrev_b32_e32 v140, 16, v8
	v_and_b32_e32 v141, 0xffff0000, v8
	v_lshlrev_b32_e32 v142, 16, v9
	v_and_b32_e32 v143, 0xffff0000, v9
	v_lshlrev_b32_e32 v216, 16, v20
	v_and_b32_e32 v217, 0xffff0000, v20
	v_lshlrev_b32_e32 v218, 16, v21
	v_and_b32_e32 v219, 0xffff0000, v21
	buffer_load_dwordx4 v[84:87], v232, s[64:67], 0 offen offset:4064 nt
	buffer_load_dwordx4 v[88:91], v232, s[64:67], 0 offen offset:4080 nt
	buffer_load_dwordx2 v[92:93], v233, s[64:67], 0 offen nt
	v_add_u32_e32 v233, 6656, v233
	v_add_u32_e32 v232, 6656, v232
	v_pk_add_f32 v[224:225], v[144:145], v[160:161] neg_lo:[0,1] neg_hi:[0,1]
	v_pk_add_f32 v[226:227], v[176:177], v[160:161] neg_lo:[0,1] neg_hi:[0,1]
	v_pk_fma_f32 v[192:193], v[96:97], v[224:225], v[160:161]
	v_pk_fma_f32 v[192:193], v[112:113], v[226:227], v[192:193]
	v_pk_add_f32 v[224:225], v[146:147], v[162:163] neg_lo:[0,1] neg_hi:[0,1]
	v_pk_add_f32 v[226:227], v[178:179], v[162:163] neg_lo:[0,1] neg_hi:[0,1]
	v_pk_fma_f32 v[194:195], v[98:99], v[224:225], v[162:163]
	v_pk_fma_f32 v[194:195], v[114:115], v[226:227], v[194:195]
	v_pk_add_f32 v[224:225], v[148:149], v[164:165] neg_lo:[0,1] neg_hi:[0,1]
	v_pk_add_f32 v[226:227], v[180:181], v[164:165] neg_lo:[0,1] neg_hi:[0,1]
	v_pk_fma_f32 v[196:197], v[100:101], v[224:225], v[164:165]
	v_pk_fma_f32 v[196:197], v[116:117], v[226:227], v[196:197]
	v_pk_add_f32 v[224:225], v[150:151], v[166:167] neg_lo:[0,1] neg_hi:[0,1]
	v_pk_add_f32 v[226:227], v[182:183], v[166:167] neg_lo:[0,1] neg_hi:[0,1]
	v_pk_fma_f32 v[198:199], v[102:103], v[224:225], v[166:167]
	v_pk_fma_f32 v[198:199], v[118:119], v[226:227], v[198:199]
	v_pk_add_f32 v[224:225], v[152:153], v[168:169] neg_lo:[0,1] neg_hi:[0,1]
; __device__ __forceinline__ float bflo(unsigned w) { return __uint_as_float(w << 16); }
; __device__ __forceinline__ float bfhi(unsigned w) { return __uint_as_float(w & 0xffff0000u); }
; __device__ __forceinline__ unsigned cvt_pk_bf16(float lo, float hi) { unsigned r; asm volatile("v_cvt_pk_bf16_f32 %0, %1, %2" : "=v"(r) : "v"(lo), "v"(hi)); return r; }
; __device__ __forceinline__ void prep_phase(const Params& p) {
;     ...
;                 float v[16]; mix16(vp, vc, vn, mpv, mnv, v);
;                 st16bf(V + (size_t)(t0 + i) * RW + c, v);
;                 const float z4[4] = {bflo(lc.x), bfhi(lc.x), bflo(lc.y), bfhi(lc.y)}, p4[4] = {bflo(lp.x), bfhi(lp.x), bflo(lp.y), bfhi(lp.y)}, n4[4] = {bflo(ln.x), bfhi(ln.x), bflo(ln.y), bfhi(ln.y)};
;                 float o4[4];
; #pragma unroll
;                 for (int j = 0; j < 4; ++j) { const float sft = z4[j] + la[j] * (p4[j] - z4[j]) + lb[j] * (n4[j] - z4[j]); o4[j] = (lane < 32) ? tanhf(sft) : sft; }
;                 u32x2 w; w.x = cvt_pk_bf16(o4[0], o4[1]); w.y = cvt_pk_bf16(o4[2], o4[3]); *(u32x2*)(AL + (size_t)(t0 + i) * 256 + alc) = w;
;                 vp = vc; vc = vn; lp = lc; lc = ln;
	v_pk_add_f32 v[226:227], v[184:185], v[168:169] neg_lo:[0,1] neg_hi:[0,1]
	v_pk_fma_f32 v[200:201], v[104:105], v[224:225], v[168:169]
	v_pk_fma_f32 v[200:201], v[120:121], v[226:227], v[200:201]
	v_pk_add_f32 v[224:225], v[154:155], v[170:171] neg_lo:[0,1] neg_hi:[0,1]
	v_pk_add_f32 v[226:227], v[186:187], v[170:171] neg_lo:[0,1] neg_hi:[0,1]
	v_pk_fma_f32 v[202:203], v[106:107], v[224:225], v[170:171]
	v_pk_fma_f32 v[202:203], v[122:123], v[226:227], v[202:203]
	v_pk_add_f32 v[224:225], v[156:157], v[172:173] neg_lo:[0,1] neg_hi:[0,1]
	v_pk_add_f32 v[226:227], v[188:189], v[172:173] neg_lo:[0,1] neg_hi:[0,1]
	v_pk_fma_f32 v[204:205], v[108:109], v[224:225], v[172:173]
	v_pk_fma_f32 v[204:205], v[124:125], v[226:227], v[204:205]
	v_pk_add_f32 v[224:225], v[158:159], v[174:175] neg_lo:[0,1] neg_hi:[0,1]
	v_pk_add_f32 v[226:227], v[190:191], v[174:175] neg_lo:[0,1] neg_hi:[0,1]
	v_pk_fma_f32 v[206:207], v[110:111], v[224:225], v[174:175]
	v_pk_fma_f32 v[206:207], v[126:127], v[226:227], v[206:207]
	v_cvt_pk_bf16_f32 v208, v192, v193
	v_cvt_pk_bf16_f32 v209, v194, v195
	v_cvt_pk_bf16_f32 v210, v196, v197
	v_cvt_pk_bf16_f32 v211, v198, v199
	v_cvt_pk_bf16_f32 v212, v200, v201
	v_cvt_pk_bf16_f32 v213, v202, v203
	v_cvt_pk_bf16_f32 v214, v204, v205
	v_cvt_pk_bf16_f32 v215, v206, v207
	buffer_store_dwordx4 v[208:211], v237, s[68:71], s73 offen offset:0
	buffer_store_dwordx4 v[212:215], v237, s[68:71], s73 offen offset:16
	v_sub_f32_e32 v224, v136, v140
	v_sub_f32_e32 v225, v216, v140
	v_fma_f32 v220, v128, v224, v140
	v_fma_f32 v220, v132, v225, v220
	v_sub_f32_e32 v224, v137, v141
	v_sub_f32_e32 v225, v217, v141
	v_fma_f32 v221, v129, v224, v141
	v_fma_f32 v221, v133, v225, v221
	v_sub_f32_e32 v224, v138, v142
	v_sub_f32_e32 v225, v218, v142
	v_fma_f32 v222, v130, v224, v142
	v_fma_f32 v222, v134, v225, v222
	v_sub_f32_e32 v224, v139, v143
	v_sub_f32_e32 v225, v219, v143
	v_fma_f32 v223, v131, v224, v143
	v_fma_f32 v223, v135, v225, v223
	v_and_b32_e32 v224, 0x7fffffff, v220
	v_mul_f32_e32 v225, 0x4038aa3b, v224
	v_exp_f32_e32 v225, v225
	v_mul_f32_e32 v226, v220, v220
	v_add_f32_e32 v225, 1.0, v225
	v_rcp_f32_e32 v225, v225
	v_mul_f32_e32 v227, 0xbeaaaaab, v226
	v_fma_f32 v225, v225, -2.0, 1.0
	v_fma_f32 v227, v227, v220, v220
	v_bfi_b32 v225, v241, v225, v220
	v_cmp_gt_f32_e32 vcc, 0x3d000000, v224
	s_nop 1
	v_cndmask_b32_e32 v225, v225, v227, vcc
	v_cmp_gt_u32_e32 vcc, 32, v240
	s_nop 1
	v_cndmask_b32_e32 v220, v220, v225, vcc
	v_and_b32_e32 v224, 0x7fffffff, v221
	v_mul_f32_e32 v225, 0x4038aa3b, v224
	v_exp_f32_e32 v225, v225
	v_mul_f32_e32 v226, v221, v221
	v_add_f32_e32 v225, 1.0, v225
	v_rcp_f32_e32 v225, v225
	v_mul_f32_e32 v227, 0xbeaaaaab, v226
	v_fma_f32 v225, v225, -2.0, 1.0
	v_fma_f32 v227, v227, v221, v221
	v_bfi_b32 v225, v241, v225, v221
	v_cmp_gt_f32_e32 vcc, 0x3d000000, v224
	s_nop 1
	v_cndmask_b32_e32 v225, v225, v227, vcc
	v_cmp_gt_u32_e32 vcc, 32, v240
	s_nop 1
	v_cndmask_b32_e32 v221, v221, v225, vcc
	v_and_b32_e32 v224, 0x7fffffff, v222
	v_mul_f32_e32 v225, 0x4038aa3b, v224
	v_exp_f32_e32 v225, v225
	v_mul_f32_e32 v226, v222, v222
	v_add_f32_e32 v225, 1.0, v225
	v_rcp_f32_e32 v225, v225
	v_mul_f32_e32 v227, 0xbeaaaaab, v226
	v_fma_f32 v225, v225, -2.0, 1.0
	v_fma_f32 v227, v227, v222, v222
	v_bfi_b32 v225, v241, v225, v222
	v_cmp_gt_f32_e32 vcc, 0x3d000000, v224
	s_nop 1
	v_cndmask_b32_e32 v225, v225, v227, vcc
	v_cmp_gt_u32_e32 vcc, 32, v240
	s_nop 1
	v_cndmask_b32_e32 v222, v222, v225, vcc
	v_and_b32_e32 v224, 0x7fffffff, v223
	v_mul_f32_e32 v225, 0x4038aa3b, v224
	v_exp_f32_e32 v225, v225
	v_mul_f32_e32 v226, v223, v223
	v_add_f32_e32 v225, 1.0, v225
	v_rcp_f32_e32 v225, v225
	v_mul_f32_e32 v227, 0xbeaaaaab, v226
	v_fma_f32 v225, v225, -2.0, 1.0
	v_fma_f32 v227, v227, v223, v223
	v_bfi_b32 v225, v241, v225, v223
	v_cmp_gt_f32_e32 vcc, 0x3d000000, v224
	s_nop 1
	v_cndmask_b32_e32 v225, v225, v227, vcc
	v_cmp_gt_u32_e32 vcc, 32, v240
	s_nop 1
	v_cndmask_b32_e32 v223, v223, v225, vcc
	v_cvt_pk_bf16_f32 v224, v220, v221
	v_cvt_pk_bf16_f32 v225, v222, v223
	buffer_store_dwordx2 v[224:225], v238, s[68:71], s74 offen
	s_add_u32 s72, s72, 0x1000
	s_add_u32 s73, s73, 0x800
	s_add_u32 s74, s74, 0x200
	s_add_u32 s75, s75, 0x40
	s_waitcnt vmcnt(33)
; __device__ __forceinline__ float bflo(unsigned w) { return __uint_as_float(w << 16); }
; __device__ __forceinline__ float bfhi(unsigned w) { return __uint_as_float(w & 0xffff0000u); }
; __device__ __forceinline__ unsigned cvt_pk_bf16(float lo, float hi) { unsigned r; asm volatile("v_cvt_pk_bf16_f32 %0, %1, %2" : "=v"(r) : "v"(lo), "v"(hi)); return r; }
; __device__ __forceinline__ void prep_phase(const Params& p) {
;     ...
;             for (int i = 0; i < 16; ++i) {
;                 const bool hn = (tt0 + i) < SEQ - 1; const u16* zn = zc + (size_t)(i + 1) * 3328;
;                 const Z16 vn = hn ? ldz(zn + 2048 + c) : zz(); const u32x2 ln = hn ? *(const u32x2*)(zn + cl) : (u32x2){0u, 0u};
;                 float v[16]; mix16(vp, vc, vn, mpv, mnv, v);
;                 st16bf(V + (size_t)(t0 + i) * RW + c, v);
;                 const float z4[4] = {bflo(lc.x), bfhi(lc.x), bflo(lc.y), bfhi(lc.y)}, p4[4] = {bflo(lp.x), bfhi(lp.x), bflo(lp.y), bfhi(lp.y)}, n4[4] = {bflo(ln.x), bfhi(ln.x), bflo(ln.y), bfhi(ln.y)};
;                 float o4[4];
; #pragma unroll
;                 for (int j = 0; j < 4; ++j) { const float sft = z4[j] + la[j] * (p4[j] - z4[j]) + lb[j] * (n4[j] - z4[j]); o4[j] = (lane < 32) ? tanhf(sft) : sft; }
;                 u32x2 w; w.x = cvt_pk_bf16(o4[0], o4[1]); w.y = cvt_pk_bf16(o4[2], o4[3]); *(u32x2*)(AL + (size_t)(t0 + i) * 256 + alc) = w;
;                 vp = vc; vc = vn; lp = lc; lc = ln;
	v_lshlrev_b32_e32 v144, 16, v0
	v_and_b32_e32 v145, 0xffff0000, v0
	v_lshlrev_b32_e32 v146, 16, v1
	v_and_b32_e32 v147, 0xffff0000, v1
	v_lshlrev_b32_e32 v148, 16, v2
	v_and_b32_e32 v149, 0xffff0000, v2
	v_lshlrev_b32_e32 v150, 16, v3
	v_and_b32_e32 v151, 0xffff0000, v3
	v_lshlrev_b32_e32 v152, 16, v4
	v_and_b32_e32 v153, 0xffff0000, v4
	v_lshlrev_b32_e32 v154, 16, v5
	v_and_b32_e32 v155, 0xffff0000, v5
	v_lshlrev_b32_e32 v156, 16, v6
	v_and_b32_e32 v157, 0xffff0000, v6
	v_lshlrev_b32_e32 v158, 16, v7
	v_and_b32_e32 v159, 0xffff0000, v7
	v_lshlrev_b32_e32 v160, 16, v12
	v_and_b32_e32 v161, 0xffff0000, v12
	v_lshlrev_b32_e32 v162, 16, v13
	v_and_b32_e32 v163, 0xffff0000, v13
	v_lshlrev_b32_e32 v164, 16, v14
	v_and_b32_e32 v165, 0xffff0000, v14
	v_lshlrev_b32_e32 v166, 16, v15
	v_and_b32_e32 v167, 0xffff0000, v15
	v_lshlrev_b32_e32 v168, 16, v16
	v_and_b32_e32 v169, 0xffff0000, v16
	v_lshlrev_b32_e32 v170, 16, v17
	v_and_b32_e32 v171, 0xffff0000, v17
	v_lshlrev_b32_e32 v172, 16, v18
	v_and_b32_e32 v173, 0xffff0000, v18
	v_lshlrev_b32_e32 v174, 16, v19
	v_and_b32_e32 v175, 0xffff0000, v19
	v_lshlrev_b32_e32 v176, 16, v24
	v_and_b32_e32 v177, 0xffff0000, v24
	v_lshlrev_b32_e32 v178, 16, v25
	v_and_b32_e32 v179, 0xffff0000, v25
	v_lshlrev_b32_e32 v180, 16, v26
	v_and_b32_e32 v181, 0xffff0000, v26
	v_lshlrev_b32_e32 v182, 16, v27
	v_and_b32_e32 v183, 0xffff0000, v27
	v_lshlrev_b32_e32 v184, 16, v28
	v_and_b32_e32 v185, 0xffff0000, v28
	v_lshlrev_b32_e32 v186, 16, v29
	v_and_b32_e32 v187, 0xffff0000, v29
	v_lshlrev_b32_e32 v188, 16, v30
	v_and_b32_e32 v189, 0xffff0000, v30
	v_lshlrev_b32_e32 v190, 16, v31
	v_and_b32_e32 v191, 0xffff0000, v31
	v_lshlrev_b32_e32 v136, 16, v8
	v_and_b32_e32 v137, 0xffff0000, v8
	v_lshlrev_b32_e32 v138, 16, v9
	v_and_b32_e32 v139, 0xffff0000, v9
	v_lshlrev_b32_e32 v140, 16, v20
	v_and_b32_e32 v141, 0xffff0000, v20
	v_lshlrev_b32_e32 v142, 16, v21
	v_and_b32_e32 v143, 0xffff0000, v21
	v_lshlrev_b32_e32 v216, 16, v32
	v_and_b32_e32 v217, 0xffff0000, v32
	v_lshlrev_b32_e32 v218, 16, v33
	v_and_b32_e32 v219, 0xffff0000, v33
	buffer_load_dwordx4 v[0:3], v232, s[64:67], 0 offen offset:4064 nt
	buffer_load_dwordx4 v[4:7], v232, s[64:67], 0 offen offset:4080 nt
	buffer_load_dwordx2 v[8:9], v233, s[64:67], 0 offen nt
	v_add_u32_e32 v233, 6656, v233
	v_add_u32_e32 v232, 6656, v232
	v_pk_add_f32 v[224:225], v[144:145], v[160:161] neg_lo:[0,1] neg_hi:[0,1]
	v_pk_add_f32 v[226:227], v[176:177], v[160:161] neg_lo:[0,1] neg_hi:[0,1]
	v_pk_fma_f32 v[192:193], v[96:97], v[224:225], v[160:161]
	v_pk_fma_f32 v[192:193], v[112:113], v[226:227], v[192:193]
	v_pk_add_f32 v[224:225], v[146:147], v[162:163] neg_lo:[0,1] neg_hi:[0,1]
	v_pk_add_f32 v[226:227], v[178:179], v[162:163] neg_lo:[0,1] neg_hi:[0,1]
	v_pk_fma_f32 v[194:195], v[98:99], v[224:225], v[162:163]
	v_pk_fma_f32 v[194:195], v[114:115], v[226:227], v[194:195]
	v_pk_add_f32 v[224:225], v[148:149], v[164:165] neg_lo:[0,1] neg_hi:[0,1]
	v_pk_add_f32 v[226:227], v[180:181], v[164:165] neg_lo:[0,1] neg_hi:[0,1]
	v_pk_fma_f32 v[196:197], v[100:101], v[224:225], v[164:165]
	v_pk_fma_f32 v[196:197], v[116:117], v[226:227], v[196:197]
	v_pk_add_f32 v[224:225], v[150:151], v[166:167] neg_lo:[0,1] neg_hi:[0,1]
	v_pk_add_f32 v[226:227], v[182:183], v[166:167] neg_lo:[0,1] neg_hi:[0,1]
	v_pk_fma_f32 v[198:199], v[102:103], v[224:225], v[166:167]
	v_pk_fma_f32 v[198:199], v[118:119], v[226:227], v[198:199]
	v_pk_add_f32 v[224:225], v[152:153], v[168:169] neg_lo:[0,1] neg_hi:[0,1]
	v_pk_add_f32 v[226:227], v[184:185], v[168:169] neg_lo:[0,1] neg_hi:[0,1]
	v_pk_fma_f32 v[200:201], v[104:105], v[224:225], v[168:169]
	v_pk_fma_f32 v[200:201], v[120:121], v[226:227], v[200:201]
	v_pk_add_f32 v[224:225], v[154:155], v[170:171] neg_lo:[0,1] neg_hi:[0,1]
	v_pk_add_f32 v[226:227], v[186:187], v[170:171] neg_lo:[0,1] neg_hi:[0,1]
	v_pk_fma_f32 v[202:203], v[106:107], v[224:225], v[170:171]
	v_pk_fma_f32 v[202:203], v[122:123], v[226:227], v[202:203]
	v_pk_add_f32 v[224:225], v[156:157], v[172:173] neg_lo:[0,1] neg_hi:[0,1]
	v_pk_add_f32 v[226:227], v[188:189], v[172:173] neg_lo:[0,1] neg_hi:[0,1]
	v_pk_fma_f32 v[204:205], v[108:109], v[224:225], v[172:173]
	v_pk_fma_f32 v[204:205], v[124:125], v[226:227], v[204:205]
	v_pk_add_f32 v[224:225], v[158:159], v[174:175] neg_lo:[0,1] neg_hi:[0,1]
	v_pk_add_f32 v[226:227], v[190:191], v[174:175] neg_lo:[0,1] neg_hi:[0,1]
	v_pk_fma_f32 v[206:207], v[110:111], v[224:225], v[174:175]
	v_pk_fma_f32 v[206:207], v[126:127], v[226:227], v[206:207]
	v_cvt_pk_bf16_f32 v208, v192, v193
	v_cvt_pk_bf16_f32 v209, v194, v195
	v_cvt_pk_bf16_f32 v210, v196, v197
	v_cvt_pk_bf16_f32 v211, v198, v199
	v_cvt_pk_bf16_f32 v212, v200, v201
	v_cvt_pk_bf16_f32 v213, v202, v203
	v_cvt_pk_bf16_f32 v214, v204, v205
	v_cvt_pk_bf16_f32 v215, v206, v207
	buffer_store_dwordx4 v[208:211], v237, s[68:71], s73 offen offset:0
	buffer_store_dwordx4 v[212:215], v237, s[68:71], s73 offen offset:16
	v_sub_f32_e32 v224, v136, v140
	v_sub_f32_e32 v225, v216, v140
	v_fma_f32 v220, v128, v224, v140
	v_fma_f32 v220, v132, v225, v220
	v_sub_f32_e32 v224, v137, v141
	v_sub_f32_e32 v225, v217, v141
	v_fma_f32 v221, v129, v224, v141
	v_fma_f32 v221, v133, v225, v221
	v_sub_f32_e32 v224, v138, v142
	v_sub_f32_e32 v225, v218, v142
	v_fma_f32 v222, v130, v224, v142
	v_fma_f32 v222, v134, v225, v222
	v_sub_f32_e32 v224, v139, v143
	v_sub_f32_e32 v225, v219, v143
	v_fma_f32 v223, v131, v224, v143
	v_fma_f32 v223, v135, v225, v223
	v_and_b32_e32 v224, 0x7fffffff, v220
	v_mul_f32_e32 v225, 0x4038aa3b, v224
	v_exp_f32_e32 v225, v225
	v_mul_f32_e32 v226, v220, v220
	v_add_f32_e32 v225, 1.0, v225
; __device__ __forceinline__ float bflo(unsigned w) { return __uint_as_float(w << 16); }
; __device__ __forceinline__ float bfhi(unsigned w) { return __uint_as_float(w & 0xffff0000u); }
; __device__ __forceinline__ unsigned cvt_pk_bf16(float lo, float hi) { unsigned r; asm volatile("v_cvt_pk_bf16_f32 %0, %1, %2" : "=v"(r) : "v"(lo), "v"(hi)); return r; }
; __device__ __forceinline__ void prep_phase(const Params& p) {
;     ...
;             for (int i = 0; i < 16; ++i) {
;                 const bool hn = (tt0 + i) < SEQ - 1; const u16* zn = zc + (size_t)(i + 1) * 3328;
;                 const Z16 vn = hn ? ldz(zn + 2048 + c) : zz(); const u32x2 ln = hn ? *(const u32x2*)(zn + cl) : (u32x2){0u, 0u};
;                 float v[16]; mix16(vp, vc, vn, mpv, mnv, v);
;                 st16bf(V + (size_t)(t0 + i) * RW + c, v);
;                 const float z4[4] = {bflo(lc.x), bfhi(lc.x), bflo(lc.y), bfhi(lc.y)}, p4[4] = {bflo(lp.x), bfhi(lp.x), bflo(lp.y), bfhi(lp.y)}, n4[4] = {bflo(ln.x), bfhi(ln.x), bflo(ln.y), bfhi(ln.y)};
;                 float o4[4];
; #pragma unroll
;                 for (int j = 0; j < 4; ++j) { const float sft = z4[j] + la[j] * (p4[j] - z4[j]) + lb[j] * (n4[j] - z4[j]); o4[j] = (lane < 32) ? tanhf(sft) : sft; }
;                 u32x2 w; w.x = cvt_pk_bf16(o4[0], o4[1]); w.y = cvt_pk_bf16(o4[2], o4[3]); *(u32x2*)(AL + (size_t)(t0 + i) * 256 + alc) = w;
;                 vp = vc; vc = vn; lp = lc; lc = ln;
	v_rcp_f32_e32 v225, v225
	v_mul_f32_e32 v227, 0xbeaaaaab, v226
	v_fma_f32 v225, v225, -2.0, 1.0
	v_fma_f32 v227, v227, v220, v220
	v_bfi_b32 v225, v241, v225, v220
	v_cmp_gt_f32_e32 vcc, 0x3d000000, v224
	s_nop 1
	v_cndmask_b32_e32 v225, v225, v227, vcc
	v_cmp_gt_u32_e32 vcc, 32, v240
	s_nop 1
	v_cndmask_b32_e32 v220, v220, v225, vcc
	v_and_b32_e32 v224, 0x7fffffff, v221
	v_mul_f32_e32 v225, 0x4038aa3b, v224
	v_exp_f32_e32 v225, v225
	v_mul_f32_e32 v226, v221, v221
	v_add_f32_e32 v225, 1.0, v225
	v_rcp_f32_e32 v225, v225
	v_mul_f32_e32 v227, 0xbeaaaaab, v226
	v_fma_f32 v225, v225, -2.0, 1.0
	v_fma_f32 v227, v227, v221, v221
	v_bfi_b32 v225, v241, v225, v221
	v_cmp_gt_f32_e32 vcc, 0x3d000000, v224
	s_nop 1
	v_cndmask_b32_e32 v225, v225, v227, vcc
	v_cmp_gt_u32_e32 vcc, 32, v240
	s_nop 1
	v_cndmask_b32_e32 v221, v221, v225, vcc
	v_and_b32_e32 v224, 0x7fffffff, v222
	v_mul_f32_e32 v225, 0x4038aa3b, v224
	v_exp_f32_e32 v225, v225
	v_mul_f32_e32 v226, v222, v222
	v_add_f32_e32 v225, 1.0, v225
	v_rcp_f32_e32 v225, v225
	v_mul_f32_e32 v227, 0xbeaaaaab, v226
	v_fma_f32 v225, v225, -2.0, 1.0
	v_fma_f32 v227, v227, v222, v222
	v_bfi_b32 v225, v241, v225, v222
	v_cmp_gt_f32_e32 vcc, 0x3d000000, v224
	s_nop 1
	v_cndmask_b32_e32 v225, v225, v227, vcc
	v_cmp_gt_u32_e32 vcc, 32, v240
	s_nop 1
	v_cndmask_b32_e32 v222, v222, v225, vcc
	v_and_b32_e32 v224, 0x7fffffff, v223
	v_mul_f32_e32 v225, 0x4038aa3b, v224
	v_exp_f32_e32 v225, v225
	v_mul_f32_e32 v226, v223, v223
	v_add_f32_e32 v225, 1.0, v225
	v_rcp_f32_e32 v225, v225
	v_mul_f32_e32 v227, 0xbeaaaaab, v226
	v_fma_f32 v225, v225, -2.0, 1.0
	v_fma_f32 v227, v227, v223, v223
	v_bfi_b32 v225, v241, v225, v223
	v_cmp_gt_f32_e32 vcc, 0x3d000000, v224
	s_nop 1
	v_cndmask_b32_e32 v225, v225, v227, vcc
	v_cmp_gt_u32_e32 vcc, 32, v240
	s_nop 1
	v_cndmask_b32_e32 v223, v223, v225, vcc
	v_cvt_pk_bf16_f32 v224, v220, v221
	v_cvt_pk_bf16_f32 v225, v222, v223
	buffer_store_dwordx2 v[224:225], v238, s[68:71], s74 offen
	s_add_u32 s72, s72, 0x1000
	s_add_u32 s73, s73, 0x800
	s_add_u32 s74, s74, 0x200
	s_add_u32 s75, s75, 0x40
	s_waitcnt vmcnt(33)
	v_lshlrev_b32_e32 v144, 16, v12
	v_and_b32_e32 v145, 0xffff0000, v12
	v_lshlrev_b32_e32 v146, 16, v13
	v_and_b32_e32 v147, 0xffff0000, v13
	v_lshlrev_b32_e32 v148, 16, v14
	v_and_b32_e32 v149, 0xffff0000, v14
	v_lshlrev_b32_e32 v150, 16, v15
	v_and_b32_e32 v151, 0xffff0000, v15
	v_lshlrev_b32_e32 v152, 16, v16
	v_and_b32_e32 v153, 0xffff0000, v16
	v_lshlrev_b32_e32 v154, 16, v17
	v_and_b32_e32 v155, 0xffff0000, v17
	v_lshlrev_b32_e32 v156, 16, v18
	v_and_b32_e32 v157, 0xffff0000, v18
	v_lshlrev_b32_e32 v158, 16, v19
	v_and_b32_e32 v159, 0xffff0000, v19
	v_lshlrev_b32_e32 v160, 16, v24
	v_and_b32_e32 v161, 0xffff0000, v24
	v_lshlrev_b32_e32 v162, 16, v25
	v_and_b32_e32 v163, 0xffff0000, v25
	v_lshlrev_b32_e32 v164, 16, v26
	v_and_b32_e32 v165, 0xffff0000, v26
	v_lshlrev_b32_e32 v166, 16, v27
	v_and_b32_e32 v167, 0xffff0000, v27
	v_lshlrev_b32_e32 v168, 16, v28
	v_and_b32_e32 v169, 0xffff0000, v28
	v_lshlrev_b32_e32 v170, 16, v29
	v_and_b32_e32 v171, 0xffff0000, v29
	v_lshlrev_b32_e32 v172, 16, v30
	v_and_b32_e32 v173, 0xffff0000, v30
	v_lshlrev_b32_e32 v174, 16, v31
	v_and_b32_e32 v175, 0xffff0000, v31
	v_lshlrev_b32_e32 v176, 16, v36
	v_and_b32_e32 v177, 0xffff0000, v36
	v_lshlrev_b32_e32 v178, 16, v37
	v_and_b32_e32 v179, 0xffff0000, v37
	v_lshlrev_b32_e32 v180, 16, v38
	v_and_b32_e32 v181, 0xffff0000, v38
	v_lshlrev_b32_e32 v182, 16, v39
	v_and_b32_e32 v183, 0xffff0000, v39
	v_lshlrev_b32_e32 v184, 16, v40
	v_and_b32_e32 v185, 0xffff0000, v40
	v_lshlrev_b32_e32 v186, 16, v41
	v_and_b32_e32 v187, 0xffff0000, v41
	v_lshlrev_b32_e32 v188, 16, v42
	v_and_b32_e32 v189, 0xffff0000, v42
	v_lshlrev_b32_e32 v190, 16, v43
	v_and_b32_e32 v191, 0xffff0000, v43
	v_lshlrev_b32_e32 v136, 16, v20
	v_and_b32_e32 v137, 0xffff0000, v20
	v_lshlrev_b32_e32 v138, 16, v21
	v_and_b32_e32 v139, 0xffff0000, v21
	v_lshlrev_b32_e32 v140, 16, v32
	v_and_b32_e32 v141, 0xffff0000, v32
	v_lshlrev_b32_e32 v142, 16, v33
	v_and_b32_e32 v143, 0xffff0000, v33
	v_lshlrev_b32_e32 v216, 16, v44
	v_and_b32_e32 v217, 0xffff0000, v44
	v_lshlrev_b32_e32 v218, 16, v45
	v_and_b32_e32 v219, 0xffff0000, v45
	buffer_load_dwordx4 v[12:15], v232, s[64:67], 0 offen offset:4064 nt
	buffer_load_dwordx4 v[16:19], v232, s[64:67], 0 offen offset:4080 nt
	buffer_load_dwordx2 v[20:21], v233, s[64:67], 0 offen nt
	v_add_u32_e32 v233, 6656, v233
	v_add_u32_e32 v232, 6656, v232
	v_pk_add_f32 v[224:225], v[144:145], v[160:161] neg_lo:[0,1] neg_hi:[0,1]
	v_pk_add_f32 v[226:227], v[176:177], v[160:161] neg_lo:[0,1] neg_hi:[0,1]
	v_pk_fma_f32 v[192:193], v[96:97], v[224:225], v[160:161]
	v_pk_fma_f32 v[192:193], v[112:113], v[226:227], v[192:193]
	v_pk_add_f32 v[224:225], v[146:147], v[162:163] neg_lo:[0,1] neg_hi:[0,1]
	v_pk_add_f32 v[226:227], v[178:179], v[162:163] neg_lo:[0,1] neg_hi:[0,1]
	v_pk_fma_f32 v[194:195], v[98:99], v[224:225], v[162:163]
	v_pk_fma_f32 v[194:195], v[114:115], v[226:227], v[194:195]
	v_pk_add_f32 v[224:225], v[148:149], v[164:165] neg_lo:[0,1] neg_hi:[0,1]
	v_pk_add_f32 v[226:227], v[180:181], v[164:165] neg_lo:[0,1] neg_hi:[0,1]
	v_pk_fma_f32 v[196:197], v[100:101], v[224:225], v[164:165]
	v_pk_fma_f32 v[196:197], v[116:117], v[226:227], v[196:197]
	v_pk_add_f32 v[224:225], v[150:151], v[166:167] neg_lo:[0,1] neg_hi:[0,1]
	v_pk_add_f32 v[226:227], v[182:183], v[166:167] neg_lo:[0,1] neg_hi:[0,1]
	v_pk_fma_f32 v[198:199], v[102:103], v[224:225], v[166:167]
	v_pk_fma_f32 v[198:199], v[118:119], v[226:227], v[198:199]
	v_pk_add_f32 v[224:225], v[152:153], v[168:169] neg_lo:[0,1] neg_hi:[0,1]
; __device__ __forceinline__ float bflo(unsigned w) { return __uint_as_float(w << 16); }
; __device__ __forceinline__ float bfhi(unsigned w) { return __uint_as_float(w & 0xffff0000u); }
; __device__ __forceinline__ unsigned cvt_pk_bf16(float lo, float hi) { unsigned r; asm volatile("v_cvt_pk_bf16_f32 %0, %1, %2" : "=v"(r) : "v"(lo), "v"(hi)); return r; }
; __device__ __forceinline__ void prep_phase(const Params& p) {
;     ...
;                 float v[16]; mix16(vp, vc, vn, mpv, mnv, v);
;                 st16bf(V + (size_t)(t0 + i) * RW + c, v);
;                 const float z4[4] = {bflo(lc.x), bfhi(lc.x), bflo(lc.y), bfhi(lc.y)}, p4[4] = {bflo(lp.x), bfhi(lp.x), bflo(lp.y), bfhi(lp.y)}, n4[4] = {bflo(ln.x), bfhi(ln.x), bflo(ln.y), bfhi(ln.y)};
;                 float o4[4];
; #pragma unroll
;                 for (int j = 0; j < 4; ++j) { const float sft = z4[j] + la[j] * (p4[j] - z4[j]) + lb[j] * (n4[j] - z4[j]); o4[j] = (lane < 32) ? tanhf(sft) : sft; }
;                 u32x2 w; w.x = cvt_pk_bf16(o4[0], o4[1]); w.y = cvt_pk_bf16(o4[2], o4[3]); *(u32x2*)(AL + (size_t)(t0 + i) * 256 + alc) = w;
;                 vp = vc; vc = vn; lp = lc; lc = ln;
	v_pk_add_f32 v[226:227], v[184:185], v[168:169] neg_lo:[0,1] neg_hi:[0,1]
	v_pk_fma_f32 v[200:201], v[104:105], v[224:225], v[168:169]
	v_pk_fma_f32 v[200:201], v[120:121], v[226:227], v[200:201]
	v_pk_add_f32 v[224:225], v[154:155], v[170:171] neg_lo:[0,1] neg_hi:[0,1]
	v_pk_add_f32 v[226:227], v[186:187], v[170:171] neg_lo:[0,1] neg_hi:[0,1]
	v_pk_fma_f32 v[202:203], v[106:107], v[224:225], v[170:171]
	v_pk_fma_f32 v[202:203], v[122:123], v[226:227], v[202:203]
	v_pk_add_f32 v[224:225], v[156:157], v[172:173] neg_lo:[0,1] neg_hi:[0,1]
	v_pk_add_f32 v[226:227], v[188:189], v[172:173] neg_lo:[0,1] neg_hi:[0,1]
	v_pk_fma_f32 v[204:205], v[108:109], v[224:225], v[172:173]
	v_pk_fma_f32 v[204:205], v[124:125], v[226:227], v[204:205]
	v_pk_add_f32 v[224:225], v[158:159], v[174:175] neg_lo:[0,1] neg_hi:[0,1]
	v_pk_add_f32 v[226:227], v[190:191], v[174:175] neg_lo:[0,1] neg_hi:[0,1]
	v_pk_fma_f32 v[206:207], v[110:111], v[224:225], v[174:175]
	v_pk_fma_f32 v[206:207], v[126:127], v[226:227], v[206:207]
	v_cvt_pk_bf16_f32 v208, v192, v193
	v_cvt_pk_bf16_f32 v209, v194, v195
	v_cvt_pk_bf16_f32 v210, v196, v197
	v_cvt_pk_bf16_f32 v211, v198, v199
	v_cvt_pk_bf16_f32 v212, v200, v201
	v_cvt_pk_bf16_f32 v213, v202, v203
	v_cvt_pk_bf16_f32 v214, v204, v205
	v_cvt_pk_bf16_f32 v215, v206, v207
	buffer_store_dwordx4 v[208:211], v237, s[68:71], s73 offen offset:0
	buffer_store_dwordx4 v[212:215], v237, s[68:71], s73 offen offset:16
	v_sub_f32_e32 v224, v136, v140
	v_sub_f32_e32 v225, v216, v140
	v_fma_f32 v220, v128, v224, v140
	v_fma_f32 v220, v132, v225, v220
	v_sub_f32_e32 v224, v137, v141
	v_sub_f32_e32 v225, v217, v141
	v_fma_f32 v221, v129, v224, v141
	v_fma_f32 v221, v133, v225, v221
	v_sub_f32_e32 v224, v138, v142
	v_sub_f32_e32 v225, v218, v142
	v_fma_f32 v222, v130, v224, v142
	v_fma_f32 v222, v134, v225, v222
	v_sub_f32_e32 v224, v139, v143
	v_sub_f32_e32 v225, v219, v143
	v_fma_f32 v223, v131, v224, v143
	v_fma_f32 v223, v135, v225, v223
	v_and_b32_e32 v224, 0x7fffffff, v220
	v_mul_f32_e32 v225, 0x4038aa3b, v224
	v_exp_f32_e32 v225, v225
	v_mul_f32_e32 v226, v220, v220
	v_add_f32_e32 v225, 1.0, v225
	v_rcp_f32_e32 v225, v225
	v_mul_f32_e32 v227, 0xbeaaaaab, v226
	v_fma_f32 v225, v225, -2.0, 1.0
	v_fma_f32 v227, v227, v220, v220
	v_bfi_b32 v225, v241, v225, v220
	v_cmp_gt_f32_e32 vcc, 0x3d000000, v224
	s_nop 1
	v_cndmask_b32_e32 v225, v225, v227, vcc
	v_cmp_gt_u32_e32 vcc, 32, v240
	s_nop 1
	v_cndmask_b32_e32 v220, v220, v225, vcc
	v_and_b32_e32 v224, 0x7fffffff, v221
	v_mul_f32_e32 v225, 0x4038aa3b, v224
	v_exp_f32_e32 v225, v225
	v_mul_f32_e32 v226, v221, v221
	v_add_f32_e32 v225, 1.0, v225
	v_rcp_f32_e32 v225, v225
	v_mul_f32_e32 v227, 0xbeaaaaab, v226
	v_fma_f32 v225, v225, -2.0, 1.0
	v_fma_f32 v227, v227, v221, v221
	v_bfi_b32 v225, v241, v225, v221
	v_cmp_gt_f32_e32 vcc, 0x3d000000, v224
	s_nop 1
	v_cndmask_b32_e32 v225, v225, v227, vcc
	v_cmp_gt_u32_e32 vcc, 32, v240
	s_nop 1
	v_cndmask_b32_e32 v221, v221, v225, vcc
	v_and_b32_e32 v224, 0x7fffffff, v222
	v_mul_f32_e32 v225, 0x4038aa3b, v224
	v_exp_f32_e32 v225, v225
	v_mul_f32_e32 v226, v222, v222
	v_add_f32_e32 v225, 1.0, v225
	v_rcp_f32_e32 v225, v225
	v_mul_f32_e32 v227, 0xbeaaaaab, v226
	v_fma_f32 v225, v225, -2.0, 1.0
	v_fma_f32 v227, v227, v222, v222
	v_bfi_b32 v225, v241, v225, v222
	v_cmp_gt_f32_e32 vcc, 0x3d000000, v224
	s_nop 1
	v_cndmask_b32_e32 v225, v225, v227, vcc
	v_cmp_gt_u32_e32 vcc, 32, v240
	s_nop 1
	v_cndmask_b32_e32 v222, v222, v225, vcc
	v_and_b32_e32 v224, 0x7fffffff, v223
	v_mul_f32_e32 v225, 0x4038aa3b, v224
	v_exp_f32_e32 v225, v225
	v_mul_f32_e32 v226, v223, v223
	v_add_f32_e32 v225, 1.0, v225
	v_rcp_f32_e32 v225, v225
	v_mul_f32_e32 v227, 0xbeaaaaab, v226
	v_fma_f32 v225, v225, -2.0, 1.0
	v_fma_f32 v227, v227, v223, v223
	v_bfi_b32 v225, v241, v225, v223
	v_cmp_gt_f32_e32 vcc, 0x3d000000, v224
	s_nop 1
	v_cndmask_b32_e32 v225, v225, v227, vcc
	v_cmp_gt_u32_e32 vcc, 32, v240
	s_nop 1
	v_cndmask_b32_e32 v223, v223, v225, vcc
	v_cvt_pk_bf16_f32 v224, v220, v221
	v_cvt_pk_bf16_f32 v225, v222, v223
	buffer_store_dwordx2 v[224:225], v238, s[68:71], s74 offen
	s_add_u32 s72, s72, 0x1000
	s_add_u32 s73, s73, 0x800
	s_add_u32 s74, s74, 0x200
	s_add_u32 s75, s75, 0x40
	s_waitcnt vmcnt(33)
; __device__ __forceinline__ float bflo(unsigned w) { return __uint_as_float(w << 16); }
; __device__ __forceinline__ float bfhi(unsigned w) { return __uint_as_float(w & 0xffff0000u); }
; __device__ __forceinline__ unsigned cvt_pk_bf16(float lo, float hi) { unsigned r; asm volatile("v_cvt_pk_bf16_f32 %0, %1, %2" : "=v"(r) : "v"(lo), "v"(hi)); return r; }
; __device__ __forceinline__ void prep_phase(const Params& p) {
;     ...
;                 const bool hn = (tt0 + i) < SEQ - 1; const u16* zn = zc + (size_t)(i + 1) * 3328;
;                 const Z16 vn = hn ? ldz(zn + 2048 + c) : zz(); const u32x2 ln = hn ? *(const u32x2*)(zn + cl) : (u32x2){0u, 0u};
;                 float v[16]; mix16(vp, vc, vn, mpv, mnv, v);
;                 st16bf(V + (size_t)(t0 + i) * RW + c, v);
;                 const float z4[4] = {bflo(lc.x), bfhi(lc.x), bflo(lc.y), bfhi(lc.y)}, p4[4] = {bflo(lp.x), bfhi(lp.x), bflo(lp.y), bfhi(lp.y)}, n4[4] = {bflo(ln.x), bfhi(ln.x), bflo(ln.y), bfhi(ln.y)};
;                 float o4[4];
; #pragma unroll
;                 for (int j = 0; j < 4; ++j) { const float sft = z4[j] + la[j] * (p4[j] - z4[j]) + lb[j] * (n4[j] - z4[j]); o4[j] = (lane < 32) ? tanhf(sft) : sft; }
;                 u32x2 w; w.x = cvt_pk_bf16(o4[0], o4[1]); w.y = cvt_pk_bf16(o4[2], o4[3]); *(u32x2*)(AL + (size_t)(t0 + i) * 256 + alc) = w;
;                 vp = vc; vc = vn; lp = lc; lc = ln;
	v_lshlrev_b32_e32 v144, 16, v24
	v_and_b32_e32 v145, 0xffff0000, v24
	v_lshlrev_b32_e32 v146, 16, v25
	v_and_b32_e32 v147, 0xffff0000, v25
	v_lshlrev_b32_e32 v148, 16, v26
	v_and_b32_e32 v149, 0xffff0000, v26
	v_lshlrev_b32_e32 v150, 16, v27
	v_and_b32_e32 v151, 0xffff0000, v27
	v_lshlrev_b32_e32 v152, 16, v28
	v_and_b32_e32 v153, 0xffff0000, v28
	v_lshlrev_b32_e32 v154, 16, v29
	v_and_b32_e32 v155, 0xffff0000, v29
	v_lshlrev_b32_e32 v156, 16, v30
	v_and_b32_e32 v157, 0xffff0000, v30
	v_lshlrev_b32_e32 v158, 16, v31
	v_and_b32_e32 v159, 0xffff0000, v31
	v_lshlrev_b32_e32 v160, 16, v36
	v_and_b32_e32 v161, 0xffff0000, v36
	v_lshlrev_b32_e32 v162, 16, v37
	v_and_b32_e32 v163, 0xffff0000, v37
	v_lshlrev_b32_e32 v164, 16, v38
	v_and_b32_e32 v165, 0xffff0000, v38
	v_lshlrev_b32_e32 v166, 16, v39
	v_and_b32_e32 v167, 0xffff0000, v39
	v_lshlrev_b32_e32 v168, 16, v40
	v_and_b32_e32 v169, 0xffff0000, v40
	v_lshlrev_b32_e32 v170, 16, v41
	v_and_b32_e32 v171, 0xffff0000, v41
	v_lshlrev_b32_e32 v172, 16, v42
	v_and_b32_e32 v173, 0xffff0000, v42
	v_lshlrev_b32_e32 v174, 16, v43
	v_and_b32_e32 v175, 0xffff0000, v43
	v_lshlrev_b32_e32 v176, 16, v48
	v_and_b32_e32 v177, 0xffff0000, v48
	v_lshlrev_b32_e32 v178, 16, v49
	v_and_b32_e32 v179, 0xffff0000, v49
	v_lshlrev_b32_e32 v180, 16, v50
	v_and_b32_e32 v181, 0xffff0000, v50
	v_lshlrev_b32_e32 v182, 16, v51
	v_and_b32_e32 v183, 0xffff0000, v51
	v_lshlrev_b32_e32 v184, 16, v52
	v_and_b32_e32 v185, 0xffff0000, v52
	v_lshlrev_b32_e32 v186, 16, v53
	v_and_b32_e32 v187, 0xffff0000, v53
	v_lshlrev_b32_e32 v188, 16, v54
	v_and_b32_e32 v189, 0xffff0000, v54
	v_lshlrev_b32_e32 v190, 16, v55
	v_and_b32_e32 v191, 0xffff0000, v55
	v_lshlrev_b32_e32 v136, 16, v32
	v_and_b32_e32 v137, 0xffff0000, v32
	v_lshlrev_b32_e32 v138, 16, v33
	v_and_b32_e32 v139, 0xffff0000, v33
	v_lshlrev_b32_e32 v140, 16, v44
	v_and_b32_e32 v141, 0xffff0000, v44
	v_lshlrev_b32_e32 v142, 16, v45
	v_and_b32_e32 v143, 0xffff0000, v45
	v_lshlrev_b32_e32 v216, 16, v56
	v_and_b32_e32 v217, 0xffff0000, v56
	v_lshlrev_b32_e32 v218, 16, v57
	v_and_b32_e32 v219, 0xffff0000, v57
	v_pk_add_f32 v[224:225], v[144:145], v[160:161] neg_lo:[0,1] neg_hi:[0,1]
	v_pk_add_f32 v[226:227], v[176:177], v[160:161] neg_lo:[0,1] neg_hi:[0,1]
	v_pk_fma_f32 v[192:193], v[96:97], v[224:225], v[160:161]
	v_pk_fma_f32 v[192:193], v[112:113], v[226:227], v[192:193]
	v_pk_add_f32 v[224:225], v[146:147], v[162:163] neg_lo:[0,1] neg_hi:[0,1]
	v_pk_add_f32 v[226:227], v[178:179], v[162:163] neg_lo:[0,1] neg_hi:[0,1]
	v_pk_fma_f32 v[194:195], v[98:99], v[224:225], v[162:163]
	v_pk_fma_f32 v[194:195], v[114:115], v[226:227], v[194:195]
	v_pk_add_f32 v[224:225], v[148:149], v[164:165] neg_lo:[0,1] neg_hi:[0,1]
	v_pk_add_f32 v[226:227], v[180:181], v[164:165] neg_lo:[0,1] neg_hi:[0,1]
	v_pk_fma_f32 v[196:197], v[100:101], v[224:225], v[164:165]
	v_pk_fma_f32 v[196:197], v[116:117], v[226:227], v[196:197]
	v_pk_add_f32 v[224:225], v[150:151], v[166:167] neg_lo:[0,1] neg_hi:[0,1]
	v_pk_add_f32 v[226:227], v[182:183], v[166:167] neg_lo:[0,1] neg_hi:[0,1]
	v_pk_fma_f32 v[198:199], v[102:103], v[224:225], v[166:167]
	v_pk_fma_f32 v[198:199], v[118:119], v[226:227], v[198:199]
	v_pk_add_f32 v[224:225], v[152:153], v[168:169] neg_lo:[0,1] neg_hi:[0,1]
	v_pk_add_f32 v[226:227], v[184:185], v[168:169] neg_lo:[0,1] neg_hi:[0,1]
	v_pk_fma_f32 v[200:201], v[104:105], v[224:225], v[168:169]
	v_pk_fma_f32 v[200:201], v[120:121], v[226:227], v[200:201]
	v_pk_add_f32 v[224:225], v[154:155], v[170:171] neg_lo:[0,1] neg_hi:[0,1]
	v_pk_add_f32 v[226:227], v[186:187], v[170:171] neg_lo:[0,1] neg_hi:[0,1]
	v_pk_fma_f32 v[202:203], v[106:107], v[224:225], v[170:171]
	v_pk_fma_f32 v[202:203], v[122:123], v[226:227], v[202:203]
	v_pk_add_f32 v[224:225], v[156:157], v[172:173] neg_lo:[0,1] neg_hi:[0,1]
	v_pk_add_f32 v[226:227], v[188:189], v[172:173] neg_lo:[0,1] neg_hi:[0,1]
	v_pk_fma_f32 v[204:205], v[108:109], v[224:225], v[172:173]
	v_pk_fma_f32 v[204:205], v[124:125], v[226:227], v[204:205]
	v_pk_add_f32 v[224:225], v[158:159], v[174:175] neg_lo:[0,1] neg_hi:[0,1]
	v_pk_add_f32 v[226:227], v[190:191], v[174:175] neg_lo:[0,1] neg_hi:[0,1]
	v_pk_fma_f32 v[206:207], v[110:111], v[224:225], v[174:175]
	v_pk_fma_f32 v[206:207], v[126:127], v[226:227], v[206:207]
	v_cvt_pk_bf16_f32 v208, v192, v193
	v_cvt_pk_bf16_f32 v209, v194, v195
	v_cvt_pk_bf16_f32 v210, v196, v197
	v_cvt_pk_bf16_f32 v211, v198, v199
	v_cvt_pk_bf16_f32 v212, v200, v201
	v_cvt_pk_bf16_f32 v213, v202, v203
	v_cvt_pk_bf16_f32 v214, v204, v205
	v_cvt_pk_bf16_f32 v215, v206, v207
	buffer_store_dwordx4 v[208:211], v237, s[68:71], s73 offen offset:0
	buffer_store_dwordx4 v[212:215], v237, s[68:71], s73 offen offset:16
	v_sub_f32_e32 v224, v136, v140
	v_sub_f32_e32 v225, v216, v140
	v_fma_f32 v220, v128, v224, v140
	v_fma_f32 v220, v132, v225, v220
	v_sub_f32_e32 v224, v137, v141
	v_sub_f32_e32 v225, v217, v141
	v_fma_f32 v221, v129, v224, v141
	v_fma_f32 v221, v133, v225, v221
	v_sub_f32_e32 v224, v138, v142
	v_sub_f32_e32 v225, v218, v142
	v_fma_f32 v222, v130, v224, v142
	v_fma_f32 v222, v134, v225, v222
	v_sub_f32_e32 v224, v139, v143
	v_sub_f32_e32 v225, v219, v143
	v_fma_f32 v223, v131, v224, v143
	v_fma_f32 v223, v135, v225, v223
	v_and_b32_e32 v224, 0x7fffffff, v220
	v_mul_f32_e32 v225, 0x4038aa3b, v224
	v_exp_f32_e32 v225, v225
	v_mul_f32_e32 v226, v220, v220
	v_add_f32_e32 v225, 1.0, v225
	v_rcp_f32_e32 v225, v225
	v_mul_f32_e32 v227, 0xbeaaaaab, v226
	v_fma_f32 v225, v225, -2.0, 1.0
	v_fma_f32 v227, v227, v220, v220
	v_bfi_b32 v225, v241, v225, v220
	v_cmp_gt_f32_e32 vcc, 0x3d000000, v224
	s_nop 1
	v_cndmask_b32_e32 v225, v225, v227, vcc
; __device__ __forceinline__ float bflo(unsigned w) { return __uint_as_float(w << 16); }
; __device__ __forceinline__ float bfhi(unsigned w) { return __uint_as_float(w & 0xffff0000u); }
; __device__ __forceinline__ unsigned cvt_pk_bf16(float lo, float hi) { unsigned r; asm volatile("v_cvt_pk_bf16_f32 %0, %1, %2" : "=v"(r) : "v"(lo), "v"(hi)); return r; }
; __device__ __forceinline__ void prep_phase(const Params& p) {
;     ...
;                 float v[16]; mix16(vp, vc, vn, mpv, mnv, v);
;                 st16bf(V + (size_t)(t0 + i) * RW + c, v);
;                 const float z4[4] = {bflo(lc.x), bfhi(lc.x), bflo(lc.y), bfhi(lc.y)}, p4[4] = {bflo(lp.x), bfhi(lp.x), bflo(lp.y), bfhi(lp.y)}, n4[4] = {bflo(ln.x), bfhi(ln.x), bflo(ln.y), bfhi(ln.y)};
;                 float o4[4];
; #pragma unroll
;                 for (int j = 0; j < 4; ++j) { const float sft = z4[j] + la[j] * (p4[j] - z4[j]) + lb[j] * (n4[j] - z4[j]); o4[j] = (lane < 32) ? tanhf(sft) : sft; }
;                 u32x2 w; w.x = cvt_pk_bf16(o4[0], o4[1]); w.y = cvt_pk_bf16(o4[2], o4[3]); *(u32x2*)(AL + (size_t)(t0 + i) * 256 + alc) = w;
;                 vp = vc; vc = vn; lp = lc; lc = ln;
	v_cmp_gt_u32_e32 vcc, 32, v240
	s_nop 1
	v_cndmask_b32_e32 v220, v220, v225, vcc
	v_and_b32_e32 v224, 0x7fffffff, v221
	v_mul_f32_e32 v225, 0x4038aa3b, v224
	v_exp_f32_e32 v225, v225
	v_mul_f32_e32 v226, v221, v221
	v_add_f32_e32 v225, 1.0, v225
	v_rcp_f32_e32 v225, v225
	v_mul_f32_e32 v227, 0xbeaaaaab, v226
	v_fma_f32 v225, v225, -2.0, 1.0
	v_fma_f32 v227, v227, v221, v221
	v_bfi_b32 v225, v241, v225, v221
	v_cmp_gt_f32_e32 vcc, 0x3d000000, v224
	s_nop 1
	v_cndmask_b32_e32 v225, v225, v227, vcc
	v_cmp_gt_u32_e32 vcc, 32, v240
	s_nop 1
	v_cndmask_b32_e32 v221, v221, v225, vcc
	v_and_b32_e32 v224, 0x7fffffff, v222
	v_mul_f32_e32 v225, 0x4038aa3b, v224
	v_exp_f32_e32 v225, v225
	v_mul_f32_e32 v226, v222, v222
	v_add_f32_e32 v225, 1.0, v225
	v_rcp_f32_e32 v225, v225
	v_mul_f32_e32 v227, 0xbeaaaaab, v226
	v_fma_f32 v225, v225, -2.0, 1.0
	v_fma_f32 v227, v227, v222, v222
	v_bfi_b32 v225, v241, v225, v222
	v_cmp_gt_f32_e32 vcc, 0x3d000000, v224
	s_nop 1
	v_cndmask_b32_e32 v225, v225, v227, vcc
	v_cmp_gt_u32_e32 vcc, 32, v240
	s_nop 1
	v_cndmask_b32_e32 v222, v222, v225, vcc
	v_and_b32_e32 v224, 0x7fffffff, v223
	v_mul_f32_e32 v225, 0x4038aa3b, v224
	v_exp_f32_e32 v225, v225
	v_mul_f32_e32 v226, v223, v223
	v_add_f32_e32 v225, 1.0, v225
	v_rcp_f32_e32 v225, v225
	v_mul_f32_e32 v227, 0xbeaaaaab, v226
	v_fma_f32 v225, v225, -2.0, 1.0
	v_fma_f32 v227, v227, v223, v223
	v_bfi_b32 v225, v241, v225, v223
	v_cmp_gt_f32_e32 vcc, 0x3d000000, v224
	s_nop 1
	v_cndmask_b32_e32 v225, v225, v227, vcc
	v_cmp_gt_u32_e32 vcc, 32, v240
	s_nop 1
	v_cndmask_b32_e32 v223, v223, v225, vcc
	v_cvt_pk_bf16_f32 v224, v220, v221
	v_cvt_pk_bf16_f32 v225, v222, v223
	buffer_store_dwordx2 v[224:225], v238, s[68:71], s74 offen
	s_add_u32 s72, s72, 0x1000
	s_add_u32 s73, s73, 0x800
	s_add_u32 s74, s74, 0x200
	s_add_u32 s75, s75, 0x40
	s_waitcnt vmcnt(30)
	v_lshlrev_b32_e32 v144, 16, v36
	v_and_b32_e32 v145, 0xffff0000, v36
	v_lshlrev_b32_e32 v146, 16, v37
	v_and_b32_e32 v147, 0xffff0000, v37
	v_lshlrev_b32_e32 v148, 16, v38
	v_and_b32_e32 v149, 0xffff0000, v38
	v_lshlrev_b32_e32 v150, 16, v39
	v_and_b32_e32 v151, 0xffff0000, v39
	v_lshlrev_b32_e32 v152, 16, v40
	v_and_b32_e32 v153, 0xffff0000, v40
	v_lshlrev_b32_e32 v154, 16, v41
	v_and_b32_e32 v155, 0xffff0000, v41
	v_lshlrev_b32_e32 v156, 16, v42
	v_and_b32_e32 v157, 0xffff0000, v42
	v_lshlrev_b32_e32 v158, 16, v43
	v_and_b32_e32 v159, 0xffff0000, v43
	v_lshlrev_b32_e32 v160, 16, v48
	v_and_b32_e32 v161, 0xffff0000, v48
	v_lshlrev_b32_e32 v162, 16, v49
	v_and_b32_e32 v163, 0xffff0000, v49
	v_lshlrev_b32_e32 v164, 16, v50
	v_and_b32_e32 v165, 0xffff0000, v50
	v_lshlrev_b32_e32 v166, 16, v51
	v_and_b32_e32 v167, 0xffff0000, v51
	v_lshlrev_b32_e32 v168, 16, v52
	v_and_b32_e32 v169, 0xffff0000, v52
	v_lshlrev_b32_e32 v170, 16, v53
	v_and_b32_e32 v171, 0xffff0000, v53
	v_lshlrev_b32_e32 v172, 16, v54
	v_and_b32_e32 v173, 0xffff0000, v54
	v_lshlrev_b32_e32 v174, 16, v55
	v_and_b32_e32 v175, 0xffff0000, v55
	v_lshlrev_b32_e32 v176, 16, v60
	v_and_b32_e32 v177, 0xffff0000, v60
	v_lshlrev_b32_e32 v178, 16, v61
	v_and_b32_e32 v179, 0xffff0000, v61
	v_lshlrev_b32_e32 v180, 16, v62
	v_and_b32_e32 v181, 0xffff0000, v62
	v_lshlrev_b32_e32 v182, 16, v63
	v_and_b32_e32 v183, 0xffff0000, v63
	v_lshlrev_b32_e32 v184, 16, v64
	v_and_b32_e32 v185, 0xffff0000, v64
	v_lshlrev_b32_e32 v186, 16, v65
	v_and_b32_e32 v187, 0xffff0000, v65
	v_lshlrev_b32_e32 v188, 16, v66
	v_and_b32_e32 v189, 0xffff0000, v66
	v_lshlrev_b32_e32 v190, 16, v67
	v_and_b32_e32 v191, 0xffff0000, v67
	v_lshlrev_b32_e32 v136, 16, v44
	v_and_b32_e32 v137, 0xffff0000, v44
	v_lshlrev_b32_e32 v138, 16, v45
	v_and_b32_e32 v139, 0xffff0000, v45
	v_lshlrev_b32_e32 v140, 16, v56
	v_and_b32_e32 v141, 0xffff0000, v56
	v_lshlrev_b32_e32 v142, 16, v57
	v_and_b32_e32 v143, 0xffff0000, v57
	v_lshlrev_b32_e32 v216, 16, v68
	v_and_b32_e32 v217, 0xffff0000, v68
	v_lshlrev_b32_e32 v218, 16, v69
	v_and_b32_e32 v219, 0xffff0000, v69
	v_pk_add_f32 v[224:225], v[144:145], v[160:161] neg_lo:[0,1] neg_hi:[0,1]
	v_pk_add_f32 v[226:227], v[176:177], v[160:161] neg_lo:[0,1] neg_hi:[0,1]
	v_pk_fma_f32 v[192:193], v[96:97], v[224:225], v[160:161]
	v_pk_fma_f32 v[192:193], v[112:113], v[226:227], v[192:193]
	v_pk_add_f32 v[224:225], v[146:147], v[162:163] neg_lo:[0,1] neg_hi:[0,1]
	v_pk_add_f32 v[226:227], v[178:179], v[162:163] neg_lo:[0,1] neg_hi:[0,1]
	v_pk_fma_f32 v[194:195], v[98:99], v[224:225], v[162:163]
	v_pk_fma_f32 v[194:195], v[114:115], v[226:227], v[194:195]
	v_pk_add_f32 v[224:225], v[148:149], v[164:165] neg_lo:[0,1] neg_hi:[0,1]
	v_pk_add_f32 v[226:227], v[180:181], v[164:165] neg_lo:[0,1] neg_hi:[0,1]
	v_pk_fma_f32 v[196:197], v[100:101], v[224:225], v[164:165]
	v_pk_fma_f32 v[196:197], v[116:117], v[226:227], v[196:197]
	v_pk_add_f32 v[224:225], v[150:151], v[166:167] neg_lo:[0,1] neg_hi:[0,1]
	v_pk_add_f32 v[226:227], v[182:183], v[166:167] neg_lo:[0,1] neg_hi:[0,1]
	v_pk_fma_f32 v[198:199], v[102:103], v[224:225], v[166:167]
	v_pk_fma_f32 v[198:199], v[118:119], v[226:227], v[198:199]
	v_pk_add_f32 v[224:225], v[152:153], v[168:169] neg_lo:[0,1] neg_hi:[0,1]
	v_pk_add_f32 v[226:227], v[184:185], v[168:169] neg_lo:[0,1] neg_hi:[0,1]
	v_pk_fma_f32 v[200:201], v[104:105], v[224:225], v[168:169]
	v_pk_fma_f32 v[200:201], v[120:121], v[226:227], v[200:201]
	v_pk_add_f32 v[224:225], v[154:155], v[170:171] neg_lo:[0,1] neg_hi:[0,1]
	v_pk_add_f32 v[226:227], v[186:187], v[170:171] neg_lo:[0,1] neg_hi:[0,1]
	v_pk_fma_f32 v[202:203], v[106:107], v[224:225], v[170:171]
	v_pk_fma_f32 v[202:203], v[122:123], v[226:227], v[202:203]
	v_pk_add_f32 v[224:225], v[156:157], v[172:173] neg_lo:[0,1] neg_hi:[0,1]
; __device__ __forceinline__ float bflo(unsigned w) { return __uint_as_float(w << 16); }
; __device__ __forceinline__ float bfhi(unsigned w) { return __uint_as_float(w & 0xffff0000u); }
; __device__ __forceinline__ unsigned cvt_pk_bf16(float lo, float hi) { unsigned r; asm volatile("v_cvt_pk_bf16_f32 %0, %1, %2" : "=v"(r) : "v"(lo), "v"(hi)); return r; }
; __device__ __forceinline__ void prep_phase(const Params& p) {
;     ...
;                 float v[16]; mix16(vp, vc, vn, mpv, mnv, v);
;                 st16bf(V + (size_t)(t0 + i) * RW + c, v);
;                 const float z4[4] = {bflo(lc.x), bfhi(lc.x), bflo(lc.y), bfhi(lc.y)}, p4[4] = {bflo(lp.x), bfhi(lp.x), bflo(lp.y), bfhi(lp.y)}, n4[4] = {bflo(ln.x), bfhi(ln.x), bflo(ln.y), bfhi(ln.y)};
;                 float o4[4];
; #pragma unroll
;                 for (int j = 0; j < 4; ++j) { const float sft = z4[j] + la[j] * (p4[j] - z4[j]) + lb[j] * (n4[j] - z4[j]); o4[j] = (lane < 32) ? tanhf(sft) : sft; }
;                 u32x2 w; w.x = cvt_pk_bf16(o4[0], o4[1]); w.y = cvt_pk_bf16(o4[2], o4[3]); *(u32x2*)(AL + (size_t)(t0 + i) * 256 + alc) = w;
;                 vp = vc; vc = vn; lp = lc; lc = ln;
	v_pk_add_f32 v[226:227], v[188:189], v[172:173] neg_lo:[0,1] neg_hi:[0,1]
	v_pk_fma_f32 v[204:205], v[108:109], v[224:225], v[172:173]
	v_pk_fma_f32 v[204:205], v[124:125], v[226:227], v[204:205]
	v_pk_add_f32 v[224:225], v[158:159], v[174:175] neg_lo:[0,1] neg_hi:[0,1]
	v_pk_add_f32 v[226:227], v[190:191], v[174:175] neg_lo:[0,1] neg_hi:[0,1]
	v_pk_fma_f32 v[206:207], v[110:111], v[224:225], v[174:175]
	v_pk_fma_f32 v[206:207], v[126:127], v[226:227], v[206:207]
	v_cvt_pk_bf16_f32 v208, v192, v193
	v_cvt_pk_bf16_f32 v209, v194, v195
	v_cvt_pk_bf16_f32 v210, v196, v197
	v_cvt_pk_bf16_f32 v211, v198, v199
	v_cvt_pk_bf16_f32 v212, v200, v201
	v_cvt_pk_bf16_f32 v213, v202, v203
	v_cvt_pk_bf16_f32 v214, v204, v205
	v_cvt_pk_bf16_f32 v215, v206, v207
	buffer_store_dwordx4 v[208:211], v237, s[68:71], s73 offen offset:0
	buffer_store_dwordx4 v[212:215], v237, s[68:71], s73 offen offset:16
	v_sub_f32_e32 v224, v136, v140
	v_sub_f32_e32 v225, v216, v140
	v_fma_f32 v220, v128, v224, v140
	v_fma_f32 v220, v132, v225, v220
	v_sub_f32_e32 v224, v137, v141
	v_sub_f32_e32 v225, v217, v141
	v_fma_f32 v221, v129, v224, v141
	v_fma_f32 v221, v133, v225, v221
	v_sub_f32_e32 v224, v138, v142
	v_sub_f32_e32 v225, v218, v142
	v_fma_f32 v222, v130, v224, v142
	v_fma_f32 v222, v134, v225, v222
	v_sub_f32_e32 v224, v139, v143
	v_sub_f32_e32 v225, v219, v143
	v_fma_f32 v223, v131, v224, v143
	v_fma_f32 v223, v135, v225, v223
	v_and_b32_e32 v224, 0x7fffffff, v220
	v_mul_f32_e32 v225, 0x4038aa3b, v224
	v_exp_f32_e32 v225, v225
	v_mul_f32_e32 v226, v220, v220
	v_add_f32_e32 v225, 1.0, v225
	v_rcp_f32_e32 v225, v225
	v_mul_f32_e32 v227, 0xbeaaaaab, v226
	v_fma_f32 v225, v225, -2.0, 1.0
	v_fma_f32 v227, v227, v220, v220
	v_bfi_b32 v225, v241, v225, v220
	v_cmp_gt_f32_e32 vcc, 0x3d000000, v224
	s_nop 1
	v_cndmask_b32_e32 v225, v225, v227, vcc
	v_cmp_gt_u32_e32 vcc, 32, v240
	s_nop 1
	v_cndmask_b32_e32 v220, v220, v225, vcc
	v_and_b32_e32 v224, 0x7fffffff, v221
	v_mul_f32_e32 v225, 0x4038aa3b, v224
	v_exp_f32_e32 v225, v225
	v_mul_f32_e32 v226, v221, v221
	v_add_f32_e32 v225, 1.0, v225
	v_rcp_f32_e32 v225, v225
	v_mul_f32_e32 v227, 0xbeaaaaab, v226
	v_fma_f32 v225, v225, -2.0, 1.0
	v_fma_f32 v227, v227, v221, v221
	v_bfi_b32 v225, v241, v225, v221
	v_cmp_gt_f32_e32 vcc, 0x3d000000, v224
	s_nop 1
	v_cndmask_b32_e32 v225, v225, v227, vcc
	v_cmp_gt_u32_e32 vcc, 32, v240
	s_nop 1
	v_cndmask_b32_e32 v221, v221, v225, vcc
	v_and_b32_e32 v224, 0x7fffffff, v222
	v_mul_f32_e32 v225, 0x4038aa3b, v224
	v_exp_f32_e32 v225, v225
	v_mul_f32_e32 v226, v222, v222
	v_add_f32_e32 v225, 1.0, v225
	v_rcp_f32_e32 v225, v225
	v_mul_f32_e32 v227, 0xbeaaaaab, v226
	v_fma_f32 v225, v225, -2.0, 1.0
	v_fma_f32 v227, v227, v222, v222
	v_bfi_b32 v225, v241, v225, v222
	v_cmp_gt_f32_e32 vcc, 0x3d000000, v224
	s_nop 1
	v_cndmask_b32_e32 v225, v225, v227, vcc
	v_cmp_gt_u32_e32 vcc, 32, v240
	s_nop 1
	v_cndmask_b32_e32 v222, v222, v225, vcc
	v_and_b32_e32 v224, 0x7fffffff, v223
	v_mul_f32_e32 v225, 0x4038aa3b, v224
	v_exp_f32_e32 v225, v225
	v_mul_f32_e32 v226, v223, v223
	v_add_f32_e32 v225, 1.0, v225
	v_rcp_f32_e32 v225, v225
	v_mul_f32_e32 v227, 0xbeaaaaab, v226
	v_fma_f32 v225, v225, -2.0, 1.0
	v_fma_f32 v227, v227, v223, v223
	v_bfi_b32 v225, v241, v225, v223
	v_cmp_gt_f32_e32 vcc, 0x3d000000, v224
	s_nop 1
	v_cndmask_b32_e32 v225, v225, v227, vcc
	v_cmp_gt_u32_e32 vcc, 32, v240
	s_nop 1
	v_cndmask_b32_e32 v223, v223, v225, vcc
	v_cvt_pk_bf16_f32 v224, v220, v221
	v_cvt_pk_bf16_f32 v225, v222, v223
	buffer_store_dwordx2 v[224:225], v238, s[68:71], s74 offen
	s_add_u32 s72, s72, 0x1000
	s_add_u32 s73, s73, 0x800
	s_add_u32 s74, s74, 0x200
	s_add_u32 s75, s75, 0x40
	s_waitcnt vmcnt(27)
	v_lshlrev_b32_e32 v144, 16, v48
	v_and_b32_e32 v145, 0xffff0000, v48
	v_lshlrev_b32_e32 v146, 16, v49
	v_and_b32_e32 v147, 0xffff0000, v49
	v_lshlrev_b32_e32 v148, 16, v50
	v_and_b32_e32 v149, 0xffff0000, v50
	v_lshlrev_b32_e32 v150, 16, v51
	v_and_b32_e32 v151, 0xffff0000, v51
	v_lshlrev_b32_e32 v152, 16, v52
	v_and_b32_e32 v153, 0xffff0000, v52
	v_lshlrev_b32_e32 v154, 16, v53
	v_and_b32_e32 v155, 0xffff0000, v53
	v_lshlrev_b32_e32 v156, 16, v54
	v_and_b32_e32 v157, 0xffff0000, v54
	v_lshlrev_b32_e32 v158, 16, v55
	v_and_b32_e32 v159, 0xffff0000, v55
	v_lshlrev_b32_e32 v160, 16, v60
	v_and_b32_e32 v161, 0xffff0000, v60
	v_lshlrev_b32_e32 v162, 16, v61
	v_and_b32_e32 v163, 0xffff0000, v61
	v_lshlrev_b32_e32 v164, 16, v62
	v_and_b32_e32 v165, 0xffff0000, v62
	v_lshlrev_b32_e32 v166, 16, v63
	v_and_b32_e32 v167, 0xffff0000, v63
	v_lshlrev_b32_e32 v168, 16, v64
	v_and_b32_e32 v169, 0xffff0000, v64
	v_lshlrev_b32_e32 v170, 16, v65
	v_and_b32_e32 v171, 0xffff0000, v65
	v_lshlrev_b32_e32 v172, 16, v66
	v_and_b32_e32 v173, 0xffff0000, v66
	v_lshlrev_b32_e32 v174, 16, v67
	v_and_b32_e32 v175, 0xffff0000, v67
	v_lshlrev_b32_e32 v176, 16, v72
	v_and_b32_e32 v177, 0xffff0000, v72
	v_lshlrev_b32_e32 v178, 16, v73
	v_and_b32_e32 v179, 0xffff0000, v73
	v_lshlrev_b32_e32 v180, 16, v74
	v_and_b32_e32 v181, 0xffff0000, v74
	v_lshlrev_b32_e32 v182, 16, v75
	v_and_b32_e32 v183, 0xffff0000, v75
	v_lshlrev_b32_e32 v184, 16, v76
	v_and_b32_e32 v185, 0xffff0000, v76
	v_lshlrev_b32_e32 v186, 16, v77
	v_and_b32_e32 v187, 0xffff0000, v77
	v_lshlrev_b32_e32 v188, 16, v78
	v_and_b32_e32 v189, 0xffff0000, v78
	v_lshlrev_b32_e32 v190, 16, v79
	v_and_b32_e32 v191, 0xffff0000, v79
	v_lshlrev_b32_e32 v136, 16, v56
	v_and_b32_e32 v137, 0xffff0000, v56
	v_lshlrev_b32_e32 v138, 16, v57
	v_and_b32_e32 v139, 0xffff0000, v57
	v_lshlrev_b32_e32 v140, 16, v68
	v_and_b32_e32 v141, 0xffff0000, v68
	v_lshlrev_b32_e32 v142, 16, v69
	v_and_b32_e32 v143, 0xffff0000, v69
; __device__ __forceinline__ float bflo(unsigned w) { return __uint_as_float(w << 16); }
; __device__ __forceinline__ float bfhi(unsigned w) { return __uint_as_float(w & 0xffff0000u); }
; __device__ __forceinline__ unsigned cvt_pk_bf16(float lo, float hi) { unsigned r; asm volatile("v_cvt_pk_bf16_f32 %0, %1, %2" : "=v"(r) : "v"(lo), "v"(hi)); return r; }
; __device__ __forceinline__ void prep_phase(const Params& p) {
;     ...
;                 float v[16]; mix16(vp, vc, vn, mpv, mnv, v);
;                 st16bf(V + (size_t)(t0 + i) * RW + c, v);
;                 const float z4[4] = {bflo(lc.x), bfhi(lc.x), bflo(lc.y), bfhi(lc.y)}, p4[4] = {bflo(lp.x), bfhi(lp.x), bflo(lp.y), bfhi(lp.y)}, n4[4] = {bflo(ln.x), bfhi(ln.x), bflo(ln.y), bfhi(ln.y)};
;                 float o4[4];
; #pragma unroll
;                 for (int j = 0; j < 4; ++j) { const float sft = z4[j] + la[j] * (p4[j] - z4[j]) + lb[j] * (n4[j] - z4[j]); o4[j] = (lane < 32) ? tanhf(sft) : sft; }
;                 u32x2 w; w.x = cvt_pk_bf16(o4[0], o4[1]); w.y = cvt_pk_bf16(o4[2], o4[3]); *(u32x2*)(AL + (size_t)(t0 + i) * 256 + alc) = w;
;                 vp = vc; vc = vn; lp = lc; lc = ln;
	v_lshlrev_b32_e32 v216, 16, v80
	v_and_b32_e32 v217, 0xffff0000, v80
	v_lshlrev_b32_e32 v218, 16, v81
	v_and_b32_e32 v219, 0xffff0000, v81
	v_pk_add_f32 v[224:225], v[144:145], v[160:161] neg_lo:[0,1] neg_hi:[0,1]
	v_pk_add_f32 v[226:227], v[176:177], v[160:161] neg_lo:[0,1] neg_hi:[0,1]
	v_pk_fma_f32 v[192:193], v[96:97], v[224:225], v[160:161]
	v_pk_fma_f32 v[192:193], v[112:113], v[226:227], v[192:193]
	v_pk_add_f32 v[224:225], v[146:147], v[162:163] neg_lo:[0,1] neg_hi:[0,1]
	v_pk_add_f32 v[226:227], v[178:179], v[162:163] neg_lo:[0,1] neg_hi:[0,1]
	v_pk_fma_f32 v[194:195], v[98:99], v[224:225], v[162:163]
	v_pk_fma_f32 v[194:195], v[114:115], v[226:227], v[194:195]
	v_pk_add_f32 v[224:225], v[148:149], v[164:165] neg_lo:[0,1] neg_hi:[0,1]
	v_pk_add_f32 v[226:227], v[180:181], v[164:165] neg_lo:[0,1] neg_hi:[0,1]
	v_pk_fma_f32 v[196:197], v[100:101], v[224:225], v[164:165]
	v_pk_fma_f32 v[196:197], v[116:117], v[226:227], v[196:197]
	v_pk_add_f32 v[224:225], v[150:151], v[166:167] neg_lo:[0,1] neg_hi:[0,1]
	v_pk_add_f32 v[226:227], v[182:183], v[166:167] neg_lo:[0,1] neg_hi:[0,1]
	v_pk_fma_f32 v[198:199], v[102:103], v[224:225], v[166:167]
	v_pk_fma_f32 v[198:199], v[118:119], v[226:227], v[198:199]
	v_pk_add_f32 v[224:225], v[152:153], v[168:169] neg_lo:[0,1] neg_hi:[0,1]
	v_pk_add_f32 v[226:227], v[184:185], v[168:169] neg_lo:[0,1] neg_hi:[0,1]
	v_pk_fma_f32 v[200:201], v[104:105], v[224:225], v[168:169]
	v_pk_fma_f32 v[200:201], v[120:121], v[226:227], v[200:201]
	v_pk_add_f32 v[224:225], v[154:155], v[170:171] neg_lo:[0,1] neg_hi:[0,1]
	v_pk_add_f32 v[226:227], v[186:187], v[170:171] neg_lo:[0,1] neg_hi:[0,1]
	v_pk_fma_f32 v[202:203], v[106:107], v[224:225], v[170:171]
	v_pk_fma_f32 v[202:203], v[122:123], v[226:227], v[202:203]
	v_pk_add_f32 v[224:225], v[156:157], v[172:173] neg_lo:[0,1] neg_hi:[0,1]
	v_pk_add_f32 v[226:227], v[188:189], v[172:173] neg_lo:[0,1] neg_hi:[0,1]
	v_pk_fma_f32 v[204:205], v[108:109], v[224:225], v[172:173]
	v_pk_fma_f32 v[204:205], v[124:125], v[226:227], v[204:205]
	v_pk_add_f32 v[224:225], v[158:159], v[174:175] neg_lo:[0,1] neg_hi:[0,1]
	v_pk_add_f32 v[226:227], v[190:191], v[174:175] neg_lo:[0,1] neg_hi:[0,1]
	v_pk_fma_f32 v[206:207], v[110:111], v[224:225], v[174:175]
	v_pk_fma_f32 v[206:207], v[126:127], v[226:227], v[206:207]
	v_cvt_pk_bf16_f32 v208, v192, v193
	v_cvt_pk_bf16_f32 v209, v194, v195
	v_cvt_pk_bf16_f32 v210, v196, v197
	v_cvt_pk_bf16_f32 v211, v198, v199
	v_cvt_pk_bf16_f32 v212, v200, v201
	v_cvt_pk_bf16_f32 v213, v202, v203
	v_cvt_pk_bf16_f32 v214, v204, v205
	v_cvt_pk_bf16_f32 v215, v206, v207
	buffer_store_dwordx4 v[208:211], v237, s[68:71], s73 offen offset:0
	buffer_store_dwordx4 v[212:215], v237, s[68:71], s73 offen offset:16
	v_sub_f32_e32 v224, v136, v140
	v_sub_f32_e32 v225, v216, v140
	v_fma_f32 v220, v128, v224, v140
	v_fma_f32 v220, v132, v225, v220
	v_sub_f32_e32 v224, v137, v141
	v_sub_f32_e32 v225, v217, v141
	v_fma_f32 v221, v129, v224, v141
	v_fma_f32 v221, v133, v225, v221
	v_sub_f32_e32 v224, v138, v142
	v_sub_f32_e32 v225, v218, v142
	v_fma_f32 v222, v130, v224, v142
	v_fma_f32 v222, v134, v225, v222
	v_sub_f32_e32 v224, v139, v143
	v_sub_f32_e32 v225, v219, v143
	v_fma_f32 v223, v131, v224, v143
	v_fma_f32 v223, v135, v225, v223
	v_and_b32_e32 v224, 0x7fffffff, v220
	v_mul_f32_e32 v225, 0x4038aa3b, v224
	v_exp_f32_e32 v225, v225
	v_mul_f32_e32 v226, v220, v220
	v_add_f32_e32 v225, 1.0, v225
	v_rcp_f32_e32 v225, v225
	v_mul_f32_e32 v227, 0xbeaaaaab, v226
	v_fma_f32 v225, v225, -2.0, 1.0
	v_fma_f32 v227, v227, v220, v220
	v_bfi_b32 v225, v241, v225, v220
	v_cmp_gt_f32_e32 vcc, 0x3d000000, v224
	s_nop 1
	v_cndmask_b32_e32 v225, v225, v227, vcc
	v_cmp_gt_u32_e32 vcc, 32, v240
	s_nop 1
	v_cndmask_b32_e32 v220, v220, v225, vcc
	v_and_b32_e32 v224, 0x7fffffff, v221
	v_mul_f32_e32 v225, 0x4038aa3b, v224
	v_exp_f32_e32 v225, v225
	v_mul_f32_e32 v226, v221, v221
	v_add_f32_e32 v225, 1.0, v225
	v_rcp_f32_e32 v225, v225
	v_mul_f32_e32 v227, 0xbeaaaaab, v226
	v_fma_f32 v225, v225, -2.0, 1.0
	v_fma_f32 v227, v227, v221, v221
	v_bfi_b32 v225, v241, v225, v221
	v_cmp_gt_f32_e32 vcc, 0x3d000000, v224
	s_nop 1
	v_cndmask_b32_e32 v225, v225, v227, vcc
	v_cmp_gt_u32_e32 vcc, 32, v240
	s_nop 1
	v_cndmask_b32_e32 v221, v221, v225, vcc
	v_and_b32_e32 v224, 0x7fffffff, v222
	v_mul_f32_e32 v225, 0x4038aa3b, v224
	v_exp_f32_e32 v225, v225
	v_mul_f32_e32 v226, v222, v222
	v_add_f32_e32 v225, 1.0, v225
	v_rcp_f32_e32 v225, v225
	v_mul_f32_e32 v227, 0xbeaaaaab, v226
	v_fma_f32 v225, v225, -2.0, 1.0
	v_fma_f32 v227, v227, v222, v222
	v_bfi_b32 v225, v241, v225, v222
	v_cmp_gt_f32_e32 vcc, 0x3d000000, v224
	s_nop 1
	v_cndmask_b32_e32 v225, v225, v227, vcc
	v_cmp_gt_u32_e32 vcc, 32, v240
	s_nop 1
	v_cndmask_b32_e32 v222, v222, v225, vcc
	v_and_b32_e32 v224, 0x7fffffff, v223
	v_mul_f32_e32 v225, 0x4038aa3b, v224
	v_exp_f32_e32 v225, v225
	v_mul_f32_e32 v226, v223, v223
	v_add_f32_e32 v225, 1.0, v225
	v_rcp_f32_e32 v225, v225
	v_mul_f32_e32 v227, 0xbeaaaaab, v226
	v_fma_f32 v225, v225, -2.0, 1.0
	v_fma_f32 v227, v227, v223, v223
	v_bfi_b32 v225, v241, v225, v223
	v_cmp_gt_f32_e32 vcc, 0x3d000000, v224
	s_nop 1
	v_cndmask_b32_e32 v225, v225, v227, vcc
	v_cmp_gt_u32_e32 vcc, 32, v240
	s_nop 1
	v_cndmask_b32_e32 v223, v223, v225, vcc
	v_cvt_pk_bf16_f32 v224, v220, v221
	v_cvt_pk_bf16_f32 v225, v222, v223
	buffer_store_dwordx2 v[224:225], v238, s[68:71], s74 offen
	s_add_u32 s72, s72, 0x1000
	s_add_u32 s73, s73, 0x800
	s_add_u32 s74, s74, 0x200
	s_add_u32 s75, s75, 0x40
	s_waitcnt vmcnt(24)
; __device__ __forceinline__ float bflo(unsigned w) { return __uint_as_float(w << 16); }
; __device__ __forceinline__ float bfhi(unsigned w) { return __uint_as_float(w & 0xffff0000u); }
; __device__ __forceinline__ unsigned cvt_pk_bf16(float lo, float hi) { unsigned r; asm volatile("v_cvt_pk_bf16_f32 %0, %1, %2" : "=v"(r) : "v"(lo), "v"(hi)); return r; }
; __device__ __forceinline__ void prep_phase(const Params& p) {
;     ...
;                 const bool hn = (tt0 + i) < SEQ - 1; const u16* zn = zc + (size_t)(i + 1) * 3328;
;                 const Z16 vn = hn ? ldz(zn + 2048 + c) : zz(); const u32x2 ln = hn ? *(const u32x2*)(zn + cl) : (u32x2){0u, 0u};
;                 float v[16]; mix16(vp, vc, vn, mpv, mnv, v);
;                 st16bf(V + (size_t)(t0 + i) * RW + c, v);
;                 const float z4[4] = {bflo(lc.x), bfhi(lc.x), bflo(lc.y), bfhi(lc.y)}, p4[4] = {bflo(lp.x), bfhi(lp.x), bflo(lp.y), bfhi(lp.y)}, n4[4] = {bflo(ln.x), bfhi(ln.x), bflo(ln.y), bfhi(ln.y)};
;                 float o4[4];
; #pragma unroll
;                 for (int j = 0; j < 4; ++j) { const float sft = z4[j] + la[j] * (p4[j] - z4[j]) + lb[j] * (n4[j] - z4[j]); o4[j] = (lane < 32) ? tanhf(sft) : sft; }
;                 u32x2 w; w.x = cvt_pk_bf16(o4[0], o4[1]); w.y = cvt_pk_bf16(o4[2], o4[3]); *(u32x2*)(AL + (size_t)(t0 + i) * 256 + alc) = w;
;                 vp = vc; vc = vn; lp = lc; lc = ln;
	v_lshlrev_b32_e32 v144, 16, v60
	v_and_b32_e32 v145, 0xffff0000, v60
	v_lshlrev_b32_e32 v146, 16, v61
	v_and_b32_e32 v147, 0xffff0000, v61
	v_lshlrev_b32_e32 v148, 16, v62
	v_and_b32_e32 v149, 0xffff0000, v62
	v_lshlrev_b32_e32 v150, 16, v63
	v_and_b32_e32 v151, 0xffff0000, v63
	v_lshlrev_b32_e32 v152, 16, v64
	v_and_b32_e32 v153, 0xffff0000, v64
	v_lshlrev_b32_e32 v154, 16, v65
	v_and_b32_e32 v155, 0xffff0000, v65
	v_lshlrev_b32_e32 v156, 16, v66
	v_and_b32_e32 v157, 0xffff0000, v66
	v_lshlrev_b32_e32 v158, 16, v67
	v_and_b32_e32 v159, 0xffff0000, v67
	v_lshlrev_b32_e32 v160, 16, v72
	v_and_b32_e32 v161, 0xffff0000, v72
	v_lshlrev_b32_e32 v162, 16, v73
	v_and_b32_e32 v163, 0xffff0000, v73
	v_lshlrev_b32_e32 v164, 16, v74
	v_and_b32_e32 v165, 0xffff0000, v74
	v_lshlrev_b32_e32 v166, 16, v75
	v_and_b32_e32 v167, 0xffff0000, v75
	v_lshlrev_b32_e32 v168, 16, v76
	v_and_b32_e32 v169, 0xffff0000, v76
	v_lshlrev_b32_e32 v170, 16, v77
	v_and_b32_e32 v171, 0xffff0000, v77
	v_lshlrev_b32_e32 v172, 16, v78
	v_and_b32_e32 v173, 0xffff0000, v78
	v_lshlrev_b32_e32 v174, 16, v79
	v_and_b32_e32 v175, 0xffff0000, v79
	v_lshlrev_b32_e32 v176, 16, v84
	v_and_b32_e32 v177, 0xffff0000, v84
	v_lshlrev_b32_e32 v178, 16, v85
	v_and_b32_e32 v179, 0xffff0000, v85
	v_lshlrev_b32_e32 v180, 16, v86
	v_and_b32_e32 v181, 0xffff0000, v86
	v_lshlrev_b32_e32 v182, 16, v87
	v_and_b32_e32 v183, 0xffff0000, v87
	v_lshlrev_b32_e32 v184, 16, v88
	v_and_b32_e32 v185, 0xffff0000, v88
	v_lshlrev_b32_e32 v186, 16, v89
	v_and_b32_e32 v187, 0xffff0000, v89
	v_lshlrev_b32_e32 v188, 16, v90
	v_and_b32_e32 v189, 0xffff0000, v90
	v_lshlrev_b32_e32 v190, 16, v91
	v_and_b32_e32 v191, 0xffff0000, v91
	v_lshlrev_b32_e32 v136, 16, v68
	v_and_b32_e32 v137, 0xffff0000, v68
	v_lshlrev_b32_e32 v138, 16, v69
	v_and_b32_e32 v139, 0xffff0000, v69
	v_lshlrev_b32_e32 v140, 16, v80
	v_and_b32_e32 v141, 0xffff0000, v80
	v_lshlrev_b32_e32 v142, 16, v81
	v_and_b32_e32 v143, 0xffff0000, v81
	v_lshlrev_b32_e32 v216, 16, v92
	v_and_b32_e32 v217, 0xffff0000, v92
	v_lshlrev_b32_e32 v218, 16, v93
	v_and_b32_e32 v219, 0xffff0000, v93
	v_pk_add_f32 v[224:225], v[144:145], v[160:161] neg_lo:[0,1] neg_hi:[0,1]
	v_pk_add_f32 v[226:227], v[176:177], v[160:161] neg_lo:[0,1] neg_hi:[0,1]
	v_pk_fma_f32 v[192:193], v[96:97], v[224:225], v[160:161]
	v_pk_fma_f32 v[192:193], v[112:113], v[226:227], v[192:193]
	v_pk_add_f32 v[224:225], v[146:147], v[162:163] neg_lo:[0,1] neg_hi:[0,1]
	v_pk_add_f32 v[226:227], v[178:179], v[162:163] neg_lo:[0,1] neg_hi:[0,1]
	v_pk_fma_f32 v[194:195], v[98:99], v[224:225], v[162:163]
	v_pk_fma_f32 v[194:195], v[114:115], v[226:227], v[194:195]
	v_pk_add_f32 v[224:225], v[148:149], v[164:165] neg_lo:[0,1] neg_hi:[0,1]
	v_pk_add_f32 v[226:227], v[180:181], v[164:165] neg_lo:[0,1] neg_hi:[0,1]
	v_pk_fma_f32 v[196:197], v[100:101], v[224:225], v[164:165]
	v_pk_fma_f32 v[196:197], v[116:117], v[226:227], v[196:197]
	v_pk_add_f32 v[224:225], v[150:151], v[166:167] neg_lo:[0,1] neg_hi:[0,1]
	v_pk_add_f32 v[226:227], v[182:183], v[166:167] neg_lo:[0,1] neg_hi:[0,1]
	v_pk_fma_f32 v[198:199], v[102:103], v[224:225], v[166:167]
	v_pk_fma_f32 v[198:199], v[118:119], v[226:227], v[198:199]
	v_pk_add_f32 v[224:225], v[152:153], v[168:169] neg_lo:[0,1] neg_hi:[0,1]
	v_pk_add_f32 v[226:227], v[184:185], v[168:169] neg_lo:[0,1] neg_hi:[0,1]
	v_pk_fma_f32 v[200:201], v[104:105], v[224:225], v[168:169]
	v_pk_fma_f32 v[200:201], v[120:121], v[226:227], v[200:201]
	v_pk_add_f32 v[224:225], v[154:155], v[170:171] neg_lo:[0,1] neg_hi:[0,1]
	v_pk_add_f32 v[226:227], v[186:187], v[170:171] neg_lo:[0,1] neg_hi:[0,1]
	v_pk_fma_f32 v[202:203], v[106:107], v[224:225], v[170:171]
	v_pk_fma_f32 v[202:203], v[122:123], v[226:227], v[202:203]
	v_pk_add_f32 v[224:225], v[156:157], v[172:173] neg_lo:[0,1] neg_hi:[0,1]
	v_pk_add_f32 v[226:227], v[188:189], v[172:173] neg_lo:[0,1] neg_hi:[0,1]
	v_pk_fma_f32 v[204:205], v[108:109], v[224:225], v[172:173]
	v_pk_fma_f32 v[204:205], v[124:125], v[226:227], v[204:205]
	v_pk_add_f32 v[224:225], v[158:159], v[174:175] neg_lo:[0,1] neg_hi:[0,1]
	v_pk_add_f32 v[226:227], v[190:191], v[174:175] neg_lo:[0,1] neg_hi:[0,1]
	v_pk_fma_f32 v[206:207], v[110:111], v[224:225], v[174:175]
	v_pk_fma_f32 v[206:207], v[126:127], v[226:227], v[206:207]
	v_cvt_pk_bf16_f32 v208, v192, v193
	v_cvt_pk_bf16_f32 v209, v194, v195
	v_cvt_pk_bf16_f32 v210, v196, v197
	v_cvt_pk_bf16_f32 v211, v198, v199
	v_cvt_pk_bf16_f32 v212, v200, v201
	v_cvt_pk_bf16_f32 v213, v202, v203
	v_cvt_pk_bf16_f32 v214, v204, v205
	v_cvt_pk_bf16_f32 v215, v206, v207
	buffer_store_dwordx4 v[208:211], v237, s[68:71], s73 offen offset:0
	buffer_store_dwordx4 v[212:215], v237, s[68:71], s73 offen offset:16
	v_sub_f32_e32 v224, v136, v140
	v_sub_f32_e32 v225, v216, v140
	v_fma_f32 v220, v128, v224, v140
	v_fma_f32 v220, v132, v225, v220
	v_sub_f32_e32 v224, v137, v141
	v_sub_f32_e32 v225, v217, v141
	v_fma_f32 v221, v129, v224, v141
	v_fma_f32 v221, v133, v225, v221
	v_sub_f32_e32 v224, v138, v142
	v_sub_f32_e32 v225, v218, v142
	v_fma_f32 v222, v130, v224, v142
	v_fma_f32 v222, v134, v225, v222
	v_sub_f32_e32 v224, v139, v143
	v_sub_f32_e32 v225, v219, v143
	v_fma_f32 v223, v131, v224, v143
	v_fma_f32 v223, v135, v225, v223
	v_and_b32_e32 v224, 0x7fffffff, v220
	v_mul_f32_e32 v225, 0x4038aa3b, v224
	v_exp_f32_e32 v225, v225
	v_mul_f32_e32 v226, v220, v220
	v_add_f32_e32 v225, 1.0, v225
	v_rcp_f32_e32 v225, v225
	v_mul_f32_e32 v227, 0xbeaaaaab, v226
	v_fma_f32 v225, v225, -2.0, 1.0
	v_fma_f32 v227, v227, v220, v220
	v_bfi_b32 v225, v241, v225, v220
	v_cmp_gt_f32_e32 vcc, 0x3d000000, v224
	s_nop 1
	v_cndmask_b32_e32 v225, v225, v227, vcc
; __device__ __forceinline__ float bflo(unsigned w) { return __uint_as_float(w << 16); }
; __device__ __forceinline__ float bfhi(unsigned w) { return __uint_as_float(w & 0xffff0000u); }
; __device__ __forceinline__ unsigned cvt_pk_bf16(float lo, float hi) { unsigned r; asm volatile("v_cvt_pk_bf16_f32 %0, %1, %2" : "=v"(r) : "v"(lo), "v"(hi)); return r; }
; __device__ __forceinline__ void prep_phase(const Params& p) {
;     ...
;                 float v[16]; mix16(vp, vc, vn, mpv, mnv, v);
;                 st16bf(V + (size_t)(t0 + i) * RW + c, v);
;                 const float z4[4] = {bflo(lc.x), bfhi(lc.x), bflo(lc.y), bfhi(lc.y)}, p4[4] = {bflo(lp.x), bfhi(lp.x), bflo(lp.y), bfhi(lp.y)}, n4[4] = {bflo(ln.x), bfhi(ln.x), bflo(ln.y), bfhi(ln.y)};
;                 float o4[4];
; #pragma unroll
;                 for (int j = 0; j < 4; ++j) { const float sft = z4[j] + la[j] * (p4[j] - z4[j]) + lb[j] * (n4[j] - z4[j]); o4[j] = (lane < 32) ? tanhf(sft) : sft; }
;                 u32x2 w; w.x = cvt_pk_bf16(o4[0], o4[1]); w.y = cvt_pk_bf16(o4[2], o4[3]); *(u32x2*)(AL + (size_t)(t0 + i) * 256 + alc) = w;
;                 vp = vc; vc = vn; lp = lc; lc = ln;
	v_cmp_gt_u32_e32 vcc, 32, v240
	s_nop 1
	v_cndmask_b32_e32 v220, v220, v225, vcc
	v_and_b32_e32 v224, 0x7fffffff, v221
	v_mul_f32_e32 v225, 0x4038aa3b, v224
	v_exp_f32_e32 v225, v225
	v_mul_f32_e32 v226, v221, v221
	v_add_f32_e32 v225, 1.0, v225
	v_rcp_f32_e32 v225, v225
	v_mul_f32_e32 v227, 0xbeaaaaab, v226
	v_fma_f32 v225, v225, -2.0, 1.0
	v_fma_f32 v227, v227, v221, v221
	v_bfi_b32 v225, v241, v225, v221
	v_cmp_gt_f32_e32 vcc, 0x3d000000, v224
	s_nop 1
	v_cndmask_b32_e32 v225, v225, v227, vcc
	v_cmp_gt_u32_e32 vcc, 32, v240
	s_nop 1
	v_cndmask_b32_e32 v221, v221, v225, vcc
	v_and_b32_e32 v224, 0x7fffffff, v222
	v_mul_f32_e32 v225, 0x4038aa3b, v224
	v_exp_f32_e32 v225, v225
	v_mul_f32_e32 v226, v222, v222
	v_add_f32_e32 v225, 1.0, v225
	v_rcp_f32_e32 v225, v225
	v_mul_f32_e32 v227, 0xbeaaaaab, v226
	v_fma_f32 v225, v225, -2.0, 1.0
	v_fma_f32 v227, v227, v222, v222
	v_bfi_b32 v225, v241, v225, v222
	v_cmp_gt_f32_e32 vcc, 0x3d000000, v224
	s_nop 1
	v_cndmask_b32_e32 v225, v225, v227, vcc
	v_cmp_gt_u32_e32 vcc, 32, v240
	s_nop 1
	v_cndmask_b32_e32 v222, v222, v225, vcc
	v_and_b32_e32 v224, 0x7fffffff, v223
	v_mul_f32_e32 v225, 0x4038aa3b, v224
	v_exp_f32_e32 v225, v225
	v_mul_f32_e32 v226, v223, v223
	v_add_f32_e32 v225, 1.0, v225
	v_rcp_f32_e32 v225, v225
	v_mul_f32_e32 v227, 0xbeaaaaab, v226
	v_fma_f32 v225, v225, -2.0, 1.0
	v_fma_f32 v227, v227, v223, v223
	v_bfi_b32 v225, v241, v225, v223
	v_cmp_gt_f32_e32 vcc, 0x3d000000, v224
	s_nop 1
	v_cndmask_b32_e32 v225, v225, v227, vcc
	v_cmp_gt_u32_e32 vcc, 32, v240
	s_nop 1
	v_cndmask_b32_e32 v223, v223, v225, vcc
	v_cvt_pk_bf16_f32 v224, v220, v221
	v_cvt_pk_bf16_f32 v225, v222, v223
	buffer_store_dwordx2 v[224:225], v238, s[68:71], s74 offen
	s_add_u32 s72, s72, 0x1000
	s_add_u32 s73, s73, 0x800
	s_add_u32 s74, s74, 0x200
	s_add_u32 s75, s75, 0x40
	s_waitcnt vmcnt(21)
	v_lshlrev_b32_e32 v144, 16, v72
	v_and_b32_e32 v145, 0xffff0000, v72
	v_lshlrev_b32_e32 v146, 16, v73
	v_and_b32_e32 v147, 0xffff0000, v73
	v_lshlrev_b32_e32 v148, 16, v74
	v_and_b32_e32 v149, 0xffff0000, v74
	v_lshlrev_b32_e32 v150, 16, v75
	v_and_b32_e32 v151, 0xffff0000, v75
	v_lshlrev_b32_e32 v152, 16, v76
	v_and_b32_e32 v153, 0xffff0000, v76
	v_lshlrev_b32_e32 v154, 16, v77
	v_and_b32_e32 v155, 0xffff0000, v77
	v_lshlrev_b32_e32 v156, 16, v78
	v_and_b32_e32 v157, 0xffff0000, v78
	v_lshlrev_b32_e32 v158, 16, v79
	v_and_b32_e32 v159, 0xffff0000, v79
	v_lshlrev_b32_e32 v160, 16, v84
	v_and_b32_e32 v161, 0xffff0000, v84
	v_lshlrev_b32_e32 v162, 16, v85
	v_and_b32_e32 v163, 0xffff0000, v85
	v_lshlrev_b32_e32 v164, 16, v86
	v_and_b32_e32 v165, 0xffff0000, v86
	v_lshlrev_b32_e32 v166, 16, v87
	v_and_b32_e32 v167, 0xffff0000, v87
	v_lshlrev_b32_e32 v168, 16, v88
	v_and_b32_e32 v169, 0xffff0000, v88
	v_lshlrev_b32_e32 v170, 16, v89
	v_and_b32_e32 v171, 0xffff0000, v89
	v_lshlrev_b32_e32 v172, 16, v90
	v_and_b32_e32 v173, 0xffff0000, v90
	v_lshlrev_b32_e32 v174, 16, v91
	v_and_b32_e32 v175, 0xffff0000, v91
	v_lshlrev_b32_e32 v176, 16, v0
	v_and_b32_e32 v177, 0xffff0000, v0
	v_lshlrev_b32_e32 v178, 16, v1
	v_and_b32_e32 v179, 0xffff0000, v1
	v_lshlrev_b32_e32 v180, 16, v2
	v_and_b32_e32 v181, 0xffff0000, v2
	v_lshlrev_b32_e32 v182, 16, v3
	v_and_b32_e32 v183, 0xffff0000, v3
	v_lshlrev_b32_e32 v184, 16, v4
	v_and_b32_e32 v185, 0xffff0000, v4
	v_lshlrev_b32_e32 v186, 16, v5
	v_and_b32_e32 v187, 0xffff0000, v5
	v_lshlrev_b32_e32 v188, 16, v6
	v_and_b32_e32 v189, 0xffff0000, v6
	v_lshlrev_b32_e32 v190, 16, v7
	v_and_b32_e32 v191, 0xffff0000, v7
	v_lshlrev_b32_e32 v136, 16, v80
	v_and_b32_e32 v137, 0xffff0000, v80
	v_lshlrev_b32_e32 v138, 16, v81
	v_and_b32_e32 v139, 0xffff0000, v81
	v_lshlrev_b32_e32 v140, 16, v92
	v_and_b32_e32 v141, 0xffff0000, v92
	v_lshlrev_b32_e32 v142, 16, v93
	v_and_b32_e32 v143, 0xffff0000, v93
	v_lshlrev_b32_e32 v216, 16, v8
	v_and_b32_e32 v217, 0xffff0000, v8
	v_lshlrev_b32_e32 v218, 16, v9
	v_and_b32_e32 v219, 0xffff0000, v9
	v_pk_add_f32 v[224:225], v[144:145], v[160:161] neg_lo:[0,1] neg_hi:[0,1]
	v_pk_add_f32 v[226:227], v[176:177], v[160:161] neg_lo:[0,1] neg_hi:[0,1]
	v_pk_fma_f32 v[192:193], v[96:97], v[224:225], v[160:161]
	v_pk_fma_f32 v[192:193], v[112:113], v[226:227], v[192:193]
	v_pk_add_f32 v[224:225], v[146:147], v[162:163] neg_lo:[0,1] neg_hi:[0,1]
	v_pk_add_f32 v[226:227], v[178:179], v[162:163] neg_lo:[0,1] neg_hi:[0,1]
	v_pk_fma_f32 v[194:195], v[98:99], v[224:225], v[162:163]
	v_pk_fma_f32 v[194:195], v[114:115], v[226:227], v[194:195]
	v_pk_add_f32 v[224:225], v[148:149], v[164:165] neg_lo:[0,1] neg_hi:[0,1]
	v_pk_add_f32 v[226:227], v[180:181], v[164:165] neg_lo:[0,1] neg_hi:[0,1]
	v_pk_fma_f32 v[196:197], v[100:101], v[224:225], v[164:165]
	v_pk_fma_f32 v[196:197], v[116:117], v[226:227], v[196:197]
	v_pk_add_f32 v[224:225], v[150:151], v[166:167] neg_lo:[0,1] neg_hi:[0,1]
	v_pk_add_f32 v[226:227], v[182:183], v[166:167] neg_lo:[0,1] neg_hi:[0,1]
	v_pk_fma_f32 v[198:199], v[102:103], v[224:225], v[166:167]
	v_pk_fma_f32 v[198:199], v[118:119], v[226:227], v[198:199]
	v_pk_add_f32 v[224:225], v[152:153], v[168:169] neg_lo:[0,1] neg_hi:[0,1]
	v_pk_add_f32 v[226:227], v[184:185], v[168:169] neg_lo:[0,1] neg_hi:[0,1]
	v_pk_fma_f32 v[200:201], v[104:105], v[224:225], v[168:169]
	v_pk_fma_f32 v[200:201], v[120:121], v[226:227], v[200:201]
	v_pk_add_f32 v[224:225], v[154:155], v[170:171] neg_lo:[0,1] neg_hi:[0,1]
	v_pk_add_f32 v[226:227], v[186:187], v[170:171] neg_lo:[0,1] neg_hi:[0,1]
	v_pk_fma_f32 v[202:203], v[106:107], v[224:225], v[170:171]
	v_pk_fma_f32 v[202:203], v[122:123], v[226:227], v[202:203]
	v_pk_add_f32 v[224:225], v[156:157], v[172:173] neg_lo:[0,1] neg_hi:[0,1]
; __device__ __forceinline__ float bflo(unsigned w) { return __uint_as_float(w << 16); }
; __device__ __forceinline__ float bfhi(unsigned w) { return __uint_as_float(w & 0xffff0000u); }
; __device__ __forceinline__ unsigned cvt_pk_bf16(float lo, float hi) { unsigned r; asm volatile("v_cvt_pk_bf16_f32 %0, %1, %2" : "=v"(r) : "v"(lo), "v"(hi)); return r; }
; __device__ __forceinline__ void prep_phase(const Params& p) {
;     ...
;                 float v[16]; mix16(vp, vc, vn, mpv, mnv, v);
;                 st16bf(V + (size_t)(t0 + i) * RW + c, v);
;                 const float z4[4] = {bflo(lc.x), bfhi(lc.x), bflo(lc.y), bfhi(lc.y)}, p4[4] = {bflo(lp.x), bfhi(lp.x), bflo(lp.y), bfhi(lp.y)}, n4[4] = {bflo(ln.x), bfhi(ln.x), bflo(ln.y), bfhi(ln.y)};
;                 float o4[4];
; #pragma unroll
;                 for (int j = 0; j < 4; ++j) { const float sft = z4[j] + la[j] * (p4[j] - z4[j]) + lb[j] * (n4[j] - z4[j]); o4[j] = (lane < 32) ? tanhf(sft) : sft; }
;                 u32x2 w; w.x = cvt_pk_bf16(o4[0], o4[1]); w.y = cvt_pk_bf16(o4[2], o4[3]); *(u32x2*)(AL + (size_t)(t0 + i) * 256 + alc) = w;
;                 vp = vc; vc = vn; lp = lc; lc = ln;
	v_pk_add_f32 v[226:227], v[188:189], v[172:173] neg_lo:[0,1] neg_hi:[0,1]
	v_pk_fma_f32 v[204:205], v[108:109], v[224:225], v[172:173]
	v_pk_fma_f32 v[204:205], v[124:125], v[226:227], v[204:205]
	v_pk_add_f32 v[224:225], v[158:159], v[174:175] neg_lo:[0,1] neg_hi:[0,1]
	v_pk_add_f32 v[226:227], v[190:191], v[174:175] neg_lo:[0,1] neg_hi:[0,1]
	v_pk_fma_f32 v[206:207], v[110:111], v[224:225], v[174:175]
	v_pk_fma_f32 v[206:207], v[126:127], v[226:227], v[206:207]
	v_cvt_pk_bf16_f32 v208, v192, v193
	v_cvt_pk_bf16_f32 v209, v194, v195
	v_cvt_pk_bf16_f32 v210, v196, v197
	v_cvt_pk_bf16_f32 v211, v198, v199
	v_cvt_pk_bf16_f32 v212, v200, v201
	v_cvt_pk_bf16_f32 v213, v202, v203
	v_cvt_pk_bf16_f32 v214, v204, v205
	v_cvt_pk_bf16_f32 v215, v206, v207
	buffer_store_dwordx4 v[208:211], v237, s[68:71], s73 offen offset:0
	buffer_store_dwordx4 v[212:215], v237, s[68:71], s73 offen offset:16
	v_sub_f32_e32 v224, v136, v140
	v_sub_f32_e32 v225, v216, v140
	v_fma_f32 v220, v128, v224, v140
	v_fma_f32 v220, v132, v225, v220
	v_sub_f32_e32 v224, v137, v141
	v_sub_f32_e32 v225, v217, v141
	v_fma_f32 v221, v129, v224, v141
	v_fma_f32 v221, v133, v225, v221
	v_sub_f32_e32 v224, v138, v142
	v_sub_f32_e32 v225, v218, v142
	v_fma_f32 v222, v130, v224, v142
	v_fma_f32 v222, v134, v225, v222
	v_sub_f32_e32 v224, v139, v143
	v_sub_f32_e32 v225, v219, v143
	v_fma_f32 v223, v131, v224, v143
	v_fma_f32 v223, v135, v225, v223
	v_and_b32_e32 v224, 0x7fffffff, v220
	v_mul_f32_e32 v225, 0x4038aa3b, v224
	v_exp_f32_e32 v225, v225
	v_mul_f32_e32 v226, v220, v220
	v_add_f32_e32 v225, 1.0, v225
	v_rcp_f32_e32 v225, v225
	v_mul_f32_e32 v227, 0xbeaaaaab, v226
	v_fma_f32 v225, v225, -2.0, 1.0
	v_fma_f32 v227, v227, v220, v220
	v_bfi_b32 v225, v241, v225, v220
	v_cmp_gt_f32_e32 vcc, 0x3d000000, v224
	s_nop 1
	v_cndmask_b32_e32 v225, v225, v227, vcc
	v_cmp_gt_u32_e32 vcc, 32, v240
	s_nop 1
	v_cndmask_b32_e32 v220, v220, v225, vcc
	v_and_b32_e32 v224, 0x7fffffff, v221
	v_mul_f32_e32 v225, 0x4038aa3b, v224
	v_exp_f32_e32 v225, v225
	v_mul_f32_e32 v226, v221, v221
	v_add_f32_e32 v225, 1.0, v225
	v_rcp_f32_e32 v225, v225
	v_mul_f32_e32 v227, 0xbeaaaaab, v226
	v_fma_f32 v225, v225, -2.0, 1.0
	v_fma_f32 v227, v227, v221, v221
	v_bfi_b32 v225, v241, v225, v221
	v_cmp_gt_f32_e32 vcc, 0x3d000000, v224
	s_nop 1
	v_cndmask_b32_e32 v225, v225, v227, vcc
	v_cmp_gt_u32_e32 vcc, 32, v240
	s_nop 1
	v_cndmask_b32_e32 v221, v221, v225, vcc
	v_and_b32_e32 v224, 0x7fffffff, v222
	v_mul_f32_e32 v225, 0x4038aa3b, v224
	v_exp_f32_e32 v225, v225
	v_mul_f32_e32 v226, v222, v222
	v_add_f32_e32 v225, 1.0, v225
	v_rcp_f32_e32 v225, v225
	v_mul_f32_e32 v227, 0xbeaaaaab, v226
	v_fma_f32 v225, v225, -2.0, 1.0
	v_fma_f32 v227, v227, v222, v222
	v_bfi_b32 v225, v241, v225, v222
	v_cmp_gt_f32_e32 vcc, 0x3d000000, v224
	s_nop 1
	v_cndmask_b32_e32 v225, v225, v227, vcc
	v_cmp_gt_u32_e32 vcc, 32, v240
	s_nop 1
	v_cndmask_b32_e32 v222, v222, v225, vcc
	v_and_b32_e32 v224, 0x7fffffff, v223
	v_mul_f32_e32 v225, 0x4038aa3b, v224
	v_exp_f32_e32 v225, v225
	v_mul_f32_e32 v226, v223, v223
	v_add_f32_e32 v225, 1.0, v225
	v_rcp_f32_e32 v225, v225
	v_mul_f32_e32 v227, 0xbeaaaaab, v226
	v_fma_f32 v225, v225, -2.0, 1.0
	v_fma_f32 v227, v227, v223, v223
	v_bfi_b32 v225, v241, v225, v223
	v_cmp_gt_f32_e32 vcc, 0x3d000000, v224
	s_nop 1
	v_cndmask_b32_e32 v225, v225, v227, vcc
	v_cmp_gt_u32_e32 vcc, 32, v240
	s_nop 1
	v_cndmask_b32_e32 v223, v223, v225, vcc
	v_cvt_pk_bf16_f32 v224, v220, v221
	v_cvt_pk_bf16_f32 v225, v222, v223
	buffer_store_dwordx2 v[224:225], v238, s[68:71], s74 offen
	s_add_u32 s72, s72, 0x1000
	s_add_u32 s73, s73, 0x800
	s_add_u32 s74, s74, 0x200
	s_add_u32 s75, s75, 0x40
	s_waitcnt vmcnt(18)
	v_lshlrev_b32_e32 v144, 16, v84
	v_and_b32_e32 v145, 0xffff0000, v84
	v_lshlrev_b32_e32 v146, 16, v85
	v_and_b32_e32 v147, 0xffff0000, v85
	v_lshlrev_b32_e32 v148, 16, v86
	v_and_b32_e32 v149, 0xffff0000, v86
	v_lshlrev_b32_e32 v150, 16, v87
	v_and_b32_e32 v151, 0xffff0000, v87
	v_lshlrev_b32_e32 v152, 16, v88
	v_and_b32_e32 v153, 0xffff0000, v88
	v_lshlrev_b32_e32 v154, 16, v89
	v_and_b32_e32 v155, 0xffff0000, v89
	v_lshlrev_b32_e32 v156, 16, v90
	v_and_b32_e32 v157, 0xffff0000, v90
	v_lshlrev_b32_e32 v158, 16, v91
	v_and_b32_e32 v159, 0xffff0000, v91
	v_lshlrev_b32_e32 v160, 16, v0
	v_and_b32_e32 v161, 0xffff0000, v0
	v_lshlrev_b32_e32 v162, 16, v1
	v_and_b32_e32 v163, 0xffff0000, v1
	v_lshlrev_b32_e32 v164, 16, v2
	v_and_b32_e32 v165, 0xffff0000, v2
	v_lshlrev_b32_e32 v166, 16, v3
	v_and_b32_e32 v167, 0xffff0000, v3
	v_lshlrev_b32_e32 v168, 16, v4
	v_and_b32_e32 v169, 0xffff0000, v4
	v_lshlrev_b32_e32 v170, 16, v5
	v_and_b32_e32 v171, 0xffff0000, v5
	v_lshlrev_b32_e32 v172, 16, v6
	v_and_b32_e32 v173, 0xffff0000, v6
	v_lshlrev_b32_e32 v174, 16, v7
	v_and_b32_e32 v175, 0xffff0000, v7
	v_lshlrev_b32_e32 v176, 16, v12
	v_and_b32_e32 v177, 0xffff0000, v12
	v_lshlrev_b32_e32 v178, 16, v13
	v_and_b32_e32 v179, 0xffff0000, v13
	v_lshlrev_b32_e32 v180, 16, v14
	v_and_b32_e32 v181, 0xffff0000, v14
	v_lshlrev_b32_e32 v182, 16, v15
	v_and_b32_e32 v183, 0xffff0000, v15
	v_lshlrev_b32_e32 v184, 16, v16
	v_and_b32_e32 v185, 0xffff0000, v16
	v_lshlrev_b32_e32 v186, 16, v17
	v_and_b32_e32 v187, 0xffff0000, v17
	v_lshlrev_b32_e32 v188, 16, v18
	v_and_b32_e32 v189, 0xffff0000, v18
	v_lshlrev_b32_e32 v190, 16, v19
	v_and_b32_e32 v191, 0xffff0000, v19
	v_lshlrev_b32_e32 v136, 16, v92
	v_and_b32_e32 v137, 0xffff0000, v92
	v_lshlrev_b32_e32 v138, 16, v93
	v_and_b32_e32 v139, 0xffff0000, v93
	v_lshlrev_b32_e32 v140, 16, v8
	v_and_b32_e32 v141, 0xffff0000, v8
; __device__ __forceinline__ float bflo(unsigned w) { return __uint_as_float(w << 16); }
; __device__ __forceinline__ float bfhi(unsigned w) { return __uint_as_float(w & 0xffff0000u); }
; __device__ __forceinline__ unsigned cvt_pk_bf16(float lo, float hi) { unsigned r; asm volatile("v_cvt_pk_bf16_f32 %0, %1, %2" : "=v"(r) : "v"(lo), "v"(hi)); return r; }
; __device__ __forceinline__ void prep_phase(const Params& p) {
;     ...
;     for (int t0 = (blockIdx.x * 8 + wid) * 16; t0 < NTOK; t0 += gridDim.x * 8 * 16) {
;     ...
;             for (int i = 0; i < 16; ++i) {
;                 const bool hn = (tt0 + i) < SEQ - 1; const u16* zn = zc + (size_t)(i + 1) * 3328;
;                 const Z16 vn = hn ? ldz(zn + 2048 + c) : zz(); const u32x2 ln = hn ? *(const u32x2*)(zn + cl) : (u32x2){0u, 0u};
;                 float v[16]; mix16(vp, vc, vn, mpv, mnv, v);
;                 st16bf(V + (size_t)(t0 + i) * RW + c, v);
;                 const float z4[4] = {bflo(lc.x), bfhi(lc.x), bflo(lc.y), bfhi(lc.y)}, p4[4] = {bflo(lp.x), bfhi(lp.x), bflo(lp.y), bfhi(lp.y)}, n4[4] = {bflo(ln.x), bfhi(ln.x), bflo(ln.y), bfhi(ln.y)};
;                 float o4[4];
; #pragma unroll
;                 for (int j = 0; j < 4; ++j) { const float sft = z4[j] + la[j] * (p4[j] - z4[j]) + lb[j] * (n4[j] - z4[j]); o4[j] = (lane < 32) ? tanhf(sft) : sft; }
;                 u32x2 w; w.x = cvt_pk_bf16(o4[0], o4[1]); w.y = cvt_pk_bf16(o4[2], o4[3]); *(u32x2*)(AL + (size_t)(t0 + i) * 256 + alc) = w;
;                 vp = vc; vc = vn; lp = lc; lc = ln;
	v_lshlrev_b32_e32 v142, 16, v9
	v_and_b32_e32 v143, 0xffff0000, v9
	v_lshlrev_b32_e32 v216, 16, v20
	v_and_b32_e32 v217, 0xffff0000, v20
	v_lshlrev_b32_e32 v218, 16, v21
	v_and_b32_e32 v219, 0xffff0000, v21
	v_pk_add_f32 v[224:225], v[144:145], v[160:161] neg_lo:[0,1] neg_hi:[0,1]
	v_pk_add_f32 v[226:227], v[176:177], v[160:161] neg_lo:[0,1] neg_hi:[0,1]
	v_pk_fma_f32 v[192:193], v[96:97], v[224:225], v[160:161]
	v_pk_fma_f32 v[192:193], v[112:113], v[226:227], v[192:193]
	v_pk_add_f32 v[224:225], v[146:147], v[162:163] neg_lo:[0,1] neg_hi:[0,1]
	v_pk_add_f32 v[226:227], v[178:179], v[162:163] neg_lo:[0,1] neg_hi:[0,1]
	v_pk_fma_f32 v[194:195], v[98:99], v[224:225], v[162:163]
	v_pk_fma_f32 v[194:195], v[114:115], v[226:227], v[194:195]
	v_pk_add_f32 v[224:225], v[148:149], v[164:165] neg_lo:[0,1] neg_hi:[0,1]
	v_pk_add_f32 v[226:227], v[180:181], v[164:165] neg_lo:[0,1] neg_hi:[0,1]
	v_pk_fma_f32 v[196:197], v[100:101], v[224:225], v[164:165]
	v_pk_fma_f32 v[196:197], v[116:117], v[226:227], v[196:197]
	v_pk_add_f32 v[224:225], v[150:151], v[166:167] neg_lo:[0,1] neg_hi:[0,1]
	v_pk_add_f32 v[226:227], v[182:183], v[166:167] neg_lo:[0,1] neg_hi:[0,1]
	v_pk_fma_f32 v[198:199], v[102:103], v[224:225], v[166:167]
	v_pk_fma_f32 v[198:199], v[118:119], v[226:227], v[198:199]
	v_pk_add_f32 v[224:225], v[152:153], v[168:169] neg_lo:[0,1] neg_hi:[0,1]
	v_pk_add_f32 v[226:227], v[184:185], v[168:169] neg_lo:[0,1] neg_hi:[0,1]
	v_pk_fma_f32 v[200:201], v[104:105], v[224:225], v[168:169]
	v_pk_fma_f32 v[200:201], v[120:121], v[226:227], v[200:201]
	v_pk_add_f32 v[224:225], v[154:155], v[170:171] neg_lo:[0,1] neg_hi:[0,1]
	v_pk_add_f32 v[226:227], v[186:187], v[170:171] neg_lo:[0,1] neg_hi:[0,1]
	v_pk_fma_f32 v[202:203], v[106:107], v[224:225], v[170:171]
	v_pk_fma_f32 v[202:203], v[122:123], v[226:227], v[202:203]
	v_pk_add_f32 v[224:225], v[156:157], v[172:173] neg_lo:[0,1] neg_hi:[0,1]
	v_pk_add_f32 v[226:227], v[188:189], v[172:173] neg_lo:[0,1] neg_hi:[0,1]
	v_pk_fma_f32 v[204:205], v[108:109], v[224:225], v[172:173]
	v_pk_fma_f32 v[204:205], v[124:125], v[226:227], v[204:205]
	v_pk_add_f32 v[224:225], v[158:159], v[174:175] neg_lo:[0,1] neg_hi:[0,1]
	v_pk_add_f32 v[226:227], v[190:191], v[174:175] neg_lo:[0,1] neg_hi:[0,1]
	v_pk_fma_f32 v[206:207], v[110:111], v[224:225], v[174:175]
	v_pk_fma_f32 v[206:207], v[126:127], v[226:227], v[206:207]
	v_cvt_pk_bf16_f32 v208, v192, v193
	v_cvt_pk_bf16_f32 v209, v194, v195
	v_cvt_pk_bf16_f32 v210, v196, v197
	v_cvt_pk_bf16_f32 v211, v198, v199
	v_cvt_pk_bf16_f32 v212, v200, v201
	v_cvt_pk_bf16_f32 v213, v202, v203
	v_cvt_pk_bf16_f32 v214, v204, v205
	v_cvt_pk_bf16_f32 v215, v206, v207
	buffer_store_dwordx4 v[208:211], v237, s[68:71], s73 offen offset:0
	buffer_store_dwordx4 v[212:215], v237, s[68:71], s73 offen offset:16
	v_sub_f32_e32 v224, v136, v140
	v_sub_f32_e32 v225, v216, v140
	v_fma_f32 v220, v128, v224, v140
	v_fma_f32 v220, v132, v225, v220
	v_sub_f32_e32 v224, v137, v141
	v_sub_f32_e32 v225, v217, v141
	v_fma_f32 v221, v129, v224, v141
	v_fma_f32 v221, v133, v225, v221
	v_sub_f32_e32 v224, v138, v142
	v_sub_f32_e32 v225, v218, v142
	v_fma_f32 v222, v130, v224, v142
	v_fma_f32 v222, v134, v225, v222
	v_sub_f32_e32 v224, v139, v143
	v_sub_f32_e32 v225, v219, v143
	v_fma_f32 v223, v131, v224, v143
	v_fma_f32 v223, v135, v225, v223
	v_and_b32_e32 v224, 0x7fffffff, v220
	v_mul_f32_e32 v225, 0x4038aa3b, v224
	v_exp_f32_e32 v225, v225
	v_mul_f32_e32 v226, v220, v220
	v_add_f32_e32 v225, 1.0, v225
	v_rcp_f32_e32 v225, v225
	v_mul_f32_e32 v227, 0xbeaaaaab, v226
	v_fma_f32 v225, v225, -2.0, 1.0
	v_fma_f32 v227, v227, v220, v220
	v_bfi_b32 v225, v241, v225, v220
	v_cmp_gt_f32_e32 vcc, 0x3d000000, v224
	s_nop 1
	v_cndmask_b32_e32 v225, v225, v227, vcc
	v_cmp_gt_u32_e32 vcc, 32, v240
	s_nop 1
	v_cndmask_b32_e32 v220, v220, v225, vcc
	v_and_b32_e32 v224, 0x7fffffff, v221
	v_mul_f32_e32 v225, 0x4038aa3b, v224
	v_exp_f32_e32 v225, v225
	v_mul_f32_e32 v226, v221, v221
	v_add_f32_e32 v225, 1.0, v225
	v_rcp_f32_e32 v225, v225
	v_mul_f32_e32 v227, 0xbeaaaaab, v226
	v_fma_f32 v225, v225, -2.0, 1.0
	v_fma_f32 v227, v227, v221, v221
	v_bfi_b32 v225, v241, v225, v221
	v_cmp_gt_f32_e32 vcc, 0x3d000000, v224
	s_nop 1
	v_cndmask_b32_e32 v225, v225, v227, vcc
	v_cmp_gt_u32_e32 vcc, 32, v240
	s_nop 1
	v_cndmask_b32_e32 v221, v221, v225, vcc
	v_and_b32_e32 v224, 0x7fffffff, v222
	v_mul_f32_e32 v225, 0x4038aa3b, v224
	v_exp_f32_e32 v225, v225
	v_mul_f32_e32 v226, v222, v222
	v_add_f32_e32 v225, 1.0, v225
	v_rcp_f32_e32 v225, v225
	v_mul_f32_e32 v227, 0xbeaaaaab, v226
	v_fma_f32 v225, v225, -2.0, 1.0
	v_fma_f32 v227, v227, v222, v222
	v_bfi_b32 v225, v241, v225, v222
	v_cmp_gt_f32_e32 vcc, 0x3d000000, v224
	s_nop 1
	v_cndmask_b32_e32 v225, v225, v227, vcc
	v_cmp_gt_u32_e32 vcc, 32, v240
	s_nop 1
	v_cndmask_b32_e32 v222, v222, v225, vcc
	v_and_b32_e32 v224, 0x7fffffff, v223
	v_mul_f32_e32 v225, 0x4038aa3b, v224
	v_exp_f32_e32 v225, v225
	v_mul_f32_e32 v226, v223, v223
	v_add_f32_e32 v225, 1.0, v225
	v_rcp_f32_e32 v225, v225
	v_mul_f32_e32 v227, 0xbeaaaaab, v226
	v_fma_f32 v225, v225, -2.0, 1.0
	v_fma_f32 v227, v227, v223, v223
	v_bfi_b32 v225, v241, v225, v223
	v_cmp_gt_f32_e32 vcc, 0x3d000000, v224
	s_nop 1
	v_cndmask_b32_e32 v225, v225, v227, vcc
	v_cmp_gt_u32_e32 vcc, 32, v240
	s_nop 1
	v_cndmask_b32_e32 v223, v223, v225, vcc
	v_cvt_pk_bf16_f32 v224, v220, v221
	v_cvt_pk_bf16_f32 v225, v222, v223
	buffer_store_dwordx2 v[224:225], v238, s[68:71], s74 offen
	s_waitcnt vmcnt(0)
	s_lshl_b32 s4, s96, 7
	s_add_u32 s0, s0, s4
	s_branch .Lmy_prep_item
